# GEMM loops: the redundant s_waitcnt lgkmcnt(0) heading each compute segment (64 sites) deleted
# speedup vs baseline: 1.0058x; 1.0058x over previous
; #define PG8_STAGE(bufoff, gbase, voff) do { _Pragma("unroll") for (int _i = 0; _i < 2; ++_i) \
;         __builtin_amdgcn_global_load_lds((const unsigned*)((const char*)(gbase) + (voff)[_i]), (LAS unsigned*)(lds + (bufoff) + ldsw + _i * 8192), 16, 0, 0); } while (0)
; #define PG8_LDA(dst, b, h) do { _Pragma("unroll") for (int m = 0; m < 4; ++m) _Pragma("unroll") for (int k = 0; k < 2; ++k) dst[m][k] = *(const LAS bf16x8*)(lds + PG8_SA(b, h) + aoff + m * 2048 + k * 1024); } while (0)
; #define PG8_LDB(dst, b, h) do { _Pragma("unroll") for (int n = 0; n < 2; ++n) _Pragma("unroll") for (int k = 0; k < 2; ++k) dst[n][k] = *(const LAS bf16x8*)(lds + PG8_SB(b, h) + boff + n * 2048 + k * 1024); } while (0)
; #define PG8_MMA(ai, bj, At, Bt) do { __builtin_amdgcn_s_setprio(1); _Pragma("unroll") for (int k = 0; k < 2; ++k) _Pragma("unroll") for (int m = 0; m < 4; ++m) _Pragma("unroll") for (int n = 0; n < 2; ++n) \
;         acc[ai][bj][m][n] = __builtin_amdgcn_mfma_f32_16x16x32_bf16(Bt[n][k], At[m][k], acc[ai][bj][m][n], 0, 0, 0); __builtin_amdgcn_s_setprio(0); } while (0)
; #define PG8_WAIT_V(n) asm volatile("s_waitcnt vmcnt(" #n ")" ::: "memory")
; #define PG8_WAIT_L(n) asm volatile("s_waitcnt lgkmcnt(" #n ")" ::: "memory")
; #define PG8_BAR __builtin_amdgcn_s_barrier()
; #define PG8_SCHED __builtin_amdgcn_sched_barrier(0)
; template <class Epi, bool ALIGN_EPI>
; __device__ __forceinline__ void gemm_phase(LAS unsigned char* lds, const Gemm g, const StaticOrder& S, const Epi& E, const int tid) {
;     ...
;         for (int t = 0; t < nt; t += 2) {
;             const bool last = (t == nt - 2);
;             const char* a1 = cA + (size_t)(t + 1) * kstep;
;             const char* a2 = last ? nA : cA + (size_t)(t + 2) * kstep; const char* b2 = last ? nB : cB + (size_t)(t + 2) * kstep;
;             const char* a3 = a2 + kstep; const char* b3 = b2 + kstep;
;             PG8_LDB(B0, 0, 0); PG8_LDB(B1, 0, 1); PG8_SCHED; PG8_LDA(At, 0, 0); PG8_STAGE(PG8_SA(1, 1), a1 + hA, voffA);
;             PG8_WAIT_V(8); PG8_WAIT_L(0); PG8_BAR; PG8_MMA(0, 0, At, B0); PG8_MMA(0, 1, At, B1); PG8_BAR; PG8_SCHED;
;             PG8_LDA(At, 0, 1); PG8_STAGE(PG8_SB(0, 0), b2, voffB); PG8_STAGE(PG8_SB(0, 1), b2 + hB, voffB); PG8_STAGE(PG8_SA(0, 0), a2, voffA);
;             PG8_WAIT_V(8); PG8_WAIT_L(0); PG8_BAR; PG8_MMA(1, 0, At, B0); PG8_MMA(1, 1, At, B1); PG8_BAR; PG8_SCHED;
.LBB0_234:
	s_andn2_b64 vcc, exec, s[36:37]
	s_waitcnt lgkmcnt(0)
	s_cbranch_vccnz .LBB0_238
	s_add_u32 s12, s46, 0x100
	v_lshl_add_u64 v[128:129], v[128:129], 0, s[92:93]
	s_addc_u32 s13, s47, 0
	s_mov_b32 s46, 0
	s_add_i32 s47, s46, 2
	s_cmp_eq_u32 s60, s46
	s_cselect_b64 vcc, -1, 0
	s_cselect_b32 s71, s15, s13
	s_cselect_b32 s70, s14, s12
	s_add_i32 s46, 0, 0x14000
	v_lshl_add_u64 v[130:131], v[128:129], 0, s[92:93]
	v_add_u32_e32 v142, s33, v218
	v_add_u32_e32 v166, s46, v218
	v_cndmask_b32_e32 v159, v131, v165, vcc
	v_cndmask_b32_e32 v158, v130, v164, vcc
	ds_read_b128 v[130:133], v142
	ds_read_b128 v[134:137], v142 offset:1024
	ds_read_b128 v[138:141], v142 offset:2048
	ds_read_b128 v[142:145], v142 offset:3072
	ds_read_b128 v[146:149], v166
	ds_read_b128 v[150:153], v166 offset:1024
	ds_read_b128 v[154:157], v166 offset:2048
	ds_read_b128 v[186:189], v166 offset:3072
	v_lshl_add_u64 v[166:167], v[128:129], 0, v[160:161]
	s_add_i32 m0, s53, 0xc000
	ds_read_b128 v[190:193], v219
	ds_read_b128 v[194:197], v219 offset:1024
	ds_read_b128 v[198:201], v219 offset:2048
	ds_read_b128 v[202:205], v219 offset:3072
	ds_read_b128 v[206:209], v219 offset:4096
	ds_read_b128 v[210:213], v219 offset:5120
	ds_read_b128 v[240:243], v219 offset:6144
	ds_read_b128 v[244:247], v219 offset:7168
	global_load_lds_dwordx4 v[166:167], off
	v_lshl_add_u64 v[166:167], v[128:129], 0, v[162:163]
	s_add_i32 m0, s53, 0xe000
	s_nop 0
	global_load_lds_dwordx4 v[166:167], off
	s_waitcnt vmcnt(8)
	s_waitcnt lgkmcnt(0)
	s_barrier
	s_setprio 1
	v_mfma_f32_16x16x32_bf16 v[120:123], v[130:133], v[190:193], 0
	v_mfma_f32_16x16x32_bf16 v[124:127], v[138:141], v[190:193], 0
	v_mfma_f32_16x16x32_bf16 v[108:111], v[130:133], v[198:201], 0
	v_mfma_f32_16x16x32_bf16 v[104:107], v[138:141], v[198:201], 0
	v_mfma_f32_16x16x32_bf16 v[92:95], v[130:133], v[206:209], 0
	v_mfma_f32_16x16x32_bf16 v[88:91], v[138:141], v[206:209], 0
	v_mfma_f32_16x16x32_bf16 v[76:79], v[130:133], v[240:243], 0
	v_mfma_f32_16x16x32_bf16 v[72:75], v[138:141], v[240:243], 0
	v_mfma_f32_16x16x32_bf16 v[120:123], v[134:137], v[194:197], v[120:123]
	v_mfma_f32_16x16x32_bf16 v[124:127], v[142:145], v[194:197], v[124:127]
	v_mfma_f32_16x16x32_bf16 v[108:111], v[134:137], v[202:205], v[108:111]
	v_mfma_f32_16x16x32_bf16 v[104:107], v[142:145], v[202:205], v[104:107]
	v_mfma_f32_16x16x32_bf16 v[92:95], v[134:137], v[210:213], v[92:95]
	v_mfma_f32_16x16x32_bf16 v[88:91], v[142:145], v[210:213], v[88:91]
	v_mfma_f32_16x16x32_bf16 v[76:79], v[134:137], v[244:247], v[76:79]
	v_mfma_f32_16x16x32_bf16 v[72:75], v[142:145], v[244:247], v[72:75]
	s_setprio 0
	s_setprio 1
	v_mfma_f32_16x16x32_bf16 v[116:119], v[146:149], v[190:193], 0
	v_mfma_f32_16x16x32_bf16 v[112:115], v[154:157], v[190:193], 0
	v_mfma_f32_16x16x32_bf16 v[100:103], v[146:149], v[198:201], 0
	v_mfma_f32_16x16x32_bf16 v[96:99], v[154:157], v[198:201], 0
	v_mfma_f32_16x16x32_bf16 v[84:87], v[146:149], v[206:209], 0
	v_mfma_f32_16x16x32_bf16 v[80:83], v[154:157], v[206:209], 0
	v_mfma_f32_16x16x32_bf16 v[68:71], v[146:149], v[240:243], 0
	v_mfma_f32_16x16x32_bf16 v[64:67], v[154:157], v[240:243], 0
	v_mfma_f32_16x16x32_bf16 v[116:119], v[150:153], v[194:197], v[116:119]
	v_mfma_f32_16x16x32_bf16 v[112:115], v[186:189], v[194:197], v[112:115]
	v_mfma_f32_16x16x32_bf16 v[100:103], v[150:153], v[202:205], v[100:103]
	v_mfma_f32_16x16x32_bf16 v[96:99], v[186:189], v[202:205], v[96:99]
	v_mfma_f32_16x16x32_bf16 v[84:87], v[150:153], v[210:213], v[84:87]
	v_mfma_f32_16x16x32_bf16 v[80:83], v[186:189], v[210:213], v[80:83]
	v_mfma_f32_16x16x32_bf16 v[68:71], v[150:153], v[244:247], v[68:71]
	v_mfma_f32_16x16x32_bf16 v[64:67], v[186:189], v[244:247], v[64:67]
	s_setprio 0
	s_barrier
	s_add_i32 s72, s33, s52
	v_lshl_add_u64 v[166:167], s[70:71], 0, v[180:181]
	s_mov_b32 m0, s72
	ds_read_b128 v[190:193], v219 offset:16384
	ds_read_b128 v[194:197], v219 offset:17408
	ds_read_b128 v[198:201], v219 offset:18432
	ds_read_b128 v[202:205], v219 offset:19456
	ds_read_b128 v[206:209], v219 offset:20480
	ds_read_b128 v[210:213], v219 offset:21504
	ds_read_b128 v[240:243], v219 offset:22528
	ds_read_b128 v[244:247], v219 offset:23552
	global_load_lds_dwordx4 v[166:167], off
	s_add_i32 m0, s72, 0x2000
	v_lshl_add_u64 v[214:215], s[70:71], 0, v[184:185]
	s_add_u32 s70, s70, s49
	s_addc_u32 s71, s71, 0
	s_add_i32 s46, s46, s52
	global_load_lds_dwordx4 v[214:215], off
	v_lshl_add_u64 v[220:221], s[70:71], 0, v[180:181]
	s_mov_b32 m0, s46
	v_lshl_add_u64 v[226:227], s[70:71], 0, v[184:185]
	global_load_lds_dwordx4 v[220:221], off
	s_add_i32 m0, s46, 0x2000
	v_lshl_add_u64 v[248:249], v[158:159], 0, v[178:179]
	global_load_lds_dwordx4 v[226:227], off
	s_mov_b32 m0, s53
	v_lshl_add_u64 v[250:251], v[158:159], 0, v[182:183]
	global_load_lds_dwordx4 v[248:249], off
	s_mov_b32 m0, s54
	s_nop 0
	global_load_lds_dwordx4 v[250:251], off
	s_waitcnt vmcnt(8)
	s_waitcnt lgkmcnt(0)
	s_barrier
; #define PG8_STAGE(bufoff, gbase, voff) do { _Pragma("unroll") for (int _i = 0; _i < 2; ++_i) \
;         __builtin_amdgcn_global_load_lds((const unsigned*)((const char*)(gbase) + (voff)[_i]), (LAS unsigned*)(lds + (bufoff) + ldsw + _i * 8192), 16, 0, 0); } while (0)
; #define PG8_LDA(dst, b, h) do { _Pragma("unroll") for (int m = 0; m < 4; ++m) _Pragma("unroll") for (int k = 0; k < 2; ++k) dst[m][k] = *(const LAS bf16x8*)(lds + PG8_SA(b, h) + aoff + m * 2048 + k * 1024); } while (0)
; #define PG8_LDB(dst, b, h) do { _Pragma("unroll") for (int n = 0; n < 2; ++n) _Pragma("unroll") for (int k = 0; k < 2; ++k) dst[n][k] = *(const LAS bf16x8*)(lds + PG8_SB(b, h) + boff + n * 2048 + k * 1024); } while (0)
; #define PG8_MMA(ai, bj, At, Bt) do { __builtin_amdgcn_s_setprio(1); _Pragma("unroll") for (int k = 0; k < 2; ++k) _Pragma("unroll") for (int m = 0; m < 4; ++m) _Pragma("unroll") for (int n = 0; n < 2; ++n) \
;         acc[ai][bj][m][n] = __builtin_amdgcn_mfma_f32_16x16x32_bf16(Bt[n][k], At[m][k], acc[ai][bj][m][n], 0, 0, 0); __builtin_amdgcn_s_setprio(0); } while (0)
; #define PG8_WAIT_V(n) asm volatile("s_waitcnt vmcnt(" #n ")" ::: "memory")
; #define PG8_WAIT_L(n) asm volatile("s_waitcnt lgkmcnt(" #n ")" ::: "memory")
; #define PG8_BAR __builtin_amdgcn_s_barrier()
; #define PG8_SCHED __builtin_amdgcn_sched_barrier(0)
; template <class Epi, bool ALIGN_EPI>
; __device__ __forceinline__ void gemm_phase(LAS unsigned char* lds, const Gemm g, const StaticOrder& S, const Epi& E, const int tid) {
;     ...
;             PG8_WAIT_V(8); PG8_WAIT_L(0); PG8_BAR; PG8_MMA(1, 0, At, B0); PG8_MMA(1, 1, At, B1); PG8_BAR; PG8_SCHED;
;             PG8_LDB(B0, 1, 0); PG8_LDB(B1, 1, 1); PG8_SCHED; PG8_LDA(At, 1, 0); PG8_STAGE(PG8_SA(0, 1), a2 + hA, voffA);
;             PG8_WAIT_V(8); PG8_WAIT_L(0); PG8_BAR; PG8_MMA(0, 0, At, B0); PG8_MMA(0, 1, At, B1); PG8_BAR; PG8_SCHED;
;             PG8_LDA(At, 1, 1); PG8_STAGE(PG8_SB(1, 0), b3, voffB); PG8_STAGE(PG8_SB(1, 1), b3 + hB, voffB); PG8_STAGE(PG8_SA(1, 0), a3, voffA);
;             PG8_WAIT_V(8); PG8_WAIT_L(0); PG8_BAR; PG8_MMA(1, 0, At, B0); PG8_MMA(1, 1, At, B1); PG8_BAR; PG8_SCHED;
	s_setprio 1
	v_mfma_f32_16x16x32_bf16 v[60:63], v[130:133], v[190:193], 0
	v_mfma_f32_16x16x32_bf16 v[56:59], v[138:141], v[190:193], 0
	v_mfma_f32_16x16x32_bf16 v[44:47], v[130:133], v[198:201], 0
	v_mfma_f32_16x16x32_bf16 v[40:43], v[138:141], v[198:201], 0
	v_mfma_f32_16x16x32_bf16 v[28:31], v[130:133], v[206:209], 0
	v_mfma_f32_16x16x32_bf16 v[24:27], v[138:141], v[206:209], 0
	v_mfma_f32_16x16x32_bf16 v[12:15], v[130:133], v[240:243], 0
	v_mfma_f32_16x16x32_bf16 v[8:11], v[138:141], v[240:243], 0
	v_mfma_f32_16x16x32_bf16 v[60:63], v[134:137], v[194:197], v[60:63]
	v_mfma_f32_16x16x32_bf16 v[56:59], v[142:145], v[194:197], v[56:59]
	v_mfma_f32_16x16x32_bf16 v[44:47], v[134:137], v[202:205], v[44:47]
	v_mfma_f32_16x16x32_bf16 v[40:43], v[142:145], v[202:205], v[40:43]
	v_mfma_f32_16x16x32_bf16 v[28:31], v[134:137], v[210:213], v[28:31]
	v_mfma_f32_16x16x32_bf16 v[24:27], v[142:145], v[210:213], v[24:27]
	v_mfma_f32_16x16x32_bf16 v[12:15], v[134:137], v[244:247], v[12:15]
	v_mfma_f32_16x16x32_bf16 v[8:11], v[142:145], v[244:247], v[8:11]
	s_setprio 0
	s_setprio 1
	v_mfma_f32_16x16x32_bf16 v[52:55], v[146:149], v[190:193], 0
	v_mfma_f32_16x16x32_bf16 v[48:51], v[154:157], v[190:193], 0
	v_mfma_f32_16x16x32_bf16 v[36:39], v[146:149], v[198:201], 0
	v_mfma_f32_16x16x32_bf16 v[32:35], v[154:157], v[198:201], 0
	v_mfma_f32_16x16x32_bf16 v[20:23], v[146:149], v[206:209], 0
	v_mfma_f32_16x16x32_bf16 v[16:19], v[154:157], v[206:209], 0
	v_mfma_f32_16x16x32_bf16 v[4:7], v[146:149], v[240:243], 0
	v_mfma_f32_16x16x32_bf16 v[0:3], v[154:157], v[240:243], 0
	v_mfma_f32_16x16x32_bf16 v[52:55], v[150:153], v[194:197], v[52:55]
	v_mfma_f32_16x16x32_bf16 v[48:51], v[186:189], v[194:197], v[48:51]
	v_mfma_f32_16x16x32_bf16 v[36:39], v[150:153], v[202:205], v[36:39]
	v_mfma_f32_16x16x32_bf16 v[32:35], v[186:189], v[202:205], v[32:35]
	v_mfma_f32_16x16x32_bf16 v[20:23], v[150:153], v[210:213], v[20:23]
	v_mfma_f32_16x16x32_bf16 v[16:19], v[186:189], v[210:213], v[16:19]
	v_mfma_f32_16x16x32_bf16 v[4:7], v[150:153], v[244:247], v[4:7]
	v_mfma_f32_16x16x32_bf16 v[0:3], v[186:189], v[244:247], v[0:3]
	s_setprio 0
	s_barrier
	s_add_i32 s46, 0, 0x18000
	s_add_i32 s70, 0, 0x1c000
	v_add_u32_e32 v142, s46, v218
	v_add_u32_e32 v168, s70, v218
	ds_read_b128 v[130:133], v142
	ds_read_b128 v[134:137], v142 offset:1024
	ds_read_b128 v[138:141], v142 offset:2048
	ds_read_b128 v[142:145], v142 offset:3072
	ds_read_b128 v[146:149], v168
	ds_read_b128 v[150:153], v168 offset:1024
	ds_read_b128 v[154:157], v168 offset:2048
	ds_read_b128 v[186:189], v168 offset:3072
	v_lshl_add_u64 v[158:159], v[158:159], 0, s[94:95]
	s_mov_b32 m0, s55
	v_lshl_add_u64 v[252:253], v[158:159], 0, v[178:179]
	ds_read_b128 v[190:193], v219 offset:32768
	ds_read_b128 v[194:197], v219 offset:33792
	ds_read_b128 v[198:201], v219 offset:34816
	ds_read_b128 v[202:205], v219 offset:35840
	ds_read_b128 v[206:209], v219 offset:36864
	ds_read_b128 v[210:213], v219 offset:37888
	ds_read_b128 v[240:243], v219 offset:38912
	ds_read_b128 v[244:247], v219 offset:39936
	global_load_lds_dwordx4 v[252:253], off
	v_lshl_add_u64 v[158:159], v[158:159], 0, v[182:183]
	s_mov_b32 m0, s56
	s_nop 0
	global_load_lds_dwordx4 v[158:159], off
	s_waitcnt vmcnt(8)
	s_waitcnt lgkmcnt(0)
	s_barrier
	s_setprio 1
	v_mfma_f32_16x16x32_bf16 v[120:123], v[130:133], v[190:193], v[120:123]
	v_mfma_f32_16x16x32_bf16 v[124:127], v[138:141], v[190:193], v[124:127]
	v_mfma_f32_16x16x32_bf16 v[108:111], v[130:133], v[198:201], v[108:111]
	v_mfma_f32_16x16x32_bf16 v[104:107], v[138:141], v[198:201], v[104:107]
	v_mfma_f32_16x16x32_bf16 v[92:95], v[130:133], v[206:209], v[92:95]
	v_mfma_f32_16x16x32_bf16 v[88:91], v[138:141], v[206:209], v[88:91]
	v_mfma_f32_16x16x32_bf16 v[76:79], v[130:133], v[240:243], v[76:79]
	v_mfma_f32_16x16x32_bf16 v[72:75], v[138:141], v[240:243], v[72:75]
	v_mfma_f32_16x16x32_bf16 v[120:123], v[134:137], v[194:197], v[120:123]
	v_mfma_f32_16x16x32_bf16 v[124:127], v[142:145], v[194:197], v[124:127]
	v_mfma_f32_16x16x32_bf16 v[108:111], v[134:137], v[202:205], v[108:111]
	v_mfma_f32_16x16x32_bf16 v[104:107], v[142:145], v[202:205], v[104:107]
	v_mfma_f32_16x16x32_bf16 v[92:95], v[134:137], v[210:213], v[92:95]
	v_mfma_f32_16x16x32_bf16 v[88:91], v[142:145], v[210:213], v[88:91]
	v_mfma_f32_16x16x32_bf16 v[76:79], v[134:137], v[244:247], v[76:79]
	v_mfma_f32_16x16x32_bf16 v[72:75], v[142:145], v[244:247], v[72:75]
	s_setprio 0
	s_setprio 1
	v_mfma_f32_16x16x32_bf16 v[116:119], v[146:149], v[190:193], v[116:119]
	v_mfma_f32_16x16x32_bf16 v[112:115], v[154:157], v[190:193], v[112:115]
	v_mfma_f32_16x16x32_bf16 v[100:103], v[146:149], v[198:201], v[100:103]
	v_mfma_f32_16x16x32_bf16 v[96:99], v[154:157], v[198:201], v[96:99]
	v_mfma_f32_16x16x32_bf16 v[84:87], v[146:149], v[206:209], v[84:87]
	v_mfma_f32_16x16x32_bf16 v[80:83], v[154:157], v[206:209], v[80:83]
	v_mfma_f32_16x16x32_bf16 v[68:71], v[146:149], v[240:243], v[68:71]
	v_mfma_f32_16x16x32_bf16 v[64:67], v[154:157], v[240:243], v[64:67]
	v_mfma_f32_16x16x32_bf16 v[116:119], v[150:153], v[194:197], v[116:119]
	v_mfma_f32_16x16x32_bf16 v[112:115], v[186:189], v[194:197], v[112:115]
	v_mfma_f32_16x16x32_bf16 v[100:103], v[150:153], v[202:205], v[100:103]
	v_mfma_f32_16x16x32_bf16 v[96:99], v[186:189], v[202:205], v[96:99]
	v_mfma_f32_16x16x32_bf16 v[84:87], v[150:153], v[210:213], v[84:87]
	v_mfma_f32_16x16x32_bf16 v[80:83], v[186:189], v[210:213], v[80:83]
	v_mfma_f32_16x16x32_bf16 v[68:71], v[150:153], v[244:247], v[68:71]
	v_mfma_f32_16x16x32_bf16 v[64:67], v[186:189], v[244:247], v[64:67]
	s_setprio 0
	s_barrier
; #define PG8_STAGE(bufoff, gbase, voff) do { _Pragma("unroll") for (int _i = 0; _i < 2; ++_i) \
;         __builtin_amdgcn_global_load_lds((const unsigned*)((const char*)(gbase) + (voff)[_i]), (LAS unsigned*)(lds + (bufoff) + ldsw + _i * 8192), 16, 0, 0); } while (0)
; #define PG8_LDA(dst, b, h) do { _Pragma("unroll") for (int m = 0; m < 4; ++m) _Pragma("unroll") for (int k = 0; k < 2; ++k) dst[m][k] = *(const LAS bf16x8*)(lds + PG8_SA(b, h) + aoff + m * 2048 + k * 1024); } while (0)
; #define PG8_LDB(dst, b, h) do { _Pragma("unroll") for (int n = 0; n < 2; ++n) _Pragma("unroll") for (int k = 0; k < 2; ++k) dst[n][k] = *(const LAS bf16x8*)(lds + PG8_SB(b, h) + boff + n * 2048 + k * 1024); } while (0)
; #define PG8_WAIT_V(n) asm volatile("s_waitcnt vmcnt(" #n ")" ::: "memory")
; #define PG8_BAR __builtin_amdgcn_s_barrier()
; template <class Epi, bool ALIGN_EPI>
; __device__ __forceinline__ void gemm_phase(LAS unsigned char* lds, const Gemm g, const StaticOrder& S, const Epi& E, const int tid) {
;     ...
;         for (int t = 0; t < nt; t += 2) {
;             const bool last = (t == nt - 2);
;             const char* a1 = cA + (size_t)(t + 1) * kstep;
;             const char* a2 = last ? nA : cA + (size_t)(t + 2) * kstep; const char* b2 = last ? nB : cB + (size_t)(t + 2) * kstep;
;             const char* a3 = a2 + kstep; const char* b3 = b2 + kstep;
;             PG8_LDB(B0, 0, 0); PG8_LDB(B1, 0, 1); PG8_SCHED; PG8_LDA(At, 0, 0); PG8_STAGE(PG8_SA(1, 1), a1 + hA, voffA);
;             PG8_WAIT_V(8); PG8_WAIT_L(0); PG8_BAR; PG8_MMA(0, 0, At, B0); PG8_MMA(0, 1, At, B1); PG8_BAR; PG8_SCHED;
;             PG8_LDA(At, 0, 1); PG8_STAGE(PG8_SB(0, 0), b2, voffB); PG8_STAGE(PG8_SB(0, 1), b2 + hB, voffB); PG8_STAGE(PG8_SA(0, 0), a2, voffA);
;             PG8_WAIT_V(8); PG8_WAIT_L(0); PG8_BAR; PG8_MMA(1, 0, At, B0); PG8_MMA(1, 1, At, B1); PG8_BAR; PG8_SCHED;
;             PG8_LDB(B0, 1, 0); PG8_LDB(B1, 1, 1); PG8_SCHED; PG8_LDA(At, 1, 0); PG8_STAGE(PG8_SA(0, 1), a2 + hA, voffA);
;             PG8_WAIT_V(8); PG8_WAIT_L(0); PG8_BAR; PG8_MMA(0, 0, At, B0); PG8_MMA(0, 1, At, B1); PG8_BAR; PG8_SCHED;
;             PG8_LDA(At, 1, 1); PG8_STAGE(PG8_SB(1, 0), b3, voffB); PG8_STAGE(PG8_SB(1, 1), b3 + hB, voffB); PG8_STAGE(PG8_SA(1, 0), a3, voffA);
;             PG8_WAIT_V(8); PG8_WAIT_L(0); PG8_BAR; PG8_MMA(1, 0, At, B0); PG8_MMA(1, 1, At, B1); PG8_BAR; PG8_SCHED;
	s_add_i32 s46, s46, s52
	v_lshl_add_u64 v[158:159], v[166:167], 0, s[92:93]
	s_mov_b32 m0, s46
	ds_read_b128 v[190:193], v219 offset:49152
	ds_read_b128 v[194:197], v219 offset:50176
	ds_read_b128 v[198:201], v219 offset:51200
	ds_read_b128 v[202:205], v219 offset:52224
	ds_read_b128 v[206:209], v219 offset:53248
	ds_read_b128 v[210:213], v219 offset:54272
	ds_read_b128 v[240:243], v219 offset:55296
	ds_read_b128 v[244:247], v219 offset:56320
	global_load_lds_dwordx4 v[158:159], off
	v_lshl_add_u64 v[158:159], v[214:215], 0, s[92:93]
	s_add_i32 m0, s46, 0x2000
	s_add_i32 s46, s70, s52
	global_load_lds_dwordx4 v[158:159], off
	v_lshl_add_u64 v[158:159], v[220:221], 0, s[92:93]
	s_mov_b32 m0, s46
	s_nop 0
	global_load_lds_dwordx4 v[158:159], off
	v_lshl_add_u64 v[158:159], v[226:227], 0, s[92:93]
	s_add_i32 m0, s46, 0x2000
	s_nop 0
	global_load_lds_dwordx4 v[158:159], off
	v_lshl_add_u64 v[158:159], v[248:249], 0, s[92:93]
	s_mov_b32 m0, s57
	s_nop 0
	global_load_lds_dwordx4 v[158:159], off
	v_lshl_add_u64 v[158:159], v[250:251], 0, s[92:93]
	s_mov_b32 m0, s58
	s_nop 0
	global_load_lds_dwordx4 v[158:159], off
	s_waitcnt vmcnt(8)
	s_waitcnt lgkmcnt(0)
	s_barrier
	s_setprio 1
	v_mfma_f32_16x16x32_bf16 v[60:63], v[130:133], v[190:193], v[60:63]
	v_mfma_f32_16x16x32_bf16 v[56:59], v[138:141], v[190:193], v[56:59]
	v_mfma_f32_16x16x32_bf16 v[44:47], v[130:133], v[198:201], v[44:47]
	v_mfma_f32_16x16x32_bf16 v[40:43], v[138:141], v[198:201], v[40:43]
	v_mfma_f32_16x16x32_bf16 v[28:31], v[130:133], v[206:209], v[28:31]
	v_mfma_f32_16x16x32_bf16 v[24:27], v[138:141], v[206:209], v[24:27]
	v_mfma_f32_16x16x32_bf16 v[12:15], v[130:133], v[240:243], v[12:15]
	v_mfma_f32_16x16x32_bf16 v[8:11], v[138:141], v[240:243], v[8:11]
	v_mfma_f32_16x16x32_bf16 v[60:63], v[134:137], v[194:197], v[60:63]
	v_mfma_f32_16x16x32_bf16 v[56:59], v[142:145], v[194:197], v[56:59]
	v_mfma_f32_16x16x32_bf16 v[44:47], v[134:137], v[202:205], v[44:47]
	v_mfma_f32_16x16x32_bf16 v[40:43], v[142:145], v[202:205], v[40:43]
	v_mfma_f32_16x16x32_bf16 v[28:31], v[134:137], v[210:213], v[28:31]
	v_mfma_f32_16x16x32_bf16 v[24:27], v[142:145], v[210:213], v[24:27]
	v_mfma_f32_16x16x32_bf16 v[12:15], v[134:137], v[244:247], v[12:15]
	v_mfma_f32_16x16x32_bf16 v[8:11], v[142:145], v[244:247], v[8:11]
	s_setprio 0
	s_setprio 1
	v_mfma_f32_16x16x32_bf16 v[52:55], v[146:149], v[190:193], v[52:55]
	v_mfma_f32_16x16x32_bf16 v[48:51], v[154:157], v[190:193], v[48:51]
	v_mfma_f32_16x16x32_bf16 v[36:39], v[146:149], v[198:201], v[36:39]
	v_mfma_f32_16x16x32_bf16 v[32:35], v[154:157], v[198:201], v[32:35]
	v_mfma_f32_16x16x32_bf16 v[20:23], v[146:149], v[206:209], v[20:23]
	v_mfma_f32_16x16x32_bf16 v[16:19], v[154:157], v[206:209], v[16:19]
	v_mfma_f32_16x16x32_bf16 v[4:7], v[146:149], v[240:243], v[4:7]
	v_mfma_f32_16x16x32_bf16 v[0:3], v[154:157], v[240:243], v[0:3]
	v_mfma_f32_16x16x32_bf16 v[52:55], v[150:153], v[194:197], v[52:55]
	v_mfma_f32_16x16x32_bf16 v[48:51], v[186:189], v[194:197], v[48:51]
	v_mfma_f32_16x16x32_bf16 v[36:39], v[150:153], v[202:205], v[36:39]
	v_mfma_f32_16x16x32_bf16 v[32:35], v[186:189], v[202:205], v[32:35]
	v_mfma_f32_16x16x32_bf16 v[20:23], v[150:153], v[210:213], v[20:23]
	v_mfma_f32_16x16x32_bf16 v[16:19], v[186:189], v[210:213], v[16:19]
	v_mfma_f32_16x16x32_bf16 v[4:7], v[150:153], v[244:247], v[4:7]
	v_mfma_f32_16x16x32_bf16 v[0:3], v[186:189], v[244:247], v[0:3]
	s_setprio 0
	s_barrier
	s_add_u32 s12, s12, 0x100
	s_addc_u32 s13, s13, 0
	v_lshl_add_u64 v[128:129], v[128:129], 0, s[80:81]
	s_cmp_ge_u32 s47, s48
	s_mov_b32 s46, s47
	s_cbranch_scc1 .Lpl1_after
.LBB0_236:
	s_add_i32 s47, s46, 2
	s_cmp_eq_u32 s60, s46
	s_cselect_b64 vcc, -1, 0
	s_cselect_b32 s71, s15, s13
	s_cselect_b32 s70, s14, s12
	s_add_i32 s46, 0, 0x14000
	v_lshl_add_u64 v[130:131], v[128:129], 0, s[92:93]
	v_add_u32_e32 v142, s33, v218
	v_add_u32_e32 v166, s46, v218
	v_cndmask_b32_e32 v159, v131, v165, vcc
	v_cndmask_b32_e32 v158, v130, v164, vcc
	ds_read_b128 v[130:133], v142
	ds_read_b128 v[134:137], v142 offset:1024
	ds_read_b128 v[138:141], v142 offset:2048
	ds_read_b128 v[142:145], v142 offset:3072
	ds_read_b128 v[146:149], v166
	ds_read_b128 v[150:153], v166 offset:1024
	ds_read_b128 v[154:157], v166 offset:2048
	ds_read_b128 v[186:189], v166 offset:3072
	v_lshl_add_u64 v[166:167], v[128:129], 0, v[160:161]
	s_add_i32 m0, s53, 0xc000
	ds_read_b128 v[190:193], v219
	ds_read_b128 v[194:197], v219 offset:1024
	ds_read_b128 v[198:201], v219 offset:2048
	ds_read_b128 v[202:205], v219 offset:3072
	ds_read_b128 v[206:209], v219 offset:4096
	ds_read_b128 v[210:213], v219 offset:5120
	ds_read_b128 v[240:243], v219 offset:6144
	ds_read_b128 v[244:247], v219 offset:7168
	global_load_lds_dwordx4 v[166:167], off
	v_lshl_add_u64 v[166:167], v[128:129], 0, v[162:163]
	s_add_i32 m0, s53, 0xe000
	s_nop 0
	global_load_lds_dwordx4 v[166:167], off
	s_waitcnt vmcnt(8)
	s_waitcnt lgkmcnt(0)
	s_barrier
; #define PG8_STAGE(bufoff, gbase, voff) do { _Pragma("unroll") for (int _i = 0; _i < 2; ++_i) \
;         __builtin_amdgcn_global_load_lds((const unsigned*)((const char*)(gbase) + (voff)[_i]), (LAS unsigned*)(lds + (bufoff) + ldsw + _i * 8192), 16, 0, 0); } while (0)
; #define PG8_LDA(dst, b, h) do { _Pragma("unroll") for (int m = 0; m < 4; ++m) _Pragma("unroll") for (int k = 0; k < 2; ++k) dst[m][k] = *(const LAS bf16x8*)(lds + PG8_SA(b, h) + aoff + m * 2048 + k * 1024); } while (0)
; #define PG8_MMA(ai, bj, At, Bt) do { __builtin_amdgcn_s_setprio(1); _Pragma("unroll") for (int k = 0; k < 2; ++k) _Pragma("unroll") for (int m = 0; m < 4; ++m) _Pragma("unroll") for (int n = 0; n < 2; ++n) \
;         acc[ai][bj][m][n] = __builtin_amdgcn_mfma_f32_16x16x32_bf16(Bt[n][k], At[m][k], acc[ai][bj][m][n], 0, 0, 0); __builtin_amdgcn_s_setprio(0); } while (0)
; #define PG8_WAIT_V(n) asm volatile("s_waitcnt vmcnt(" #n ")" ::: "memory")
; #define PG8_WAIT_L(n) asm volatile("s_waitcnt lgkmcnt(" #n ")" ::: "memory")
; #define PG8_BAR __builtin_amdgcn_s_barrier()
; #define PG8_SCHED __builtin_amdgcn_sched_barrier(0)
; template <class Epi, bool ALIGN_EPI>
; __device__ __forceinline__ void gemm_phase(LAS unsigned char* lds, const Gemm g, const StaticOrder& S, const Epi& E, const int tid) {
;     ...
;             PG8_WAIT_V(8); PG8_WAIT_L(0); PG8_BAR; PG8_MMA(0, 0, At, B0); PG8_MMA(0, 1, At, B1); PG8_BAR; PG8_SCHED;
;             PG8_LDA(At, 0, 1); PG8_STAGE(PG8_SB(0, 0), b2, voffB); PG8_STAGE(PG8_SB(0, 1), b2 + hB, voffB); PG8_STAGE(PG8_SA(0, 0), a2, voffA);
;             PG8_WAIT_V(8); PG8_WAIT_L(0); PG8_BAR; PG8_MMA(1, 0, At, B0); PG8_MMA(1, 1, At, B1); PG8_BAR; PG8_SCHED;
	s_setprio 1
	v_mfma_f32_16x16x32_bf16 v[120:123], v[130:133], v[190:193], v[120:123]
	v_mfma_f32_16x16x32_bf16 v[124:127], v[138:141], v[190:193], v[124:127]
	v_mfma_f32_16x16x32_bf16 v[108:111], v[130:133], v[198:201], v[108:111]
	v_mfma_f32_16x16x32_bf16 v[104:107], v[138:141], v[198:201], v[104:107]
	v_mfma_f32_16x16x32_bf16 v[92:95], v[130:133], v[206:209], v[92:95]
	v_mfma_f32_16x16x32_bf16 v[88:91], v[138:141], v[206:209], v[88:91]
	v_mfma_f32_16x16x32_bf16 v[76:79], v[130:133], v[240:243], v[76:79]
	v_mfma_f32_16x16x32_bf16 v[72:75], v[138:141], v[240:243], v[72:75]
	v_mfma_f32_16x16x32_bf16 v[120:123], v[134:137], v[194:197], v[120:123]
	v_mfma_f32_16x16x32_bf16 v[124:127], v[142:145], v[194:197], v[124:127]
	v_mfma_f32_16x16x32_bf16 v[108:111], v[134:137], v[202:205], v[108:111]
	v_mfma_f32_16x16x32_bf16 v[104:107], v[142:145], v[202:205], v[104:107]
	v_mfma_f32_16x16x32_bf16 v[92:95], v[134:137], v[210:213], v[92:95]
	v_mfma_f32_16x16x32_bf16 v[88:91], v[142:145], v[210:213], v[88:91]
	v_mfma_f32_16x16x32_bf16 v[76:79], v[134:137], v[244:247], v[76:79]
	v_mfma_f32_16x16x32_bf16 v[72:75], v[142:145], v[244:247], v[72:75]
	s_setprio 0
	s_setprio 1
	v_mfma_f32_16x16x32_bf16 v[116:119], v[146:149], v[190:193], v[116:119]
	v_mfma_f32_16x16x32_bf16 v[112:115], v[154:157], v[190:193], v[112:115]
	v_mfma_f32_16x16x32_bf16 v[100:103], v[146:149], v[198:201], v[100:103]
	v_mfma_f32_16x16x32_bf16 v[96:99], v[154:157], v[198:201], v[96:99]
	v_mfma_f32_16x16x32_bf16 v[84:87], v[146:149], v[206:209], v[84:87]
	v_mfma_f32_16x16x32_bf16 v[80:83], v[154:157], v[206:209], v[80:83]
	v_mfma_f32_16x16x32_bf16 v[68:71], v[146:149], v[240:243], v[68:71]
	v_mfma_f32_16x16x32_bf16 v[64:67], v[154:157], v[240:243], v[64:67]
	v_mfma_f32_16x16x32_bf16 v[116:119], v[150:153], v[194:197], v[116:119]
	v_mfma_f32_16x16x32_bf16 v[112:115], v[186:189], v[194:197], v[112:115]
	v_mfma_f32_16x16x32_bf16 v[100:103], v[150:153], v[202:205], v[100:103]
	v_mfma_f32_16x16x32_bf16 v[96:99], v[186:189], v[202:205], v[96:99]
	v_mfma_f32_16x16x32_bf16 v[84:87], v[150:153], v[210:213], v[84:87]
	v_mfma_f32_16x16x32_bf16 v[80:83], v[186:189], v[210:213], v[80:83]
	v_mfma_f32_16x16x32_bf16 v[68:71], v[150:153], v[244:247], v[68:71]
	v_mfma_f32_16x16x32_bf16 v[64:67], v[186:189], v[244:247], v[64:67]
	s_setprio 0
	s_barrier
	s_add_i32 s72, s33, s52
	v_lshl_add_u64 v[166:167], s[70:71], 0, v[180:181]
	s_mov_b32 m0, s72
	ds_read_b128 v[190:193], v219 offset:16384
	ds_read_b128 v[194:197], v219 offset:17408
	ds_read_b128 v[198:201], v219 offset:18432
	ds_read_b128 v[202:205], v219 offset:19456
	ds_read_b128 v[206:209], v219 offset:20480
	ds_read_b128 v[210:213], v219 offset:21504
	ds_read_b128 v[240:243], v219 offset:22528
	ds_read_b128 v[244:247], v219 offset:23552
	global_load_lds_dwordx4 v[166:167], off
	s_add_i32 m0, s72, 0x2000
	v_lshl_add_u64 v[214:215], s[70:71], 0, v[184:185]
	s_add_u32 s70, s70, s49
	s_addc_u32 s71, s71, 0
	s_add_i32 s46, s46, s52
	global_load_lds_dwordx4 v[214:215], off
	v_lshl_add_u64 v[220:221], s[70:71], 0, v[180:181]
	s_mov_b32 m0, s46
	v_lshl_add_u64 v[226:227], s[70:71], 0, v[184:185]
	global_load_lds_dwordx4 v[220:221], off
	s_add_i32 m0, s46, 0x2000
	v_lshl_add_u64 v[248:249], v[158:159], 0, v[178:179]
	global_load_lds_dwordx4 v[226:227], off
	s_mov_b32 m0, s53
	v_lshl_add_u64 v[250:251], v[158:159], 0, v[182:183]
	global_load_lds_dwordx4 v[248:249], off
	s_mov_b32 m0, s54
	s_nop 0
	global_load_lds_dwordx4 v[250:251], off
	s_waitcnt vmcnt(8)
	s_waitcnt lgkmcnt(0)
	s_barrier
	s_setprio 1
	v_mfma_f32_16x16x32_bf16 v[60:63], v[130:133], v[190:193], v[60:63]
	v_mfma_f32_16x16x32_bf16 v[56:59], v[138:141], v[190:193], v[56:59]
	v_mfma_f32_16x16x32_bf16 v[44:47], v[130:133], v[198:201], v[44:47]
	v_mfma_f32_16x16x32_bf16 v[40:43], v[138:141], v[198:201], v[40:43]
	v_mfma_f32_16x16x32_bf16 v[28:31], v[130:133], v[206:209], v[28:31]
	v_mfma_f32_16x16x32_bf16 v[24:27], v[138:141], v[206:209], v[24:27]
	v_mfma_f32_16x16x32_bf16 v[12:15], v[130:133], v[240:243], v[12:15]
	v_mfma_f32_16x16x32_bf16 v[8:11], v[138:141], v[240:243], v[8:11]
	v_mfma_f32_16x16x32_bf16 v[60:63], v[134:137], v[194:197], v[60:63]
	v_mfma_f32_16x16x32_bf16 v[56:59], v[142:145], v[194:197], v[56:59]
	v_mfma_f32_16x16x32_bf16 v[44:47], v[134:137], v[202:205], v[44:47]
	v_mfma_f32_16x16x32_bf16 v[40:43], v[142:145], v[202:205], v[40:43]
	v_mfma_f32_16x16x32_bf16 v[28:31], v[134:137], v[210:213], v[28:31]
	v_mfma_f32_16x16x32_bf16 v[24:27], v[142:145], v[210:213], v[24:27]
	v_mfma_f32_16x16x32_bf16 v[12:15], v[134:137], v[244:247], v[12:15]
	v_mfma_f32_16x16x32_bf16 v[8:11], v[142:145], v[244:247], v[8:11]
	s_setprio 0
	s_setprio 1
	v_mfma_f32_16x16x32_bf16 v[52:55], v[146:149], v[190:193], v[52:55]
	v_mfma_f32_16x16x32_bf16 v[48:51], v[154:157], v[190:193], v[48:51]
	v_mfma_f32_16x16x32_bf16 v[36:39], v[146:149], v[198:201], v[36:39]
	v_mfma_f32_16x16x32_bf16 v[32:35], v[154:157], v[198:201], v[32:35]
	v_mfma_f32_16x16x32_bf16 v[20:23], v[146:149], v[206:209], v[20:23]
	v_mfma_f32_16x16x32_bf16 v[16:19], v[154:157], v[206:209], v[16:19]
	v_mfma_f32_16x16x32_bf16 v[4:7], v[146:149], v[240:243], v[4:7]
	v_mfma_f32_16x16x32_bf16 v[0:3], v[154:157], v[240:243], v[0:3]
	v_mfma_f32_16x16x32_bf16 v[52:55], v[150:153], v[194:197], v[52:55]
	v_mfma_f32_16x16x32_bf16 v[48:51], v[186:189], v[194:197], v[48:51]
	v_mfma_f32_16x16x32_bf16 v[36:39], v[150:153], v[202:205], v[36:39]
	v_mfma_f32_16x16x32_bf16 v[32:35], v[186:189], v[202:205], v[32:35]
	v_mfma_f32_16x16x32_bf16 v[20:23], v[150:153], v[210:213], v[20:23]
	v_mfma_f32_16x16x32_bf16 v[16:19], v[186:189], v[210:213], v[16:19]
	v_mfma_f32_16x16x32_bf16 v[4:7], v[150:153], v[244:247], v[4:7]
	v_mfma_f32_16x16x32_bf16 v[0:3], v[186:189], v[244:247], v[0:3]
	s_setprio 0
	s_barrier
; #define PG8_STAGE(bufoff, gbase, voff) do { _Pragma("unroll") for (int _i = 0; _i < 2; ++_i) \
;         __builtin_amdgcn_global_load_lds((const unsigned*)((const char*)(gbase) + (voff)[_i]), (LAS unsigned*)(lds + (bufoff) + ldsw + _i * 8192), 16, 0, 0); } while (0)
; #define PG8_LDA(dst, b, h) do { _Pragma("unroll") for (int m = 0; m < 4; ++m) _Pragma("unroll") for (int k = 0; k < 2; ++k) dst[m][k] = *(const LAS bf16x8*)(lds + PG8_SA(b, h) + aoff + m * 2048 + k * 1024); } while (0)
; #define PG8_LDB(dst, b, h) do { _Pragma("unroll") for (int n = 0; n < 2; ++n) _Pragma("unroll") for (int k = 0; k < 2; ++k) dst[n][k] = *(const LAS bf16x8*)(lds + PG8_SB(b, h) + boff + n * 2048 + k * 1024); } while (0)
; #define PG8_MMA(ai, bj, At, Bt) do { __builtin_amdgcn_s_setprio(1); _Pragma("unroll") for (int k = 0; k < 2; ++k) _Pragma("unroll") for (int m = 0; m < 4; ++m) _Pragma("unroll") for (int n = 0; n < 2; ++n) \
;         acc[ai][bj][m][n] = __builtin_amdgcn_mfma_f32_16x16x32_bf16(Bt[n][k], At[m][k], acc[ai][bj][m][n], 0, 0, 0); __builtin_amdgcn_s_setprio(0); } while (0)
; #define PG8_WAIT_V(n) asm volatile("s_waitcnt vmcnt(" #n ")" ::: "memory")
; #define PG8_WAIT_L(n) asm volatile("s_waitcnt lgkmcnt(" #n ")" ::: "memory")
; #define PG8_BAR __builtin_amdgcn_s_barrier()
; #define PG8_SCHED __builtin_amdgcn_sched_barrier(0)
; template <class Epi, bool ALIGN_EPI>
; __device__ __forceinline__ void gemm_phase(LAS unsigned char* lds, const Gemm g, const StaticOrder& S, const Epi& E, const int tid) {
;     ...
;             PG8_LDB(B0, 1, 0); PG8_LDB(B1, 1, 1); PG8_SCHED; PG8_LDA(At, 1, 0); PG8_STAGE(PG8_SA(0, 1), a2 + hA, voffA);
;             PG8_WAIT_V(8); PG8_WAIT_L(0); PG8_BAR; PG8_MMA(0, 0, At, B0); PG8_MMA(0, 1, At, B1); PG8_BAR; PG8_SCHED;
	s_add_i32 s46, 0, 0x18000
	s_add_i32 s70, 0, 0x1c000
	v_add_u32_e32 v142, s46, v218
	v_add_u32_e32 v168, s70, v218
	ds_read_b128 v[130:133], v142
	ds_read_b128 v[134:137], v142 offset:1024
	ds_read_b128 v[138:141], v142 offset:2048
	ds_read_b128 v[142:145], v142 offset:3072
	ds_read_b128 v[146:149], v168
	ds_read_b128 v[150:153], v168 offset:1024
	ds_read_b128 v[154:157], v168 offset:2048
	ds_read_b128 v[186:189], v168 offset:3072
	v_lshl_add_u64 v[158:159], v[158:159], 0, s[94:95]
	s_mov_b32 m0, s55
	v_lshl_add_u64 v[252:253], v[158:159], 0, v[178:179]
	ds_read_b128 v[190:193], v219 offset:32768
	ds_read_b128 v[194:197], v219 offset:33792
	ds_read_b128 v[198:201], v219 offset:34816
	ds_read_b128 v[202:205], v219 offset:35840
	ds_read_b128 v[206:209], v219 offset:36864
	ds_read_b128 v[210:213], v219 offset:37888
	ds_read_b128 v[240:243], v219 offset:38912
	ds_read_b128 v[244:247], v219 offset:39936
	global_load_lds_dwordx4 v[252:253], off
	v_lshl_add_u64 v[158:159], v[158:159], 0, v[182:183]
	s_mov_b32 m0, s56
	s_nop 0
	global_load_lds_dwordx4 v[158:159], off
	s_waitcnt vmcnt(8)
	s_waitcnt lgkmcnt(0)
	s_barrier
	s_setprio 1
	v_mfma_f32_16x16x32_bf16 v[120:123], v[130:133], v[190:193], v[120:123]
	v_mfma_f32_16x16x32_bf16 v[124:127], v[138:141], v[190:193], v[124:127]
	v_mfma_f32_16x16x32_bf16 v[108:111], v[130:133], v[198:201], v[108:111]
	v_mfma_f32_16x16x32_bf16 v[104:107], v[138:141], v[198:201], v[104:107]
	v_mfma_f32_16x16x32_bf16 v[92:95], v[130:133], v[206:209], v[92:95]
	v_mfma_f32_16x16x32_bf16 v[88:91], v[138:141], v[206:209], v[88:91]
	v_mfma_f32_16x16x32_bf16 v[76:79], v[130:133], v[240:243], v[76:79]
	v_mfma_f32_16x16x32_bf16 v[72:75], v[138:141], v[240:243], v[72:75]
	v_mfma_f32_16x16x32_bf16 v[120:123], v[134:137], v[194:197], v[120:123]
	v_mfma_f32_16x16x32_bf16 v[124:127], v[142:145], v[194:197], v[124:127]
	v_mfma_f32_16x16x32_bf16 v[108:111], v[134:137], v[202:205], v[108:111]
	v_mfma_f32_16x16x32_bf16 v[104:107], v[142:145], v[202:205], v[104:107]
	v_mfma_f32_16x16x32_bf16 v[92:95], v[134:137], v[210:213], v[92:95]
	v_mfma_f32_16x16x32_bf16 v[88:91], v[142:145], v[210:213], v[88:91]
	v_mfma_f32_16x16x32_bf16 v[76:79], v[134:137], v[244:247], v[76:79]
	v_mfma_f32_16x16x32_bf16 v[72:75], v[142:145], v[244:247], v[72:75]
	s_setprio 0
	s_setprio 1
	v_mfma_f32_16x16x32_bf16 v[116:119], v[146:149], v[190:193], v[116:119]
	v_mfma_f32_16x16x32_bf16 v[112:115], v[154:157], v[190:193], v[112:115]
	v_mfma_f32_16x16x32_bf16 v[100:103], v[146:149], v[198:201], v[100:103]
	v_mfma_f32_16x16x32_bf16 v[96:99], v[154:157], v[198:201], v[96:99]
	v_mfma_f32_16x16x32_bf16 v[84:87], v[146:149], v[206:209], v[84:87]
	v_mfma_f32_16x16x32_bf16 v[80:83], v[154:157], v[206:209], v[80:83]
	v_mfma_f32_16x16x32_bf16 v[68:71], v[146:149], v[240:243], v[68:71]
	v_mfma_f32_16x16x32_bf16 v[64:67], v[154:157], v[240:243], v[64:67]
	v_mfma_f32_16x16x32_bf16 v[116:119], v[150:153], v[194:197], v[116:119]
	v_mfma_f32_16x16x32_bf16 v[112:115], v[186:189], v[194:197], v[112:115]
	v_mfma_f32_16x16x32_bf16 v[100:103], v[150:153], v[202:205], v[100:103]
	v_mfma_f32_16x16x32_bf16 v[96:99], v[186:189], v[202:205], v[96:99]
	v_mfma_f32_16x16x32_bf16 v[84:87], v[150:153], v[210:213], v[84:87]
	v_mfma_f32_16x16x32_bf16 v[80:83], v[186:189], v[210:213], v[80:83]
	v_mfma_f32_16x16x32_bf16 v[68:71], v[150:153], v[244:247], v[68:71]
	v_mfma_f32_16x16x32_bf16 v[64:67], v[186:189], v[244:247], v[64:67]
	s_setprio 0
	s_barrier
; #define PG8_STAGE(bufoff, gbase, voff) do { _Pragma("unroll") for (int _i = 0; _i < 2; ++_i) \
;         __builtin_amdgcn_global_load_lds((const unsigned*)((const char*)(gbase) + (voff)[_i]), (LAS unsigned*)(lds + (bufoff) + ldsw + _i * 8192), 16, 0, 0); } while (0)
; #define PG8_LDA(dst, b, h) do { _Pragma("unroll") for (int m = 0; m < 4; ++m) _Pragma("unroll") for (int k = 0; k < 2; ++k) dst[m][k] = *(const LAS bf16x8*)(lds + PG8_SA(b, h) + aoff + m * 2048 + k * 1024); } while (0)
; #define PG8_MMA(ai, bj, At, Bt) do { __builtin_amdgcn_s_setprio(1); _Pragma("unroll") for (int k = 0; k < 2; ++k) _Pragma("unroll") for (int m = 0; m < 4; ++m) _Pragma("unroll") for (int n = 0; n < 2; ++n) \
;         acc[ai][bj][m][n] = __builtin_amdgcn_mfma_f32_16x16x32_bf16(Bt[n][k], At[m][k], acc[ai][bj][m][n], 0, 0, 0); __builtin_amdgcn_s_setprio(0); } while (0)
; #define PG8_WAIT_V(n) asm volatile("s_waitcnt vmcnt(" #n ")" ::: "memory")
; #define PG8_WAIT_L(n) asm volatile("s_waitcnt lgkmcnt(" #n ")" ::: "memory")
; #define PG8_BAR __builtin_amdgcn_s_barrier()
; #define PG8_SCHED __builtin_amdgcn_sched_barrier(0)
; template <class Epi, bool ALIGN_EPI>
; __device__ __forceinline__ void gemm_phase(LAS unsigned char* lds, const Gemm g, const StaticOrder& S, const Epi& E, const int tid) {
;     ...
;             PG8_LDA(At, 1, 1); PG8_STAGE(PG8_SB(1, 0), b3, voffB); PG8_STAGE(PG8_SB(1, 1), b3 + hB, voffB); PG8_STAGE(PG8_SA(1, 0), a3, voffA);
;             PG8_WAIT_V(8); PG8_WAIT_L(0); PG8_BAR; PG8_MMA(1, 0, At, B0); PG8_MMA(1, 1, At, B1); PG8_BAR; PG8_SCHED;
;         }
	s_add_i32 s46, s46, s52
	v_lshl_add_u64 v[158:159], v[166:167], 0, s[92:93]
	s_mov_b32 m0, s46
	ds_read_b128 v[190:193], v219 offset:49152
	ds_read_b128 v[194:197], v219 offset:50176
	ds_read_b128 v[198:201], v219 offset:51200
	ds_read_b128 v[202:205], v219 offset:52224
	ds_read_b128 v[206:209], v219 offset:53248
	ds_read_b128 v[210:213], v219 offset:54272
	ds_read_b128 v[240:243], v219 offset:55296
	ds_read_b128 v[244:247], v219 offset:56320
	global_load_lds_dwordx4 v[158:159], off
	v_lshl_add_u64 v[158:159], v[214:215], 0, s[92:93]
	s_add_i32 m0, s46, 0x2000
	s_add_i32 s46, s70, s52
	global_load_lds_dwordx4 v[158:159], off
	v_lshl_add_u64 v[158:159], v[220:221], 0, s[92:93]
	s_mov_b32 m0, s46
	s_nop 0
	global_load_lds_dwordx4 v[158:159], off
	v_lshl_add_u64 v[158:159], v[226:227], 0, s[92:93]
	s_add_i32 m0, s46, 0x2000
	s_nop 0
	global_load_lds_dwordx4 v[158:159], off
	v_lshl_add_u64 v[158:159], v[248:249], 0, s[92:93]
	s_mov_b32 m0, s57
	s_nop 0
	global_load_lds_dwordx4 v[158:159], off
	v_lshl_add_u64 v[158:159], v[250:251], 0, s[92:93]
	s_mov_b32 m0, s58
	s_nop 0
	global_load_lds_dwordx4 v[158:159], off
	s_waitcnt vmcnt(8)
	s_waitcnt lgkmcnt(0)
	s_barrier
	s_setprio 1
	v_mfma_f32_16x16x32_bf16 v[60:63], v[130:133], v[190:193], v[60:63]
	v_mfma_f32_16x16x32_bf16 v[56:59], v[138:141], v[190:193], v[56:59]
	v_mfma_f32_16x16x32_bf16 v[44:47], v[130:133], v[198:201], v[44:47]
	v_mfma_f32_16x16x32_bf16 v[40:43], v[138:141], v[198:201], v[40:43]
	v_mfma_f32_16x16x32_bf16 v[28:31], v[130:133], v[206:209], v[28:31]
	v_mfma_f32_16x16x32_bf16 v[24:27], v[138:141], v[206:209], v[24:27]
	v_mfma_f32_16x16x32_bf16 v[12:15], v[130:133], v[240:243], v[12:15]
	v_mfma_f32_16x16x32_bf16 v[8:11], v[138:141], v[240:243], v[8:11]
	v_mfma_f32_16x16x32_bf16 v[60:63], v[134:137], v[194:197], v[60:63]
	v_mfma_f32_16x16x32_bf16 v[56:59], v[142:145], v[194:197], v[56:59]
	v_mfma_f32_16x16x32_bf16 v[44:47], v[134:137], v[202:205], v[44:47]
	v_mfma_f32_16x16x32_bf16 v[40:43], v[142:145], v[202:205], v[40:43]
	v_mfma_f32_16x16x32_bf16 v[28:31], v[134:137], v[210:213], v[28:31]
	v_mfma_f32_16x16x32_bf16 v[24:27], v[142:145], v[210:213], v[24:27]
	v_mfma_f32_16x16x32_bf16 v[12:15], v[134:137], v[244:247], v[12:15]
	v_mfma_f32_16x16x32_bf16 v[8:11], v[142:145], v[244:247], v[8:11]
	s_setprio 0
	s_setprio 1
	v_mfma_f32_16x16x32_bf16 v[52:55], v[146:149], v[190:193], v[52:55]
	v_mfma_f32_16x16x32_bf16 v[48:51], v[154:157], v[190:193], v[48:51]
	v_mfma_f32_16x16x32_bf16 v[36:39], v[146:149], v[198:201], v[36:39]
	v_mfma_f32_16x16x32_bf16 v[32:35], v[154:157], v[198:201], v[32:35]
	v_mfma_f32_16x16x32_bf16 v[20:23], v[146:149], v[206:209], v[20:23]
	v_mfma_f32_16x16x32_bf16 v[16:19], v[154:157], v[206:209], v[16:19]
	v_mfma_f32_16x16x32_bf16 v[4:7], v[146:149], v[240:243], v[4:7]
	v_mfma_f32_16x16x32_bf16 v[0:3], v[154:157], v[240:243], v[0:3]
	v_mfma_f32_16x16x32_bf16 v[52:55], v[150:153], v[194:197], v[52:55]
	v_mfma_f32_16x16x32_bf16 v[48:51], v[186:189], v[194:197], v[48:51]
	v_mfma_f32_16x16x32_bf16 v[36:39], v[150:153], v[202:205], v[36:39]
	v_mfma_f32_16x16x32_bf16 v[32:35], v[186:189], v[202:205], v[32:35]
	v_mfma_f32_16x16x32_bf16 v[20:23], v[150:153], v[210:213], v[20:23]
	v_mfma_f32_16x16x32_bf16 v[16:19], v[186:189], v[210:213], v[16:19]
	v_mfma_f32_16x16x32_bf16 v[4:7], v[150:153], v[244:247], v[4:7]
	v_mfma_f32_16x16x32_bf16 v[0:3], v[186:189], v[244:247], v[0:3]
	s_setprio 0
	s_barrier
	s_add_u32 s12, s12, 0x100
	s_addc_u32 s13, s13, 0
	v_lshl_add_u64 v[128:129], v[128:129], 0, s[80:81]
	s_cmp_ge_u32 s47, s48
	s_mov_b32 s46, s47
	s_cbranch_scc0 .LBB0_236

; #define PG8_STAGE(bufoff, gbase, voff) do { _Pragma("unroll") for (int _i = 0; _i < 2; ++_i) \
;         __builtin_amdgcn_global_load_lds((const unsigned*)((const char*)(gbase) + (voff)[_i]), (LAS unsigned*)(lds + (bufoff) + ldsw + _i * 8192), 16, 0, 0); } while (0)
; #define PG8_LDA(dst, b, h) do { _Pragma("unroll") for (int m = 0; m < 4; ++m) _Pragma("unroll") for (int k = 0; k < 2; ++k) dst[m][k] = *(const LAS bf16x8*)(lds + PG8_SA(b, h) + aoff + m * 2048 + k * 1024); } while (0)
; #define PG8_LDB(dst, b, h) do { _Pragma("unroll") for (int n = 0; n < 2; ++n) _Pragma("unroll") for (int k = 0; k < 2; ++k) dst[n][k] = *(const LAS bf16x8*)(lds + PG8_SB(b, h) + boff + n * 2048 + k * 1024); } while (0)
; #define PG8_MMA(ai, bj, At, Bt) do { __builtin_amdgcn_s_setprio(1); _Pragma("unroll") for (int k = 0; k < 2; ++k) _Pragma("unroll") for (int m = 0; m < 4; ++m) _Pragma("unroll") for (int n = 0; n < 2; ++n) \
;         acc[ai][bj][m][n] = __builtin_amdgcn_mfma_f32_16x16x32_bf16(Bt[n][k], At[m][k], acc[ai][bj][m][n], 0, 0, 0); __builtin_amdgcn_s_setprio(0); } while (0)
; #define PG8_WAIT_V(n) asm volatile("s_waitcnt vmcnt(" #n ")" ::: "memory")
; #define PG8_WAIT_L(n) asm volatile("s_waitcnt lgkmcnt(" #n ")" ::: "memory")
; #define PG8_BAR __builtin_amdgcn_s_barrier()
; #define PG8_SCHED __builtin_amdgcn_sched_barrier(0)
; template <class Epi, bool ALIGN_EPI>
; __device__ __forceinline__ void gemm_phase(LAS unsigned char* lds, const Gemm g, const StaticOrder& S, const Epi& E, const int tid) {
;     ...
;         for (int t = 0; t < nt; t += 2) {
;             const bool last = (t == nt - 2);
;             const char* a1 = cA + (size_t)(t + 1) * kstep;
;             const char* a2 = last ? nA : cA + (size_t)(t + 2) * kstep; const char* b2 = last ? nB : cB + (size_t)(t + 2) * kstep;
;             const char* a3 = a2 + kstep; const char* b3 = b2 + kstep;
;             PG8_LDB(B0, 0, 0); PG8_LDB(B1, 0, 1); PG8_SCHED; PG8_LDA(At, 0, 0); PG8_STAGE(PG8_SA(1, 1), a1 + hA, voffA);
;             PG8_WAIT_V(8); PG8_WAIT_L(0); PG8_BAR; PG8_MMA(0, 0, At, B0); PG8_MMA(0, 1, At, B1); PG8_BAR; PG8_SCHED;
;             PG8_LDA(At, 0, 1); PG8_STAGE(PG8_SB(0, 0), b2, voffB); PG8_STAGE(PG8_SB(0, 1), b2 + hB, voffB); PG8_STAGE(PG8_SA(0, 0), a2, voffA);
;             PG8_WAIT_V(8); PG8_WAIT_L(0); PG8_BAR; PG8_MMA(1, 0, At, B0); PG8_MMA(1, 1, At, B1); PG8_BAR; PG8_SCHED;
.LBB0_272:
	s_andn2_b64 vcc, exec, s[36:37]
	s_cbranch_vccnz .LBB0_276
	s_add_u32 s10, s14, 0x100
	v_lshl_add_u64 v[128:129], v[128:129], 0, s[92:93]
	s_addc_u32 s11, s15, 0
	s_mov_b32 s14, 0
	s_add_i32 s15, s14, 2
	s_cmp_eq_u32 s57, s14
	s_cselect_b64 vcc, -1, 0
	s_cselect_b32 s69, s13, s11
	s_cselect_b32 s68, s12, s10
	s_add_i32 s14, 0, 0x14000
	v_lshl_add_u64 v[130:131], v[128:129], 0, s[92:93]
	v_add_u32_e32 v142, s33, v239
	v_add_u32_e32 v158, s14, v239
	v_cndmask_b32_e32 v167, v131, v191, vcc
	v_cndmask_b32_e32 v166, v130, v190, vcc
	ds_read_b128 v[130:133], v142
	ds_read_b128 v[134:137], v142 offset:1024
	ds_read_b128 v[138:141], v142 offset:2048
	ds_read_b128 v[142:145], v142 offset:3072
	ds_read_b128 v[146:149], v158
	ds_read_b128 v[150:153], v158 offset:1024
	ds_read_b128 v[154:157], v158 offset:2048
	ds_read_b128 v[158:161], v158 offset:3072
	v_lshl_add_u64 v[220:221], v[128:129], 0, v[186:187]
	s_add_i32 m0, s51, 0xc000
	ds_read_b128 v[162:165], v171
	ds_read_b128 v[192:195], v171 offset:1024
	ds_read_b128 v[196:199], v171 offset:2048
	ds_read_b128 v[200:203], v171 offset:3072
	ds_read_b128 v[204:207], v171 offset:4096
	ds_read_b128 v[208:211], v171 offset:5120
	ds_read_b128 v[212:215], v171 offset:6144
	ds_read_b128 v[216:219], v171 offset:7168
	global_load_lds_dwordx4 v[220:221], off
	v_lshl_add_u64 v[220:221], v[128:129], 0, v[188:189]
	s_add_i32 m0, s51, 0xe000
	s_nop 0
	global_load_lds_dwordx4 v[220:221], off
	s_waitcnt vmcnt(8)
	s_waitcnt lgkmcnt(0)
	s_barrier
	s_setprio 1
	v_mfma_f32_16x16x32_bf16 v[124:127], v[130:133], v[162:165], 0
	v_mfma_f32_16x16x32_bf16 v[120:123], v[138:141], v[162:165], 0
	v_mfma_f32_16x16x32_bf16 v[108:111], v[130:133], v[196:199], 0
	v_mfma_f32_16x16x32_bf16 v[104:107], v[138:141], v[196:199], 0
	v_mfma_f32_16x16x32_bf16 v[92:95], v[130:133], v[204:207], 0
	v_mfma_f32_16x16x32_bf16 v[88:91], v[138:141], v[204:207], 0
	v_mfma_f32_16x16x32_bf16 v[76:79], v[130:133], v[212:215], 0
	v_mfma_f32_16x16x32_bf16 v[72:75], v[138:141], v[212:215], 0
	v_mfma_f32_16x16x32_bf16 v[124:127], v[134:137], v[192:195], v[124:127]
	v_mfma_f32_16x16x32_bf16 v[120:123], v[142:145], v[192:195], v[120:123]
	v_mfma_f32_16x16x32_bf16 v[108:111], v[134:137], v[200:203], v[108:111]
	v_mfma_f32_16x16x32_bf16 v[104:107], v[142:145], v[200:203], v[104:107]
	v_mfma_f32_16x16x32_bf16 v[92:95], v[134:137], v[208:211], v[92:95]
	v_mfma_f32_16x16x32_bf16 v[88:91], v[142:145], v[208:211], v[88:91]
	v_mfma_f32_16x16x32_bf16 v[76:79], v[134:137], v[216:219], v[76:79]
	v_mfma_f32_16x16x32_bf16 v[72:75], v[142:145], v[216:219], v[72:75]
	s_setprio 0
	s_setprio 1
	v_mfma_f32_16x16x32_bf16 v[116:119], v[146:149], v[162:165], 0
	v_mfma_f32_16x16x32_bf16 v[112:115], v[154:157], v[162:165], 0
	v_mfma_f32_16x16x32_bf16 v[100:103], v[146:149], v[196:199], 0
	v_mfma_f32_16x16x32_bf16 v[96:99], v[154:157], v[196:199], 0
	v_mfma_f32_16x16x32_bf16 v[84:87], v[146:149], v[204:207], 0
	v_mfma_f32_16x16x32_bf16 v[80:83], v[154:157], v[204:207], 0
	v_mfma_f32_16x16x32_bf16 v[68:71], v[146:149], v[212:215], 0
	v_mfma_f32_16x16x32_bf16 v[64:67], v[154:157], v[212:215], 0
	v_mfma_f32_16x16x32_bf16 v[116:119], v[150:153], v[192:195], v[116:119]
	v_mfma_f32_16x16x32_bf16 v[112:115], v[158:161], v[192:195], v[112:115]
	v_mfma_f32_16x16x32_bf16 v[100:103], v[150:153], v[200:203], v[100:103]
	v_mfma_f32_16x16x32_bf16 v[96:99], v[158:161], v[200:203], v[96:99]
	v_mfma_f32_16x16x32_bf16 v[84:87], v[150:153], v[208:211], v[84:87]
	v_mfma_f32_16x16x32_bf16 v[80:83], v[158:161], v[208:211], v[80:83]
	v_mfma_f32_16x16x32_bf16 v[68:71], v[150:153], v[216:219], v[68:71]
	v_mfma_f32_16x16x32_bf16 v[64:67], v[158:161], v[216:219], v[64:67]
	s_setprio 0
	s_barrier
	s_add_i32 s70, s33, s47
	v_lshl_add_u64 v[220:221], s[68:69], 0, v[180:181]
	s_mov_b32 m0, s70
	ds_read_b128 v[162:165], v171 offset:16384
	ds_read_b128 v[192:195], v171 offset:17408
	ds_read_b128 v[196:199], v171 offset:18432
	ds_read_b128 v[200:203], v171 offset:19456
	ds_read_b128 v[204:207], v171 offset:20480
	ds_read_b128 v[208:211], v171 offset:21504
	ds_read_b128 v[212:215], v171 offset:22528
	ds_read_b128 v[216:219], v171 offset:23552
	global_load_lds_dwordx4 v[220:221], off
	s_add_i32 m0, s70, 0x2000
	v_lshl_add_u64 v[226:227], s[68:69], 0, v[184:185]
	s_add_u32 s68, s68, s49
	s_addc_u32 s69, s69, 0
	s_add_i32 s14, s14, s47
	global_load_lds_dwordx4 v[226:227], off
	v_lshl_add_u64 v[240:241], s[68:69], 0, v[180:181]
	s_mov_b32 m0, s14
	v_lshl_add_u64 v[242:243], s[68:69], 0, v[184:185]
	global_load_lds_dwordx4 v[240:241], off
	s_add_i32 m0, s14, 0x2000
	v_lshl_add_u64 v[244:245], v[166:167], 0, v[178:179]
	global_load_lds_dwordx4 v[242:243], off
	s_mov_b32 m0, s51
	v_lshl_add_u64 v[246:247], v[166:167], 0, v[182:183]
	global_load_lds_dwordx4 v[244:245], off
	s_mov_b32 m0, s52
	s_nop 0
	global_load_lds_dwordx4 v[246:247], off
	s_waitcnt vmcnt(8)
	s_waitcnt lgkmcnt(0)
	s_barrier
; #define PG8_STAGE(bufoff, gbase, voff) do { _Pragma("unroll") for (int _i = 0; _i < 2; ++_i) \
;         __builtin_amdgcn_global_load_lds((const unsigned*)((const char*)(gbase) + (voff)[_i]), (LAS unsigned*)(lds + (bufoff) + ldsw + _i * 8192), 16, 0, 0); } while (0)
; #define PG8_LDA(dst, b, h) do { _Pragma("unroll") for (int m = 0; m < 4; ++m) _Pragma("unroll") for (int k = 0; k < 2; ++k) dst[m][k] = *(const LAS bf16x8*)(lds + PG8_SA(b, h) + aoff + m * 2048 + k * 1024); } while (0)
; #define PG8_LDB(dst, b, h) do { _Pragma("unroll") for (int n = 0; n < 2; ++n) _Pragma("unroll") for (int k = 0; k < 2; ++k) dst[n][k] = *(const LAS bf16x8*)(lds + PG8_SB(b, h) + boff + n * 2048 + k * 1024); } while (0)
; #define PG8_MMA(ai, bj, At, Bt) do { __builtin_amdgcn_s_setprio(1); _Pragma("unroll") for (int k = 0; k < 2; ++k) _Pragma("unroll") for (int m = 0; m < 4; ++m) _Pragma("unroll") for (int n = 0; n < 2; ++n) \
;         acc[ai][bj][m][n] = __builtin_amdgcn_mfma_f32_16x16x32_bf16(Bt[n][k], At[m][k], acc[ai][bj][m][n], 0, 0, 0); __builtin_amdgcn_s_setprio(0); } while (0)
; #define PG8_WAIT_V(n) asm volatile("s_waitcnt vmcnt(" #n ")" ::: "memory")
; #define PG8_WAIT_L(n) asm volatile("s_waitcnt lgkmcnt(" #n ")" ::: "memory")
; #define PG8_BAR __builtin_amdgcn_s_barrier()
; #define PG8_SCHED __builtin_amdgcn_sched_barrier(0)
; template <class Epi, bool ALIGN_EPI>
; __device__ __forceinline__ void gemm_phase(LAS unsigned char* lds, const Gemm g, const StaticOrder& S, const Epi& E, const int tid) {
;     ...
;             PG8_WAIT_V(8); PG8_WAIT_L(0); PG8_BAR; PG8_MMA(1, 0, At, B0); PG8_MMA(1, 1, At, B1); PG8_BAR; PG8_SCHED;
;             PG8_LDB(B0, 1, 0); PG8_LDB(B1, 1, 1); PG8_SCHED; PG8_LDA(At, 1, 0); PG8_STAGE(PG8_SA(0, 1), a2 + hA, voffA);
;             PG8_WAIT_V(8); PG8_WAIT_L(0); PG8_BAR; PG8_MMA(0, 0, At, B0); PG8_MMA(0, 1, At, B1); PG8_BAR; PG8_SCHED;
;             PG8_LDA(At, 1, 1); PG8_STAGE(PG8_SB(1, 0), b3, voffB); PG8_STAGE(PG8_SB(1, 1), b3 + hB, voffB); PG8_STAGE(PG8_SA(1, 0), a3, voffA);
;             PG8_WAIT_V(8); PG8_WAIT_L(0); PG8_BAR; PG8_MMA(1, 0, At, B0); PG8_MMA(1, 1, At, B1); PG8_BAR; PG8_SCHED;
	s_setprio 1
	v_mfma_f32_16x16x32_bf16 v[60:63], v[130:133], v[162:165], 0
	v_mfma_f32_16x16x32_bf16 v[56:59], v[138:141], v[162:165], 0
	v_mfma_f32_16x16x32_bf16 v[44:47], v[130:133], v[196:199], 0
	v_mfma_f32_16x16x32_bf16 v[40:43], v[138:141], v[196:199], 0
	v_mfma_f32_16x16x32_bf16 v[28:31], v[130:133], v[204:207], 0
	v_mfma_f32_16x16x32_bf16 v[24:27], v[138:141], v[204:207], 0
	v_mfma_f32_16x16x32_bf16 v[12:15], v[130:133], v[212:215], 0
	v_mfma_f32_16x16x32_bf16 v[8:11], v[138:141], v[212:215], 0
	v_mfma_f32_16x16x32_bf16 v[60:63], v[134:137], v[192:195], v[60:63]
	v_mfma_f32_16x16x32_bf16 v[56:59], v[142:145], v[192:195], v[56:59]
	v_mfma_f32_16x16x32_bf16 v[44:47], v[134:137], v[200:203], v[44:47]
	v_mfma_f32_16x16x32_bf16 v[40:43], v[142:145], v[200:203], v[40:43]
	v_mfma_f32_16x16x32_bf16 v[28:31], v[134:137], v[208:211], v[28:31]
	v_mfma_f32_16x16x32_bf16 v[24:27], v[142:145], v[208:211], v[24:27]
	v_mfma_f32_16x16x32_bf16 v[12:15], v[134:137], v[216:219], v[12:15]
	v_mfma_f32_16x16x32_bf16 v[8:11], v[142:145], v[216:219], v[8:11]
	s_setprio 0
	s_setprio 1
	v_mfma_f32_16x16x32_bf16 v[52:55], v[146:149], v[162:165], 0
	v_mfma_f32_16x16x32_bf16 v[48:51], v[154:157], v[162:165], 0
	v_mfma_f32_16x16x32_bf16 v[36:39], v[146:149], v[196:199], 0
	v_mfma_f32_16x16x32_bf16 v[32:35], v[154:157], v[196:199], 0
	v_mfma_f32_16x16x32_bf16 v[20:23], v[146:149], v[204:207], 0
	v_mfma_f32_16x16x32_bf16 v[16:19], v[154:157], v[204:207], 0
	v_mfma_f32_16x16x32_bf16 v[4:7], v[146:149], v[212:215], 0
	v_mfma_f32_16x16x32_bf16 v[0:3], v[154:157], v[212:215], 0
	v_mfma_f32_16x16x32_bf16 v[52:55], v[150:153], v[192:195], v[52:55]
	v_mfma_f32_16x16x32_bf16 v[48:51], v[158:161], v[192:195], v[48:51]
	v_mfma_f32_16x16x32_bf16 v[36:39], v[150:153], v[200:203], v[36:39]
	v_mfma_f32_16x16x32_bf16 v[32:35], v[158:161], v[200:203], v[32:35]
	v_mfma_f32_16x16x32_bf16 v[20:23], v[150:153], v[208:211], v[20:23]
	v_mfma_f32_16x16x32_bf16 v[16:19], v[158:161], v[208:211], v[16:19]
	v_mfma_f32_16x16x32_bf16 v[4:7], v[150:153], v[216:219], v[4:7]
	v_mfma_f32_16x16x32_bf16 v[0:3], v[158:161], v[216:219], v[0:3]
	s_setprio 0
	s_barrier
	s_add_i32 s14, 0, 0x18000
	s_add_i32 s68, 0, 0x1c000
	v_add_u32_e32 v142, s14, v239
	v_add_u32_e32 v158, s68, v239
	ds_read_b128 v[130:133], v142
	ds_read_b128 v[134:137], v142 offset:1024
	ds_read_b128 v[138:141], v142 offset:2048
	ds_read_b128 v[142:145], v142 offset:3072
	ds_read_b128 v[146:149], v158
	ds_read_b128 v[150:153], v158 offset:1024
	ds_read_b128 v[154:157], v158 offset:2048
	ds_read_b128 v[158:161], v158 offset:3072
	v_lshl_add_u64 v[166:167], v[166:167], 0, s[94:95]
	s_mov_b32 m0, s53
	v_lshl_add_u64 v[248:249], v[166:167], 0, v[178:179]
	ds_read_b128 v[162:165], v171 offset:32768
	ds_read_b128 v[192:195], v171 offset:33792
	ds_read_b128 v[196:199], v171 offset:34816
	ds_read_b128 v[200:203], v171 offset:35840
	ds_read_b128 v[204:207], v171 offset:36864
	ds_read_b128 v[208:211], v171 offset:37888
	ds_read_b128 v[212:215], v171 offset:38912
	ds_read_b128 v[216:219], v171 offset:39936
	global_load_lds_dwordx4 v[248:249], off
	v_lshl_add_u64 v[166:167], v[166:167], 0, v[182:183]
	s_mov_b32 m0, s54
	s_nop 0
	global_load_lds_dwordx4 v[166:167], off
	s_waitcnt vmcnt(8)
	s_waitcnt lgkmcnt(0)
	s_barrier
	s_setprio 1
	v_mfma_f32_16x16x32_bf16 v[124:127], v[130:133], v[162:165], v[124:127]
	v_mfma_f32_16x16x32_bf16 v[120:123], v[138:141], v[162:165], v[120:123]
	v_mfma_f32_16x16x32_bf16 v[108:111], v[130:133], v[196:199], v[108:111]
	v_mfma_f32_16x16x32_bf16 v[104:107], v[138:141], v[196:199], v[104:107]
	v_mfma_f32_16x16x32_bf16 v[92:95], v[130:133], v[204:207], v[92:95]
	v_mfma_f32_16x16x32_bf16 v[88:91], v[138:141], v[204:207], v[88:91]
	v_mfma_f32_16x16x32_bf16 v[76:79], v[130:133], v[212:215], v[76:79]
	v_mfma_f32_16x16x32_bf16 v[72:75], v[138:141], v[212:215], v[72:75]
	v_mfma_f32_16x16x32_bf16 v[124:127], v[134:137], v[192:195], v[124:127]
	v_mfma_f32_16x16x32_bf16 v[120:123], v[142:145], v[192:195], v[120:123]
	v_mfma_f32_16x16x32_bf16 v[108:111], v[134:137], v[200:203], v[108:111]
	v_mfma_f32_16x16x32_bf16 v[104:107], v[142:145], v[200:203], v[104:107]
	v_mfma_f32_16x16x32_bf16 v[92:95], v[134:137], v[208:211], v[92:95]
	v_mfma_f32_16x16x32_bf16 v[88:91], v[142:145], v[208:211], v[88:91]
	v_mfma_f32_16x16x32_bf16 v[76:79], v[134:137], v[216:219], v[76:79]
	v_mfma_f32_16x16x32_bf16 v[72:75], v[142:145], v[216:219], v[72:75]
	s_setprio 0
	s_setprio 1
	v_mfma_f32_16x16x32_bf16 v[116:119], v[146:149], v[162:165], v[116:119]
	v_mfma_f32_16x16x32_bf16 v[112:115], v[154:157], v[162:165], v[112:115]
	v_mfma_f32_16x16x32_bf16 v[100:103], v[146:149], v[196:199], v[100:103]
	v_mfma_f32_16x16x32_bf16 v[96:99], v[154:157], v[196:199], v[96:99]
	v_mfma_f32_16x16x32_bf16 v[84:87], v[146:149], v[204:207], v[84:87]
	v_mfma_f32_16x16x32_bf16 v[80:83], v[154:157], v[204:207], v[80:83]
	v_mfma_f32_16x16x32_bf16 v[68:71], v[146:149], v[212:215], v[68:71]
	v_mfma_f32_16x16x32_bf16 v[64:67], v[154:157], v[212:215], v[64:67]
	v_mfma_f32_16x16x32_bf16 v[116:119], v[150:153], v[192:195], v[116:119]
	v_mfma_f32_16x16x32_bf16 v[112:115], v[158:161], v[192:195], v[112:115]
	v_mfma_f32_16x16x32_bf16 v[100:103], v[150:153], v[200:203], v[100:103]
	v_mfma_f32_16x16x32_bf16 v[96:99], v[158:161], v[200:203], v[96:99]
	v_mfma_f32_16x16x32_bf16 v[84:87], v[150:153], v[208:211], v[84:87]
	v_mfma_f32_16x16x32_bf16 v[80:83], v[158:161], v[208:211], v[80:83]
	v_mfma_f32_16x16x32_bf16 v[68:71], v[150:153], v[216:219], v[68:71]
	v_mfma_f32_16x16x32_bf16 v[64:67], v[158:161], v[216:219], v[64:67]
	s_setprio 0
	s_barrier
; #define PG8_STAGE(bufoff, gbase, voff) do { _Pragma("unroll") for (int _i = 0; _i < 2; ++_i) \
;         __builtin_amdgcn_global_load_lds((const unsigned*)((const char*)(gbase) + (voff)[_i]), (LAS unsigned*)(lds + (bufoff) + ldsw + _i * 8192), 16, 0, 0); } while (0)
; #define PG8_LDA(dst, b, h) do { _Pragma("unroll") for (int m = 0; m < 4; ++m) _Pragma("unroll") for (int k = 0; k < 2; ++k) dst[m][k] = *(const LAS bf16x8*)(lds + PG8_SA(b, h) + aoff + m * 2048 + k * 1024); } while (0)
; #define PG8_LDB(dst, b, h) do { _Pragma("unroll") for (int n = 0; n < 2; ++n) _Pragma("unroll") for (int k = 0; k < 2; ++k) dst[n][k] = *(const LAS bf16x8*)(lds + PG8_SB(b, h) + boff + n * 2048 + k * 1024); } while (0)
; #define PG8_WAIT_V(n) asm volatile("s_waitcnt vmcnt(" #n ")" ::: "memory")
; #define PG8_BAR __builtin_amdgcn_s_barrier()
; template <class Epi, bool ALIGN_EPI>
; __device__ __forceinline__ void gemm_phase(LAS unsigned char* lds, const Gemm g, const StaticOrder& S, const Epi& E, const int tid) {
;     ...
;         for (int t = 0; t < nt; t += 2) {
;             const bool last = (t == nt - 2);
;             const char* a1 = cA + (size_t)(t + 1) * kstep;
;             const char* a2 = last ? nA : cA + (size_t)(t + 2) * kstep; const char* b2 = last ? nB : cB + (size_t)(t + 2) * kstep;
;             const char* a3 = a2 + kstep; const char* b3 = b2 + kstep;
;             PG8_LDB(B0, 0, 0); PG8_LDB(B1, 0, 1); PG8_SCHED; PG8_LDA(At, 0, 0); PG8_STAGE(PG8_SA(1, 1), a1 + hA, voffA);
;             PG8_WAIT_V(8); PG8_WAIT_L(0); PG8_BAR; PG8_MMA(0, 0, At, B0); PG8_MMA(0, 1, At, B1); PG8_BAR; PG8_SCHED;
;             PG8_LDA(At, 0, 1); PG8_STAGE(PG8_SB(0, 0), b2, voffB); PG8_STAGE(PG8_SB(0, 1), b2 + hB, voffB); PG8_STAGE(PG8_SA(0, 0), a2, voffA);
;             PG8_WAIT_V(8); PG8_WAIT_L(0); PG8_BAR; PG8_MMA(1, 0, At, B0); PG8_MMA(1, 1, At, B1); PG8_BAR; PG8_SCHED;
;             PG8_LDB(B0, 1, 0); PG8_LDB(B1, 1, 1); PG8_SCHED; PG8_LDA(At, 1, 0); PG8_STAGE(PG8_SA(0, 1), a2 + hA, voffA);
;             PG8_WAIT_V(8); PG8_WAIT_L(0); PG8_BAR; PG8_MMA(0, 0, At, B0); PG8_MMA(0, 1, At, B1); PG8_BAR; PG8_SCHED;
;             PG8_LDA(At, 1, 1); PG8_STAGE(PG8_SB(1, 0), b3, voffB); PG8_STAGE(PG8_SB(1, 1), b3 + hB, voffB); PG8_STAGE(PG8_SA(1, 0), a3, voffA);
;             PG8_WAIT_V(8); PG8_WAIT_L(0); PG8_BAR; PG8_MMA(1, 0, At, B0); PG8_MMA(1, 1, At, B1); PG8_BAR; PG8_SCHED;
	s_add_i32 s14, s14, s47
	v_lshl_add_u64 v[166:167], v[220:221], 0, s[92:93]
	s_mov_b32 m0, s14
	ds_read_b128 v[162:165], v171 offset:49152
	ds_read_b128 v[192:195], v171 offset:50176
	ds_read_b128 v[196:199], v171 offset:51200
	ds_read_b128 v[200:203], v171 offset:52224
	ds_read_b128 v[204:207], v171 offset:53248
	ds_read_b128 v[208:211], v171 offset:54272
	ds_read_b128 v[212:215], v171 offset:55296
	ds_read_b128 v[216:219], v171 offset:56320
	global_load_lds_dwordx4 v[166:167], off
	v_lshl_add_u64 v[166:167], v[226:227], 0, s[92:93]
	s_add_i32 m0, s14, 0x2000
	s_add_i32 s14, s68, s47
	global_load_lds_dwordx4 v[166:167], off
	v_lshl_add_u64 v[166:167], v[240:241], 0, s[92:93]
	s_mov_b32 m0, s14
	s_nop 0
	global_load_lds_dwordx4 v[166:167], off
	v_lshl_add_u64 v[166:167], v[242:243], 0, s[92:93]
	s_add_i32 m0, s14, 0x2000
	s_nop 0
	global_load_lds_dwordx4 v[166:167], off
	v_lshl_add_u64 v[166:167], v[244:245], 0, s[92:93]
	s_mov_b32 m0, s55
	s_nop 0
	global_load_lds_dwordx4 v[166:167], off
	v_lshl_add_u64 v[166:167], v[246:247], 0, s[92:93]
	s_mov_b32 m0, s56
	s_nop 0
	global_load_lds_dwordx4 v[166:167], off
	s_waitcnt vmcnt(8)
	s_waitcnt lgkmcnt(0)
	s_barrier
	s_setprio 1
	v_mfma_f32_16x16x32_bf16 v[60:63], v[130:133], v[162:165], v[60:63]
	v_mfma_f32_16x16x32_bf16 v[56:59], v[138:141], v[162:165], v[56:59]
	v_mfma_f32_16x16x32_bf16 v[44:47], v[130:133], v[196:199], v[44:47]
	v_mfma_f32_16x16x32_bf16 v[40:43], v[138:141], v[196:199], v[40:43]
	v_mfma_f32_16x16x32_bf16 v[28:31], v[130:133], v[204:207], v[28:31]
	v_mfma_f32_16x16x32_bf16 v[24:27], v[138:141], v[204:207], v[24:27]
	v_mfma_f32_16x16x32_bf16 v[12:15], v[130:133], v[212:215], v[12:15]
	v_mfma_f32_16x16x32_bf16 v[8:11], v[138:141], v[212:215], v[8:11]
	v_mfma_f32_16x16x32_bf16 v[60:63], v[134:137], v[192:195], v[60:63]
	v_mfma_f32_16x16x32_bf16 v[56:59], v[142:145], v[192:195], v[56:59]
	v_mfma_f32_16x16x32_bf16 v[44:47], v[134:137], v[200:203], v[44:47]
	v_mfma_f32_16x16x32_bf16 v[40:43], v[142:145], v[200:203], v[40:43]
	v_mfma_f32_16x16x32_bf16 v[28:31], v[134:137], v[208:211], v[28:31]
	v_mfma_f32_16x16x32_bf16 v[24:27], v[142:145], v[208:211], v[24:27]
	v_mfma_f32_16x16x32_bf16 v[12:15], v[134:137], v[216:219], v[12:15]
	v_mfma_f32_16x16x32_bf16 v[8:11], v[142:145], v[216:219], v[8:11]
	s_setprio 0
	s_setprio 1
	v_mfma_f32_16x16x32_bf16 v[52:55], v[146:149], v[162:165], v[52:55]
	v_mfma_f32_16x16x32_bf16 v[48:51], v[154:157], v[162:165], v[48:51]
	v_mfma_f32_16x16x32_bf16 v[36:39], v[146:149], v[196:199], v[36:39]
	v_mfma_f32_16x16x32_bf16 v[32:35], v[154:157], v[196:199], v[32:35]
	v_mfma_f32_16x16x32_bf16 v[20:23], v[146:149], v[204:207], v[20:23]
	v_mfma_f32_16x16x32_bf16 v[16:19], v[154:157], v[204:207], v[16:19]
	v_mfma_f32_16x16x32_bf16 v[4:7], v[146:149], v[212:215], v[4:7]
	v_mfma_f32_16x16x32_bf16 v[0:3], v[154:157], v[212:215], v[0:3]
	v_mfma_f32_16x16x32_bf16 v[52:55], v[150:153], v[192:195], v[52:55]
	v_mfma_f32_16x16x32_bf16 v[48:51], v[158:161], v[192:195], v[48:51]
	v_mfma_f32_16x16x32_bf16 v[36:39], v[150:153], v[200:203], v[36:39]
	v_mfma_f32_16x16x32_bf16 v[32:35], v[158:161], v[200:203], v[32:35]
	v_mfma_f32_16x16x32_bf16 v[20:23], v[150:153], v[208:211], v[20:23]
	v_mfma_f32_16x16x32_bf16 v[16:19], v[158:161], v[208:211], v[16:19]
	v_mfma_f32_16x16x32_bf16 v[4:7], v[150:153], v[216:219], v[4:7]
	v_mfma_f32_16x16x32_bf16 v[0:3], v[158:161], v[216:219], v[0:3]
	s_setprio 0
	s_barrier
	s_add_u32 s10, s10, 0x100
	s_addc_u32 s11, s11, 0
	v_lshl_add_u64 v[128:129], v[128:129], 0, s[80:81]
	s_cmp_ge_u32 s15, s48
	s_mov_b32 s14, s15
	s_cbranch_scc1 .Lpl2_after
.LBB0_274:
	s_add_i32 s15, s14, 2
	s_cmp_eq_u32 s57, s14
	s_cselect_b64 vcc, -1, 0
	s_cselect_b32 s69, s13, s11
	s_cselect_b32 s68, s12, s10
	s_add_i32 s14, 0, 0x14000
	v_lshl_add_u64 v[130:131], v[128:129], 0, s[92:93]
	v_add_u32_e32 v142, s33, v239
	v_add_u32_e32 v158, s14, v239
	v_cndmask_b32_e32 v167, v131, v191, vcc
	v_cndmask_b32_e32 v166, v130, v190, vcc
	ds_read_b128 v[130:133], v142
	ds_read_b128 v[134:137], v142 offset:1024
	ds_read_b128 v[138:141], v142 offset:2048
	ds_read_b128 v[142:145], v142 offset:3072
	ds_read_b128 v[146:149], v158
	ds_read_b128 v[150:153], v158 offset:1024
	ds_read_b128 v[154:157], v158 offset:2048
	ds_read_b128 v[158:161], v158 offset:3072
	v_lshl_add_u64 v[220:221], v[128:129], 0, v[186:187]
	s_add_i32 m0, s51, 0xc000
	ds_read_b128 v[162:165], v171
	ds_read_b128 v[192:195], v171 offset:1024
	ds_read_b128 v[196:199], v171 offset:2048
	ds_read_b128 v[200:203], v171 offset:3072
	ds_read_b128 v[204:207], v171 offset:4096
	ds_read_b128 v[208:211], v171 offset:5120
	ds_read_b128 v[212:215], v171 offset:6144
	ds_read_b128 v[216:219], v171 offset:7168
	global_load_lds_dwordx4 v[220:221], off
	v_lshl_add_u64 v[220:221], v[128:129], 0, v[188:189]
	s_add_i32 m0, s51, 0xe000
	s_nop 0
	global_load_lds_dwordx4 v[220:221], off
	s_waitcnt vmcnt(8)
	s_waitcnt lgkmcnt(0)
	s_barrier
; #define PG8_STAGE(bufoff, gbase, voff) do { _Pragma("unroll") for (int _i = 0; _i < 2; ++_i) \
;         __builtin_amdgcn_global_load_lds((const unsigned*)((const char*)(gbase) + (voff)[_i]), (LAS unsigned*)(lds + (bufoff) + ldsw + _i * 8192), 16, 0, 0); } while (0)
; #define PG8_LDA(dst, b, h) do { _Pragma("unroll") for (int m = 0; m < 4; ++m) _Pragma("unroll") for (int k = 0; k < 2; ++k) dst[m][k] = *(const LAS bf16x8*)(lds + PG8_SA(b, h) + aoff + m * 2048 + k * 1024); } while (0)
; #define PG8_MMA(ai, bj, At, Bt) do { __builtin_amdgcn_s_setprio(1); _Pragma("unroll") for (int k = 0; k < 2; ++k) _Pragma("unroll") for (int m = 0; m < 4; ++m) _Pragma("unroll") for (int n = 0; n < 2; ++n) \
;         acc[ai][bj][m][n] = __builtin_amdgcn_mfma_f32_16x16x32_bf16(Bt[n][k], At[m][k], acc[ai][bj][m][n], 0, 0, 0); __builtin_amdgcn_s_setprio(0); } while (0)
; #define PG8_WAIT_V(n) asm volatile("s_waitcnt vmcnt(" #n ")" ::: "memory")
; #define PG8_WAIT_L(n) asm volatile("s_waitcnt lgkmcnt(" #n ")" ::: "memory")
; #define PG8_BAR __builtin_amdgcn_s_barrier()
; #define PG8_SCHED __builtin_amdgcn_sched_barrier(0)
; template <class Epi, bool ALIGN_EPI>
; __device__ __forceinline__ void gemm_phase(LAS unsigned char* lds, const Gemm g, const StaticOrder& S, const Epi& E, const int tid) {
;     ...
;             PG8_WAIT_V(8); PG8_WAIT_L(0); PG8_BAR; PG8_MMA(0, 0, At, B0); PG8_MMA(0, 1, At, B1); PG8_BAR; PG8_SCHED;
;             PG8_LDA(At, 0, 1); PG8_STAGE(PG8_SB(0, 0), b2, voffB); PG8_STAGE(PG8_SB(0, 1), b2 + hB, voffB); PG8_STAGE(PG8_SA(0, 0), a2, voffA);
;             PG8_WAIT_V(8); PG8_WAIT_L(0); PG8_BAR; PG8_MMA(1, 0, At, B0); PG8_MMA(1, 1, At, B1); PG8_BAR; PG8_SCHED;
	s_setprio 1
	v_mfma_f32_16x16x32_bf16 v[124:127], v[130:133], v[162:165], v[124:127]
	v_mfma_f32_16x16x32_bf16 v[120:123], v[138:141], v[162:165], v[120:123]
	v_mfma_f32_16x16x32_bf16 v[108:111], v[130:133], v[196:199], v[108:111]
	v_mfma_f32_16x16x32_bf16 v[104:107], v[138:141], v[196:199], v[104:107]
	v_mfma_f32_16x16x32_bf16 v[92:95], v[130:133], v[204:207], v[92:95]
	v_mfma_f32_16x16x32_bf16 v[88:91], v[138:141], v[204:207], v[88:91]
	v_mfma_f32_16x16x32_bf16 v[76:79], v[130:133], v[212:215], v[76:79]
	v_mfma_f32_16x16x32_bf16 v[72:75], v[138:141], v[212:215], v[72:75]
	v_mfma_f32_16x16x32_bf16 v[124:127], v[134:137], v[192:195], v[124:127]
	v_mfma_f32_16x16x32_bf16 v[120:123], v[142:145], v[192:195], v[120:123]
	v_mfma_f32_16x16x32_bf16 v[108:111], v[134:137], v[200:203], v[108:111]
	v_mfma_f32_16x16x32_bf16 v[104:107], v[142:145], v[200:203], v[104:107]
	v_mfma_f32_16x16x32_bf16 v[92:95], v[134:137], v[208:211], v[92:95]
	v_mfma_f32_16x16x32_bf16 v[88:91], v[142:145], v[208:211], v[88:91]
	v_mfma_f32_16x16x32_bf16 v[76:79], v[134:137], v[216:219], v[76:79]
	v_mfma_f32_16x16x32_bf16 v[72:75], v[142:145], v[216:219], v[72:75]
	s_setprio 0
	s_setprio 1
	v_mfma_f32_16x16x32_bf16 v[116:119], v[146:149], v[162:165], v[116:119]
	v_mfma_f32_16x16x32_bf16 v[112:115], v[154:157], v[162:165], v[112:115]
	v_mfma_f32_16x16x32_bf16 v[100:103], v[146:149], v[196:199], v[100:103]
	v_mfma_f32_16x16x32_bf16 v[96:99], v[154:157], v[196:199], v[96:99]
	v_mfma_f32_16x16x32_bf16 v[84:87], v[146:149], v[204:207], v[84:87]
	v_mfma_f32_16x16x32_bf16 v[80:83], v[154:157], v[204:207], v[80:83]
	v_mfma_f32_16x16x32_bf16 v[68:71], v[146:149], v[212:215], v[68:71]
	v_mfma_f32_16x16x32_bf16 v[64:67], v[154:157], v[212:215], v[64:67]
	v_mfma_f32_16x16x32_bf16 v[116:119], v[150:153], v[192:195], v[116:119]
	v_mfma_f32_16x16x32_bf16 v[112:115], v[158:161], v[192:195], v[112:115]
	v_mfma_f32_16x16x32_bf16 v[100:103], v[150:153], v[200:203], v[100:103]
	v_mfma_f32_16x16x32_bf16 v[96:99], v[158:161], v[200:203], v[96:99]
	v_mfma_f32_16x16x32_bf16 v[84:87], v[150:153], v[208:211], v[84:87]
	v_mfma_f32_16x16x32_bf16 v[80:83], v[158:161], v[208:211], v[80:83]
	v_mfma_f32_16x16x32_bf16 v[68:71], v[150:153], v[216:219], v[68:71]
	v_mfma_f32_16x16x32_bf16 v[64:67], v[158:161], v[216:219], v[64:67]
	s_setprio 0
	s_barrier
	s_add_i32 s70, s33, s47
	v_lshl_add_u64 v[220:221], s[68:69], 0, v[180:181]
	s_mov_b32 m0, s70
	ds_read_b128 v[162:165], v171 offset:16384
	ds_read_b128 v[192:195], v171 offset:17408
	ds_read_b128 v[196:199], v171 offset:18432
	ds_read_b128 v[200:203], v171 offset:19456
	ds_read_b128 v[204:207], v171 offset:20480
	ds_read_b128 v[208:211], v171 offset:21504
	ds_read_b128 v[212:215], v171 offset:22528
	ds_read_b128 v[216:219], v171 offset:23552
	global_load_lds_dwordx4 v[220:221], off
	s_add_i32 m0, s70, 0x2000
	v_lshl_add_u64 v[226:227], s[68:69], 0, v[184:185]
	s_add_u32 s68, s68, s49
	s_addc_u32 s69, s69, 0
	s_add_i32 s14, s14, s47
	global_load_lds_dwordx4 v[226:227], off
	v_lshl_add_u64 v[240:241], s[68:69], 0, v[180:181]
	s_mov_b32 m0, s14
	v_lshl_add_u64 v[242:243], s[68:69], 0, v[184:185]
	global_load_lds_dwordx4 v[240:241], off
	s_add_i32 m0, s14, 0x2000
	v_lshl_add_u64 v[244:245], v[166:167], 0, v[178:179]
	global_load_lds_dwordx4 v[242:243], off
	s_mov_b32 m0, s51
	v_lshl_add_u64 v[246:247], v[166:167], 0, v[182:183]
	global_load_lds_dwordx4 v[244:245], off
	s_mov_b32 m0, s52
	s_nop 0
	global_load_lds_dwordx4 v[246:247], off
	s_waitcnt vmcnt(8)
	s_waitcnt lgkmcnt(0)
	s_barrier
	s_setprio 1
	v_mfma_f32_16x16x32_bf16 v[60:63], v[130:133], v[162:165], v[60:63]
	v_mfma_f32_16x16x32_bf16 v[56:59], v[138:141], v[162:165], v[56:59]
	v_mfma_f32_16x16x32_bf16 v[44:47], v[130:133], v[196:199], v[44:47]
	v_mfma_f32_16x16x32_bf16 v[40:43], v[138:141], v[196:199], v[40:43]
	v_mfma_f32_16x16x32_bf16 v[28:31], v[130:133], v[204:207], v[28:31]
	v_mfma_f32_16x16x32_bf16 v[24:27], v[138:141], v[204:207], v[24:27]
	v_mfma_f32_16x16x32_bf16 v[12:15], v[130:133], v[212:215], v[12:15]
	v_mfma_f32_16x16x32_bf16 v[8:11], v[138:141], v[212:215], v[8:11]
	v_mfma_f32_16x16x32_bf16 v[60:63], v[134:137], v[192:195], v[60:63]
	v_mfma_f32_16x16x32_bf16 v[56:59], v[142:145], v[192:195], v[56:59]
	v_mfma_f32_16x16x32_bf16 v[44:47], v[134:137], v[200:203], v[44:47]
	v_mfma_f32_16x16x32_bf16 v[40:43], v[142:145], v[200:203], v[40:43]
	v_mfma_f32_16x16x32_bf16 v[28:31], v[134:137], v[208:211], v[28:31]
	v_mfma_f32_16x16x32_bf16 v[24:27], v[142:145], v[208:211], v[24:27]
	v_mfma_f32_16x16x32_bf16 v[12:15], v[134:137], v[216:219], v[12:15]
	v_mfma_f32_16x16x32_bf16 v[8:11], v[142:145], v[216:219], v[8:11]
	s_setprio 0
	s_setprio 1
	v_mfma_f32_16x16x32_bf16 v[52:55], v[146:149], v[162:165], v[52:55]
	v_mfma_f32_16x16x32_bf16 v[48:51], v[154:157], v[162:165], v[48:51]
	v_mfma_f32_16x16x32_bf16 v[36:39], v[146:149], v[196:199], v[36:39]
	v_mfma_f32_16x16x32_bf16 v[32:35], v[154:157], v[196:199], v[32:35]
	v_mfma_f32_16x16x32_bf16 v[20:23], v[146:149], v[204:207], v[20:23]
	v_mfma_f32_16x16x32_bf16 v[16:19], v[154:157], v[204:207], v[16:19]
	v_mfma_f32_16x16x32_bf16 v[4:7], v[146:149], v[212:215], v[4:7]
	v_mfma_f32_16x16x32_bf16 v[0:3], v[154:157], v[212:215], v[0:3]
	v_mfma_f32_16x16x32_bf16 v[52:55], v[150:153], v[192:195], v[52:55]
	v_mfma_f32_16x16x32_bf16 v[48:51], v[158:161], v[192:195], v[48:51]
	v_mfma_f32_16x16x32_bf16 v[36:39], v[150:153], v[200:203], v[36:39]
	v_mfma_f32_16x16x32_bf16 v[32:35], v[158:161], v[200:203], v[32:35]
	v_mfma_f32_16x16x32_bf16 v[20:23], v[150:153], v[208:211], v[20:23]
	v_mfma_f32_16x16x32_bf16 v[16:19], v[158:161], v[208:211], v[16:19]
	v_mfma_f32_16x16x32_bf16 v[4:7], v[150:153], v[216:219], v[4:7]
	v_mfma_f32_16x16x32_bf16 v[0:3], v[158:161], v[216:219], v[0:3]
	s_setprio 0
	s_barrier
; #define PG8_STAGE(bufoff, gbase, voff) do { _Pragma("unroll") for (int _i = 0; _i < 2; ++_i) \
;         __builtin_amdgcn_global_load_lds((const unsigned*)((const char*)(gbase) + (voff)[_i]), (LAS unsigned*)(lds + (bufoff) + ldsw + _i * 8192), 16, 0, 0); } while (0)
; #define PG8_LDA(dst, b, h) do { _Pragma("unroll") for (int m = 0; m < 4; ++m) _Pragma("unroll") for (int k = 0; k < 2; ++k) dst[m][k] = *(const LAS bf16x8*)(lds + PG8_SA(b, h) + aoff + m * 2048 + k * 1024); } while (0)
; #define PG8_LDB(dst, b, h) do { _Pragma("unroll") for (int n = 0; n < 2; ++n) _Pragma("unroll") for (int k = 0; k < 2; ++k) dst[n][k] = *(const LAS bf16x8*)(lds + PG8_SB(b, h) + boff + n * 2048 + k * 1024); } while (0)
; #define PG8_MMA(ai, bj, At, Bt) do { __builtin_amdgcn_s_setprio(1); _Pragma("unroll") for (int k = 0; k < 2; ++k) _Pragma("unroll") for (int m = 0; m < 4; ++m) _Pragma("unroll") for (int n = 0; n < 2; ++n) \
;         acc[ai][bj][m][n] = __builtin_amdgcn_mfma_f32_16x16x32_bf16(Bt[n][k], At[m][k], acc[ai][bj][m][n], 0, 0, 0); __builtin_amdgcn_s_setprio(0); } while (0)
; #define PG8_WAIT_V(n) asm volatile("s_waitcnt vmcnt(" #n ")" ::: "memory")
; #define PG8_WAIT_L(n) asm volatile("s_waitcnt lgkmcnt(" #n ")" ::: "memory")
; #define PG8_BAR __builtin_amdgcn_s_barrier()
; #define PG8_SCHED __builtin_amdgcn_sched_barrier(0)
; template <class Epi, bool ALIGN_EPI>
; __device__ __forceinline__ void gemm_phase(LAS unsigned char* lds, const Gemm g, const StaticOrder& S, const Epi& E, const int tid) {
;     ...
;             PG8_LDB(B0, 1, 0); PG8_LDB(B1, 1, 1); PG8_SCHED; PG8_LDA(At, 1, 0); PG8_STAGE(PG8_SA(0, 1), a2 + hA, voffA);
;             PG8_WAIT_V(8); PG8_WAIT_L(0); PG8_BAR; PG8_MMA(0, 0, At, B0); PG8_MMA(0, 1, At, B1); PG8_BAR; PG8_SCHED;
	s_add_i32 s14, 0, 0x18000
	s_add_i32 s68, 0, 0x1c000
	v_add_u32_e32 v142, s14, v239
	v_add_u32_e32 v158, s68, v239
	ds_read_b128 v[130:133], v142
	ds_read_b128 v[134:137], v142 offset:1024
	ds_read_b128 v[138:141], v142 offset:2048
	ds_read_b128 v[142:145], v142 offset:3072
	ds_read_b128 v[146:149], v158
	ds_read_b128 v[150:153], v158 offset:1024
	ds_read_b128 v[154:157], v158 offset:2048
	ds_read_b128 v[158:161], v158 offset:3072
	v_lshl_add_u64 v[166:167], v[166:167], 0, s[94:95]
	s_mov_b32 m0, s53
	v_lshl_add_u64 v[248:249], v[166:167], 0, v[178:179]
	ds_read_b128 v[162:165], v171 offset:32768
	ds_read_b128 v[192:195], v171 offset:33792
	ds_read_b128 v[196:199], v171 offset:34816
	ds_read_b128 v[200:203], v171 offset:35840
	ds_read_b128 v[204:207], v171 offset:36864
	ds_read_b128 v[208:211], v171 offset:37888
	ds_read_b128 v[212:215], v171 offset:38912
	ds_read_b128 v[216:219], v171 offset:39936
	global_load_lds_dwordx4 v[248:249], off
	v_lshl_add_u64 v[166:167], v[166:167], 0, v[182:183]
	s_mov_b32 m0, s54
	s_nop 0
	global_load_lds_dwordx4 v[166:167], off
	s_waitcnt vmcnt(8)
	s_waitcnt lgkmcnt(0)
	s_barrier
	s_setprio 1
	v_mfma_f32_16x16x32_bf16 v[124:127], v[130:133], v[162:165], v[124:127]
	v_mfma_f32_16x16x32_bf16 v[120:123], v[138:141], v[162:165], v[120:123]
	v_mfma_f32_16x16x32_bf16 v[108:111], v[130:133], v[196:199], v[108:111]
	v_mfma_f32_16x16x32_bf16 v[104:107], v[138:141], v[196:199], v[104:107]
	v_mfma_f32_16x16x32_bf16 v[92:95], v[130:133], v[204:207], v[92:95]
	v_mfma_f32_16x16x32_bf16 v[88:91], v[138:141], v[204:207], v[88:91]
	v_mfma_f32_16x16x32_bf16 v[76:79], v[130:133], v[212:215], v[76:79]
	v_mfma_f32_16x16x32_bf16 v[72:75], v[138:141], v[212:215], v[72:75]
	v_mfma_f32_16x16x32_bf16 v[124:127], v[134:137], v[192:195], v[124:127]
	v_mfma_f32_16x16x32_bf16 v[120:123], v[142:145], v[192:195], v[120:123]
	v_mfma_f32_16x16x32_bf16 v[108:111], v[134:137], v[200:203], v[108:111]
	v_mfma_f32_16x16x32_bf16 v[104:107], v[142:145], v[200:203], v[104:107]
	v_mfma_f32_16x16x32_bf16 v[92:95], v[134:137], v[208:211], v[92:95]
	v_mfma_f32_16x16x32_bf16 v[88:91], v[142:145], v[208:211], v[88:91]
	v_mfma_f32_16x16x32_bf16 v[76:79], v[134:137], v[216:219], v[76:79]
	v_mfma_f32_16x16x32_bf16 v[72:75], v[142:145], v[216:219], v[72:75]
	s_setprio 0
	s_setprio 1
	v_mfma_f32_16x16x32_bf16 v[116:119], v[146:149], v[162:165], v[116:119]
	v_mfma_f32_16x16x32_bf16 v[112:115], v[154:157], v[162:165], v[112:115]
	v_mfma_f32_16x16x32_bf16 v[100:103], v[146:149], v[196:199], v[100:103]
	v_mfma_f32_16x16x32_bf16 v[96:99], v[154:157], v[196:199], v[96:99]
	v_mfma_f32_16x16x32_bf16 v[84:87], v[146:149], v[204:207], v[84:87]
	v_mfma_f32_16x16x32_bf16 v[80:83], v[154:157], v[204:207], v[80:83]
	v_mfma_f32_16x16x32_bf16 v[68:71], v[146:149], v[212:215], v[68:71]
	v_mfma_f32_16x16x32_bf16 v[64:67], v[154:157], v[212:215], v[64:67]
	v_mfma_f32_16x16x32_bf16 v[116:119], v[150:153], v[192:195], v[116:119]
	v_mfma_f32_16x16x32_bf16 v[112:115], v[158:161], v[192:195], v[112:115]
	v_mfma_f32_16x16x32_bf16 v[100:103], v[150:153], v[200:203], v[100:103]
	v_mfma_f32_16x16x32_bf16 v[96:99], v[158:161], v[200:203], v[96:99]
	v_mfma_f32_16x16x32_bf16 v[84:87], v[150:153], v[208:211], v[84:87]
	v_mfma_f32_16x16x32_bf16 v[80:83], v[158:161], v[208:211], v[80:83]
	v_mfma_f32_16x16x32_bf16 v[68:71], v[150:153], v[216:219], v[68:71]
	v_mfma_f32_16x16x32_bf16 v[64:67], v[158:161], v[216:219], v[64:67]
	s_setprio 0
	s_barrier
; #define PG8_STAGE(bufoff, gbase, voff) do { _Pragma("unroll") for (int _i = 0; _i < 2; ++_i) \
;         __builtin_amdgcn_global_load_lds((const unsigned*)((const char*)(gbase) + (voff)[_i]), (LAS unsigned*)(lds + (bufoff) + ldsw + _i * 8192), 16, 0, 0); } while (0)
; #define PG8_LDA(dst, b, h) do { _Pragma("unroll") for (int m = 0; m < 4; ++m) _Pragma("unroll") for (int k = 0; k < 2; ++k) dst[m][k] = *(const LAS bf16x8*)(lds + PG8_SA(b, h) + aoff + m * 2048 + k * 1024); } while (0)
; #define PG8_MMA(ai, bj, At, Bt) do { __builtin_amdgcn_s_setprio(1); _Pragma("unroll") for (int k = 0; k < 2; ++k) _Pragma("unroll") for (int m = 0; m < 4; ++m) _Pragma("unroll") for (int n = 0; n < 2; ++n) \
;         acc[ai][bj][m][n] = __builtin_amdgcn_mfma_f32_16x16x32_bf16(Bt[n][k], At[m][k], acc[ai][bj][m][n], 0, 0, 0); __builtin_amdgcn_s_setprio(0); } while (0)
; #define PG8_WAIT_V(n) asm volatile("s_waitcnt vmcnt(" #n ")" ::: "memory")
; #define PG8_WAIT_L(n) asm volatile("s_waitcnt lgkmcnt(" #n ")" ::: "memory")
; #define PG8_BAR __builtin_amdgcn_s_barrier()
; #define PG8_SCHED __builtin_amdgcn_sched_barrier(0)
; template <class Epi, bool ALIGN_EPI>
; __device__ __forceinline__ void gemm_phase(LAS unsigned char* lds, const Gemm g, const StaticOrder& S, const Epi& E, const int tid) {
;     ...
;             PG8_LDA(At, 1, 1); PG8_STAGE(PG8_SB(1, 0), b3, voffB); PG8_STAGE(PG8_SB(1, 1), b3 + hB, voffB); PG8_STAGE(PG8_SA(1, 0), a3, voffA);
;             PG8_WAIT_V(8); PG8_WAIT_L(0); PG8_BAR; PG8_MMA(1, 0, At, B0); PG8_MMA(1, 1, At, B1); PG8_BAR; PG8_SCHED;
;         }
	s_add_i32 s14, s14, s47
	v_lshl_add_u64 v[166:167], v[220:221], 0, s[92:93]
	s_mov_b32 m0, s14
	ds_read_b128 v[162:165], v171 offset:49152
	ds_read_b128 v[192:195], v171 offset:50176
	ds_read_b128 v[196:199], v171 offset:51200
	ds_read_b128 v[200:203], v171 offset:52224
	ds_read_b128 v[204:207], v171 offset:53248
	ds_read_b128 v[208:211], v171 offset:54272
	ds_read_b128 v[212:215], v171 offset:55296
	ds_read_b128 v[216:219], v171 offset:56320
	global_load_lds_dwordx4 v[166:167], off
	v_lshl_add_u64 v[166:167], v[226:227], 0, s[92:93]
	s_add_i32 m0, s14, 0x2000
	s_add_i32 s14, s68, s47
	global_load_lds_dwordx4 v[166:167], off
	v_lshl_add_u64 v[166:167], v[240:241], 0, s[92:93]
	s_mov_b32 m0, s14
	s_nop 0
	global_load_lds_dwordx4 v[166:167], off
	v_lshl_add_u64 v[166:167], v[242:243], 0, s[92:93]
	s_add_i32 m0, s14, 0x2000
	s_nop 0
	global_load_lds_dwordx4 v[166:167], off
	v_lshl_add_u64 v[166:167], v[244:245], 0, s[92:93]
	s_mov_b32 m0, s55
	s_nop 0
	global_load_lds_dwordx4 v[166:167], off
	v_lshl_add_u64 v[166:167], v[246:247], 0, s[92:93]
	s_mov_b32 m0, s56
	s_nop 0
	global_load_lds_dwordx4 v[166:167], off
	s_waitcnt vmcnt(8)
	s_waitcnt lgkmcnt(0)
	s_barrier
	s_setprio 1
	v_mfma_f32_16x16x32_bf16 v[60:63], v[130:133], v[162:165], v[60:63]
	v_mfma_f32_16x16x32_bf16 v[56:59], v[138:141], v[162:165], v[56:59]
	v_mfma_f32_16x16x32_bf16 v[44:47], v[130:133], v[196:199], v[44:47]
	v_mfma_f32_16x16x32_bf16 v[40:43], v[138:141], v[196:199], v[40:43]
	v_mfma_f32_16x16x32_bf16 v[28:31], v[130:133], v[204:207], v[28:31]
	v_mfma_f32_16x16x32_bf16 v[24:27], v[138:141], v[204:207], v[24:27]
	v_mfma_f32_16x16x32_bf16 v[12:15], v[130:133], v[212:215], v[12:15]
	v_mfma_f32_16x16x32_bf16 v[8:11], v[138:141], v[212:215], v[8:11]
	v_mfma_f32_16x16x32_bf16 v[60:63], v[134:137], v[192:195], v[60:63]
	v_mfma_f32_16x16x32_bf16 v[56:59], v[142:145], v[192:195], v[56:59]
	v_mfma_f32_16x16x32_bf16 v[44:47], v[134:137], v[200:203], v[44:47]
	v_mfma_f32_16x16x32_bf16 v[40:43], v[142:145], v[200:203], v[40:43]
	v_mfma_f32_16x16x32_bf16 v[28:31], v[134:137], v[208:211], v[28:31]
	v_mfma_f32_16x16x32_bf16 v[24:27], v[142:145], v[208:211], v[24:27]
	v_mfma_f32_16x16x32_bf16 v[12:15], v[134:137], v[216:219], v[12:15]
	v_mfma_f32_16x16x32_bf16 v[8:11], v[142:145], v[216:219], v[8:11]
	s_setprio 0
	s_setprio 1
	v_mfma_f32_16x16x32_bf16 v[52:55], v[146:149], v[162:165], v[52:55]
	v_mfma_f32_16x16x32_bf16 v[48:51], v[154:157], v[162:165], v[48:51]
	v_mfma_f32_16x16x32_bf16 v[36:39], v[146:149], v[196:199], v[36:39]
	v_mfma_f32_16x16x32_bf16 v[32:35], v[154:157], v[196:199], v[32:35]
	v_mfma_f32_16x16x32_bf16 v[20:23], v[146:149], v[204:207], v[20:23]
	v_mfma_f32_16x16x32_bf16 v[16:19], v[154:157], v[204:207], v[16:19]
	v_mfma_f32_16x16x32_bf16 v[4:7], v[146:149], v[212:215], v[4:7]
	v_mfma_f32_16x16x32_bf16 v[0:3], v[154:157], v[212:215], v[0:3]
	v_mfma_f32_16x16x32_bf16 v[52:55], v[150:153], v[192:195], v[52:55]
	v_mfma_f32_16x16x32_bf16 v[48:51], v[158:161], v[192:195], v[48:51]
	v_mfma_f32_16x16x32_bf16 v[36:39], v[150:153], v[200:203], v[36:39]
	v_mfma_f32_16x16x32_bf16 v[32:35], v[158:161], v[200:203], v[32:35]
	v_mfma_f32_16x16x32_bf16 v[20:23], v[150:153], v[208:211], v[20:23]
	v_mfma_f32_16x16x32_bf16 v[16:19], v[158:161], v[208:211], v[16:19]
	v_mfma_f32_16x16x32_bf16 v[4:7], v[150:153], v[216:219], v[4:7]
	v_mfma_f32_16x16x32_bf16 v[0:3], v[158:161], v[216:219], v[0:3]
	s_setprio 0
	s_barrier
	s_add_u32 s10, s10, 0x100
	s_addc_u32 s11, s11, 0
	v_lshl_add_u64 v[128:129], v[128:129], 0, s[80:81]
	s_cmp_ge_u32 s15, s48
	s_mov_b32 s14, s15
	s_cbranch_scc0 .LBB0_274

; __device__ __forceinline__ unsigned cvt_pk_bf16(float lo, float hi) { unsigned r; asm volatile("v_cvt_pk_bf16_f32 %0, %1, %2" : "=v"(r) : "v"(lo), "v"(hi)); return r; }
; __device__ __forceinline__ float siluf_(float x) { return x * sigmoidf_(x); }
; #define PG8_STAGE(bufoff, gbase, voff) do { _Pragma("unroll") for (int _i = 0; _i < 2; ++_i) \
;         __builtin_amdgcn_global_load_lds((const unsigned*)((const char*)(gbase) + (voff)[_i]), (LAS unsigned*)(lds + (bufoff) + ldsw + _i * 8192), 16, 0, 0); } while (0)
; #define PG8_LDA(dst, b, h) do { _Pragma("unroll") for (int m = 0; m < 4; ++m) _Pragma("unroll") for (int k = 0; k < 2; ++k) dst[m][k] = *(const LAS bf16x8*)(lds + PG8_SA(b, h) + aoff + m * 2048 + k * 1024); } while (0)
; #define PG8_LDB(dst, b, h) do { _Pragma("unroll") for (int n = 0; n < 2; ++n) _Pragma("unroll") for (int k = 0; k < 2; ++k) dst[n][k] = *(const LAS bf16x8*)(lds + PG8_SB(b, h) + boff + n * 2048 + k * 1024); } while (0)
; #define PG8_WAIT_V(n) asm volatile("s_waitcnt vmcnt(" #n ")" ::: "memory")
; #define PG8_WAIT_L(n) asm volatile("s_waitcnt lgkmcnt(" #n ")" ::: "memory")
; #define PG8_BAR __builtin_amdgcn_s_barrier()
; #define PG8_SCHED __builtin_amdgcn_sched_barrier(0)
;     __device__ __forceinline__ void operator()(const f32x4 (&acc)[2][2][4][2], const Unit& u, int wr, int wc, int fr, int fq) const {
;     ...
;             for (int m = 0; m < 4; ++m) { const int row = row0 + ai * HALF + m * 16; bf16_t* rowp = O + (size_t)row * ldc + col0; const float rs = rsv[ai][m];
;                 f32x4 v0, v1;
; #pragma unroll
;                 for (int j = 0; j < 4; ++j) { v0[j] = siluf_(acc[ai][0][m][0][j] * rs) * (acc[ai][1][m][0][j] * rs); v1[j] = siluf_(acc[ai][0][m][1][j] * rs) * (acc[ai][1][m][1][j] * rs); }
;                 u32x4 w; w.x = cvt_pk_bf16(v0[0], v0[1]); w.y = cvt_pk_bf16(v0[2], v0[3]); w.z = cvt_pk_bf16(v1[0], v1[1]); w.w = cvt_pk_bf16(v1[2], v1[3]);
;                 *(u32x4*)rowp = w; }
; template <class Epi, bool ALIGN_EPI>
; __device__ __forceinline__ void gemm_phase(LAS unsigned char* lds, const Gemm g, const StaticOrder& S, const Epi& E, const int tid) {
;     ...
;             PG8_LDB(B0, 0, 0); PG8_LDB(B1, 0, 1); PG8_SCHED; PG8_LDA(At, 0, 0); PG8_STAGE(PG8_SA(1, 1), a1 + hA, voffA);
;             PG8_WAIT_V(8); PG8_WAIT_L(0); PG8_BAR; PG8_MMA(0, 0, At, B0); PG8_MMA(0, 1, At, B1); PG8_BAR; PG8_SCHED;
.Lgu_first_epi:
	s_add_i32 s11, s10, 2
	s_cmp_eq_u32 s58, s10
	v_lshl_add_u64 v[146:147], v[142:143], 0, s[92:93]
	s_cselect_b64 vcc, -1, 0
	v_add_u32_e32 v150, s33, v151
	s_add_i32 s10, 0, 0x14000
	v_cndmask_b32_e32 v167, v147, v139, vcc
	v_cndmask_b32_e32 v166, v146, v138, vcc
	ds_read_b128 v[146:149], v150
	ds_read_b128 v[154:157], v150 offset:1024
	ds_read_b128 v[158:161], v150 offset:2048
	ds_read_b128 v[162:165], v150 offset:3072
	v_add_u32_e32 v150, s10, v151
	ds_read_b128 v[176:179], v150
	ds_read_b128 v[180:183], v150 offset:1024
	ds_read_b128 v[184:187], v150 offset:2048
	ds_read_b128 v[188:191], v150 offset:3072
	v_cndmask_b32_e32 v221, v145, v141, vcc
	v_cndmask_b32_e32 v220, v144, v140, vcc
	v_lshl_add_u64 v[226:227], v[142:143], 0, v[134:135]
	s_add_i32 m0, s51, 0xc000
	ds_read_b128 v[192:195], v153
	ds_read_b128 v[196:199], v153 offset:1024
	ds_read_b128 v[200:203], v153 offset:2048
	ds_read_b128 v[204:207], v153 offset:3072
	ds_read_b128 v[208:211], v153 offset:4096
	ds_read_b128 v[212:215], v153 offset:5120
	ds_read_b128 v[216:219], v153 offset:6144
	ds_read_b128 v[240:243], v153 offset:7168
	global_load_lds_dwordx4 v[226:227], off
	v_lshl_add_u64 v[226:227], v[142:143], 0, v[136:137]
	s_add_i32 m0, s51, 0xe000
	s_nop 0
	global_load_lds_dwordx4 v[226:227], off
	s_waitcnt vmcnt(12)
	s_waitcnt lgkmcnt(0)
	s_barrier
	s_setprio 1
	v_mfma_f32_16x16x32_bf16 v[120:123], v[146:149], v[192:195], 0
	s_lshl_b32 s98, s28, 5
	s_mov_b32 s99, 0
	s_mov_b32 s100, 0xbfb8aa3b
	s_mov_b32 s101, 0xbfb8aa3b
	v_mul_f32_e32 v56, v238, v56
	v_mul_f32_e32 v57, v238, v57
	v_mul_f32_e32 v58, v238, v58
	v_mul_f32_e32 v59, v238, v59
	v_mul_f32_e32 v60, v238, v60
	v_mul_f32_e32 v61, v238, v61
	v_mfma_f32_16x16x32_bf16 v[112:115], v[158:161], v[192:195], 0
	v_mul_f32_e32 v62, v238, v62
	v_mul_f32_e32 v63, v238, v63
	v_mul_f32_e32 v224, s100, v56
	v_mul_f32_e32 v225, s101, v57
	v_mul_f32_e32 v228, s100, v58
	v_mul_f32_e32 v229, s101, v59
	v_exp_f32_e32 v224, v224
	v_exp_f32_e32 v225, v225
	v_exp_f32_e32 v228, v228
	v_exp_f32_e32 v229, v229
	v_mfma_f32_16x16x32_bf16 v[104:107], v[146:149], v[200:203], 0
	v_add_f32_e32 v224, 1.0, v224
	v_add_f32_e32 v225, 1.0, v225
	v_add_f32_e32 v228, 1.0, v228
	v_add_f32_e32 v229, 1.0, v229
	v_rcp_f32_e32 v224, v224
	v_rcp_f32_e32 v225, v225
	v_rcp_f32_e32 v228, v228
	v_rcp_f32_e32 v229, v229
	v_nop
	v_mul_f32_e32 v56, v224, v56
	v_mfma_f32_16x16x32_bf16 v[96:99], v[158:161], v[200:203], 0
	v_mul_f32_e32 v57, v225, v57
	v_mul_f32_e32 v58, v228, v58
	v_mul_f32_e32 v59, v229, v59
	v_mul_f32_e32 v56, v60, v56
	v_mul_f32_e32 v57, v61, v57
	v_mul_f32_e32 v58, v62, v58
	v_mul_f32_e32 v59, v63, v59
	v_mul_f32_e32 v48, v238, v48
	v_mul_f32_e32 v49, v238, v49
	v_mul_f32_e32 v50, v238, v50
	v_mfma_f32_16x16x32_bf16 v[88:91], v[146:149], v[208:211], 0
	v_mul_f32_e32 v51, v238, v51
	v_mul_f32_e32 v52, v238, v52
	v_mul_f32_e32 v53, v238, v53
	v_mul_f32_e32 v54, v238, v54
	v_mul_f32_e32 v55, v238, v55
	v_mul_f32_e32 v224, s100, v48
	v_mul_f32_e32 v225, s101, v49
	v_mul_f32_e32 v228, s100, v50
	v_mul_f32_e32 v229, s101, v51
	v_exp_f32_e32 v224, v224
	v_mfma_f32_16x16x32_bf16 v[80:83], v[158:161], v[208:211], 0
	v_exp_f32_e32 v225, v225
	v_exp_f32_e32 v228, v228
	v_exp_f32_e32 v229, v229
	v_add_f32_e32 v224, 1.0, v224
	v_add_f32_e32 v225, 1.0, v225
	v_add_f32_e32 v228, 1.0, v228
	v_add_f32_e32 v229, 1.0, v229
	v_rcp_f32_e32 v224, v224
	v_rcp_f32_e32 v225, v225
	v_rcp_f32_e32 v228, v228
	v_mfma_f32_16x16x32_bf16 v[72:75], v[146:149], v[216:219], 0
	v_rcp_f32_e32 v229, v229
	v_nop
	v_mul_f32_e32 v48, v224, v48
	v_mul_f32_e32 v49, v225, v49
	v_mul_f32_e32 v50, v228, v50
	v_mul_f32_e32 v51, v229, v51
	v_mul_f32_e32 v48, v52, v48
	v_mul_f32_e32 v49, v53, v49
	v_mul_f32_e32 v50, v54, v50
	v_mul_f32_e32 v51, v55, v51
	v_mfma_f32_16x16x32_bf16 v[64:67], v[158:161], v[216:219], 0
	v_cvt_pk_bf16_f32 v56, v56, v57
	v_cvt_pk_bf16_f32 v57, v58, v59
	v_cvt_pk_bf16_f32 v58, v48, v49
	v_cvt_pk_bf16_f32 v59, v50, v51
	global_store_dwordx4 v[232:233], v[56:59], off
	v_lshl_add_u64 v[232:233], v[232:233], 0, s[98:99]
	v_mul_f32_e32 v40, v239, v40
	v_mul_f32_e32 v41, v239, v41
	v_mul_f32_e32 v42, v239, v42
	v_mul_f32_e32 v43, v239, v43
	v_mfma_f32_16x16x32_bf16 v[120:123], v[154:157], v[196:199], v[120:123]
	v_mul_f32_e32 v44, v239, v44
	v_mul_f32_e32 v45, v239, v45
	v_mul_f32_e32 v46, v239, v46
	v_mul_f32_e32 v47, v239, v47
	v_mul_f32_e32 v224, s100, v40
	v_mul_f32_e32 v225, s101, v41
	v_mul_f32_e32 v228, s100, v42
	v_mul_f32_e32 v229, s101, v43
	v_exp_f32_e32 v224, v224
	v_exp_f32_e32 v225, v225
	v_mfma_f32_16x16x32_bf16 v[112:115], v[162:165], v[196:199], v[112:115]
	v_exp_f32_e32 v228, v228
	v_exp_f32_e32 v229, v229
	v_add_f32_e32 v224, 1.0, v224
	v_add_f32_e32 v225, 1.0, v225
	v_add_f32_e32 v228, 1.0, v228
	v_add_f32_e32 v229, 1.0, v229
	v_rcp_f32_e32 v224, v224
	v_rcp_f32_e32 v225, v225
	v_rcp_f32_e32 v228, v228
	v_rcp_f32_e32 v229, v229
	v_mfma_f32_16x16x32_bf16 v[104:107], v[154:157], v[204:207], v[104:107]
	v_nop
	v_mul_f32_e32 v40, v224, v40
	v_mul_f32_e32 v41, v225, v41
	v_mul_f32_e32 v42, v228, v42
	v_mul_f32_e32 v43, v229, v43
	v_mul_f32_e32 v40, v44, v40
	v_mul_f32_e32 v41, v45, v41
	v_mul_f32_e32 v42, v46, v42
	v_mul_f32_e32 v43, v47, v43
	v_mul_f32_e32 v32, v239, v32
	v_mfma_f32_16x16x32_bf16 v[96:99], v[162:165], v[204:207], v[96:99]
	v_mul_f32_e32 v33, v239, v33
	v_mul_f32_e32 v34, v239, v34
	v_mul_f32_e32 v35, v239, v35
	v_mul_f32_e32 v36, v239, v36
	v_mul_f32_e32 v37, v239, v37
	v_mul_f32_e32 v38, v239, v38
	v_mul_f32_e32 v39, v239, v39
	v_mul_f32_e32 v224, s100, v32
	v_mul_f32_e32 v225, s101, v33
	v_mul_f32_e32 v228, s100, v34
; __device__ __forceinline__ unsigned cvt_pk_bf16(float lo, float hi) { unsigned r; asm volatile("v_cvt_pk_bf16_f32 %0, %1, %2" : "=v"(r) : "v"(lo), "v"(hi)); return r; }
; __device__ __forceinline__ float siluf_(float x) { return x * sigmoidf_(x); }
; #define PG8_STAGE(bufoff, gbase, voff) do { _Pragma("unroll") for (int _i = 0; _i < 2; ++_i) \
;         __builtin_amdgcn_global_load_lds((const unsigned*)((const char*)(gbase) + (voff)[_i]), (LAS unsigned*)(lds + (bufoff) + ldsw + _i * 8192), 16, 0, 0); } while (0)
; #define PG8_LDA(dst, b, h) do { _Pragma("unroll") for (int m = 0; m < 4; ++m) _Pragma("unroll") for (int k = 0; k < 2; ++k) dst[m][k] = *(const LAS bf16x8*)(lds + PG8_SA(b, h) + aoff + m * 2048 + k * 1024); } while (0)
; #define PG8_LDB(dst, b, h) do { _Pragma("unroll") for (int n = 0; n < 2; ++n) _Pragma("unroll") for (int k = 0; k < 2; ++k) dst[n][k] = *(const LAS bf16x8*)(lds + PG8_SB(b, h) + boff + n * 2048 + k * 1024); } while (0)
; #define PG8_WAIT_V(n) asm volatile("s_waitcnt vmcnt(" #n ")" ::: "memory")
; #define PG8_WAIT_L(n) asm volatile("s_waitcnt lgkmcnt(" #n ")" ::: "memory")
; #define PG8_BAR __builtin_amdgcn_s_barrier()
; #define PG8_SCHED __builtin_amdgcn_sched_barrier(0)
;     __device__ __forceinline__ void operator()(const f32x4 (&acc)[2][2][4][2], const Unit& u, int wr, int wc, int fr, int fq) const {
;     ...
;             for (int m = 0; m < 4; ++m) { const int row = row0 + ai * HALF + m * 16; bf16_t* rowp = O + (size_t)row * ldc + col0; const float rs = rsv[ai][m];
;                 f32x4 v0, v1;
; #pragma unroll
;                 for (int j = 0; j < 4; ++j) { v0[j] = siluf_(acc[ai][0][m][0][j] * rs) * (acc[ai][1][m][0][j] * rs); v1[j] = siluf_(acc[ai][0][m][1][j] * rs) * (acc[ai][1][m][1][j] * rs); }
;                 u32x4 w; w.x = cvt_pk_bf16(v0[0], v0[1]); w.y = cvt_pk_bf16(v0[2], v0[3]); w.z = cvt_pk_bf16(v1[0], v1[1]); w.w = cvt_pk_bf16(v1[2], v1[3]);
;                 *(u32x4*)rowp = w; }
; template <class Epi, bool ALIGN_EPI>
; __device__ __forceinline__ void gemm_phase(LAS unsigned char* lds, const Gemm g, const StaticOrder& S, const Epi& E, const int tid) {
;     ...
;             PG8_LDB(B0, 0, 0); PG8_LDB(B1, 0, 1); PG8_SCHED; PG8_LDA(At, 0, 0); PG8_STAGE(PG8_SA(1, 1), a1 + hA, voffA);
;             PG8_WAIT_V(8); PG8_WAIT_L(0); PG8_BAR; PG8_MMA(0, 0, At, B0); PG8_MMA(0, 1, At, B1); PG8_BAR; PG8_SCHED;
	v_mfma_f32_16x16x32_bf16 v[88:91], v[154:157], v[212:215], v[88:91]
	v_mul_f32_e32 v229, s101, v35
	v_exp_f32_e32 v224, v224
	v_exp_f32_e32 v225, v225
	v_exp_f32_e32 v228, v228
	v_exp_f32_e32 v229, v229
	v_add_f32_e32 v224, 1.0, v224
	v_add_f32_e32 v225, 1.0, v225
	v_add_f32_e32 v228, 1.0, v228
	v_add_f32_e32 v229, 1.0, v229
	v_rcp_f32_e32 v224, v224
	v_mfma_f32_16x16x32_bf16 v[80:83], v[162:165], v[212:215], v[80:83]
	v_rcp_f32_e32 v225, v225
	v_rcp_f32_e32 v228, v228
	v_rcp_f32_e32 v229, v229
	v_nop
	v_mul_f32_e32 v32, v224, v32
	v_mul_f32_e32 v33, v225, v33
	v_mul_f32_e32 v34, v228, v34
	v_mul_f32_e32 v35, v229, v35
	v_mul_f32_e32 v32, v36, v32
	v_mul_f32_e32 v33, v37, v33
	v_mfma_f32_16x16x32_bf16 v[72:75], v[154:157], v[240:243], v[72:75]
	v_mul_f32_e32 v34, v38, v34
	v_mul_f32_e32 v35, v39, v35
	v_cvt_pk_bf16_f32 v40, v40, v41
	v_cvt_pk_bf16_f32 v41, v42, v43
	v_cvt_pk_bf16_f32 v42, v32, v33
	v_cvt_pk_bf16_f32 v43, v34, v35
	global_store_dwordx4 v[232:233], v[40:43], off
	v_lshl_add_u64 v[232:233], v[232:233], 0, s[98:99]
	v_mul_f32_e32 v24, v230, v24
	v_mul_f32_e32 v25, v230, v25
	v_mfma_f32_16x16x32_bf16 v[64:67], v[162:165], v[240:243], v[64:67]
	v_mul_f32_e32 v26, v230, v26
	v_mul_f32_e32 v27, v230, v27
	v_mul_f32_e32 v28, v230, v28
	v_mul_f32_e32 v29, v230, v29
	v_mul_f32_e32 v30, v230, v30
	v_mul_f32_e32 v31, v230, v31
	v_mul_f32_e32 v224, s100, v24
	v_mul_f32_e32 v225, s101, v25
	v_mul_f32_e32 v228, s100, v26
	v_mul_f32_e32 v229, s101, v27
	s_setprio 0
	s_setprio 1
	v_mfma_f32_16x16x32_bf16 v[124:127], v[176:179], v[192:195], 0
	v_exp_f32_e32 v224, v224
	v_exp_f32_e32 v225, v225
	v_exp_f32_e32 v228, v228
	v_exp_f32_e32 v229, v229
	v_add_f32_e32 v224, 1.0, v224
	v_add_f32_e32 v225, 1.0, v225
	v_add_f32_e32 v228, 1.0, v228
	v_add_f32_e32 v229, 1.0, v229
	v_rcp_f32_e32 v224, v224
	v_rcp_f32_e32 v225, v225
	v_mfma_f32_16x16x32_bf16 v[116:119], v[184:187], v[192:195], 0
	v_rcp_f32_e32 v228, v228
	v_rcp_f32_e32 v229, v229
	v_nop
	v_mul_f32_e32 v24, v224, v24
	v_mul_f32_e32 v25, v225, v25
	v_mul_f32_e32 v26, v228, v26
	v_mul_f32_e32 v27, v229, v27
	v_mul_f32_e32 v24, v28, v24
	v_mul_f32_e32 v25, v29, v25
	v_mul_f32_e32 v26, v30, v26
	v_mfma_f32_16x16x32_bf16 v[108:111], v[176:179], v[200:203], 0
	v_mul_f32_e32 v27, v31, v27
	v_mul_f32_e32 v16, v230, v16
	v_mul_f32_e32 v17, v230, v17
	v_mul_f32_e32 v18, v230, v18
	v_mul_f32_e32 v19, v230, v19
	v_mul_f32_e32 v20, v230, v20
	v_mul_f32_e32 v21, v230, v21
	v_mul_f32_e32 v22, v230, v22
	v_mul_f32_e32 v23, v230, v23
	v_mul_f32_e32 v224, s100, v16
	v_mfma_f32_16x16x32_bf16 v[100:103], v[184:187], v[200:203], 0
	v_mul_f32_e32 v225, s101, v17
	v_mul_f32_e32 v228, s100, v18
	v_mul_f32_e32 v229, s101, v19
	v_exp_f32_e32 v224, v224
	v_exp_f32_e32 v225, v225
	v_exp_f32_e32 v228, v228
	v_exp_f32_e32 v229, v229
	v_add_f32_e32 v224, 1.0, v224
	v_add_f32_e32 v225, 1.0, v225
	v_add_f32_e32 v228, 1.0, v228
	v_mfma_f32_16x16x32_bf16 v[92:95], v[176:179], v[208:211], 0
	v_add_f32_e32 v229, 1.0, v229
	v_rcp_f32_e32 v224, v224
	v_rcp_f32_e32 v225, v225
	v_rcp_f32_e32 v228, v228
	v_rcp_f32_e32 v229, v229
	v_nop
	v_mul_f32_e32 v16, v224, v16
	v_mul_f32_e32 v17, v225, v17
	v_mul_f32_e32 v18, v228, v18
	v_mul_f32_e32 v19, v229, v19
	v_mfma_f32_16x16x32_bf16 v[84:87], v[184:187], v[208:211], 0
	v_mul_f32_e32 v16, v20, v16
	v_mul_f32_e32 v17, v21, v17
	v_mul_f32_e32 v18, v22, v18
	v_mul_f32_e32 v19, v23, v19
	v_cvt_pk_bf16_f32 v24, v24, v25
	v_cvt_pk_bf16_f32 v25, v26, v27
	v_cvt_pk_bf16_f32 v26, v16, v17
	v_cvt_pk_bf16_f32 v27, v18, v19
	global_store_dwordx4 v[232:233], v[24:27], off
	v_lshl_add_u64 v[232:233], v[232:233], 0, s[98:99]
	v_mfma_f32_16x16x32_bf16 v[76:79], v[176:179], v[216:219], 0
	v_mul_f32_e32 v8, v231, v8
	v_mul_f32_e32 v9, v231, v9
	v_mul_f32_e32 v10, v231, v10
	v_mul_f32_e32 v11, v231, v11
	v_mul_f32_e32 v12, v231, v12
	v_mul_f32_e32 v13, v231, v13
	v_mul_f32_e32 v14, v231, v14
	v_mul_f32_e32 v15, v231, v15
	v_mul_f32_e32 v224, s100, v8
	v_mul_f32_e32 v225, s101, v9
	v_mfma_f32_16x16x32_bf16 v[68:71], v[184:187], v[216:219], 0
	v_mul_f32_e32 v228, s100, v10
	v_mul_f32_e32 v229, s101, v11
	v_exp_f32_e32 v224, v224
	v_exp_f32_e32 v225, v225
	v_exp_f32_e32 v228, v228
	v_exp_f32_e32 v229, v229
	v_add_f32_e32 v224, 1.0, v224
	v_add_f32_e32 v225, 1.0, v225
	v_add_f32_e32 v228, 1.0, v228
	v_add_f32_e32 v229, 1.0, v229
	v_mfma_f32_16x16x32_bf16 v[124:127], v[180:183], v[196:199], v[124:127]
	v_rcp_f32_e32 v224, v224
	v_rcp_f32_e32 v225, v225
	v_rcp_f32_e32 v228, v228
	v_rcp_f32_e32 v229, v229
	v_nop
	v_mul_f32_e32 v8, v224, v8
	v_mul_f32_e32 v9, v225, v9
	v_mul_f32_e32 v10, v228, v10
	v_mul_f32_e32 v11, v229, v11
	v_mul_f32_e32 v8, v12, v8
	v_mfma_f32_16x16x32_bf16 v[116:119], v[188:191], v[196:199], v[116:119]
	v_mul_f32_e32 v9, v13, v9
	v_mul_f32_e32 v10, v14, v10
	v_mul_f32_e32 v11, v15, v11
	v_mul_f32_e32 v4, v231, v4
	v_mul_f32_e32 v5, v231, v5
	v_mul_f32_e32 v6, v231, v6
	v_mul_f32_e32 v7, v231, v7
	v_mul_f32_e32 v0, v231, v0
	v_mul_f32_e32 v1, v231, v1
	v_mul_f32_e32 v2, v231, v2
	v_mfma_f32_16x16x32_bf16 v[108:111], v[180:183], v[204:207], v[108:111]
	v_mul_f32_e32 v3, v231, v3
	v_mul_f32_e32 v224, s100, v4
	v_mul_f32_e32 v225, s101, v5
	v_mul_f32_e32 v228, s100, v6
	v_mul_f32_e32 v229, s101, v7
	v_exp_f32_e32 v224, v224
	v_exp_f32_e32 v225, v225
	v_exp_f32_e32 v228, v228
	v_exp_f32_e32 v229, v229
	v_add_f32_e32 v224, 1.0, v224
	v_mfma_f32_16x16x32_bf16 v[100:103], v[188:191], v[204:207], v[100:103]
	v_add_f32_e32 v225, 1.0, v225
	v_add_f32_e32 v228, 1.0, v228
	v_add_f32_e32 v229, 1.0, v229
	v_rcp_f32_e32 v224, v224
	v_rcp_f32_e32 v225, v225
	v_rcp_f32_e32 v228, v228
	v_rcp_f32_e32 v229, v229
	v_nop
	v_mul_f32_e32 v4, v224, v4
	v_mul_f32_e32 v5, v225, v5
	v_mfma_f32_16x16x32_bf16 v[92:95], v[180:183], v[212:215], v[92:95]
	v_mul_f32_e32 v6, v228, v6
	v_mul_f32_e32 v7, v229, v7
	v_mul_f32_e32 v4, v0, v4
	v_mul_f32_e32 v5, v1, v5
	v_mul_f32_e32 v6, v2, v6
	v_mul_f32_e32 v7, v3, v7
	v_cvt_pk_bf16_f32 v8, v8, v9
	v_cvt_pk_bf16_f32 v9, v10, v11
	v_cvt_pk_bf16_f32 v10, v4, v5
	v_cvt_pk_bf16_f32 v11, v6, v7
	v_mfma_f32_16x16x32_bf16 v[84:87], v[188:191], v[212:215], v[84:87]
	global_store_dwordx4 v[232:233], v[8:11], off
	v_mfma_f32_16x16x32_bf16 v[76:79], v[180:183], v[240:243], v[76:79]
	v_mfma_f32_16x16x32_bf16 v[68:71], v[188:191], v[240:243], v[68:71]
	s_setprio 0
	s_barrier
; #define PG8_STAGE(bufoff, gbase, voff) do { _Pragma("unroll") for (int _i = 0; _i < 2; ++_i) \
;         __builtin_amdgcn_global_load_lds((const unsigned*)((const char*)(gbase) + (voff)[_i]), (LAS unsigned*)(lds + (bufoff) + ldsw + _i * 8192), 16, 0, 0); } while (0)
; #define PG8_LDA(dst, b, h) do { _Pragma("unroll") for (int m = 0; m < 4; ++m) _Pragma("unroll") for (int k = 0; k < 2; ++k) dst[m][k] = *(const LAS bf16x8*)(lds + PG8_SA(b, h) + aoff + m * 2048 + k * 1024); } while (0)
; #define PG8_LDB(dst, b, h) do { _Pragma("unroll") for (int n = 0; n < 2; ++n) _Pragma("unroll") for (int k = 0; k < 2; ++k) dst[n][k] = *(const LAS bf16x8*)(lds + PG8_SB(b, h) + boff + n * 2048 + k * 1024); } while (0)
; #define PG8_MMA(ai, bj, At, Bt) do { __builtin_amdgcn_s_setprio(1); _Pragma("unroll") for (int k = 0; k < 2; ++k) _Pragma("unroll") for (int m = 0; m < 4; ++m) _Pragma("unroll") for (int n = 0; n < 2; ++n) \
;         acc[ai][bj][m][n] = __builtin_amdgcn_mfma_f32_16x16x32_bf16(Bt[n][k], At[m][k], acc[ai][bj][m][n], 0, 0, 0); __builtin_amdgcn_s_setprio(0); } while (0)
; #define PG8_WAIT_V(n) asm volatile("s_waitcnt vmcnt(" #n ")" ::: "memory")
; #define PG8_WAIT_L(n) asm volatile("s_waitcnt lgkmcnt(" #n ")" ::: "memory")
; #define PG8_BAR __builtin_amdgcn_s_barrier()
; #define PG8_SCHED __builtin_amdgcn_sched_barrier(0)
; template <class Epi, bool ALIGN_EPI>
; __device__ __forceinline__ void gemm_phase(LAS unsigned char* lds, const Gemm g, const StaticOrder& S, const Epi& E, const int tid) {
;     ...
;             PG8_LDA(At, 0, 1); PG8_STAGE(PG8_SB(0, 0), b2, voffB); PG8_STAGE(PG8_SB(0, 1), b2 + hB, voffB); PG8_STAGE(PG8_SA(0, 0), a2, voffA);
;             PG8_WAIT_V(8); PG8_WAIT_L(0); PG8_BAR; PG8_MMA(1, 0, At, B0); PG8_MMA(1, 1, At, B1); PG8_BAR; PG8_SCHED;
;             PG8_LDB(B0, 1, 0); PG8_LDB(B1, 1, 1); PG8_SCHED; PG8_LDA(At, 1, 0); PG8_STAGE(PG8_SA(0, 1), a2 + hA, voffA);
;             PG8_WAIT_V(8); PG8_WAIT_L(0); PG8_BAR; PG8_MMA(0, 0, At, B0); PG8_MMA(0, 1, At, B1); PG8_BAR; PG8_SCHED;
	s_add_i32 s65, s33, s45
	v_lshl_add_u64 v[226:227], v[220:221], 0, v[168:169]
	s_mov_b32 m0, s65
	ds_read_b128 v[192:195], v153 offset:16384
	ds_read_b128 v[196:199], v153 offset:17408
	ds_read_b128 v[200:203], v153 offset:18432
	ds_read_b128 v[204:207], v153 offset:19456
	ds_read_b128 v[208:211], v153 offset:20480
	ds_read_b128 v[212:215], v153 offset:21504
	ds_read_b128 v[216:219], v153 offset:22528
	ds_read_b128 v[240:243], v153 offset:23552
	global_load_lds_dwordx4 v[226:227], off
	v_lshl_add_u64 v[244:245], v[220:221], 0, v[128:129]
	s_add_i32 m0, s65, 0x2000
	v_lshl_add_u64 v[220:221], v[220:221], 0, s[12:13]
	s_add_i32 s10, s10, s45
	global_load_lds_dwordx4 v[244:245], off
	v_lshl_add_u64 v[246:247], v[220:221], 0, v[168:169]
	s_mov_b32 m0, s10
	v_lshl_add_u64 v[220:221], v[220:221], 0, v[128:129]
	global_load_lds_dwordx4 v[246:247], off
	s_add_i32 m0, s10, 0x2000
	v_lshl_add_u64 v[248:249], v[166:167], 0, v[132:133]
	global_load_lds_dwordx4 v[220:221], off
	s_mov_b32 m0, s51
	v_lshl_add_u64 v[250:251], v[166:167], 0, v[130:131]
	global_load_lds_dwordx4 v[248:249], off
	s_mov_b32 m0, s52
	s_nop 0
	global_load_lds_dwordx4 v[250:251], off
	s_waitcnt vmcnt(16)
	s_waitcnt lgkmcnt(0)
	s_barrier
	s_setprio 1
	v_mfma_f32_16x16x32_bf16 v[56:59], v[146:149], v[192:195], 0
	v_mfma_f32_16x16x32_bf16 v[48:51], v[158:161], v[192:195], 0
	v_mfma_f32_16x16x32_bf16 v[40:43], v[146:149], v[200:203], 0
	v_mfma_f32_16x16x32_bf16 v[32:35], v[158:161], v[200:203], 0
	v_mfma_f32_16x16x32_bf16 v[24:27], v[146:149], v[208:211], 0
	v_mfma_f32_16x16x32_bf16 v[16:19], v[158:161], v[208:211], 0
	v_mfma_f32_16x16x32_bf16 v[8:11], v[146:149], v[216:219], 0
	v_mfma_f32_16x16x32_bf16 v[4:7], v[158:161], v[216:219], 0
	v_mfma_f32_16x16x32_bf16 v[56:59], v[154:157], v[196:199], v[56:59]
	v_mfma_f32_16x16x32_bf16 v[48:51], v[162:165], v[196:199], v[48:51]
	v_mfma_f32_16x16x32_bf16 v[40:43], v[154:157], v[204:207], v[40:43]
	v_mfma_f32_16x16x32_bf16 v[32:35], v[162:165], v[204:207], v[32:35]
	v_mfma_f32_16x16x32_bf16 v[24:27], v[154:157], v[212:215], v[24:27]
	v_mfma_f32_16x16x32_bf16 v[16:19], v[162:165], v[212:215], v[16:19]
	v_mfma_f32_16x16x32_bf16 v[8:11], v[154:157], v[240:243], v[8:11]
	v_mfma_f32_16x16x32_bf16 v[4:7], v[162:165], v[240:243], v[4:7]
	s_setprio 0
	s_setprio 1
	v_mfma_f32_16x16x32_bf16 v[60:63], v[176:179], v[192:195], 0
	v_mfma_f32_16x16x32_bf16 v[52:55], v[184:187], v[192:195], 0
	v_mfma_f32_16x16x32_bf16 v[44:47], v[176:179], v[200:203], 0
	v_mfma_f32_16x16x32_bf16 v[36:39], v[184:187], v[200:203], 0
	v_mfma_f32_16x16x32_bf16 v[28:31], v[176:179], v[208:211], 0
	v_mfma_f32_16x16x32_bf16 v[20:23], v[184:187], v[208:211], 0
	v_mfma_f32_16x16x32_bf16 v[12:15], v[176:179], v[216:219], 0
	v_mfma_f32_16x16x32_bf16 v[0:3], v[184:187], v[216:219], 0
	v_mfma_f32_16x16x32_bf16 v[60:63], v[180:183], v[196:199], v[60:63]
	v_mfma_f32_16x16x32_bf16 v[52:55], v[188:191], v[196:199], v[52:55]
	v_mfma_f32_16x16x32_bf16 v[44:47], v[180:183], v[204:207], v[44:47]
	v_mfma_f32_16x16x32_bf16 v[36:39], v[188:191], v[204:207], v[36:39]
	v_mfma_f32_16x16x32_bf16 v[28:31], v[180:183], v[212:215], v[28:31]
	v_mfma_f32_16x16x32_bf16 v[20:23], v[188:191], v[212:215], v[20:23]
	v_mfma_f32_16x16x32_bf16 v[12:15], v[180:183], v[240:243], v[12:15]
	v_mfma_f32_16x16x32_bf16 v[0:3], v[188:191], v[240:243], v[0:3]
	s_setprio 0
	s_barrier
	s_add_i32 s10, 0, 0x18000
	v_add_u32_e32 v150, s10, v151
	s_add_i32 s65, 0, 0x1c000
	ds_read_b128 v[146:149], v150
	ds_read_b128 v[154:157], v150 offset:1024
	ds_read_b128 v[158:161], v150 offset:2048
	ds_read_b128 v[162:165], v150 offset:3072
	v_add_u32_e32 v150, s65, v151
	ds_read_b128 v[176:179], v150
	ds_read_b128 v[180:183], v150 offset:1024
	ds_read_b128 v[184:187], v150 offset:2048
	ds_read_b128 v[188:191], v150 offset:3072
	v_lshl_add_u64 v[166:167], v[166:167], 0, s[94:95]
	s_mov_b32 m0, s53
	v_lshl_add_u64 v[252:253], v[166:167], 0, v[132:133]
	ds_read_b128 v[192:195], v153 offset:32768
	ds_read_b128 v[196:199], v153 offset:33792
	ds_read_b128 v[200:203], v153 offset:34816
	ds_read_b128 v[204:207], v153 offset:35840
	ds_read_b128 v[208:211], v153 offset:36864
	ds_read_b128 v[212:215], v153 offset:37888
	ds_read_b128 v[216:219], v153 offset:38912
	ds_read_b128 v[240:243], v153 offset:39936
	global_load_lds_dwordx4 v[252:253], off
	v_lshl_add_u64 v[166:167], v[166:167], 0, v[130:131]
	s_mov_b32 m0, s54
	s_nop 0
	global_load_lds_dwordx4 v[166:167], off
	s_waitcnt vmcnt(12)
	s_waitcnt lgkmcnt(0)
	s_barrier
; #define PG8_STAGE(bufoff, gbase, voff) do { _Pragma("unroll") for (int _i = 0; _i < 2; ++_i) \
;         __builtin_amdgcn_global_load_lds((const unsigned*)((const char*)(gbase) + (voff)[_i]), (LAS unsigned*)(lds + (bufoff) + ldsw + _i * 8192), 16, 0, 0); } while (0)
; #define PG8_LDA(dst, b, h) do { _Pragma("unroll") for (int m = 0; m < 4; ++m) _Pragma("unroll") for (int k = 0; k < 2; ++k) dst[m][k] = *(const LAS bf16x8*)(lds + PG8_SA(b, h) + aoff + m * 2048 + k * 1024); } while (0)
; #define PG8_MMA(ai, bj, At, Bt) do { __builtin_amdgcn_s_setprio(1); _Pragma("unroll") for (int k = 0; k < 2; ++k) _Pragma("unroll") for (int m = 0; m < 4; ++m) _Pragma("unroll") for (int n = 0; n < 2; ++n) \
;         acc[ai][bj][m][n] = __builtin_amdgcn_mfma_f32_16x16x32_bf16(Bt[n][k], At[m][k], acc[ai][bj][m][n], 0, 0, 0); __builtin_amdgcn_s_setprio(0); } while (0)
; #define PG8_WAIT_V(n) asm volatile("s_waitcnt vmcnt(" #n ")" ::: "memory")
; #define PG8_WAIT_L(n) asm volatile("s_waitcnt lgkmcnt(" #n ")" ::: "memory")
; #define PG8_BAR __builtin_amdgcn_s_barrier()
; #define PG8_SCHED __builtin_amdgcn_sched_barrier(0)
; template <class Epi, bool ALIGN_EPI>
; __device__ __forceinline__ void gemm_phase(LAS unsigned char* lds, const Gemm g, const StaticOrder& S, const Epi& E, const int tid) {
;     ...
;             PG8_WAIT_V(8); PG8_WAIT_L(0); PG8_BAR; PG8_MMA(0, 0, At, B0); PG8_MMA(0, 1, At, B1); PG8_BAR; PG8_SCHED;
;             PG8_LDA(At, 1, 1); PG8_STAGE(PG8_SB(1, 0), b3, voffB); PG8_STAGE(PG8_SB(1, 1), b3 + hB, voffB); PG8_STAGE(PG8_SA(1, 0), a3, voffA);
;             PG8_WAIT_V(8); PG8_WAIT_L(0); PG8_BAR; PG8_MMA(1, 0, At, B0); PG8_MMA(1, 1, At, B1); PG8_BAR; PG8_SCHED;
;         }
	s_setprio 1
	v_mfma_f32_16x16x32_bf16 v[120:123], v[146:149], v[192:195], v[120:123]
	v_mfma_f32_16x16x32_bf16 v[112:115], v[158:161], v[192:195], v[112:115]
	v_mfma_f32_16x16x32_bf16 v[104:107], v[146:149], v[200:203], v[104:107]
	v_mfma_f32_16x16x32_bf16 v[96:99], v[158:161], v[200:203], v[96:99]
	v_mfma_f32_16x16x32_bf16 v[88:91], v[146:149], v[208:211], v[88:91]
	v_mfma_f32_16x16x32_bf16 v[80:83], v[158:161], v[208:211], v[80:83]
	v_mfma_f32_16x16x32_bf16 v[72:75], v[146:149], v[216:219], v[72:75]
	v_mfma_f32_16x16x32_bf16 v[64:67], v[158:161], v[216:219], v[64:67]
	v_mfma_f32_16x16x32_bf16 v[120:123], v[154:157], v[196:199], v[120:123]
	v_mfma_f32_16x16x32_bf16 v[112:115], v[162:165], v[196:199], v[112:115]
	v_mfma_f32_16x16x32_bf16 v[104:107], v[154:157], v[204:207], v[104:107]
	v_mfma_f32_16x16x32_bf16 v[96:99], v[162:165], v[204:207], v[96:99]
	v_mfma_f32_16x16x32_bf16 v[88:91], v[154:157], v[212:215], v[88:91]
	v_mfma_f32_16x16x32_bf16 v[80:83], v[162:165], v[212:215], v[80:83]
	v_mfma_f32_16x16x32_bf16 v[72:75], v[154:157], v[240:243], v[72:75]
	v_mfma_f32_16x16x32_bf16 v[64:67], v[162:165], v[240:243], v[64:67]
	s_setprio 0
	s_setprio 1
	v_mfma_f32_16x16x32_bf16 v[124:127], v[176:179], v[192:195], v[124:127]
	v_mfma_f32_16x16x32_bf16 v[116:119], v[184:187], v[192:195], v[116:119]
	v_mfma_f32_16x16x32_bf16 v[108:111], v[176:179], v[200:203], v[108:111]
	v_mfma_f32_16x16x32_bf16 v[100:103], v[184:187], v[200:203], v[100:103]
	v_mfma_f32_16x16x32_bf16 v[92:95], v[176:179], v[208:211], v[92:95]
	v_mfma_f32_16x16x32_bf16 v[84:87], v[184:187], v[208:211], v[84:87]
	v_mfma_f32_16x16x32_bf16 v[76:79], v[176:179], v[216:219], v[76:79]
	v_mfma_f32_16x16x32_bf16 v[68:71], v[184:187], v[216:219], v[68:71]
	v_mfma_f32_16x16x32_bf16 v[124:127], v[180:183], v[196:199], v[124:127]
	v_mfma_f32_16x16x32_bf16 v[116:119], v[188:191], v[196:199], v[116:119]
	v_mfma_f32_16x16x32_bf16 v[108:111], v[180:183], v[204:207], v[108:111]
	v_mfma_f32_16x16x32_bf16 v[100:103], v[188:191], v[204:207], v[100:103]
	v_mfma_f32_16x16x32_bf16 v[92:95], v[180:183], v[212:215], v[92:95]
	v_mfma_f32_16x16x32_bf16 v[84:87], v[188:191], v[212:215], v[84:87]
	v_mfma_f32_16x16x32_bf16 v[76:79], v[180:183], v[240:243], v[76:79]
	v_mfma_f32_16x16x32_bf16 v[68:71], v[188:191], v[240:243], v[68:71]
	s_setprio 0
	s_barrier
	s_add_i32 s10, s10, s45
	v_lshl_add_u64 v[166:167], v[226:227], 0, s[92:93]
	s_mov_b32 m0, s10
	ds_read_b128 v[192:195], v153 offset:49152
	ds_read_b128 v[196:199], v153 offset:50176
	ds_read_b128 v[200:203], v153 offset:51200
	ds_read_b128 v[204:207], v153 offset:52224
	ds_read_b128 v[208:211], v153 offset:53248
	ds_read_b128 v[212:215], v153 offset:54272
	ds_read_b128 v[216:219], v153 offset:55296
	ds_read_b128 v[240:243], v153 offset:56320
	global_load_lds_dwordx4 v[166:167], off
	v_lshl_add_u64 v[166:167], v[244:245], 0, s[92:93]
	s_add_i32 m0, s10, 0x2000
	s_add_i32 s10, s65, s45
	global_load_lds_dwordx4 v[166:167], off
	v_lshl_add_u64 v[166:167], v[246:247], 0, s[92:93]
	s_mov_b32 m0, s10
	s_nop 0
	global_load_lds_dwordx4 v[166:167], off
	v_lshl_add_u64 v[166:167], v[220:221], 0, s[92:93]
	s_add_i32 m0, s10, 0x2000
	s_nop 0
	global_load_lds_dwordx4 v[166:167], off
	v_lshl_add_u64 v[166:167], v[248:249], 0, s[92:93]
	s_mov_b32 m0, s56
	s_nop 0
	global_load_lds_dwordx4 v[166:167], off
	v_lshl_add_u64 v[166:167], v[250:251], 0, s[92:93]
	s_mov_b32 m0, s57
	s_nop 0
	global_load_lds_dwordx4 v[166:167], off
	s_waitcnt vmcnt(8)
	s_waitcnt lgkmcnt(0)
	s_barrier
	s_setprio 1
	v_mfma_f32_16x16x32_bf16 v[56:59], v[146:149], v[192:195], v[56:59]
	v_mfma_f32_16x16x32_bf16 v[48:51], v[158:161], v[192:195], v[48:51]
	v_mfma_f32_16x16x32_bf16 v[40:43], v[146:149], v[200:203], v[40:43]
	v_mfma_f32_16x16x32_bf16 v[32:35], v[158:161], v[200:203], v[32:35]
	v_mfma_f32_16x16x32_bf16 v[24:27], v[146:149], v[208:211], v[24:27]
	v_mfma_f32_16x16x32_bf16 v[16:19], v[158:161], v[208:211], v[16:19]
	v_mfma_f32_16x16x32_bf16 v[8:11], v[146:149], v[216:219], v[8:11]
	v_mfma_f32_16x16x32_bf16 v[4:7], v[158:161], v[216:219], v[4:7]
	v_mfma_f32_16x16x32_bf16 v[56:59], v[154:157], v[196:199], v[56:59]
	v_mfma_f32_16x16x32_bf16 v[48:51], v[162:165], v[196:199], v[48:51]
	v_mfma_f32_16x16x32_bf16 v[40:43], v[154:157], v[204:207], v[40:43]
	v_mfma_f32_16x16x32_bf16 v[32:35], v[162:165], v[204:207], v[32:35]
	v_mfma_f32_16x16x32_bf16 v[24:27], v[154:157], v[212:215], v[24:27]
	v_mfma_f32_16x16x32_bf16 v[16:19], v[162:165], v[212:215], v[16:19]
	v_mfma_f32_16x16x32_bf16 v[8:11], v[154:157], v[240:243], v[8:11]
	v_mfma_f32_16x16x32_bf16 v[4:7], v[162:165], v[240:243], v[4:7]
	s_setprio 0
	s_setprio 1
	v_mfma_f32_16x16x32_bf16 v[60:63], v[176:179], v[192:195], v[60:63]
	v_mfma_f32_16x16x32_bf16 v[52:55], v[184:187], v[192:195], v[52:55]
	v_mfma_f32_16x16x32_bf16 v[44:47], v[176:179], v[200:203], v[44:47]
	v_mfma_f32_16x16x32_bf16 v[36:39], v[184:187], v[200:203], v[36:39]
	v_mfma_f32_16x16x32_bf16 v[28:31], v[176:179], v[208:211], v[28:31]
	v_mfma_f32_16x16x32_bf16 v[20:23], v[184:187], v[208:211], v[20:23]
	v_mfma_f32_16x16x32_bf16 v[12:15], v[176:179], v[216:219], v[12:15]
	v_mfma_f32_16x16x32_bf16 v[0:3], v[184:187], v[216:219], v[0:3]
	v_mfma_f32_16x16x32_bf16 v[60:63], v[180:183], v[196:199], v[60:63]
	v_mfma_f32_16x16x32_bf16 v[52:55], v[188:191], v[196:199], v[52:55]
	v_mfma_f32_16x16x32_bf16 v[44:47], v[180:183], v[204:207], v[44:47]
	v_mfma_f32_16x16x32_bf16 v[36:39], v[188:191], v[204:207], v[36:39]
	v_mfma_f32_16x16x32_bf16 v[28:31], v[180:183], v[212:215], v[28:31]
	v_mfma_f32_16x16x32_bf16 v[20:23], v[188:191], v[212:215], v[20:23]
	v_mfma_f32_16x16x32_bf16 v[12:15], v[180:183], v[240:243], v[12:15]
	v_mfma_f32_16x16x32_bf16 v[0:3], v[188:191], v[240:243], v[0:3]
	s_setprio 0
	s_barrier
	v_lshl_add_u64 v[142:143], v[142:143], 0, s[80:81]
	v_lshl_add_u64 v[144:145], v[144:145], 0, s[80:81]
	s_mov_b32 s10, s11
	s_cmp_eq_u32 s10, s58
	s_cbranch_scc1 .Lgu_last
	s_branch .LBB0_308
; #define PG8_STAGE(bufoff, gbase, voff) do { _Pragma("unroll") for (int _i = 0; _i < 2; ++_i) \
;         __builtin_amdgcn_global_load_lds((const unsigned*)((const char*)(gbase) + (voff)[_i]), (LAS unsigned*)(lds + (bufoff) + ldsw + _i * 8192), 16, 0, 0); } while (0)
; #define PG8_LDA(dst, b, h) do { _Pragma("unroll") for (int m = 0; m < 4; ++m) _Pragma("unroll") for (int k = 0; k < 2; ++k) dst[m][k] = *(const LAS bf16x8*)(lds + PG8_SA(b, h) + aoff + m * 2048 + k * 1024); } while (0)
; #define PG8_WAIT_V(n) asm volatile("s_waitcnt vmcnt(" #n ")" ::: "memory")
; #define PG8_BAR __builtin_amdgcn_s_barrier()
; template <class Epi, bool ALIGN_EPI>
; __device__ __forceinline__ void gemm_phase(LAS unsigned char* lds, const Gemm g, const StaticOrder& S, const Epi& E, const int tid) {
;     ...
;         const bool has_next = S.next(ui + 1, nxt);
;         const char* nA = has_next ? (const char*)g.A + (size_t)nxt.pm * tA + (size_t)nxt.pn * g.apn * 2 : cA; const char* nB = has_next ? (const char*)g.Bt + (size_t)nxt.pn * tB : cB;
;         for (int t = 0; t < nt; t += 2) {
;             const bool last = (t == nt - 2);
;             const char* a1 = cA + (size_t)(t + 1) * kstep;
;             const char* a2 = last ? nA : cA + (size_t)(t + 2) * kstep; const char* b2 = last ? nB : cB + (size_t)(t + 2) * kstep;
;             const char* a3 = a2 + kstep; const char* b3 = b2 + kstep;
;             PG8_LDB(B0, 0, 0); PG8_LDB(B1, 0, 1); PG8_SCHED; PG8_LDA(At, 0, 0); PG8_STAGE(PG8_SA(1, 1), a1 + hA, voffA);
;             PG8_WAIT_V(8); PG8_WAIT_L(0); PG8_BAR; PG8_MMA(0, 0, At, B0); PG8_MMA(0, 1, At, B1); PG8_BAR; PG8_SCHED;
;             PG8_LDA(At, 0, 1); PG8_STAGE(PG8_SB(0, 0), b2, voffB); PG8_STAGE(PG8_SB(0, 1), b2 + hB, voffB); PG8_STAGE(PG8_SA(0, 0), a2, voffA);
;             PG8_WAIT_V(8); PG8_WAIT_L(0); PG8_BAR; PG8_MMA(1, 0, At, B0); PG8_MMA(1, 1, At, B1); PG8_BAR; PG8_SCHED;
;             PG8_LDB(B0, 1, 0); PG8_LDB(B1, 1, 1); PG8_SCHED; PG8_LDA(At, 1, 0); PG8_STAGE(PG8_SA(0, 1), a2 + hA, voffA);
;             PG8_WAIT_V(8); PG8_WAIT_L(0); PG8_BAR; PG8_MMA(0, 0, At, B0); PG8_MMA(0, 1, At, B1); PG8_BAR; PG8_SCHED;
;             PG8_LDA(At, 1, 1); PG8_STAGE(PG8_SB(1, 0), b3, voffB); PG8_STAGE(PG8_SB(1, 1), b3 + hB, voffB); PG8_STAGE(PG8_SA(1, 0), a3, voffA);
;             PG8_WAIT_V(8); PG8_WAIT_L(0); PG8_BAR; PG8_MMA(1, 0, At, B0); PG8_MMA(1, 1, At, B1); PG8_BAR; PG8_SCHED;
.Lgu_first:
	s_add_i32 s11, s10, 2
	s_cmp_eq_u32 s58, s10
	v_lshl_add_u64 v[146:147], v[142:143], 0, s[92:93]
	s_cselect_b64 vcc, -1, 0
	v_add_u32_e32 v150, s33, v151
	s_add_i32 s10, 0, 0x14000
	v_cndmask_b32_e32 v167, v147, v139, vcc
	v_cndmask_b32_e32 v166, v146, v138, vcc
	ds_read_b128 v[146:149], v150
	ds_read_b128 v[154:157], v150 offset:1024
	ds_read_b128 v[158:161], v150 offset:2048
	ds_read_b128 v[162:165], v150 offset:3072
	v_add_u32_e32 v150, s10, v151
	ds_read_b128 v[176:179], v150
	ds_read_b128 v[180:183], v150 offset:1024
	ds_read_b128 v[184:187], v150 offset:2048
	ds_read_b128 v[188:191], v150 offset:3072
	v_cndmask_b32_e32 v221, v145, v141, vcc
	v_cndmask_b32_e32 v220, v144, v140, vcc
	v_lshl_add_u64 v[226:227], v[142:143], 0, v[134:135]
	s_add_i32 m0, s51, 0xc000
	ds_read_b128 v[192:195], v153
	ds_read_b128 v[196:199], v153 offset:1024
	ds_read_b128 v[200:203], v153 offset:2048
	ds_read_b128 v[204:207], v153 offset:3072
	ds_read_b128 v[208:211], v153 offset:4096
	ds_read_b128 v[212:215], v153 offset:5120
	ds_read_b128 v[216:219], v153 offset:6144
	ds_read_b128 v[240:243], v153 offset:7168
	global_load_lds_dwordx4 v[226:227], off
	v_lshl_add_u64 v[226:227], v[142:143], 0, v[136:137]
	s_add_i32 m0, s51, 0xe000
	s_nop 0
	global_load_lds_dwordx4 v[226:227], off
	s_waitcnt vmcnt(8)
	s_waitcnt lgkmcnt(0)
	s_barrier
	s_setprio 1
	v_mfma_f32_16x16x32_bf16 v[120:123], v[146:149], v[192:195], 0
	v_mfma_f32_16x16x32_bf16 v[112:115], v[158:161], v[192:195], 0
	v_mfma_f32_16x16x32_bf16 v[104:107], v[146:149], v[200:203], 0
	v_mfma_f32_16x16x32_bf16 v[96:99], v[158:161], v[200:203], 0
	v_mfma_f32_16x16x32_bf16 v[88:91], v[146:149], v[208:211], 0
	v_mfma_f32_16x16x32_bf16 v[80:83], v[158:161], v[208:211], 0
	v_mfma_f32_16x16x32_bf16 v[72:75], v[146:149], v[216:219], 0
	v_mfma_f32_16x16x32_bf16 v[64:67], v[158:161], v[216:219], 0
	v_mfma_f32_16x16x32_bf16 v[120:123], v[154:157], v[196:199], v[120:123]
	v_mfma_f32_16x16x32_bf16 v[112:115], v[162:165], v[196:199], v[112:115]
	v_mfma_f32_16x16x32_bf16 v[104:107], v[154:157], v[204:207], v[104:107]
	v_mfma_f32_16x16x32_bf16 v[96:99], v[162:165], v[204:207], v[96:99]
	v_mfma_f32_16x16x32_bf16 v[88:91], v[154:157], v[212:215], v[88:91]
	v_mfma_f32_16x16x32_bf16 v[80:83], v[162:165], v[212:215], v[80:83]
	v_mfma_f32_16x16x32_bf16 v[72:75], v[154:157], v[240:243], v[72:75]
	v_mfma_f32_16x16x32_bf16 v[64:67], v[162:165], v[240:243], v[64:67]
	s_setprio 0
	s_setprio 1
	v_mfma_f32_16x16x32_bf16 v[124:127], v[176:179], v[192:195], 0
	v_mfma_f32_16x16x32_bf16 v[116:119], v[184:187], v[192:195], 0
	v_mfma_f32_16x16x32_bf16 v[108:111], v[176:179], v[200:203], 0
	v_mfma_f32_16x16x32_bf16 v[100:103], v[184:187], v[200:203], 0
	v_mfma_f32_16x16x32_bf16 v[92:95], v[176:179], v[208:211], 0
	v_mfma_f32_16x16x32_bf16 v[84:87], v[184:187], v[208:211], 0
	v_mfma_f32_16x16x32_bf16 v[76:79], v[176:179], v[216:219], 0
	v_mfma_f32_16x16x32_bf16 v[68:71], v[184:187], v[216:219], 0
	v_mfma_f32_16x16x32_bf16 v[124:127], v[180:183], v[196:199], v[124:127]
	v_mfma_f32_16x16x32_bf16 v[116:119], v[188:191], v[196:199], v[116:119]
	v_mfma_f32_16x16x32_bf16 v[108:111], v[180:183], v[204:207], v[108:111]
	v_mfma_f32_16x16x32_bf16 v[100:103], v[188:191], v[204:207], v[100:103]
	v_mfma_f32_16x16x32_bf16 v[92:95], v[180:183], v[212:215], v[92:95]
	v_mfma_f32_16x16x32_bf16 v[84:87], v[188:191], v[212:215], v[84:87]
	v_mfma_f32_16x16x32_bf16 v[76:79], v[180:183], v[240:243], v[76:79]
	v_mfma_f32_16x16x32_bf16 v[68:71], v[188:191], v[240:243], v[68:71]
	s_setprio 0
	s_barrier
	s_add_i32 s65, s33, s45
	v_lshl_add_u64 v[226:227], v[220:221], 0, v[168:169]
	s_mov_b32 m0, s65
	ds_read_b128 v[192:195], v153 offset:16384
	ds_read_b128 v[196:199], v153 offset:17408
	ds_read_b128 v[200:203], v153 offset:18432
	ds_read_b128 v[204:207], v153 offset:19456
	ds_read_b128 v[208:211], v153 offset:20480
	ds_read_b128 v[212:215], v153 offset:21504
	ds_read_b128 v[216:219], v153 offset:22528
	ds_read_b128 v[240:243], v153 offset:23552
	global_load_lds_dwordx4 v[226:227], off
	v_lshl_add_u64 v[244:245], v[220:221], 0, v[128:129]
	s_add_i32 m0, s65, 0x2000
	v_lshl_add_u64 v[220:221], v[220:221], 0, s[12:13]
	s_add_i32 s10, s10, s45
	global_load_lds_dwordx4 v[244:245], off
	v_lshl_add_u64 v[246:247], v[220:221], 0, v[168:169]
	s_mov_b32 m0, s10
	v_lshl_add_u64 v[220:221], v[220:221], 0, v[128:129]
	global_load_lds_dwordx4 v[246:247], off
	s_add_i32 m0, s10, 0x2000
	v_lshl_add_u64 v[248:249], v[166:167], 0, v[132:133]
	global_load_lds_dwordx4 v[220:221], off
	s_mov_b32 m0, s51
	v_lshl_add_u64 v[250:251], v[166:167], 0, v[130:131]
	global_load_lds_dwordx4 v[248:249], off
	s_mov_b32 m0, s52
	s_nop 0
	global_load_lds_dwordx4 v[250:251], off
	s_waitcnt vmcnt(8)
	s_waitcnt lgkmcnt(0)
	s_barrier
; #define PG8_STAGE(bufoff, gbase, voff) do { _Pragma("unroll") for (int _i = 0; _i < 2; ++_i) \
;         __builtin_amdgcn_global_load_lds((const unsigned*)((const char*)(gbase) + (voff)[_i]), (LAS unsigned*)(lds + (bufoff) + ldsw + _i * 8192), 16, 0, 0); } while (0)
; #define PG8_LDA(dst, b, h) do { _Pragma("unroll") for (int m = 0; m < 4; ++m) _Pragma("unroll") for (int k = 0; k < 2; ++k) dst[m][k] = *(const LAS bf16x8*)(lds + PG8_SA(b, h) + aoff + m * 2048 + k * 1024); } while (0)
; #define PG8_LDB(dst, b, h) do { _Pragma("unroll") for (int n = 0; n < 2; ++n) _Pragma("unroll") for (int k = 0; k < 2; ++k) dst[n][k] = *(const LAS bf16x8*)(lds + PG8_SB(b, h) + boff + n * 2048 + k * 1024); } while (0)
; #define PG8_MMA(ai, bj, At, Bt) do { __builtin_amdgcn_s_setprio(1); _Pragma("unroll") for (int k = 0; k < 2; ++k) _Pragma("unroll") for (int m = 0; m < 4; ++m) _Pragma("unroll") for (int n = 0; n < 2; ++n) \
;         acc[ai][bj][m][n] = __builtin_amdgcn_mfma_f32_16x16x32_bf16(Bt[n][k], At[m][k], acc[ai][bj][m][n], 0, 0, 0); __builtin_amdgcn_s_setprio(0); } while (0)
; #define PG8_WAIT_V(n) asm volatile("s_waitcnt vmcnt(" #n ")" ::: "memory")
; #define PG8_WAIT_L(n) asm volatile("s_waitcnt lgkmcnt(" #n ")" ::: "memory")
; #define PG8_BAR __builtin_amdgcn_s_barrier()
; #define PG8_SCHED __builtin_amdgcn_sched_barrier(0)
; template <class Epi, bool ALIGN_EPI>
; __device__ __forceinline__ void gemm_phase(LAS unsigned char* lds, const Gemm g, const StaticOrder& S, const Epi& E, const int tid) {
;     ...
;             PG8_WAIT_V(8); PG8_WAIT_L(0); PG8_BAR; PG8_MMA(1, 0, At, B0); PG8_MMA(1, 1, At, B1); PG8_BAR; PG8_SCHED;
;             PG8_LDB(B0, 1, 0); PG8_LDB(B1, 1, 1); PG8_SCHED; PG8_LDA(At, 1, 0); PG8_STAGE(PG8_SA(0, 1), a2 + hA, voffA);
;             PG8_WAIT_V(8); PG8_WAIT_L(0); PG8_BAR; PG8_MMA(0, 0, At, B0); PG8_MMA(0, 1, At, B1); PG8_BAR; PG8_SCHED;
;             PG8_LDA(At, 1, 1); PG8_STAGE(PG8_SB(1, 0), b3, voffB); PG8_STAGE(PG8_SB(1, 1), b3 + hB, voffB); PG8_STAGE(PG8_SA(1, 0), a3, voffA);
;             PG8_WAIT_V(8); PG8_WAIT_L(0); PG8_BAR; PG8_MMA(1, 0, At, B0); PG8_MMA(1, 1, At, B1); PG8_BAR; PG8_SCHED;
	s_setprio 1
	v_mfma_f32_16x16x32_bf16 v[56:59], v[146:149], v[192:195], 0
	v_mfma_f32_16x16x32_bf16 v[48:51], v[158:161], v[192:195], 0
	v_mfma_f32_16x16x32_bf16 v[40:43], v[146:149], v[200:203], 0
	v_mfma_f32_16x16x32_bf16 v[32:35], v[158:161], v[200:203], 0
	v_mfma_f32_16x16x32_bf16 v[24:27], v[146:149], v[208:211], 0
	v_mfma_f32_16x16x32_bf16 v[16:19], v[158:161], v[208:211], 0
	v_mfma_f32_16x16x32_bf16 v[8:11], v[146:149], v[216:219], 0
	v_mfma_f32_16x16x32_bf16 v[4:7], v[158:161], v[216:219], 0
	v_mfma_f32_16x16x32_bf16 v[56:59], v[154:157], v[196:199], v[56:59]
	v_mfma_f32_16x16x32_bf16 v[48:51], v[162:165], v[196:199], v[48:51]
	v_mfma_f32_16x16x32_bf16 v[40:43], v[154:157], v[204:207], v[40:43]
	v_mfma_f32_16x16x32_bf16 v[32:35], v[162:165], v[204:207], v[32:35]
	v_mfma_f32_16x16x32_bf16 v[24:27], v[154:157], v[212:215], v[24:27]
	v_mfma_f32_16x16x32_bf16 v[16:19], v[162:165], v[212:215], v[16:19]
	v_mfma_f32_16x16x32_bf16 v[8:11], v[154:157], v[240:243], v[8:11]
	v_mfma_f32_16x16x32_bf16 v[4:7], v[162:165], v[240:243], v[4:7]
	s_setprio 0
	s_setprio 1
	v_mfma_f32_16x16x32_bf16 v[60:63], v[176:179], v[192:195], 0
	v_mfma_f32_16x16x32_bf16 v[52:55], v[184:187], v[192:195], 0
	v_mfma_f32_16x16x32_bf16 v[44:47], v[176:179], v[200:203], 0
	v_mfma_f32_16x16x32_bf16 v[36:39], v[184:187], v[200:203], 0
	v_mfma_f32_16x16x32_bf16 v[28:31], v[176:179], v[208:211], 0
	v_mfma_f32_16x16x32_bf16 v[20:23], v[184:187], v[208:211], 0
	v_mfma_f32_16x16x32_bf16 v[12:15], v[176:179], v[216:219], 0
	v_mfma_f32_16x16x32_bf16 v[0:3], v[184:187], v[216:219], 0
	v_mfma_f32_16x16x32_bf16 v[60:63], v[180:183], v[196:199], v[60:63]
	v_mfma_f32_16x16x32_bf16 v[52:55], v[188:191], v[196:199], v[52:55]
	v_mfma_f32_16x16x32_bf16 v[44:47], v[180:183], v[204:207], v[44:47]
	v_mfma_f32_16x16x32_bf16 v[36:39], v[188:191], v[204:207], v[36:39]
	v_mfma_f32_16x16x32_bf16 v[28:31], v[180:183], v[212:215], v[28:31]
	v_mfma_f32_16x16x32_bf16 v[20:23], v[188:191], v[212:215], v[20:23]
	v_mfma_f32_16x16x32_bf16 v[12:15], v[180:183], v[240:243], v[12:15]
	v_mfma_f32_16x16x32_bf16 v[0:3], v[188:191], v[240:243], v[0:3]
	s_setprio 0
	s_barrier
	s_add_i32 s10, 0, 0x18000
	v_add_u32_e32 v150, s10, v151
	s_add_i32 s65, 0, 0x1c000
	ds_read_b128 v[146:149], v150
	ds_read_b128 v[154:157], v150 offset:1024
	ds_read_b128 v[158:161], v150 offset:2048
	ds_read_b128 v[162:165], v150 offset:3072
	v_add_u32_e32 v150, s65, v151
	ds_read_b128 v[176:179], v150
	ds_read_b128 v[180:183], v150 offset:1024
	ds_read_b128 v[184:187], v150 offset:2048
	ds_read_b128 v[188:191], v150 offset:3072
	v_lshl_add_u64 v[166:167], v[166:167], 0, s[94:95]
	s_mov_b32 m0, s53
	v_lshl_add_u64 v[252:253], v[166:167], 0, v[132:133]
	ds_read_b128 v[192:195], v153 offset:32768
	ds_read_b128 v[196:199], v153 offset:33792
	ds_read_b128 v[200:203], v153 offset:34816
	ds_read_b128 v[204:207], v153 offset:35840
	ds_read_b128 v[208:211], v153 offset:36864
	ds_read_b128 v[212:215], v153 offset:37888
	ds_read_b128 v[216:219], v153 offset:38912
	ds_read_b128 v[240:243], v153 offset:39936
	global_load_lds_dwordx4 v[252:253], off
	v_lshl_add_u64 v[166:167], v[166:167], 0, v[130:131]
	s_mov_b32 m0, s54
	s_nop 0
	global_load_lds_dwordx4 v[166:167], off
	s_waitcnt vmcnt(8)
	s_waitcnt lgkmcnt(0)
	s_barrier
	s_setprio 1
	v_mfma_f32_16x16x32_bf16 v[120:123], v[146:149], v[192:195], v[120:123]
	v_mfma_f32_16x16x32_bf16 v[112:115], v[158:161], v[192:195], v[112:115]
	v_mfma_f32_16x16x32_bf16 v[104:107], v[146:149], v[200:203], v[104:107]
	v_mfma_f32_16x16x32_bf16 v[96:99], v[158:161], v[200:203], v[96:99]
	v_mfma_f32_16x16x32_bf16 v[88:91], v[146:149], v[208:211], v[88:91]
	v_mfma_f32_16x16x32_bf16 v[80:83], v[158:161], v[208:211], v[80:83]
	v_mfma_f32_16x16x32_bf16 v[72:75], v[146:149], v[216:219], v[72:75]
	v_mfma_f32_16x16x32_bf16 v[64:67], v[158:161], v[216:219], v[64:67]
	v_mfma_f32_16x16x32_bf16 v[120:123], v[154:157], v[196:199], v[120:123]
	v_mfma_f32_16x16x32_bf16 v[112:115], v[162:165], v[196:199], v[112:115]
	v_mfma_f32_16x16x32_bf16 v[104:107], v[154:157], v[204:207], v[104:107]
	v_mfma_f32_16x16x32_bf16 v[96:99], v[162:165], v[204:207], v[96:99]
	v_mfma_f32_16x16x32_bf16 v[88:91], v[154:157], v[212:215], v[88:91]
	v_mfma_f32_16x16x32_bf16 v[80:83], v[162:165], v[212:215], v[80:83]
	v_mfma_f32_16x16x32_bf16 v[72:75], v[154:157], v[240:243], v[72:75]
	v_mfma_f32_16x16x32_bf16 v[64:67], v[162:165], v[240:243], v[64:67]
	s_setprio 0
	s_setprio 1
	v_mfma_f32_16x16x32_bf16 v[124:127], v[176:179], v[192:195], v[124:127]
	v_mfma_f32_16x16x32_bf16 v[116:119], v[184:187], v[192:195], v[116:119]
	v_mfma_f32_16x16x32_bf16 v[108:111], v[176:179], v[200:203], v[108:111]
	v_mfma_f32_16x16x32_bf16 v[100:103], v[184:187], v[200:203], v[100:103]
	v_mfma_f32_16x16x32_bf16 v[92:95], v[176:179], v[208:211], v[92:95]
	v_mfma_f32_16x16x32_bf16 v[84:87], v[184:187], v[208:211], v[84:87]
	v_mfma_f32_16x16x32_bf16 v[76:79], v[176:179], v[216:219], v[76:79]
	v_mfma_f32_16x16x32_bf16 v[68:71], v[184:187], v[216:219], v[68:71]
	v_mfma_f32_16x16x32_bf16 v[124:127], v[180:183], v[196:199], v[124:127]
	v_mfma_f32_16x16x32_bf16 v[116:119], v[188:191], v[196:199], v[116:119]
	v_mfma_f32_16x16x32_bf16 v[108:111], v[180:183], v[204:207], v[108:111]
	v_mfma_f32_16x16x32_bf16 v[100:103], v[188:191], v[204:207], v[100:103]
	v_mfma_f32_16x16x32_bf16 v[92:95], v[180:183], v[212:215], v[92:95]
	v_mfma_f32_16x16x32_bf16 v[84:87], v[188:191], v[212:215], v[84:87]
	v_mfma_f32_16x16x32_bf16 v[76:79], v[180:183], v[240:243], v[76:79]
	v_mfma_f32_16x16x32_bf16 v[68:71], v[188:191], v[240:243], v[68:71]
	s_setprio 0
	s_barrier
; #define PG8_STAGE(bufoff, gbase, voff) do { _Pragma("unroll") for (int _i = 0; _i < 2; ++_i) \
;         __builtin_amdgcn_global_load_lds((const unsigned*)((const char*)(gbase) + (voff)[_i]), (LAS unsigned*)(lds + (bufoff) + ldsw + _i * 8192), 16, 0, 0); } while (0)
; #define PG8_LDA(dst, b, h) do { _Pragma("unroll") for (int m = 0; m < 4; ++m) _Pragma("unroll") for (int k = 0; k < 2; ++k) dst[m][k] = *(const LAS bf16x8*)(lds + PG8_SA(b, h) + aoff + m * 2048 + k * 1024); } while (0)
; #define PG8_MMA(ai, bj, At, Bt) do { __builtin_amdgcn_s_setprio(1); _Pragma("unroll") for (int k = 0; k < 2; ++k) _Pragma("unroll") for (int m = 0; m < 4; ++m) _Pragma("unroll") for (int n = 0; n < 2; ++n) \
;         acc[ai][bj][m][n] = __builtin_amdgcn_mfma_f32_16x16x32_bf16(Bt[n][k], At[m][k], acc[ai][bj][m][n], 0, 0, 0); __builtin_amdgcn_s_setprio(0); } while (0)
; #define PG8_WAIT_V(n) asm volatile("s_waitcnt vmcnt(" #n ")" ::: "memory")
; #define PG8_WAIT_L(n) asm volatile("s_waitcnt lgkmcnt(" #n ")" ::: "memory")
; #define PG8_BAR __builtin_amdgcn_s_barrier()
; #define PG8_SCHED __builtin_amdgcn_sched_barrier(0)
; template <class Epi, bool ALIGN_EPI>
; __device__ __forceinline__ void gemm_phase(LAS unsigned char* lds, const Gemm g, const StaticOrder& S, const Epi& E, const int tid) {
;     ...
;             PG8_LDA(At, 1, 1); PG8_STAGE(PG8_SB(1, 0), b3, voffB); PG8_STAGE(PG8_SB(1, 1), b3 + hB, voffB); PG8_STAGE(PG8_SA(1, 0), a3, voffA);
;             PG8_WAIT_V(8); PG8_WAIT_L(0); PG8_BAR; PG8_MMA(1, 0, At, B0); PG8_MMA(1, 1, At, B1); PG8_BAR; PG8_SCHED;
;     ...
;         cur = nxt; cA = nA; cB = nB; ++ui;
	s_add_i32 s10, s10, s45
	v_lshl_add_u64 v[166:167], v[226:227], 0, s[92:93]
	s_mov_b32 m0, s10
	ds_read_b128 v[192:195], v153 offset:49152
	ds_read_b128 v[196:199], v153 offset:50176
	ds_read_b128 v[200:203], v153 offset:51200
	ds_read_b128 v[204:207], v153 offset:52224
	ds_read_b128 v[208:211], v153 offset:53248
	ds_read_b128 v[212:215], v153 offset:54272
	ds_read_b128 v[216:219], v153 offset:55296
	ds_read_b128 v[240:243], v153 offset:56320
	global_load_lds_dwordx4 v[166:167], off
	v_lshl_add_u64 v[166:167], v[244:245], 0, s[92:93]
	s_add_i32 m0, s10, 0x2000
	s_add_i32 s10, s65, s45
	global_load_lds_dwordx4 v[166:167], off
	v_lshl_add_u64 v[166:167], v[246:247], 0, s[92:93]
	s_mov_b32 m0, s10
	s_nop 0
	global_load_lds_dwordx4 v[166:167], off
	v_lshl_add_u64 v[166:167], v[220:221], 0, s[92:93]
	s_add_i32 m0, s10, 0x2000
	s_nop 0
	global_load_lds_dwordx4 v[166:167], off
	v_lshl_add_u64 v[166:167], v[248:249], 0, s[92:93]
	s_mov_b32 m0, s56
	s_nop 0
	global_load_lds_dwordx4 v[166:167], off
	v_lshl_add_u64 v[166:167], v[250:251], 0, s[92:93]
	s_mov_b32 m0, s57
	s_nop 0
	global_load_lds_dwordx4 v[166:167], off
	s_waitcnt vmcnt(8)
	s_waitcnt lgkmcnt(0)
	s_barrier
	s_setprio 1
	v_mfma_f32_16x16x32_bf16 v[56:59], v[146:149], v[192:195], v[56:59]
	v_mfma_f32_16x16x32_bf16 v[48:51], v[158:161], v[192:195], v[48:51]
	v_mfma_f32_16x16x32_bf16 v[40:43], v[146:149], v[200:203], v[40:43]
	v_mfma_f32_16x16x32_bf16 v[32:35], v[158:161], v[200:203], v[32:35]
	v_mfma_f32_16x16x32_bf16 v[24:27], v[146:149], v[208:211], v[24:27]
	v_mfma_f32_16x16x32_bf16 v[16:19], v[158:161], v[208:211], v[16:19]
	v_mfma_f32_16x16x32_bf16 v[8:11], v[146:149], v[216:219], v[8:11]
	v_mfma_f32_16x16x32_bf16 v[4:7], v[158:161], v[216:219], v[4:7]
	v_mfma_f32_16x16x32_bf16 v[56:59], v[154:157], v[196:199], v[56:59]
	v_mfma_f32_16x16x32_bf16 v[48:51], v[162:165], v[196:199], v[48:51]
	v_mfma_f32_16x16x32_bf16 v[40:43], v[154:157], v[204:207], v[40:43]
	v_mfma_f32_16x16x32_bf16 v[32:35], v[162:165], v[204:207], v[32:35]
	v_mfma_f32_16x16x32_bf16 v[24:27], v[154:157], v[212:215], v[24:27]
	v_mfma_f32_16x16x32_bf16 v[16:19], v[162:165], v[212:215], v[16:19]
	v_mfma_f32_16x16x32_bf16 v[8:11], v[154:157], v[240:243], v[8:11]
	v_mfma_f32_16x16x32_bf16 v[4:7], v[162:165], v[240:243], v[4:7]
	s_setprio 0
	s_setprio 1
	v_mfma_f32_16x16x32_bf16 v[60:63], v[176:179], v[192:195], v[60:63]
	v_mfma_f32_16x16x32_bf16 v[52:55], v[184:187], v[192:195], v[52:55]
	v_mfma_f32_16x16x32_bf16 v[44:47], v[176:179], v[200:203], v[44:47]
	v_mfma_f32_16x16x32_bf16 v[36:39], v[184:187], v[200:203], v[36:39]
	v_mfma_f32_16x16x32_bf16 v[28:31], v[176:179], v[208:211], v[28:31]
	v_mfma_f32_16x16x32_bf16 v[20:23], v[184:187], v[208:211], v[20:23]
	v_mfma_f32_16x16x32_bf16 v[12:15], v[176:179], v[216:219], v[12:15]
	v_mfma_f32_16x16x32_bf16 v[0:3], v[184:187], v[216:219], v[0:3]
	v_mfma_f32_16x16x32_bf16 v[60:63], v[180:183], v[196:199], v[60:63]
	v_mfma_f32_16x16x32_bf16 v[52:55], v[188:191], v[196:199], v[52:55]
	v_mfma_f32_16x16x32_bf16 v[44:47], v[180:183], v[204:207], v[44:47]
	v_mfma_f32_16x16x32_bf16 v[36:39], v[188:191], v[204:207], v[36:39]
	v_mfma_f32_16x16x32_bf16 v[28:31], v[180:183], v[212:215], v[28:31]
	v_mfma_f32_16x16x32_bf16 v[20:23], v[188:191], v[212:215], v[20:23]
	v_mfma_f32_16x16x32_bf16 v[12:15], v[180:183], v[240:243], v[12:15]
	v_mfma_f32_16x16x32_bf16 v[0:3], v[188:191], v[240:243], v[0:3]
	s_setprio 0
	s_barrier
	v_lshl_add_u64 v[142:143], v[142:143], 0, s[80:81]
	v_lshl_add_u64 v[144:145], v[144:145], 0, s[80:81]
	s_mov_b32 s10, s11
	s_cmp_eq_u32 s10, s58
	s_cbranch_scc1 .Lgu_last
.LBB0_308:
	s_add_i32 s11, s10, 2
	s_cmp_eq_u32 s58, s10
	v_lshl_add_u64 v[146:147], v[142:143], 0, s[92:93]
	s_cselect_b64 vcc, -1, 0
	v_add_u32_e32 v150, s33, v151
	s_add_i32 s10, 0, 0x14000
	v_cndmask_b32_e32 v167, v147, v139, vcc
	v_cndmask_b32_e32 v166, v146, v138, vcc
	ds_read_b128 v[146:149], v150
	ds_read_b128 v[154:157], v150 offset:1024
	ds_read_b128 v[158:161], v150 offset:2048
	ds_read_b128 v[162:165], v150 offset:3072
	v_add_u32_e32 v150, s10, v151
	ds_read_b128 v[176:179], v150
	ds_read_b128 v[180:183], v150 offset:1024
	ds_read_b128 v[184:187], v150 offset:2048
	ds_read_b128 v[188:191], v150 offset:3072
	v_cndmask_b32_e32 v221, v145, v141, vcc
	v_cndmask_b32_e32 v220, v144, v140, vcc
	v_lshl_add_u64 v[226:227], v[142:143], 0, v[134:135]
	s_add_i32 m0, s51, 0xc000
	ds_read_b128 v[192:195], v153
	ds_read_b128 v[196:199], v153 offset:1024
	ds_read_b128 v[200:203], v153 offset:2048
	ds_read_b128 v[204:207], v153 offset:3072
	ds_read_b128 v[208:211], v153 offset:4096
	ds_read_b128 v[212:215], v153 offset:5120
	ds_read_b128 v[216:219], v153 offset:6144
	ds_read_b128 v[240:243], v153 offset:7168
	global_load_lds_dwordx4 v[226:227], off
	v_lshl_add_u64 v[226:227], v[142:143], 0, v[136:137]
	s_add_i32 m0, s51, 0xe000
	s_nop 0
	global_load_lds_dwordx4 v[226:227], off
	s_waitcnt vmcnt(8)
	s_waitcnt lgkmcnt(0)
	s_barrier
; #define PG8_STAGE(bufoff, gbase, voff) do { _Pragma("unroll") for (int _i = 0; _i < 2; ++_i) \
;         __builtin_amdgcn_global_load_lds((const unsigned*)((const char*)(gbase) + (voff)[_i]), (LAS unsigned*)(lds + (bufoff) + ldsw + _i * 8192), 16, 0, 0); } while (0)
; #define PG8_LDA(dst, b, h) do { _Pragma("unroll") for (int m = 0; m < 4; ++m) _Pragma("unroll") for (int k = 0; k < 2; ++k) dst[m][k] = *(const LAS bf16x8*)(lds + PG8_SA(b, h) + aoff + m * 2048 + k * 1024); } while (0)
; #define PG8_LDB(dst, b, h) do { _Pragma("unroll") for (int n = 0; n < 2; ++n) _Pragma("unroll") for (int k = 0; k < 2; ++k) dst[n][k] = *(const LAS bf16x8*)(lds + PG8_SB(b, h) + boff + n * 2048 + k * 1024); } while (0)
; #define PG8_MMA(ai, bj, At, Bt) do { __builtin_amdgcn_s_setprio(1); _Pragma("unroll") for (int k = 0; k < 2; ++k) _Pragma("unroll") for (int m = 0; m < 4; ++m) _Pragma("unroll") for (int n = 0; n < 2; ++n) \
;         acc[ai][bj][m][n] = __builtin_amdgcn_mfma_f32_16x16x32_bf16(Bt[n][k], At[m][k], acc[ai][bj][m][n], 0, 0, 0); __builtin_amdgcn_s_setprio(0); } while (0)
; #define PG8_WAIT_V(n) asm volatile("s_waitcnt vmcnt(" #n ")" ::: "memory")
; #define PG8_WAIT_L(n) asm volatile("s_waitcnt lgkmcnt(" #n ")" ::: "memory")
; #define PG8_BAR __builtin_amdgcn_s_barrier()
; #define PG8_SCHED __builtin_amdgcn_sched_barrier(0)
; template <class Epi, bool ALIGN_EPI>
; __device__ __forceinline__ void gemm_phase(LAS unsigned char* lds, const Gemm g, const StaticOrder& S, const Epi& E, const int tid) {
;     ...
;             PG8_WAIT_V(8); PG8_WAIT_L(0); PG8_BAR; PG8_MMA(0, 0, At, B0); PG8_MMA(0, 1, At, B1); PG8_BAR; PG8_SCHED;
;             PG8_LDA(At, 0, 1); PG8_STAGE(PG8_SB(0, 0), b2, voffB); PG8_STAGE(PG8_SB(0, 1), b2 + hB, voffB); PG8_STAGE(PG8_SA(0, 0), a2, voffA);
;             PG8_WAIT_V(8); PG8_WAIT_L(0); PG8_BAR; PG8_MMA(1, 0, At, B0); PG8_MMA(1, 1, At, B1); PG8_BAR; PG8_SCHED;
;             PG8_LDB(B0, 1, 0); PG8_LDB(B1, 1, 1); PG8_SCHED; PG8_LDA(At, 1, 0); PG8_STAGE(PG8_SA(0, 1), a2 + hA, voffA);
;             PG8_WAIT_V(8); PG8_WAIT_L(0); PG8_BAR; PG8_MMA(0, 0, At, B0); PG8_MMA(0, 1, At, B1); PG8_BAR; PG8_SCHED;
	s_setprio 1
	v_mfma_f32_16x16x32_bf16 v[120:123], v[146:149], v[192:195], v[120:123]
	v_mfma_f32_16x16x32_bf16 v[112:115], v[158:161], v[192:195], v[112:115]
	v_mfma_f32_16x16x32_bf16 v[104:107], v[146:149], v[200:203], v[104:107]
	v_mfma_f32_16x16x32_bf16 v[96:99], v[158:161], v[200:203], v[96:99]
	v_mfma_f32_16x16x32_bf16 v[88:91], v[146:149], v[208:211], v[88:91]
	v_mfma_f32_16x16x32_bf16 v[80:83], v[158:161], v[208:211], v[80:83]
	v_mfma_f32_16x16x32_bf16 v[72:75], v[146:149], v[216:219], v[72:75]
	v_mfma_f32_16x16x32_bf16 v[64:67], v[158:161], v[216:219], v[64:67]
	v_mfma_f32_16x16x32_bf16 v[120:123], v[154:157], v[196:199], v[120:123]
	v_mfma_f32_16x16x32_bf16 v[112:115], v[162:165], v[196:199], v[112:115]
	v_mfma_f32_16x16x32_bf16 v[104:107], v[154:157], v[204:207], v[104:107]
	v_mfma_f32_16x16x32_bf16 v[96:99], v[162:165], v[204:207], v[96:99]
	v_mfma_f32_16x16x32_bf16 v[88:91], v[154:157], v[212:215], v[88:91]
	v_mfma_f32_16x16x32_bf16 v[80:83], v[162:165], v[212:215], v[80:83]
	v_mfma_f32_16x16x32_bf16 v[72:75], v[154:157], v[240:243], v[72:75]
	v_mfma_f32_16x16x32_bf16 v[64:67], v[162:165], v[240:243], v[64:67]
	s_setprio 0
	s_setprio 1
	v_mfma_f32_16x16x32_bf16 v[124:127], v[176:179], v[192:195], v[124:127]
	v_mfma_f32_16x16x32_bf16 v[116:119], v[184:187], v[192:195], v[116:119]
	v_mfma_f32_16x16x32_bf16 v[108:111], v[176:179], v[200:203], v[108:111]
	v_mfma_f32_16x16x32_bf16 v[100:103], v[184:187], v[200:203], v[100:103]
	v_mfma_f32_16x16x32_bf16 v[92:95], v[176:179], v[208:211], v[92:95]
	v_mfma_f32_16x16x32_bf16 v[84:87], v[184:187], v[208:211], v[84:87]
	v_mfma_f32_16x16x32_bf16 v[76:79], v[176:179], v[216:219], v[76:79]
	v_mfma_f32_16x16x32_bf16 v[68:71], v[184:187], v[216:219], v[68:71]
	v_mfma_f32_16x16x32_bf16 v[124:127], v[180:183], v[196:199], v[124:127]
	v_mfma_f32_16x16x32_bf16 v[116:119], v[188:191], v[196:199], v[116:119]
	v_mfma_f32_16x16x32_bf16 v[108:111], v[180:183], v[204:207], v[108:111]
	v_mfma_f32_16x16x32_bf16 v[100:103], v[188:191], v[204:207], v[100:103]
	v_mfma_f32_16x16x32_bf16 v[92:95], v[180:183], v[212:215], v[92:95]
	v_mfma_f32_16x16x32_bf16 v[84:87], v[188:191], v[212:215], v[84:87]
	v_mfma_f32_16x16x32_bf16 v[76:79], v[180:183], v[240:243], v[76:79]
	v_mfma_f32_16x16x32_bf16 v[68:71], v[188:191], v[240:243], v[68:71]
	s_setprio 0
	s_barrier
	s_add_i32 s65, s33, s45
	v_lshl_add_u64 v[226:227], v[220:221], 0, v[168:169]
	s_mov_b32 m0, s65
	ds_read_b128 v[192:195], v153 offset:16384
	ds_read_b128 v[196:199], v153 offset:17408
	ds_read_b128 v[200:203], v153 offset:18432
	ds_read_b128 v[204:207], v153 offset:19456
	ds_read_b128 v[208:211], v153 offset:20480
	ds_read_b128 v[212:215], v153 offset:21504
	ds_read_b128 v[216:219], v153 offset:22528
	ds_read_b128 v[240:243], v153 offset:23552
	global_load_lds_dwordx4 v[226:227], off
	v_lshl_add_u64 v[244:245], v[220:221], 0, v[128:129]
	s_add_i32 m0, s65, 0x2000
	v_lshl_add_u64 v[220:221], v[220:221], 0, s[12:13]
	s_add_i32 s10, s10, s45
	global_load_lds_dwordx4 v[244:245], off
	v_lshl_add_u64 v[246:247], v[220:221], 0, v[168:169]
	s_mov_b32 m0, s10
	v_lshl_add_u64 v[220:221], v[220:221], 0, v[128:129]
	global_load_lds_dwordx4 v[246:247], off
	s_add_i32 m0, s10, 0x2000
	v_lshl_add_u64 v[248:249], v[166:167], 0, v[132:133]
	global_load_lds_dwordx4 v[220:221], off
	s_mov_b32 m0, s51
	v_lshl_add_u64 v[250:251], v[166:167], 0, v[130:131]
	global_load_lds_dwordx4 v[248:249], off
	s_mov_b32 m0, s52
	s_nop 0
	global_load_lds_dwordx4 v[250:251], off
	s_waitcnt vmcnt(8)
	s_waitcnt lgkmcnt(0)
	s_barrier
	s_setprio 1
	v_mfma_f32_16x16x32_bf16 v[56:59], v[146:149], v[192:195], v[56:59]
	v_mfma_f32_16x16x32_bf16 v[48:51], v[158:161], v[192:195], v[48:51]
	v_mfma_f32_16x16x32_bf16 v[40:43], v[146:149], v[200:203], v[40:43]
	v_mfma_f32_16x16x32_bf16 v[32:35], v[158:161], v[200:203], v[32:35]
	v_mfma_f32_16x16x32_bf16 v[24:27], v[146:149], v[208:211], v[24:27]
	v_mfma_f32_16x16x32_bf16 v[16:19], v[158:161], v[208:211], v[16:19]
	v_mfma_f32_16x16x32_bf16 v[8:11], v[146:149], v[216:219], v[8:11]
	v_mfma_f32_16x16x32_bf16 v[4:7], v[158:161], v[216:219], v[4:7]
	v_mfma_f32_16x16x32_bf16 v[56:59], v[154:157], v[196:199], v[56:59]
	v_mfma_f32_16x16x32_bf16 v[48:51], v[162:165], v[196:199], v[48:51]
	v_mfma_f32_16x16x32_bf16 v[40:43], v[154:157], v[204:207], v[40:43]
	v_mfma_f32_16x16x32_bf16 v[32:35], v[162:165], v[204:207], v[32:35]
	v_mfma_f32_16x16x32_bf16 v[24:27], v[154:157], v[212:215], v[24:27]
	v_mfma_f32_16x16x32_bf16 v[16:19], v[162:165], v[212:215], v[16:19]
	v_mfma_f32_16x16x32_bf16 v[8:11], v[154:157], v[240:243], v[8:11]
	v_mfma_f32_16x16x32_bf16 v[4:7], v[162:165], v[240:243], v[4:7]
	s_setprio 0
	s_setprio 1
	v_mfma_f32_16x16x32_bf16 v[60:63], v[176:179], v[192:195], v[60:63]
	v_mfma_f32_16x16x32_bf16 v[52:55], v[184:187], v[192:195], v[52:55]
	v_mfma_f32_16x16x32_bf16 v[44:47], v[176:179], v[200:203], v[44:47]
	v_mfma_f32_16x16x32_bf16 v[36:39], v[184:187], v[200:203], v[36:39]
	v_mfma_f32_16x16x32_bf16 v[28:31], v[176:179], v[208:211], v[28:31]
	v_mfma_f32_16x16x32_bf16 v[20:23], v[184:187], v[208:211], v[20:23]
	v_mfma_f32_16x16x32_bf16 v[12:15], v[176:179], v[216:219], v[12:15]
	v_mfma_f32_16x16x32_bf16 v[0:3], v[184:187], v[216:219], v[0:3]
	v_mfma_f32_16x16x32_bf16 v[60:63], v[180:183], v[196:199], v[60:63]
	v_mfma_f32_16x16x32_bf16 v[52:55], v[188:191], v[196:199], v[52:55]
	v_mfma_f32_16x16x32_bf16 v[44:47], v[180:183], v[204:207], v[44:47]
	v_mfma_f32_16x16x32_bf16 v[36:39], v[188:191], v[204:207], v[36:39]
	v_mfma_f32_16x16x32_bf16 v[28:31], v[180:183], v[212:215], v[28:31]
	v_mfma_f32_16x16x32_bf16 v[20:23], v[188:191], v[212:215], v[20:23]
	v_mfma_f32_16x16x32_bf16 v[12:15], v[180:183], v[240:243], v[12:15]
	v_mfma_f32_16x16x32_bf16 v[0:3], v[188:191], v[240:243], v[0:3]
	s_setprio 0
	s_barrier
; #define PG8_STAGE(bufoff, gbase, voff) do { _Pragma("unroll") for (int _i = 0; _i < 2; ++_i) \
;         __builtin_amdgcn_global_load_lds((const unsigned*)((const char*)(gbase) + (voff)[_i]), (LAS unsigned*)(lds + (bufoff) + ldsw + _i * 8192), 16, 0, 0); } while (0)
; #define PG8_LDA(dst, b, h) do { _Pragma("unroll") for (int m = 0; m < 4; ++m) _Pragma("unroll") for (int k = 0; k < 2; ++k) dst[m][k] = *(const LAS bf16x8*)(lds + PG8_SA(b, h) + aoff + m * 2048 + k * 1024); } while (0)
; #define PG8_LDB(dst, b, h) do { _Pragma("unroll") for (int n = 0; n < 2; ++n) _Pragma("unroll") for (int k = 0; k < 2; ++k) dst[n][k] = *(const LAS bf16x8*)(lds + PG8_SB(b, h) + boff + n * 2048 + k * 1024); } while (0)
; #define PG8_MMA(ai, bj, At, Bt) do { __builtin_amdgcn_s_setprio(1); _Pragma("unroll") for (int k = 0; k < 2; ++k) _Pragma("unroll") for (int m = 0; m < 4; ++m) _Pragma("unroll") for (int n = 0; n < 2; ++n) \
;         acc[ai][bj][m][n] = __builtin_amdgcn_mfma_f32_16x16x32_bf16(Bt[n][k], At[m][k], acc[ai][bj][m][n], 0, 0, 0); __builtin_amdgcn_s_setprio(0); } while (0)
; #define PG8_WAIT_V(n) asm volatile("s_waitcnt vmcnt(" #n ")" ::: "memory")
; #define PG8_WAIT_L(n) asm volatile("s_waitcnt lgkmcnt(" #n ")" ::: "memory")
; #define PG8_BAR __builtin_amdgcn_s_barrier()
; #define PG8_SCHED __builtin_amdgcn_sched_barrier(0)
; template <class Epi, bool ALIGN_EPI>
; __device__ __forceinline__ void gemm_phase(LAS unsigned char* lds, const Gemm g, const StaticOrder& S, const Epi& E, const int tid) {
;     ...
;             PG8_LDB(B0, 1, 0); PG8_LDB(B1, 1, 1); PG8_SCHED; PG8_LDA(At, 1, 0); PG8_STAGE(PG8_SA(0, 1), a2 + hA, voffA);
;             PG8_WAIT_V(8); PG8_WAIT_L(0); PG8_BAR; PG8_MMA(0, 0, At, B0); PG8_MMA(0, 1, At, B1); PG8_BAR; PG8_SCHED;
;             PG8_LDA(At, 1, 1); PG8_STAGE(PG8_SB(1, 0), b3, voffB); PG8_STAGE(PG8_SB(1, 1), b3 + hB, voffB); PG8_STAGE(PG8_SA(1, 0), a3, voffA);
;             PG8_WAIT_V(8); PG8_WAIT_L(0); PG8_BAR; PG8_MMA(1, 0, At, B0); PG8_MMA(1, 1, At, B1); PG8_BAR; PG8_SCHED;
	s_add_i32 s10, 0, 0x18000
	v_add_u32_e32 v150, s10, v151
	s_add_i32 s65, 0, 0x1c000
	ds_read_b128 v[146:149], v150
	ds_read_b128 v[154:157], v150 offset:1024
	ds_read_b128 v[158:161], v150 offset:2048
	ds_read_b128 v[162:165], v150 offset:3072
	v_add_u32_e32 v150, s65, v151
	ds_read_b128 v[176:179], v150
	ds_read_b128 v[180:183], v150 offset:1024
	ds_read_b128 v[184:187], v150 offset:2048
	ds_read_b128 v[188:191], v150 offset:3072
	v_lshl_add_u64 v[166:167], v[166:167], 0, s[94:95]
	s_mov_b32 m0, s53
	v_lshl_add_u64 v[252:253], v[166:167], 0, v[132:133]
	ds_read_b128 v[192:195], v153 offset:32768
	ds_read_b128 v[196:199], v153 offset:33792
	ds_read_b128 v[200:203], v153 offset:34816
	ds_read_b128 v[204:207], v153 offset:35840
	ds_read_b128 v[208:211], v153 offset:36864
	ds_read_b128 v[212:215], v153 offset:37888
	ds_read_b128 v[216:219], v153 offset:38912
	ds_read_b128 v[240:243], v153 offset:39936
	global_load_lds_dwordx4 v[252:253], off
	v_lshl_add_u64 v[166:167], v[166:167], 0, v[130:131]
	s_mov_b32 m0, s54
	s_nop 0
	global_load_lds_dwordx4 v[166:167], off
	s_waitcnt vmcnt(8)
	s_waitcnt lgkmcnt(0)
	s_barrier
	s_setprio 1
	v_mfma_f32_16x16x32_bf16 v[120:123], v[146:149], v[192:195], v[120:123]
	v_mfma_f32_16x16x32_bf16 v[112:115], v[158:161], v[192:195], v[112:115]
	v_mfma_f32_16x16x32_bf16 v[104:107], v[146:149], v[200:203], v[104:107]
	v_mfma_f32_16x16x32_bf16 v[96:99], v[158:161], v[200:203], v[96:99]
	v_mfma_f32_16x16x32_bf16 v[88:91], v[146:149], v[208:211], v[88:91]
	v_mfma_f32_16x16x32_bf16 v[80:83], v[158:161], v[208:211], v[80:83]
	v_mfma_f32_16x16x32_bf16 v[72:75], v[146:149], v[216:219], v[72:75]
	v_mfma_f32_16x16x32_bf16 v[64:67], v[158:161], v[216:219], v[64:67]
	v_mfma_f32_16x16x32_bf16 v[120:123], v[154:157], v[196:199], v[120:123]
	v_mfma_f32_16x16x32_bf16 v[112:115], v[162:165], v[196:199], v[112:115]
	v_mfma_f32_16x16x32_bf16 v[104:107], v[154:157], v[204:207], v[104:107]
	v_mfma_f32_16x16x32_bf16 v[96:99], v[162:165], v[204:207], v[96:99]
	v_mfma_f32_16x16x32_bf16 v[88:91], v[154:157], v[212:215], v[88:91]
	v_mfma_f32_16x16x32_bf16 v[80:83], v[162:165], v[212:215], v[80:83]
	v_mfma_f32_16x16x32_bf16 v[72:75], v[154:157], v[240:243], v[72:75]
	v_mfma_f32_16x16x32_bf16 v[64:67], v[162:165], v[240:243], v[64:67]
	s_setprio 0
	s_setprio 1
	v_mfma_f32_16x16x32_bf16 v[124:127], v[176:179], v[192:195], v[124:127]
	v_mfma_f32_16x16x32_bf16 v[116:119], v[184:187], v[192:195], v[116:119]
	v_mfma_f32_16x16x32_bf16 v[108:111], v[176:179], v[200:203], v[108:111]
	v_mfma_f32_16x16x32_bf16 v[100:103], v[184:187], v[200:203], v[100:103]
	v_mfma_f32_16x16x32_bf16 v[92:95], v[176:179], v[208:211], v[92:95]
	v_mfma_f32_16x16x32_bf16 v[84:87], v[184:187], v[208:211], v[84:87]
	v_mfma_f32_16x16x32_bf16 v[76:79], v[176:179], v[216:219], v[76:79]
	v_mfma_f32_16x16x32_bf16 v[68:71], v[184:187], v[216:219], v[68:71]
	v_mfma_f32_16x16x32_bf16 v[124:127], v[180:183], v[196:199], v[124:127]
	v_mfma_f32_16x16x32_bf16 v[116:119], v[188:191], v[196:199], v[116:119]
	v_mfma_f32_16x16x32_bf16 v[108:111], v[180:183], v[204:207], v[108:111]
	v_mfma_f32_16x16x32_bf16 v[100:103], v[188:191], v[204:207], v[100:103]
	v_mfma_f32_16x16x32_bf16 v[92:95], v[180:183], v[212:215], v[92:95]
	v_mfma_f32_16x16x32_bf16 v[84:87], v[188:191], v[212:215], v[84:87]
	v_mfma_f32_16x16x32_bf16 v[76:79], v[180:183], v[240:243], v[76:79]
	v_mfma_f32_16x16x32_bf16 v[68:71], v[188:191], v[240:243], v[68:71]
	s_setprio 0
	s_barrier
	s_add_i32 s10, s10, s45
	v_lshl_add_u64 v[166:167], v[226:227], 0, s[92:93]
	s_mov_b32 m0, s10
	ds_read_b128 v[192:195], v153 offset:49152
	ds_read_b128 v[196:199], v153 offset:50176
	ds_read_b128 v[200:203], v153 offset:51200
	ds_read_b128 v[204:207], v153 offset:52224
	ds_read_b128 v[208:211], v153 offset:53248
	ds_read_b128 v[212:215], v153 offset:54272
	ds_read_b128 v[216:219], v153 offset:55296
	ds_read_b128 v[240:243], v153 offset:56320
	global_load_lds_dwordx4 v[166:167], off
	v_lshl_add_u64 v[166:167], v[244:245], 0, s[92:93]
	s_add_i32 m0, s10, 0x2000
	s_add_i32 s10, s65, s45
	global_load_lds_dwordx4 v[166:167], off
	v_lshl_add_u64 v[166:167], v[246:247], 0, s[92:93]
	s_mov_b32 m0, s10
	s_nop 0
	global_load_lds_dwordx4 v[166:167], off
	v_lshl_add_u64 v[166:167], v[220:221], 0, s[92:93]
	s_add_i32 m0, s10, 0x2000
	s_nop 0
	global_load_lds_dwordx4 v[166:167], off
	v_lshl_add_u64 v[166:167], v[248:249], 0, s[92:93]
	s_mov_b32 m0, s56
	s_nop 0
	global_load_lds_dwordx4 v[166:167], off
	v_lshl_add_u64 v[166:167], v[250:251], 0, s[92:93]
	s_mov_b32 m0, s57
	s_nop 0
	global_load_lds_dwordx4 v[166:167], off
	s_waitcnt vmcnt(8)
	s_waitcnt lgkmcnt(0)
	s_barrier
; #define PG8_STAGE(bufoff, gbase, voff) do { _Pragma("unroll") for (int _i = 0; _i < 2; ++_i) \
;         __builtin_amdgcn_global_load_lds((const unsigned*)((const char*)(gbase) + (voff)[_i]), (LAS unsigned*)(lds + (bufoff) + ldsw + _i * 8192), 16, 0, 0); } while (0)
; #define PG8_LDA(dst, b, h) do { _Pragma("unroll") for (int m = 0; m < 4; ++m) _Pragma("unroll") for (int k = 0; k < 2; ++k) dst[m][k] = *(const LAS bf16x8*)(lds + PG8_SA(b, h) + aoff + m * 2048 + k * 1024); } while (0)
; #define PG8_LDB(dst, b, h) do { _Pragma("unroll") for (int n = 0; n < 2; ++n) _Pragma("unroll") for (int k = 0; k < 2; ++k) dst[n][k] = *(const LAS bf16x8*)(lds + PG8_SB(b, h) + boff + n * 2048 + k * 1024); } while (0)
; #define PG8_MMA(ai, bj, At, Bt) do { __builtin_amdgcn_s_setprio(1); _Pragma("unroll") for (int k = 0; k < 2; ++k) _Pragma("unroll") for (int m = 0; m < 4; ++m) _Pragma("unroll") for (int n = 0; n < 2; ++n) \
;         acc[ai][bj][m][n] = __builtin_amdgcn_mfma_f32_16x16x32_bf16(Bt[n][k], At[m][k], acc[ai][bj][m][n], 0, 0, 0); __builtin_amdgcn_s_setprio(0); } while (0)
; #define PG8_WAIT_V(n) asm volatile("s_waitcnt vmcnt(" #n ")" ::: "memory")
; template <class Epi, bool ALIGN_EPI>
; __device__ __forceinline__ void gemm_phase(LAS unsigned char* lds, const Gemm g, const StaticOrder& S, const Epi& E, const int tid) {
;     ...
;             PG8_LDB(B0, 0, 0); PG8_LDB(B1, 0, 1); PG8_SCHED; PG8_LDA(At, 0, 0); PG8_STAGE(PG8_SA(1, 1), a1 + hA, voffA);
;             PG8_WAIT_V(8); PG8_WAIT_L(0); PG8_BAR; PG8_MMA(0, 0, At, B0); PG8_MMA(0, 1, At, B1); PG8_BAR; PG8_SCHED;
;             PG8_LDA(At, 0, 1); PG8_STAGE(PG8_SB(0, 0), b2, voffB); PG8_STAGE(PG8_SB(0, 1), b2 + hB, voffB); PG8_STAGE(PG8_SA(0, 0), a2, voffA);
;             PG8_WAIT_V(8); PG8_WAIT_L(0); PG8_BAR; PG8_MMA(1, 0, At, B0); PG8_MMA(1, 1, At, B1); PG8_BAR; PG8_SCHED;
;             PG8_LDB(B0, 1, 0); PG8_LDB(B1, 1, 1); PG8_SCHED; PG8_LDA(At, 1, 0); PG8_STAGE(PG8_SA(0, 1), a2 + hA, voffA);
;             PG8_WAIT_V(8); PG8_WAIT_L(0); PG8_BAR; PG8_MMA(0, 0, At, B0); PG8_MMA(0, 1, At, B1); PG8_BAR; PG8_SCHED;
;             PG8_LDA(At, 1, 1); PG8_STAGE(PG8_SB(1, 0), b3, voffB); PG8_STAGE(PG8_SB(1, 1), b3 + hB, voffB); PG8_STAGE(PG8_SA(1, 0), a3, voffA);
;             PG8_WAIT_V(8); PG8_WAIT_L(0); PG8_BAR; PG8_MMA(1, 0, At, B0); PG8_MMA(1, 1, At, B1); PG8_BAR; PG8_SCHED;
;     ...
;         cur = nxt; cA = nA; cB = nB; ++ui;
	s_setprio 1
	v_mfma_f32_16x16x32_bf16 v[56:59], v[146:149], v[192:195], v[56:59]
	v_mfma_f32_16x16x32_bf16 v[48:51], v[158:161], v[192:195], v[48:51]
	v_mfma_f32_16x16x32_bf16 v[40:43], v[146:149], v[200:203], v[40:43]
	v_mfma_f32_16x16x32_bf16 v[32:35], v[158:161], v[200:203], v[32:35]
	v_mfma_f32_16x16x32_bf16 v[24:27], v[146:149], v[208:211], v[24:27]
	v_mfma_f32_16x16x32_bf16 v[16:19], v[158:161], v[208:211], v[16:19]
	v_mfma_f32_16x16x32_bf16 v[8:11], v[146:149], v[216:219], v[8:11]
	v_mfma_f32_16x16x32_bf16 v[4:7], v[158:161], v[216:219], v[4:7]
	v_mfma_f32_16x16x32_bf16 v[56:59], v[154:157], v[196:199], v[56:59]
	v_mfma_f32_16x16x32_bf16 v[48:51], v[162:165], v[196:199], v[48:51]
	v_mfma_f32_16x16x32_bf16 v[40:43], v[154:157], v[204:207], v[40:43]
	v_mfma_f32_16x16x32_bf16 v[32:35], v[162:165], v[204:207], v[32:35]
	v_mfma_f32_16x16x32_bf16 v[24:27], v[154:157], v[212:215], v[24:27]
	v_mfma_f32_16x16x32_bf16 v[16:19], v[162:165], v[212:215], v[16:19]
	v_mfma_f32_16x16x32_bf16 v[8:11], v[154:157], v[240:243], v[8:11]
	v_mfma_f32_16x16x32_bf16 v[4:7], v[162:165], v[240:243], v[4:7]
	s_setprio 0
	s_setprio 1
	v_mfma_f32_16x16x32_bf16 v[60:63], v[176:179], v[192:195], v[60:63]
	v_mfma_f32_16x16x32_bf16 v[52:55], v[184:187], v[192:195], v[52:55]
	v_mfma_f32_16x16x32_bf16 v[44:47], v[176:179], v[200:203], v[44:47]
	v_mfma_f32_16x16x32_bf16 v[36:39], v[184:187], v[200:203], v[36:39]
	v_mfma_f32_16x16x32_bf16 v[28:31], v[176:179], v[208:211], v[28:31]
	v_mfma_f32_16x16x32_bf16 v[20:23], v[184:187], v[208:211], v[20:23]
	v_mfma_f32_16x16x32_bf16 v[12:15], v[176:179], v[216:219], v[12:15]
	v_mfma_f32_16x16x32_bf16 v[0:3], v[184:187], v[216:219], v[0:3]
	v_mfma_f32_16x16x32_bf16 v[60:63], v[180:183], v[196:199], v[60:63]
	v_mfma_f32_16x16x32_bf16 v[52:55], v[188:191], v[196:199], v[52:55]
	v_mfma_f32_16x16x32_bf16 v[44:47], v[180:183], v[204:207], v[44:47]
	v_mfma_f32_16x16x32_bf16 v[36:39], v[188:191], v[204:207], v[36:39]
	v_mfma_f32_16x16x32_bf16 v[28:31], v[180:183], v[212:215], v[28:31]
	v_mfma_f32_16x16x32_bf16 v[20:23], v[188:191], v[212:215], v[20:23]
	v_mfma_f32_16x16x32_bf16 v[12:15], v[180:183], v[240:243], v[12:15]
	v_mfma_f32_16x16x32_bf16 v[0:3], v[188:191], v[240:243], v[0:3]
	s_setprio 0
	s_barrier
	v_lshl_add_u64 v[142:143], v[142:143], 0, s[80:81]
	v_lshl_add_u64 v[144:145], v[144:145], 0, s[80:81]
	s_mov_b32 s10, s11
	s_cmp_lg_u32 s10, s58
	s_cbranch_scc1 .LBB0_308
.Lgu_last:
	s_add_i32 s11, s10, 2
	s_cmp_eq_u32 s58, s10
	v_lshl_add_u64 v[146:147], v[142:143], 0, s[92:93]
	s_cselect_b64 vcc, -1, 0
	v_add_u32_e32 v150, s33, v151
	s_add_i32 s10, 0, 0x14000
	v_cndmask_b32_e32 v167, v147, v139, vcc
	v_cndmask_b32_e32 v166, v146, v138, vcc
	ds_read_b128 v[146:149], v150
	ds_read_b128 v[154:157], v150 offset:1024
	ds_read_b128 v[158:161], v150 offset:2048
	ds_read_b128 v[162:165], v150 offset:3072
	v_add_u32_e32 v150, s10, v151
	ds_read_b128 v[176:179], v150
	ds_read_b128 v[180:183], v150 offset:1024
	ds_read_b128 v[184:187], v150 offset:2048
	ds_read_b128 v[188:191], v150 offset:3072
	v_cndmask_b32_e32 v221, v145, v141, vcc
	v_cndmask_b32_e32 v220, v144, v140, vcc
	v_lshl_add_u64 v[226:227], v[142:143], 0, v[134:135]
	s_add_i32 m0, s51, 0xc000
	ds_read_b128 v[192:195], v153
	ds_read_b128 v[196:199], v153 offset:1024
	ds_read_b128 v[200:203], v153 offset:2048
	ds_read_b128 v[204:207], v153 offset:3072
	ds_read_b128 v[208:211], v153 offset:4096
	ds_read_b128 v[212:215], v153 offset:5120
	ds_read_b128 v[216:219], v153 offset:6144
	ds_read_b128 v[240:243], v153 offset:7168
	global_load_lds_dwordx4 v[226:227], off
	v_lshl_add_u64 v[226:227], v[142:143], 0, v[136:137]
	s_add_i32 m0, s51, 0xe000
	s_nop 0
	global_load_lds_dwordx4 v[226:227], off
	s_waitcnt vmcnt(8)
	s_waitcnt lgkmcnt(0)
	s_barrier
	s_setprio 1
	v_mfma_f32_16x16x32_bf16 v[120:123], v[146:149], v[192:195], v[120:123]
	v_mfma_f32_16x16x32_bf16 v[112:115], v[158:161], v[192:195], v[112:115]
	v_mfma_f32_16x16x32_bf16 v[104:107], v[146:149], v[200:203], v[104:107]
	v_mfma_f32_16x16x32_bf16 v[96:99], v[158:161], v[200:203], v[96:99]
	v_mfma_f32_16x16x32_bf16 v[88:91], v[146:149], v[208:211], v[88:91]
	v_mfma_f32_16x16x32_bf16 v[80:83], v[158:161], v[208:211], v[80:83]
	v_mfma_f32_16x16x32_bf16 v[72:75], v[146:149], v[216:219], v[72:75]
	v_mfma_f32_16x16x32_bf16 v[64:67], v[158:161], v[216:219], v[64:67]
	v_mfma_f32_16x16x32_bf16 v[120:123], v[154:157], v[196:199], v[120:123]
	v_mfma_f32_16x16x32_bf16 v[112:115], v[162:165], v[196:199], v[112:115]
	v_mfma_f32_16x16x32_bf16 v[104:107], v[154:157], v[204:207], v[104:107]
	v_mfma_f32_16x16x32_bf16 v[96:99], v[162:165], v[204:207], v[96:99]
	v_mfma_f32_16x16x32_bf16 v[88:91], v[154:157], v[212:215], v[88:91]
	v_mfma_f32_16x16x32_bf16 v[80:83], v[162:165], v[212:215], v[80:83]
	v_mfma_f32_16x16x32_bf16 v[72:75], v[154:157], v[240:243], v[72:75]
	v_mfma_f32_16x16x32_bf16 v[64:67], v[162:165], v[240:243], v[64:67]
	s_setprio 0
	s_setprio 1
	v_mfma_f32_16x16x32_bf16 v[124:127], v[176:179], v[192:195], v[124:127]
	v_mfma_f32_16x16x32_bf16 v[116:119], v[184:187], v[192:195], v[116:119]
	v_mfma_f32_16x16x32_bf16 v[108:111], v[176:179], v[200:203], v[108:111]
	v_mfma_f32_16x16x32_bf16 v[100:103], v[184:187], v[200:203], v[100:103]
	v_mfma_f32_16x16x32_bf16 v[92:95], v[176:179], v[208:211], v[92:95]
	v_mfma_f32_16x16x32_bf16 v[84:87], v[184:187], v[208:211], v[84:87]
	v_mfma_f32_16x16x32_bf16 v[76:79], v[176:179], v[216:219], v[76:79]
	v_mfma_f32_16x16x32_bf16 v[68:71], v[184:187], v[216:219], v[68:71]
	v_mfma_f32_16x16x32_bf16 v[124:127], v[180:183], v[196:199], v[124:127]
	v_mfma_f32_16x16x32_bf16 v[116:119], v[188:191], v[196:199], v[116:119]
	v_mfma_f32_16x16x32_bf16 v[108:111], v[180:183], v[204:207], v[108:111]
	v_mfma_f32_16x16x32_bf16 v[100:103], v[188:191], v[204:207], v[100:103]
	v_mfma_f32_16x16x32_bf16 v[92:95], v[180:183], v[212:215], v[92:95]
	v_mfma_f32_16x16x32_bf16 v[84:87], v[188:191], v[212:215], v[84:87]
	v_mfma_f32_16x16x32_bf16 v[76:79], v[180:183], v[240:243], v[76:79]
	v_mfma_f32_16x16x32_bf16 v[68:71], v[188:191], v[240:243], v[68:71]
	s_setprio 0
	s_barrier
; #define PG8_STAGE(bufoff, gbase, voff) do { _Pragma("unroll") for (int _i = 0; _i < 2; ++_i) \
;         __builtin_amdgcn_global_load_lds((const unsigned*)((const char*)(gbase) + (voff)[_i]), (LAS unsigned*)(lds + (bufoff) + ldsw + _i * 8192), 16, 0, 0); } while (0)
; #define PG8_LDA(dst, b, h) do { _Pragma("unroll") for (int m = 0; m < 4; ++m) _Pragma("unroll") for (int k = 0; k < 2; ++k) dst[m][k] = *(const LAS bf16x8*)(lds + PG8_SA(b, h) + aoff + m * 2048 + k * 1024); } while (0)
; #define PG8_LDB(dst, b, h) do { _Pragma("unroll") for (int n = 0; n < 2; ++n) _Pragma("unroll") for (int k = 0; k < 2; ++k) dst[n][k] = *(const LAS bf16x8*)(lds + PG8_SB(b, h) + boff + n * 2048 + k * 1024); } while (0)
; #define PG8_MMA(ai, bj, At, Bt) do { __builtin_amdgcn_s_setprio(1); _Pragma("unroll") for (int k = 0; k < 2; ++k) _Pragma("unroll") for (int m = 0; m < 4; ++m) _Pragma("unroll") for (int n = 0; n < 2; ++n) \
;         acc[ai][bj][m][n] = __builtin_amdgcn_mfma_f32_16x16x32_bf16(Bt[n][k], At[m][k], acc[ai][bj][m][n], 0, 0, 0); __builtin_amdgcn_s_setprio(0); } while (0)
; #define PG8_WAIT_V(n) asm volatile("s_waitcnt vmcnt(" #n ")" ::: "memory")
; #define PG8_WAIT_L(n) asm volatile("s_waitcnt lgkmcnt(" #n ")" ::: "memory")
; #define PG8_BAR __builtin_amdgcn_s_barrier()
; #define PG8_SCHED __builtin_amdgcn_sched_barrier(0)
; template <class Epi, bool ALIGN_EPI>
; __device__ __forceinline__ void gemm_phase(LAS unsigned char* lds, const Gemm g, const StaticOrder& S, const Epi& E, const int tid) {
;     ...
;             PG8_LDA(At, 0, 1); PG8_STAGE(PG8_SB(0, 0), b2, voffB); PG8_STAGE(PG8_SB(0, 1), b2 + hB, voffB); PG8_STAGE(PG8_SA(0, 0), a2, voffA);
;             PG8_WAIT_V(8); PG8_WAIT_L(0); PG8_BAR; PG8_MMA(1, 0, At, B0); PG8_MMA(1, 1, At, B1); PG8_BAR; PG8_SCHED;
;             PG8_LDB(B0, 1, 0); PG8_LDB(B1, 1, 1); PG8_SCHED; PG8_LDA(At, 1, 0); PG8_STAGE(PG8_SA(0, 1), a2 + hA, voffA);
;             PG8_WAIT_V(8); PG8_WAIT_L(0); PG8_BAR; PG8_MMA(0, 0, At, B0); PG8_MMA(0, 1, At, B1); PG8_BAR; PG8_SCHED;
;             PG8_LDA(At, 1, 1); PG8_STAGE(PG8_SB(1, 0), b3, voffB); PG8_STAGE(PG8_SB(1, 1), b3 + hB, voffB); PG8_STAGE(PG8_SA(1, 0), a3, voffA);
;             PG8_WAIT_V(8); PG8_WAIT_L(0); PG8_BAR; PG8_MMA(1, 0, At, B0); PG8_MMA(1, 1, At, B1); PG8_BAR; PG8_SCHED;
	s_add_i32 s65, s33, s45
	v_lshl_add_u64 v[226:227], v[220:221], 0, v[168:169]
	s_mov_b32 m0, s65
	ds_read_b128 v[192:195], v153 offset:16384
	ds_read_b128 v[196:199], v153 offset:17408
	ds_read_b128 v[200:203], v153 offset:18432
	ds_read_b128 v[204:207], v153 offset:19456
	ds_read_b128 v[208:211], v153 offset:20480
	ds_read_b128 v[212:215], v153 offset:21504
	ds_read_b128 v[216:219], v153 offset:22528
	ds_read_b128 v[240:243], v153 offset:23552
	global_load_lds_dwordx4 v[226:227], off
	v_lshl_add_u64 v[244:245], v[220:221], 0, v[128:129]
	s_add_i32 m0, s65, 0x2000
	v_lshl_add_u64 v[220:221], v[220:221], 0, s[12:13]
	s_add_i32 s10, s10, s45
	global_load_lds_dwordx4 v[244:245], off
	v_lshl_add_u64 v[246:247], v[220:221], 0, v[168:169]
	s_mov_b32 m0, s10
	v_lshl_add_u64 v[220:221], v[220:221], 0, v[128:129]
	global_load_lds_dwordx4 v[246:247], off
	s_add_i32 m0, s10, 0x2000
	v_lshl_add_u64 v[248:249], v[166:167], 0, v[132:133]
	global_load_lds_dwordx4 v[220:221], off
	s_mov_b32 m0, s51
	v_lshl_add_u64 v[250:251], v[166:167], 0, v[130:131]
	global_load_lds_dwordx4 v[248:249], off
	s_mov_b32 m0, s52
	s_nop 0
	global_load_lds_dwordx4 v[250:251], off
	s_waitcnt vmcnt(8)
	s_waitcnt lgkmcnt(0)
	s_barrier
	s_setprio 1
	v_mfma_f32_16x16x32_bf16 v[56:59], v[146:149], v[192:195], v[56:59]
	v_mfma_f32_16x16x32_bf16 v[48:51], v[158:161], v[192:195], v[48:51]
	v_mfma_f32_16x16x32_bf16 v[40:43], v[146:149], v[200:203], v[40:43]
	v_mfma_f32_16x16x32_bf16 v[32:35], v[158:161], v[200:203], v[32:35]
	v_mfma_f32_16x16x32_bf16 v[24:27], v[146:149], v[208:211], v[24:27]
	v_mfma_f32_16x16x32_bf16 v[16:19], v[158:161], v[208:211], v[16:19]
	v_mfma_f32_16x16x32_bf16 v[8:11], v[146:149], v[216:219], v[8:11]
	v_mfma_f32_16x16x32_bf16 v[4:7], v[158:161], v[216:219], v[4:7]
	v_mfma_f32_16x16x32_bf16 v[56:59], v[154:157], v[196:199], v[56:59]
	v_mfma_f32_16x16x32_bf16 v[48:51], v[162:165], v[196:199], v[48:51]
	v_mfma_f32_16x16x32_bf16 v[40:43], v[154:157], v[204:207], v[40:43]
	v_mfma_f32_16x16x32_bf16 v[32:35], v[162:165], v[204:207], v[32:35]
	v_mfma_f32_16x16x32_bf16 v[24:27], v[154:157], v[212:215], v[24:27]
	v_mfma_f32_16x16x32_bf16 v[16:19], v[162:165], v[212:215], v[16:19]
	v_mfma_f32_16x16x32_bf16 v[8:11], v[154:157], v[240:243], v[8:11]
	v_mfma_f32_16x16x32_bf16 v[4:7], v[162:165], v[240:243], v[4:7]
	s_setprio 0
	s_setprio 1
	v_mfma_f32_16x16x32_bf16 v[60:63], v[176:179], v[192:195], v[60:63]
	v_mfma_f32_16x16x32_bf16 v[52:55], v[184:187], v[192:195], v[52:55]
	v_mfma_f32_16x16x32_bf16 v[44:47], v[176:179], v[200:203], v[44:47]
	v_mfma_f32_16x16x32_bf16 v[36:39], v[184:187], v[200:203], v[36:39]
	v_mfma_f32_16x16x32_bf16 v[28:31], v[176:179], v[208:211], v[28:31]
	v_mfma_f32_16x16x32_bf16 v[20:23], v[184:187], v[208:211], v[20:23]
	v_mfma_f32_16x16x32_bf16 v[12:15], v[176:179], v[216:219], v[12:15]
	v_mfma_f32_16x16x32_bf16 v[0:3], v[184:187], v[216:219], v[0:3]
	v_mfma_f32_16x16x32_bf16 v[60:63], v[180:183], v[196:199], v[60:63]
	v_mfma_f32_16x16x32_bf16 v[52:55], v[188:191], v[196:199], v[52:55]
	v_mfma_f32_16x16x32_bf16 v[44:47], v[180:183], v[204:207], v[44:47]
	v_mfma_f32_16x16x32_bf16 v[36:39], v[188:191], v[204:207], v[36:39]
	v_mfma_f32_16x16x32_bf16 v[28:31], v[180:183], v[212:215], v[28:31]
	v_mfma_f32_16x16x32_bf16 v[20:23], v[188:191], v[212:215], v[20:23]
	v_mfma_f32_16x16x32_bf16 v[12:15], v[180:183], v[240:243], v[12:15]
	v_mfma_f32_16x16x32_bf16 v[0:3], v[188:191], v[240:243], v[0:3]
	s_setprio 0
	s_barrier
	s_add_i32 s10, 0, 0x18000
	v_add_u32_e32 v150, s10, v151
	s_add_i32 s65, 0, 0x1c000
	ds_read_b128 v[146:149], v150
	ds_read_b128 v[154:157], v150 offset:1024
	ds_read_b128 v[158:161], v150 offset:2048
	ds_read_b128 v[162:165], v150 offset:3072
	v_add_u32_e32 v150, s65, v151
	ds_read_b128 v[176:179], v150
	ds_read_b128 v[180:183], v150 offset:1024
	ds_read_b128 v[184:187], v150 offset:2048
	ds_read_b128 v[188:191], v150 offset:3072
	v_lshl_add_u64 v[166:167], v[166:167], 0, s[94:95]
	s_mov_b32 m0, s53
	v_lshl_add_u64 v[252:253], v[166:167], 0, v[132:133]
	ds_read_b128 v[192:195], v153 offset:32768
	ds_read_b128 v[196:199], v153 offset:33792
	ds_read_b128 v[200:203], v153 offset:34816
	ds_read_b128 v[204:207], v153 offset:35840
	ds_read_b128 v[208:211], v153 offset:36864
	ds_read_b128 v[212:215], v153 offset:37888
	ds_read_b128 v[216:219], v153 offset:38912
	ds_read_b128 v[240:243], v153 offset:39936
	global_load_lds_dwordx4 v[252:253], off
	v_lshl_add_u64 v[166:167], v[166:167], 0, v[130:131]
	s_mov_b32 m0, s54
	s_nop 0
	global_load_lds_dwordx4 v[166:167], off
	s_waitcnt vmcnt(8)
	s_waitcnt lgkmcnt(0)
	s_barrier
; __device__ __forceinline__ float siluf_(float x) { return x * sigmoidf_(x); }
; #define PG8_STAGE(bufoff, gbase, voff) do { _Pragma("unroll") for (int _i = 0; _i < 2; ++_i) \
;         __builtin_amdgcn_global_load_lds((const unsigned*)((const char*)(gbase) + (voff)[_i]), (LAS unsigned*)(lds + (bufoff) + ldsw + _i * 8192), 16, 0, 0); } while (0)
; #define PG8_LDA(dst, b, h) do { _Pragma("unroll") for (int m = 0; m < 4; ++m) _Pragma("unroll") for (int k = 0; k < 2; ++k) dst[m][k] = *(const LAS bf16x8*)(lds + PG8_SA(b, h) + aoff + m * 2048 + k * 1024); } while (0)
; #define PG8_MMA(ai, bj, At, Bt) do { __builtin_amdgcn_s_setprio(1); _Pragma("unroll") for (int k = 0; k < 2; ++k) _Pragma("unroll") for (int m = 0; m < 4; ++m) _Pragma("unroll") for (int n = 0; n < 2; ++n) \
;         acc[ai][bj][m][n] = __builtin_amdgcn_mfma_f32_16x16x32_bf16(Bt[n][k], At[m][k], acc[ai][bj][m][n], 0, 0, 0); __builtin_amdgcn_s_setprio(0); } while (0)
; #define PG8_WAIT_V(n) asm volatile("s_waitcnt vmcnt(" #n ")" ::: "memory")
; #define PG8_WAIT_L(n) asm volatile("s_waitcnt lgkmcnt(" #n ")" ::: "memory")
; #define PG8_BAR __builtin_amdgcn_s_barrier()
; #define PG8_SCHED __builtin_amdgcn_sched_barrier(0)
;     __device__ __forceinline__ void operator()(const f32x4 (&acc)[2][2][4][2], const Unit& u, int wr, int wc, int fr, int fq) const {
;     ...
;             for (int m = 0; m < 4; ++m) { const int row = row0 + ai * HALF + m * 16; bf16_t* rowp = O + (size_t)row * ldc + col0; const float rs = rsv[ai][m];
;                 f32x4 v0, v1;
; #pragma unroll
;                 for (int j = 0; j < 4; ++j) { v0[j] = siluf_(acc[ai][0][m][0][j] * rs) * (acc[ai][1][m][0][j] * rs); v1[j] = siluf_(acc[ai][0][m][1][j] * rs) * (acc[ai][1][m][1][j] * rs); }
; template <class Epi, bool ALIGN_EPI>
; __device__ __forceinline__ void gemm_phase(LAS unsigned char* lds, const Gemm g, const StaticOrder& S, const Epi& E, const int tid) {
;     ...
;             PG8_WAIT_V(8); PG8_WAIT_L(0); PG8_BAR; PG8_MMA(0, 0, At, B0); PG8_MMA(0, 1, At, B1); PG8_BAR; PG8_SCHED;
;             PG8_LDA(At, 1, 1); PG8_STAGE(PG8_SB(1, 0), b3, voffB); PG8_STAGE(PG8_SB(1, 1), b3 + hB, voffB); PG8_STAGE(PG8_SA(1, 0), a3, voffA);
;             PG8_WAIT_V(8); PG8_WAIT_L(0); PG8_BAR; PG8_MMA(1, 0, At, B0); PG8_MMA(1, 1, At, B1); PG8_BAR; PG8_SCHED;
	s_setprio 1
	v_mfma_f32_16x16x32_bf16 v[120:123], v[146:149], v[192:195], v[120:123]
	v_mfma_f32_16x16x32_bf16 v[112:115], v[158:161], v[192:195], v[112:115]
	v_mfma_f32_16x16x32_bf16 v[104:107], v[146:149], v[200:203], v[104:107]
	v_mfma_f32_16x16x32_bf16 v[96:99], v[158:161], v[200:203], v[96:99]
	v_mfma_f32_16x16x32_bf16 v[88:91], v[146:149], v[208:211], v[88:91]
	v_mfma_f32_16x16x32_bf16 v[80:83], v[158:161], v[208:211], v[80:83]
	v_mfma_f32_16x16x32_bf16 v[72:75], v[146:149], v[216:219], v[72:75]
	v_mfma_f32_16x16x32_bf16 v[64:67], v[158:161], v[216:219], v[64:67]
	v_mfma_f32_16x16x32_bf16 v[120:123], v[154:157], v[196:199], v[120:123]
	v_mfma_f32_16x16x32_bf16 v[112:115], v[162:165], v[196:199], v[112:115]
	v_mfma_f32_16x16x32_bf16 v[104:107], v[154:157], v[204:207], v[104:107]
	v_mfma_f32_16x16x32_bf16 v[96:99], v[162:165], v[204:207], v[96:99]
	v_mfma_f32_16x16x32_bf16 v[88:91], v[154:157], v[212:215], v[88:91]
	v_mfma_f32_16x16x32_bf16 v[80:83], v[162:165], v[212:215], v[80:83]
	v_mfma_f32_16x16x32_bf16 v[72:75], v[154:157], v[240:243], v[72:75]
	v_mfma_f32_16x16x32_bf16 v[64:67], v[162:165], v[240:243], v[64:67]
	s_setprio 0
	s_setprio 1
	v_mfma_f32_16x16x32_bf16 v[124:127], v[176:179], v[192:195], v[124:127]
	v_mfma_f32_16x16x32_bf16 v[116:119], v[184:187], v[192:195], v[116:119]
	v_mfma_f32_16x16x32_bf16 v[108:111], v[176:179], v[200:203], v[108:111]
	v_mfma_f32_16x16x32_bf16 v[100:103], v[184:187], v[200:203], v[100:103]
	v_mfma_f32_16x16x32_bf16 v[92:95], v[176:179], v[208:211], v[92:95]
	v_mfma_f32_16x16x32_bf16 v[84:87], v[184:187], v[208:211], v[84:87]
	v_mfma_f32_16x16x32_bf16 v[76:79], v[176:179], v[216:219], v[76:79]
	v_mfma_f32_16x16x32_bf16 v[68:71], v[184:187], v[216:219], v[68:71]
	v_mfma_f32_16x16x32_bf16 v[124:127], v[180:183], v[196:199], v[124:127]
	v_mfma_f32_16x16x32_bf16 v[116:119], v[188:191], v[196:199], v[116:119]
	v_mfma_f32_16x16x32_bf16 v[108:111], v[180:183], v[204:207], v[108:111]
	v_mfma_f32_16x16x32_bf16 v[100:103], v[188:191], v[204:207], v[100:103]
	v_mfma_f32_16x16x32_bf16 v[92:95], v[180:183], v[212:215], v[92:95]
	v_mfma_f32_16x16x32_bf16 v[84:87], v[188:191], v[212:215], v[84:87]
	v_mfma_f32_16x16x32_bf16 v[76:79], v[180:183], v[240:243], v[76:79]
	v_mfma_f32_16x16x32_bf16 v[68:71], v[188:191], v[240:243], v[68:71]
	s_setprio 0
	s_barrier
	s_add_i32 s10, s10, s45
	v_lshl_add_u64 v[166:167], v[226:227], 0, s[92:93]
	s_mov_b32 m0, s10
	ds_read_b128 v[192:195], v153 offset:49152
	ds_read_b128 v[196:199], v153 offset:50176
	ds_read_b128 v[200:203], v153 offset:51200
	ds_read_b128 v[204:207], v153 offset:52224
	ds_read_b128 v[208:211], v153 offset:53248
	ds_read_b128 v[212:215], v153 offset:54272
	ds_read_b128 v[216:219], v153 offset:55296
	ds_read_b128 v[240:243], v153 offset:56320
	global_load_lds_dwordx4 v[166:167], off
	v_lshl_add_u64 v[166:167], v[244:245], 0, s[92:93]
	s_add_i32 m0, s10, 0x2000
	s_add_i32 s10, s65, s45
	global_load_lds_dwordx4 v[166:167], off
	v_lshl_add_u64 v[166:167], v[246:247], 0, s[92:93]
	s_mov_b32 m0, s10
	s_nop 0
	global_load_lds_dwordx4 v[166:167], off
	v_lshl_add_u64 v[166:167], v[220:221], 0, s[92:93]
	s_add_i32 m0, s10, 0x2000
	s_nop 0
	global_load_lds_dwordx4 v[166:167], off
	v_lshl_add_u64 v[166:167], v[248:249], 0, s[92:93]
	s_mov_b32 m0, s56
	s_nop 0
	global_load_lds_dwordx4 v[166:167], off
	v_lshl_add_u64 v[166:167], v[250:251], 0, s[92:93]
	s_mov_b32 m0, s57
	s_nop 0
	global_load_lds_dwordx4 v[166:167], off
	s_waitcnt vmcnt(8)
	s_waitcnt lgkmcnt(0)
	s_barrier
	s_setprio 1
	v_mfma_f32_16x16x32_bf16 v[56:59], v[146:149], v[192:195], v[56:59]
	v_lshrrev_b32_e32 v171, 8, v170
	v_and_b32_e32 v234, 15, v170
	v_lshl_add_u32 v171, v171, 6, v234
	s_lshl_b32 s98, s64, 8
	v_add_u32_e32 v171, s98, v171
	v_mul_lo_u32 v171, v171, s28
	v_bfe_u32 v234, v170, 6, 2
	v_bfe_u32 v224, v170, 4, 2
	v_lshlrev_b32_e32 v234, 5, v234
	v_lshl_or_b32 v234, v224, 3, v234
	v_mfma_f32_16x16x32_bf16 v[48:51], v[158:161], v[192:195], v[48:51]
	s_lshl_b32 s98, s63, 7
	v_add_u32_e32 v234, s98, v234
	v_add_lshl_u32 v232, v171, v234, 1
	v_mov_b32_e32 v233, 0
	v_lshl_add_u64 v[232:233], v[232:233], 0, s[30:31]
	s_lshl_b32 s98, s28, 5
	s_mov_b32 s99, 0
	s_mov_b32 s100, 0xbfb8aa3b
	s_mov_b32 s101, 0xbfb8aa3b
	v_mul_f32_e32 v120, v172, v120
	v_mfma_f32_16x16x32_bf16 v[40:43], v[146:149], v[200:203], v[40:43]
	v_mul_f32_e32 v121, v172, v121
	v_mul_f32_e32 v122, v172, v122
	v_mul_f32_e32 v123, v172, v123
	v_mul_f32_e32 v124, v172, v124
	v_mul_f32_e32 v125, v172, v125
	v_mul_f32_e32 v126, v172, v126
	v_mul_f32_e32 v127, v172, v127
	v_mul_f32_e32 v224, s100, v120
	v_mul_f32_e32 v225, s101, v121
	v_mul_f32_e32 v228, s100, v122
	v_mfma_f32_16x16x32_bf16 v[32:35], v[158:161], v[200:203], v[32:35]
	v_mul_f32_e32 v229, s101, v123
	v_exp_f32_e32 v224, v224
	v_exp_f32_e32 v225, v225
	v_exp_f32_e32 v228, v228
	v_exp_f32_e32 v229, v229
	v_add_f32_e32 v224, 1.0, v224
	v_add_f32_e32 v225, 1.0, v225
	v_add_f32_e32 v228, 1.0, v228
	v_add_f32_e32 v229, 1.0, v229
	v_rcp_f32_e32 v224, v224
	v_mfma_f32_16x16x32_bf16 v[24:27], v[146:149], v[208:211], v[24:27]
	v_rcp_f32_e32 v225, v225
	v_rcp_f32_e32 v228, v228
	v_rcp_f32_e32 v229, v229
	v_nop
	v_mul_f32_e32 v120, v224, v120
	v_mul_f32_e32 v121, v225, v121
	v_mul_f32_e32 v122, v228, v122
	v_mul_f32_e32 v123, v229, v123
	v_mul_f32_e32 v120, v124, v120
	v_mul_f32_e32 v121, v125, v121
	v_mfma_f32_16x16x32_bf16 v[16:19], v[158:161], v[208:211], v[16:19]
	v_mul_f32_e32 v122, v126, v122
	v_mul_f32_e32 v123, v127, v123
	v_mul_f32_e32 v112, v172, v112
	v_mul_f32_e32 v113, v172, v113
	v_mul_f32_e32 v114, v172, v114
	v_mul_f32_e32 v115, v172, v115
	v_mul_f32_e32 v116, v172, v116
; __device__ __forceinline__ unsigned cvt_pk_bf16(float lo, float hi) { unsigned r; asm volatile("v_cvt_pk_bf16_f32 %0, %1, %2" : "=v"(r) : "v"(lo), "v"(hi)); return r; }
; __device__ __forceinline__ float siluf_(float x) { return x * sigmoidf_(x); }
;     __device__ __forceinline__ void operator()(const f32x4 (&acc)[2][2][4][2], const Unit& u, int wr, int wc, int fr, int fq) const {
;     ...
;             for (int m = 0; m < 4; ++m) { const int row = row0 + ai * HALF + m * 16; bf16_t* rowp = O + (size_t)row * ldc + col0; const float rs = rsv[ai][m];
;                 f32x4 v0, v1;
; #pragma unroll
;                 for (int j = 0; j < 4; ++j) { v0[j] = siluf_(acc[ai][0][m][0][j] * rs) * (acc[ai][1][m][0][j] * rs); v1[j] = siluf_(acc[ai][0][m][1][j] * rs) * (acc[ai][1][m][1][j] * rs); }
;                 u32x4 w; w.x = cvt_pk_bf16(v0[0], v0[1]); w.y = cvt_pk_bf16(v0[2], v0[3]); w.z = cvt_pk_bf16(v1[0], v1[1]); w.w = cvt_pk_bf16(v1[2], v1[3]);
;                 *(u32x4*)rowp = w; }
	v_mul_f32_e32 v117, v172, v117
	v_mul_f32_e32 v118, v172, v118
	v_mul_f32_e32 v119, v172, v119
	v_mfma_f32_16x16x32_bf16 v[8:11], v[146:149], v[216:219], v[8:11]
	v_mul_f32_e32 v224, s100, v112
	v_mul_f32_e32 v225, s101, v113
	v_mul_f32_e32 v228, s100, v114
	v_mul_f32_e32 v229, s101, v115
	v_exp_f32_e32 v224, v224
	v_exp_f32_e32 v225, v225
	v_exp_f32_e32 v228, v228
	v_exp_f32_e32 v229, v229
	v_add_f32_e32 v224, 1.0, v224
	v_add_f32_e32 v225, 1.0, v225
	v_mfma_f32_16x16x32_bf16 v[4:7], v[158:161], v[216:219], v[4:7]
	v_add_f32_e32 v228, 1.0, v228
	v_add_f32_e32 v229, 1.0, v229
	v_rcp_f32_e32 v224, v224
	v_rcp_f32_e32 v225, v225
	v_rcp_f32_e32 v228, v228
	v_rcp_f32_e32 v229, v229
	v_nop
	v_mul_f32_e32 v112, v224, v112
	v_mul_f32_e32 v113, v225, v113
	v_mul_f32_e32 v114, v228, v114
	v_mfma_f32_16x16x32_bf16 v[56:59], v[154:157], v[196:199], v[56:59]
	v_mul_f32_e32 v115, v229, v115
	v_mul_f32_e32 v112, v116, v112
	v_mul_f32_e32 v113, v117, v113
	v_mul_f32_e32 v114, v118, v114
	v_mul_f32_e32 v115, v119, v115
	v_cvt_pk_bf16_f32 v120, v120, v121
	v_cvt_pk_bf16_f32 v121, v122, v123
	v_cvt_pk_bf16_f32 v122, v112, v113
	v_cvt_pk_bf16_f32 v123, v114, v115
	global_store_dwordx4 v[232:233], v[120:123], off
	v_mfma_f32_16x16x32_bf16 v[48:51], v[162:165], v[196:199], v[48:51]
	v_lshl_add_u64 v[232:233], v[232:233], 0, s[98:99]
	v_mul_f32_e32 v104, v173, v104
	v_mul_f32_e32 v105, v173, v105
	v_mul_f32_e32 v106, v173, v106
	v_mul_f32_e32 v107, v173, v107
	v_mul_f32_e32 v108, v173, v108
	v_mul_f32_e32 v109, v173, v109
	v_mul_f32_e32 v110, v173, v110
	v_mul_f32_e32 v111, v173, v111
	v_mul_f32_e32 v224, s100, v104
	v_mfma_f32_16x16x32_bf16 v[40:43], v[154:157], v[204:207], v[40:43]
	v_mul_f32_e32 v225, s101, v105
	v_mul_f32_e32 v228, s100, v106
	v_mul_f32_e32 v229, s101, v107
	v_exp_f32_e32 v224, v224
	v_exp_f32_e32 v225, v225
	v_exp_f32_e32 v228, v228
	v_exp_f32_e32 v229, v229
	v_add_f32_e32 v224, 1.0, v224
	v_add_f32_e32 v225, 1.0, v225
	v_add_f32_e32 v228, 1.0, v228
	v_mfma_f32_16x16x32_bf16 v[32:35], v[162:165], v[204:207], v[32:35]
	v_add_f32_e32 v229, 1.0, v229
	v_rcp_f32_e32 v224, v224
	v_rcp_f32_e32 v225, v225
	v_rcp_f32_e32 v228, v228
	v_rcp_f32_e32 v229, v229
	v_nop
	v_mul_f32_e32 v104, v224, v104
	v_mul_f32_e32 v105, v225, v105
	v_mul_f32_e32 v106, v228, v106
	v_mul_f32_e32 v107, v229, v107
	v_mfma_f32_16x16x32_bf16 v[24:27], v[154:157], v[212:215], v[24:27]
	v_mul_f32_e32 v104, v108, v104
	v_mul_f32_e32 v105, v109, v105
	v_mul_f32_e32 v106, v110, v106
	v_mul_f32_e32 v107, v111, v107
	v_mul_f32_e32 v96, v173, v96
	v_mul_f32_e32 v97, v173, v97
	v_mul_f32_e32 v98, v173, v98
	v_mul_f32_e32 v99, v173, v99
	v_mul_f32_e32 v100, v173, v100
	v_mul_f32_e32 v101, v173, v101
	v_mfma_f32_16x16x32_bf16 v[16:19], v[162:165], v[212:215], v[16:19]
	v_mul_f32_e32 v102, v173, v102
	v_mul_f32_e32 v103, v173, v103
	v_mul_f32_e32 v224, s100, v96
	v_mul_f32_e32 v225, s101, v97
	v_mul_f32_e32 v228, s100, v98
	v_mul_f32_e32 v229, s101, v99
	v_exp_f32_e32 v224, v224
	v_exp_f32_e32 v225, v225
	v_exp_f32_e32 v228, v228
	v_exp_f32_e32 v229, v229
	v_mfma_f32_16x16x32_bf16 v[8:11], v[154:157], v[240:243], v[8:11]
	v_add_f32_e32 v224, 1.0, v224
	v_add_f32_e32 v225, 1.0, v225
	v_add_f32_e32 v228, 1.0, v228
	v_add_f32_e32 v229, 1.0, v229
	v_rcp_f32_e32 v224, v224
	v_rcp_f32_e32 v225, v225
	v_rcp_f32_e32 v228, v228
	v_rcp_f32_e32 v229, v229
	v_nop
	v_mul_f32_e32 v96, v224, v96
	v_mfma_f32_16x16x32_bf16 v[4:7], v[162:165], v[240:243], v[4:7]
	v_mul_f32_e32 v97, v225, v97
	v_mul_f32_e32 v98, v228, v98
	v_mul_f32_e32 v99, v229, v99
	v_mul_f32_e32 v96, v100, v96
	v_mul_f32_e32 v97, v101, v97
	v_mul_f32_e32 v98, v102, v98
	v_mul_f32_e32 v99, v103, v99
	v_cvt_pk_bf16_f32 v104, v104, v105
	v_cvt_pk_bf16_f32 v105, v106, v107
	v_cvt_pk_bf16_f32 v106, v96, v97
	s_setprio 0
	s_setprio 1
	v_mfma_f32_16x16x32_bf16 v[60:63], v[176:179], v[192:195], v[60:63]
	v_cvt_pk_bf16_f32 v107, v98, v99
	global_store_dwordx4 v[232:233], v[104:107], off
	v_lshl_add_u64 v[232:233], v[232:233], 0, s[98:99]
	v_mul_f32_e32 v88, v236, v88
	v_mul_f32_e32 v89, v236, v89
	v_mul_f32_e32 v90, v236, v90
	v_mul_f32_e32 v91, v236, v91
	v_mul_f32_e32 v92, v236, v92
	v_mul_f32_e32 v93, v236, v93
	v_mul_f32_e32 v94, v236, v94
	v_mfma_f32_16x16x32_bf16 v[52:55], v[184:187], v[192:195], v[52:55]
	v_mul_f32_e32 v95, v236, v95
	v_mul_f32_e32 v224, s100, v88
	v_mul_f32_e32 v225, s101, v89
	v_mul_f32_e32 v228, s100, v90
	v_mul_f32_e32 v229, s101, v91
	v_exp_f32_e32 v224, v224
	v_exp_f32_e32 v225, v225
	v_exp_f32_e32 v228, v228
	v_exp_f32_e32 v229, v229
	v_add_f32_e32 v224, 1.0, v224
	v_mfma_f32_16x16x32_bf16 v[44:47], v[176:179], v[200:203], v[44:47]
	v_add_f32_e32 v225, 1.0, v225
	v_add_f32_e32 v228, 1.0, v228
	v_add_f32_e32 v229, 1.0, v229
	v_rcp_f32_e32 v224, v224
	v_rcp_f32_e32 v225, v225
	v_rcp_f32_e32 v228, v228
	v_rcp_f32_e32 v229, v229
	v_nop
	v_mul_f32_e32 v88, v224, v88
	v_mul_f32_e32 v89, v225, v89
; __device__ __forceinline__ unsigned cvt_pk_bf16(float lo, float hi) { unsigned r; asm volatile("v_cvt_pk_bf16_f32 %0, %1, %2" : "=v"(r) : "v"(lo), "v"(hi)); return r; }
; __device__ __forceinline__ float siluf_(float x) { return x * sigmoidf_(x); }
; #define PG8_BAR __builtin_amdgcn_s_barrier()
;     __device__ __forceinline__ void operator()(const f32x4 (&acc)[2][2][4][2], const Unit& u, int wr, int wc, int fr, int fq) const {
;     ...
;             for (int m = 0; m < 4; ++m) { const int row = row0 + ai * HALF + m * 16; bf16_t* rowp = O + (size_t)row * ldc + col0; const float rs = rsv[ai][m];
;                 f32x4 v0, v1;
; #pragma unroll
;                 for (int j = 0; j < 4; ++j) { v0[j] = siluf_(acc[ai][0][m][0][j] * rs) * (acc[ai][1][m][0][j] * rs); v1[j] = siluf_(acc[ai][0][m][1][j] * rs) * (acc[ai][1][m][1][j] * rs); }
;                 u32x4 w; w.x = cvt_pk_bf16(v0[0], v0[1]); w.y = cvt_pk_bf16(v0[2], v0[3]); w.z = cvt_pk_bf16(v1[0], v1[1]); w.w = cvt_pk_bf16(v1[2], v1[3]);
;                 *(u32x4*)rowp = w; }
; template <class Epi, bool ALIGN_EPI>
; __device__ __forceinline__ void gemm_phase(LAS unsigned char* lds, const Gemm g, const StaticOrder& S, const Epi& E, const int tid) {
;     ...
;         if constexpr (ALIGN_EPI) { if (wr == 0) PG8_BAR; }
;         { int t2 = tid; asm volatile("" : "+v"(t2)); const int l2 = t2 & 63, w2 = __builtin_amdgcn_readfirstlane(t2 >> 6); E(acc, cur, w2 >> 2, w2 & 3, l2 & 15, l2 >> 4); }
;         if (!has_next) break;
; #pragma unroll
;         for (int a = 0; a < 2; ++a)
; #pragma unroll
;             for (int b = 0; b < 2; ++b)
; #pragma unroll
;                 for (int m = 0; m < 4; ++m)
; #pragma unroll
;                     for (int n = 0; n < 2; ++n) acc[a][b][m][n] = (f32x4){0.f, 0.f, 0.f, 0.f};
;         cur = nxt; cA = nA; cB = nB; ++ui;
;         if constexpr (ALIGN_EPI) { if (wr == 1) PG8_BAR; }
	v_mfma_f32_16x16x32_bf16 v[36:39], v[184:187], v[200:203], v[36:39]
	v_mul_f32_e32 v90, v228, v90
	v_mul_f32_e32 v91, v229, v91
	v_mul_f32_e32 v88, v92, v88
	v_mul_f32_e32 v89, v93, v89
	v_mul_f32_e32 v90, v94, v90
	v_mul_f32_e32 v91, v95, v91
	v_mul_f32_e32 v80, v236, v80
	v_mul_f32_e32 v81, v236, v81
	v_mul_f32_e32 v82, v236, v82
	v_mul_f32_e32 v83, v236, v83
	v_mfma_f32_16x16x32_bf16 v[28:31], v[176:179], v[208:211], v[28:31]
	v_mul_f32_e32 v84, v236, v84
	v_mul_f32_e32 v85, v236, v85
	v_mul_f32_e32 v86, v236, v86
	v_mul_f32_e32 v87, v236, v87
	v_mul_f32_e32 v224, s100, v80
	v_mul_f32_e32 v225, s101, v81
	v_mul_f32_e32 v228, s100, v82
	v_mul_f32_e32 v229, s101, v83
	v_exp_f32_e32 v224, v224
	v_exp_f32_e32 v225, v225
	v_mfma_f32_16x16x32_bf16 v[20:23], v[184:187], v[208:211], v[20:23]
	v_exp_f32_e32 v228, v228
	v_exp_f32_e32 v229, v229
	v_add_f32_e32 v224, 1.0, v224
	v_add_f32_e32 v225, 1.0, v225
	v_add_f32_e32 v228, 1.0, v228
	v_add_f32_e32 v229, 1.0, v229
	v_rcp_f32_e32 v224, v224
	v_rcp_f32_e32 v225, v225
	v_rcp_f32_e32 v228, v228
	v_rcp_f32_e32 v229, v229
	v_mfma_f32_16x16x32_bf16 v[12:15], v[176:179], v[216:219], v[12:15]
	v_nop
	v_mul_f32_e32 v80, v224, v80
	v_mul_f32_e32 v81, v225, v81
	v_mul_f32_e32 v82, v228, v82
	v_mul_f32_e32 v83, v229, v83
	v_mul_f32_e32 v80, v84, v80
	v_mul_f32_e32 v81, v85, v81
	v_mul_f32_e32 v82, v86, v82
	v_mul_f32_e32 v83, v87, v83
	v_cvt_pk_bf16_f32 v88, v88, v89
	v_mfma_f32_16x16x32_bf16 v[0:3], v[184:187], v[216:219], v[0:3]
	v_cvt_pk_bf16_f32 v89, v90, v91
	v_cvt_pk_bf16_f32 v90, v80, v81
	v_cvt_pk_bf16_f32 v91, v82, v83
	global_store_dwordx4 v[232:233], v[88:91], off
	v_lshl_add_u64 v[232:233], v[232:233], 0, s[98:99]
	v_mul_f32_e32 v72, v237, v72
	v_mul_f32_e32 v73, v237, v73
	v_mul_f32_e32 v74, v237, v74
	v_mul_f32_e32 v75, v237, v75
	v_mul_f32_e32 v76, v237, v76
	v_mfma_f32_16x16x32_bf16 v[60:63], v[180:183], v[196:199], v[60:63]
	v_mul_f32_e32 v77, v237, v77
	v_mul_f32_e32 v78, v237, v78
	v_mul_f32_e32 v79, v237, v79
	v_mul_f32_e32 v224, s100, v72
	v_mul_f32_e32 v225, s101, v73
	v_mul_f32_e32 v228, s100, v74
	v_mul_f32_e32 v229, s101, v75
	v_exp_f32_e32 v224, v224
	v_exp_f32_e32 v225, v225
	v_exp_f32_e32 v228, v228
	v_mfma_f32_16x16x32_bf16 v[52:55], v[188:191], v[196:199], v[52:55]
	v_exp_f32_e32 v229, v229
	v_add_f32_e32 v224, 1.0, v224
	v_add_f32_e32 v225, 1.0, v225
	v_add_f32_e32 v228, 1.0, v228
	v_add_f32_e32 v229, 1.0, v229
	v_rcp_f32_e32 v224, v224
	v_rcp_f32_e32 v225, v225
	v_rcp_f32_e32 v228, v228
	v_rcp_f32_e32 v229, v229
	v_nop
	v_mfma_f32_16x16x32_bf16 v[44:47], v[180:183], v[204:207], v[44:47]
	v_mul_f32_e32 v72, v224, v72
	v_mul_f32_e32 v73, v225, v73
	v_mul_f32_e32 v74, v228, v74
	v_mul_f32_e32 v75, v229, v75
	v_mul_f32_e32 v72, v76, v72
	v_mul_f32_e32 v73, v77, v73
	v_mul_f32_e32 v74, v78, v74
	v_mul_f32_e32 v75, v79, v75
	v_mul_f32_e32 v64, v237, v64
	v_mul_f32_e32 v65, v237, v65
	v_mfma_f32_16x16x32_bf16 v[36:39], v[188:191], v[204:207], v[36:39]
	v_mul_f32_e32 v66, v237, v66
	v_mul_f32_e32 v67, v237, v67
	v_mul_f32_e32 v68, v237, v68
	v_mul_f32_e32 v69, v237, v69
	v_mul_f32_e32 v70, v237, v70
	v_mul_f32_e32 v71, v237, v71
	v_mul_f32_e32 v224, s100, v64
	v_mul_f32_e32 v225, s101, v65
	v_mul_f32_e32 v228, s100, v66
	v_mul_f32_e32 v229, s101, v67
	v_mfma_f32_16x16x32_bf16 v[28:31], v[180:183], v[212:215], v[28:31]
	v_exp_f32_e32 v224, v224
	v_exp_f32_e32 v225, v225
	v_exp_f32_e32 v228, v228
	v_exp_f32_e32 v229, v229
	v_add_f32_e32 v224, 1.0, v224
	v_add_f32_e32 v225, 1.0, v225
	v_add_f32_e32 v228, 1.0, v228
	v_add_f32_e32 v229, 1.0, v229
	v_rcp_f32_e32 v224, v224
	v_rcp_f32_e32 v225, v225
	v_mfma_f32_16x16x32_bf16 v[20:23], v[188:191], v[212:215], v[20:23]
	v_rcp_f32_e32 v228, v228
	v_rcp_f32_e32 v229, v229
	v_nop
	v_mul_f32_e32 v64, v224, v64
	v_mul_f32_e32 v65, v225, v65
	v_mul_f32_e32 v66, v228, v66
	v_mul_f32_e32 v67, v229, v67
	v_mul_f32_e32 v64, v68, v64
	v_mul_f32_e32 v65, v69, v65
	v_mul_f32_e32 v66, v70, v66
	v_mfma_f32_16x16x32_bf16 v[12:15], v[180:183], v[240:243], v[12:15]
	v_mul_f32_e32 v67, v71, v67
	v_cvt_pk_bf16_f32 v72, v72, v73
	v_cvt_pk_bf16_f32 v73, v74, v75
	v_cvt_pk_bf16_f32 v74, v64, v65
	v_cvt_pk_bf16_f32 v75, v66, v67
	global_store_dwordx4 v[232:233], v[72:75], off
	v_lshl_add_u64 v[232:233], v[232:233], 0, s[98:99]
	v_lshl_add_u64 v[232:233], v[232:233], 0, s[98:99]
	v_lshl_add_u64 v[232:233], v[232:233], 0, s[98:99]
	v_lshl_add_u64 v[232:233], v[232:233], 0, s[98:99]
	v_mfma_f32_16x16x32_bf16 v[0:3], v[188:191], v[240:243], v[0:3]
	v_lshl_add_u64 v[232:233], v[232:233], 0, s[98:99]
	s_setprio 0
	s_barrier
	v_lshl_add_u64 v[142:143], v[142:143], 0, s[80:81]
	v_lshl_add_u64 v[144:145], v[144:145], 0, s[80:81]
	s_and_b64 vcc, exec, s[8:9]
	s_cbranch_vccnz .Lgu_notdefer
	s_cmp_lg_u32 s62, s64
	s_cbranch_scc1 .Lgu_notdefer
	s_mov_b32 s101, 1
	s_mov_b32 s63, s61
	s_mov_b32 s64, s62
	v_mov_b64_e32 v[144:145], v[140:141]
	v_mov_b64_e32 v[142:143], v[138:139]
	s_branch .LBB0_300

; #define PG8_STAGE(bufoff, gbase, voff) do { _Pragma("unroll") for (int _i = 0; _i < 2; ++_i) \
;         __builtin_amdgcn_global_load_lds((const unsigned*)((const char*)(gbase) + (voff)[_i]), (LAS unsigned*)(lds + (bufoff) + ldsw + _i * 8192), 16, 0, 0); } while (0)
; #define PG8_LDA(dst, b, h) do { _Pragma("unroll") for (int m = 0; m < 4; ++m) _Pragma("unroll") for (int k = 0; k < 2; ++k) dst[m][k] = *(const LAS bf16x8*)(lds + PG8_SA(b, h) + aoff + m * 2048 + k * 1024); } while (0)
; #define PG8_LDB(dst, b, h) do { _Pragma("unroll") for (int n = 0; n < 2; ++n) _Pragma("unroll") for (int k = 0; k < 2; ++k) dst[n][k] = *(const LAS bf16x8*)(lds + PG8_SB(b, h) + boff + n * 2048 + k * 1024); } while (0)
; #define PG8_WAIT_V(n) asm volatile("s_waitcnt vmcnt(" #n ")" ::: "memory")
; #define PG8_WAIT_L(n) asm volatile("s_waitcnt lgkmcnt(" #n ")" ::: "memory")
; template <class Epi, bool ALIGN_EPI>
; __device__ __forceinline__ void gemm_phase(LAS unsigned char* lds, const Gemm g, const StaticOrder& S, const Epi& E, const int tid) {
;     ...
;         const bool has_next = S.next(ui + 1, nxt);
;         const char* nA = has_next ? (const char*)g.A + (size_t)nxt.pm * tA + (size_t)nxt.pn * g.apn * 2 : cA; const char* nB = has_next ? (const char*)g.Bt + (size_t)nxt.pn * tB : cB;
;         for (int t = 0; t < nt; t += 2) {
;             const bool last = (t == nt - 2);
;             const char* a1 = cA + (size_t)(t + 1) * kstep;
;             const char* a2 = last ? nA : cA + (size_t)(t + 2) * kstep; const char* b2 = last ? nB : cB + (size_t)(t + 2) * kstep;
;             const char* a3 = a2 + kstep; const char* b3 = b2 + kstep;
;             PG8_LDB(B0, 0, 0); PG8_LDB(B1, 0, 1); PG8_SCHED; PG8_LDA(At, 0, 0); PG8_STAGE(PG8_SA(1, 1), a1 + hA, voffA);
;             PG8_WAIT_V(8); PG8_WAIT_L(0); PG8_BAR; PG8_MMA(0, 0, At, B0); PG8_MMA(0, 1, At, B1); PG8_BAR; PG8_SCHED;
;             PG8_LDA(At, 0, 1); PG8_STAGE(PG8_SB(0, 0), b2, voffB); PG8_STAGE(PG8_SB(0, 1), b2 + hB, voffB); PG8_STAGE(PG8_SA(0, 0), a2, voffA);
;             PG8_WAIT_V(8); PG8_WAIT_L(0); PG8_BAR; PG8_MMA(1, 0, At, B0); PG8_MMA(1, 1, At, B1); PG8_BAR; PG8_SCHED;
;             PG8_LDB(B0, 1, 0); PG8_LDB(B1, 1, 1); PG8_SCHED; PG8_LDA(At, 1, 0); PG8_STAGE(PG8_SA(0, 1), a2 + hA, voffA);
;             PG8_WAIT_V(8); PG8_WAIT_L(0); PG8_BAR; PG8_MMA(0, 0, At, B0); PG8_MMA(0, 1, At, B1); PG8_BAR; PG8_SCHED;
.LBB0_329:
	s_andn2_b64 vcc, exec, s[36:37]
	s_cbranch_vccnz .LBB0_332
	v_lshl_add_u64 v[142:143], v[142:143], 0, s[92:93]
	v_lshl_add_u64 v[144:145], v[144:145], 0, s[80:81]
	s_mov_b32 s10, 0
	s_add_i32 s11, s10, 2
	s_cmp_eq_u32 s58, s10
	v_lshl_add_u64 v[146:147], v[142:143], 0, s[92:93]
	s_cselect_b64 vcc, -1, 0
	v_add_u32_e32 v152, s33, v153
	s_add_i32 s10, 0, 0x14000
	v_cndmask_b32_e32 v151, v147, v139, vcc
	v_cndmask_b32_e32 v150, v146, v138, vcc
	ds_read_b128 v[146:149], v152
	ds_read_b128 v[156:159], v152 offset:1024
	ds_read_b128 v[160:163], v152 offset:2048
	ds_read_b128 v[164:167], v152 offset:3072
	v_add_u32_e32 v152, s10, v153
	ds_read_b128 v[176:179], v152
	ds_read_b128 v[180:183], v152 offset:1024
	ds_read_b128 v[184:187], v152 offset:2048
	ds_read_b128 v[188:191], v152 offset:3072
	v_cndmask_b32_e32 v221, v145, v141, vcc
	v_cndmask_b32_e32 v220, v144, v140, vcc
	v_lshl_add_u64 v[226:227], v[142:143], 0, v[134:135]
	s_add_i32 m0, s51, 0xc000
	ds_read_b128 v[192:195], v155
	ds_read_b128 v[196:199], v155 offset:1024
	ds_read_b128 v[200:203], v155 offset:2048
	ds_read_b128 v[204:207], v155 offset:3072
	ds_read_b128 v[208:211], v155 offset:4096
	ds_read_b128 v[212:215], v155 offset:5120
	ds_read_b128 v[216:219], v155 offset:6144
	ds_read_b128 v[240:243], v155 offset:7168
	global_load_lds_dwordx4 v[226:227], off
	v_lshl_add_u64 v[226:227], v[142:143], 0, v[136:137]
	s_add_i32 m0, s51, 0xe000
	s_nop 0
	global_load_lds_dwordx4 v[226:227], off
	s_waitcnt vmcnt(8)
	s_waitcnt lgkmcnt(0)
	s_barrier
	s_setprio 1
	v_mfma_f32_16x16x32_bf16 v[120:123], v[146:149], v[192:195], 0
	v_mfma_f32_16x16x32_bf16 v[124:127], v[160:163], v[192:195], 0
	v_mfma_f32_16x16x32_bf16 v[108:111], v[146:149], v[200:203], 0
	v_mfma_f32_16x16x32_bf16 v[104:107], v[160:163], v[200:203], 0
	v_mfma_f32_16x16x32_bf16 v[92:95], v[146:149], v[208:211], 0
	v_mfma_f32_16x16x32_bf16 v[88:91], v[160:163], v[208:211], 0
	v_mfma_f32_16x16x32_bf16 v[76:79], v[146:149], v[216:219], 0
	v_mfma_f32_16x16x32_bf16 v[72:75], v[160:163], v[216:219], 0
	v_mfma_f32_16x16x32_bf16 v[120:123], v[156:159], v[196:199], v[120:123]
	v_mfma_f32_16x16x32_bf16 v[124:127], v[164:167], v[196:199], v[124:127]
	v_mfma_f32_16x16x32_bf16 v[108:111], v[156:159], v[204:207], v[108:111]
	v_mfma_f32_16x16x32_bf16 v[104:107], v[164:167], v[204:207], v[104:107]
	v_mfma_f32_16x16x32_bf16 v[92:95], v[156:159], v[212:215], v[92:95]
	v_mfma_f32_16x16x32_bf16 v[88:91], v[164:167], v[212:215], v[88:91]
	v_mfma_f32_16x16x32_bf16 v[76:79], v[156:159], v[240:243], v[76:79]
	v_mfma_f32_16x16x32_bf16 v[72:75], v[164:167], v[240:243], v[72:75]
	s_setprio 0
	s_setprio 1
	v_mfma_f32_16x16x32_bf16 v[116:119], v[176:179], v[192:195], 0
	v_mfma_f32_16x16x32_bf16 v[112:115], v[184:187], v[192:195], 0
	v_mfma_f32_16x16x32_bf16 v[100:103], v[176:179], v[200:203], 0
	v_mfma_f32_16x16x32_bf16 v[96:99], v[184:187], v[200:203], 0
	v_mfma_f32_16x16x32_bf16 v[84:87], v[176:179], v[208:211], 0
	v_mfma_f32_16x16x32_bf16 v[80:83], v[184:187], v[208:211], 0
	v_mfma_f32_16x16x32_bf16 v[68:71], v[176:179], v[216:219], 0
	v_mfma_f32_16x16x32_bf16 v[64:67], v[184:187], v[216:219], 0
	v_mfma_f32_16x16x32_bf16 v[116:119], v[180:183], v[196:199], v[116:119]
	v_mfma_f32_16x16x32_bf16 v[112:115], v[188:191], v[196:199], v[112:115]
	v_mfma_f32_16x16x32_bf16 v[100:103], v[180:183], v[204:207], v[100:103]
	v_mfma_f32_16x16x32_bf16 v[96:99], v[188:191], v[204:207], v[96:99]
	v_mfma_f32_16x16x32_bf16 v[84:87], v[180:183], v[212:215], v[84:87]
	v_mfma_f32_16x16x32_bf16 v[80:83], v[188:191], v[212:215], v[80:83]
	v_mfma_f32_16x16x32_bf16 v[68:71], v[180:183], v[240:243], v[68:71]
	v_mfma_f32_16x16x32_bf16 v[64:67], v[188:191], v[240:243], v[64:67]
	s_setprio 0
	s_barrier
	s_add_i32 s65, s33, s45
	v_lshl_add_u64 v[226:227], v[220:221], 0, v[168:169]
	s_mov_b32 m0, s65
	ds_read_b128 v[192:195], v155 offset:16384
	ds_read_b128 v[196:199], v155 offset:17408
	ds_read_b128 v[200:203], v155 offset:18432
	ds_read_b128 v[204:207], v155 offset:19456
	ds_read_b128 v[208:211], v155 offset:20480
	ds_read_b128 v[212:215], v155 offset:21504
	ds_read_b128 v[216:219], v155 offset:22528
	ds_read_b128 v[240:243], v155 offset:23552
	global_load_lds_dwordx4 v[226:227], off
	v_lshl_add_u64 v[244:245], v[220:221], 0, v[128:129]
	s_add_i32 m0, s65, 0x2000
	v_lshl_add_u64 v[220:221], v[220:221], 0, s[12:13]
	s_add_i32 s10, s10, s45
	global_load_lds_dwordx4 v[244:245], off
	v_lshl_add_u64 v[246:247], v[220:221], 0, v[168:169]
	s_mov_b32 m0, s10
	v_lshl_add_u64 v[220:221], v[220:221], 0, v[128:129]
	global_load_lds_dwordx4 v[246:247], off
	s_add_i32 m0, s10, 0x2000
	v_lshl_add_u64 v[248:249], v[150:151], 0, v[132:133]
	global_load_lds_dwordx4 v[220:221], off
	s_mov_b32 m0, s51
	v_lshl_add_u64 v[250:251], v[150:151], 0, v[130:131]
	global_load_lds_dwordx4 v[248:249], off
	s_mov_b32 m0, s52
	s_nop 0
	global_load_lds_dwordx4 v[250:251], off
	s_waitcnt vmcnt(8)
	s_waitcnt lgkmcnt(0)
	s_barrier
; #define PG8_STAGE(bufoff, gbase, voff) do { _Pragma("unroll") for (int _i = 0; _i < 2; ++_i) \
;         __builtin_amdgcn_global_load_lds((const unsigned*)((const char*)(gbase) + (voff)[_i]), (LAS unsigned*)(lds + (bufoff) + ldsw + _i * 8192), 16, 0, 0); } while (0)
; #define PG8_LDA(dst, b, h) do { _Pragma("unroll") for (int m = 0; m < 4; ++m) _Pragma("unroll") for (int k = 0; k < 2; ++k) dst[m][k] = *(const LAS bf16x8*)(lds + PG8_SA(b, h) + aoff + m * 2048 + k * 1024); } while (0)
; #define PG8_LDB(dst, b, h) do { _Pragma("unroll") for (int n = 0; n < 2; ++n) _Pragma("unroll") for (int k = 0; k < 2; ++k) dst[n][k] = *(const LAS bf16x8*)(lds + PG8_SB(b, h) + boff + n * 2048 + k * 1024); } while (0)
; #define PG8_MMA(ai, bj, At, Bt) do { __builtin_amdgcn_s_setprio(1); _Pragma("unroll") for (int k = 0; k < 2; ++k) _Pragma("unroll") for (int m = 0; m < 4; ++m) _Pragma("unroll") for (int n = 0; n < 2; ++n) \
;         acc[ai][bj][m][n] = __builtin_amdgcn_mfma_f32_16x16x32_bf16(Bt[n][k], At[m][k], acc[ai][bj][m][n], 0, 0, 0); __builtin_amdgcn_s_setprio(0); } while (0)
; #define PG8_WAIT_V(n) asm volatile("s_waitcnt vmcnt(" #n ")" ::: "memory")
; #define PG8_WAIT_L(n) asm volatile("s_waitcnt lgkmcnt(" #n ")" ::: "memory")
; #define PG8_BAR __builtin_amdgcn_s_barrier()
; #define PG8_SCHED __builtin_amdgcn_sched_barrier(0)
; template <class Epi, bool ALIGN_EPI>
; __device__ __forceinline__ void gemm_phase(LAS unsigned char* lds, const Gemm g, const StaticOrder& S, const Epi& E, const int tid) {
;     ...
;             PG8_WAIT_V(8); PG8_WAIT_L(0); PG8_BAR; PG8_MMA(1, 0, At, B0); PG8_MMA(1, 1, At, B1); PG8_BAR; PG8_SCHED;
;             PG8_LDB(B0, 1, 0); PG8_LDB(B1, 1, 1); PG8_SCHED; PG8_LDA(At, 1, 0); PG8_STAGE(PG8_SA(0, 1), a2 + hA, voffA);
;             PG8_WAIT_V(8); PG8_WAIT_L(0); PG8_BAR; PG8_MMA(0, 0, At, B0); PG8_MMA(0, 1, At, B1); PG8_BAR; PG8_SCHED;
;             PG8_LDA(At, 1, 1); PG8_STAGE(PG8_SB(1, 0), b3, voffB); PG8_STAGE(PG8_SB(1, 1), b3 + hB, voffB); PG8_STAGE(PG8_SA(1, 0), a3, voffA);
;             PG8_WAIT_V(8); PG8_WAIT_L(0); PG8_BAR; PG8_MMA(1, 0, At, B0); PG8_MMA(1, 1, At, B1); PG8_BAR; PG8_SCHED;
	s_setprio 1
	v_mfma_f32_16x16x32_bf16 v[60:63], v[146:149], v[192:195], 0
	v_mfma_f32_16x16x32_bf16 v[56:59], v[160:163], v[192:195], 0
	v_mfma_f32_16x16x32_bf16 v[44:47], v[146:149], v[200:203], 0
	v_mfma_f32_16x16x32_bf16 v[40:43], v[160:163], v[200:203], 0
	v_mfma_f32_16x16x32_bf16 v[28:31], v[146:149], v[208:211], 0
	v_mfma_f32_16x16x32_bf16 v[24:27], v[160:163], v[208:211], 0
	v_mfma_f32_16x16x32_bf16 v[12:15], v[146:149], v[216:219], 0
	v_mfma_f32_16x16x32_bf16 v[8:11], v[160:163], v[216:219], 0
	v_mfma_f32_16x16x32_bf16 v[60:63], v[156:159], v[196:199], v[60:63]
	v_mfma_f32_16x16x32_bf16 v[56:59], v[164:167], v[196:199], v[56:59]
	v_mfma_f32_16x16x32_bf16 v[44:47], v[156:159], v[204:207], v[44:47]
	v_mfma_f32_16x16x32_bf16 v[40:43], v[164:167], v[204:207], v[40:43]
	v_mfma_f32_16x16x32_bf16 v[28:31], v[156:159], v[212:215], v[28:31]
	v_mfma_f32_16x16x32_bf16 v[24:27], v[164:167], v[212:215], v[24:27]
	v_mfma_f32_16x16x32_bf16 v[12:15], v[156:159], v[240:243], v[12:15]
	v_mfma_f32_16x16x32_bf16 v[8:11], v[164:167], v[240:243], v[8:11]
	s_setprio 0
	s_setprio 1
	v_mfma_f32_16x16x32_bf16 v[52:55], v[176:179], v[192:195], 0
	v_mfma_f32_16x16x32_bf16 v[48:51], v[184:187], v[192:195], 0
	v_mfma_f32_16x16x32_bf16 v[36:39], v[176:179], v[200:203], 0
	v_mfma_f32_16x16x32_bf16 v[32:35], v[184:187], v[200:203], 0
	v_mfma_f32_16x16x32_bf16 v[20:23], v[176:179], v[208:211], 0
	v_mfma_f32_16x16x32_bf16 v[16:19], v[184:187], v[208:211], 0
	v_mfma_f32_16x16x32_bf16 v[4:7], v[176:179], v[216:219], 0
	v_mfma_f32_16x16x32_bf16 v[0:3], v[184:187], v[216:219], 0
	v_mfma_f32_16x16x32_bf16 v[52:55], v[180:183], v[196:199], v[52:55]
	v_mfma_f32_16x16x32_bf16 v[48:51], v[188:191], v[196:199], v[48:51]
	v_mfma_f32_16x16x32_bf16 v[36:39], v[180:183], v[204:207], v[36:39]
	v_mfma_f32_16x16x32_bf16 v[32:35], v[188:191], v[204:207], v[32:35]
	v_mfma_f32_16x16x32_bf16 v[20:23], v[180:183], v[212:215], v[20:23]
	v_mfma_f32_16x16x32_bf16 v[16:19], v[188:191], v[212:215], v[16:19]
	v_mfma_f32_16x16x32_bf16 v[4:7], v[180:183], v[240:243], v[4:7]
	v_mfma_f32_16x16x32_bf16 v[0:3], v[188:191], v[240:243], v[0:3]
	s_setprio 0
	s_barrier
	s_add_i32 s10, 0, 0x18000
	v_add_u32_e32 v152, s10, v153
	s_add_i32 s65, 0, 0x1c000
	ds_read_b128 v[146:149], v152
	ds_read_b128 v[156:159], v152 offset:1024
	ds_read_b128 v[160:163], v152 offset:2048
	ds_read_b128 v[164:167], v152 offset:3072
	v_add_u32_e32 v152, s65, v153
	ds_read_b128 v[176:179], v152
	ds_read_b128 v[180:183], v152 offset:1024
	ds_read_b128 v[184:187], v152 offset:2048
	ds_read_b128 v[188:191], v152 offset:3072
	v_lshl_add_u64 v[150:151], v[150:151], 0, s[94:95]
	s_mov_b32 m0, s53
	v_lshl_add_u64 v[252:253], v[150:151], 0, v[132:133]
	ds_read_b128 v[192:195], v155 offset:32768
	ds_read_b128 v[196:199], v155 offset:33792
	ds_read_b128 v[200:203], v155 offset:34816
	ds_read_b128 v[204:207], v155 offset:35840
	ds_read_b128 v[208:211], v155 offset:36864
	ds_read_b128 v[212:215], v155 offset:37888
	ds_read_b128 v[216:219], v155 offset:38912
	ds_read_b128 v[240:243], v155 offset:39936
	global_load_lds_dwordx4 v[252:253], off
	v_lshl_add_u64 v[150:151], v[150:151], 0, v[130:131]
	s_mov_b32 m0, s54
	s_nop 0
	global_load_lds_dwordx4 v[150:151], off
	s_waitcnt vmcnt(8)
	s_waitcnt lgkmcnt(0)
	s_barrier
	s_setprio 1
	v_mfma_f32_16x16x32_bf16 v[120:123], v[146:149], v[192:195], v[120:123]
	v_mfma_f32_16x16x32_bf16 v[124:127], v[160:163], v[192:195], v[124:127]
	v_mfma_f32_16x16x32_bf16 v[108:111], v[146:149], v[200:203], v[108:111]
	v_mfma_f32_16x16x32_bf16 v[104:107], v[160:163], v[200:203], v[104:107]
	v_mfma_f32_16x16x32_bf16 v[92:95], v[146:149], v[208:211], v[92:95]
	v_mfma_f32_16x16x32_bf16 v[88:91], v[160:163], v[208:211], v[88:91]
	v_mfma_f32_16x16x32_bf16 v[76:79], v[146:149], v[216:219], v[76:79]
	v_mfma_f32_16x16x32_bf16 v[72:75], v[160:163], v[216:219], v[72:75]
	v_mfma_f32_16x16x32_bf16 v[120:123], v[156:159], v[196:199], v[120:123]
	v_mfma_f32_16x16x32_bf16 v[124:127], v[164:167], v[196:199], v[124:127]
	v_mfma_f32_16x16x32_bf16 v[108:111], v[156:159], v[204:207], v[108:111]
	v_mfma_f32_16x16x32_bf16 v[104:107], v[164:167], v[204:207], v[104:107]
	v_mfma_f32_16x16x32_bf16 v[92:95], v[156:159], v[212:215], v[92:95]
	v_mfma_f32_16x16x32_bf16 v[88:91], v[164:167], v[212:215], v[88:91]
	v_mfma_f32_16x16x32_bf16 v[76:79], v[156:159], v[240:243], v[76:79]
	v_mfma_f32_16x16x32_bf16 v[72:75], v[164:167], v[240:243], v[72:75]
	s_setprio 0
	s_setprio 1
	v_mfma_f32_16x16x32_bf16 v[116:119], v[176:179], v[192:195], v[116:119]
	v_mfma_f32_16x16x32_bf16 v[112:115], v[184:187], v[192:195], v[112:115]
	v_mfma_f32_16x16x32_bf16 v[100:103], v[176:179], v[200:203], v[100:103]
	v_mfma_f32_16x16x32_bf16 v[96:99], v[184:187], v[200:203], v[96:99]
	v_mfma_f32_16x16x32_bf16 v[84:87], v[176:179], v[208:211], v[84:87]
	v_mfma_f32_16x16x32_bf16 v[80:83], v[184:187], v[208:211], v[80:83]
	v_mfma_f32_16x16x32_bf16 v[68:71], v[176:179], v[216:219], v[68:71]
	v_mfma_f32_16x16x32_bf16 v[64:67], v[184:187], v[216:219], v[64:67]
	v_mfma_f32_16x16x32_bf16 v[116:119], v[180:183], v[196:199], v[116:119]
	v_mfma_f32_16x16x32_bf16 v[112:115], v[188:191], v[196:199], v[112:115]
	v_mfma_f32_16x16x32_bf16 v[100:103], v[180:183], v[204:207], v[100:103]
	v_mfma_f32_16x16x32_bf16 v[96:99], v[188:191], v[204:207], v[96:99]
	v_mfma_f32_16x16x32_bf16 v[84:87], v[180:183], v[212:215], v[84:87]
	v_mfma_f32_16x16x32_bf16 v[80:83], v[188:191], v[212:215], v[80:83]
	v_mfma_f32_16x16x32_bf16 v[68:71], v[180:183], v[240:243], v[68:71]
	v_mfma_f32_16x16x32_bf16 v[64:67], v[188:191], v[240:243], v[64:67]
	s_setprio 0
	s_barrier
; #define PG8_STAGE(bufoff, gbase, voff) do { _Pragma("unroll") for (int _i = 0; _i < 2; ++_i) \
;         __builtin_amdgcn_global_load_lds((const unsigned*)((const char*)(gbase) + (voff)[_i]), (LAS unsigned*)(lds + (bufoff) + ldsw + _i * 8192), 16, 0, 0); } while (0)
; #define PG8_LDA(dst, b, h) do { _Pragma("unroll") for (int m = 0; m < 4; ++m) _Pragma("unroll") for (int k = 0; k < 2; ++k) dst[m][k] = *(const LAS bf16x8*)(lds + PG8_SA(b, h) + aoff + m * 2048 + k * 1024); } while (0)
; #define PG8_MMA(ai, bj, At, Bt) do { __builtin_amdgcn_s_setprio(1); _Pragma("unroll") for (int k = 0; k < 2; ++k) _Pragma("unroll") for (int m = 0; m < 4; ++m) _Pragma("unroll") for (int n = 0; n < 2; ++n) \
;         acc[ai][bj][m][n] = __builtin_amdgcn_mfma_f32_16x16x32_bf16(Bt[n][k], At[m][k], acc[ai][bj][m][n], 0, 0, 0); __builtin_amdgcn_s_setprio(0); } while (0)
; #define PG8_WAIT_V(n) asm volatile("s_waitcnt vmcnt(" #n ")" ::: "memory")
; #define PG8_WAIT_L(n) asm volatile("s_waitcnt lgkmcnt(" #n ")" ::: "memory")
; #define PG8_BAR __builtin_amdgcn_s_barrier()
; #define PG8_SCHED __builtin_amdgcn_sched_barrier(0)
; template <class Epi, bool ALIGN_EPI>
; __device__ __forceinline__ void gemm_phase(LAS unsigned char* lds, const Gemm g, const StaticOrder& S, const Epi& E, const int tid) {
;     ...
;             PG8_LDA(At, 1, 1); PG8_STAGE(PG8_SB(1, 0), b3, voffB); PG8_STAGE(PG8_SB(1, 1), b3 + hB, voffB); PG8_STAGE(PG8_SA(1, 0), a3, voffA);
;             PG8_WAIT_V(8); PG8_WAIT_L(0); PG8_BAR; PG8_MMA(1, 0, At, B0); PG8_MMA(1, 1, At, B1); PG8_BAR; PG8_SCHED;
;     ...
;         cur = nxt; cA = nA; cB = nB; ++ui;
	s_add_i32 s10, s10, s45
	v_lshl_add_u64 v[150:151], v[226:227], 0, s[92:93]
	s_mov_b32 m0, s10
	ds_read_b128 v[192:195], v155 offset:49152
	ds_read_b128 v[196:199], v155 offset:50176
	ds_read_b128 v[200:203], v155 offset:51200
	ds_read_b128 v[204:207], v155 offset:52224
	ds_read_b128 v[208:211], v155 offset:53248
	ds_read_b128 v[212:215], v155 offset:54272
	ds_read_b128 v[216:219], v155 offset:55296
	ds_read_b128 v[240:243], v155 offset:56320
	global_load_lds_dwordx4 v[150:151], off
	v_lshl_add_u64 v[150:151], v[244:245], 0, s[92:93]
	s_add_i32 m0, s10, 0x2000
	s_add_i32 s10, s65, s45
	global_load_lds_dwordx4 v[150:151], off
	v_lshl_add_u64 v[150:151], v[246:247], 0, s[92:93]
	s_mov_b32 m0, s10
	s_nop 0
	global_load_lds_dwordx4 v[150:151], off
	v_lshl_add_u64 v[150:151], v[220:221], 0, s[92:93]
	s_add_i32 m0, s10, 0x2000
	s_nop 0
	global_load_lds_dwordx4 v[150:151], off
	v_lshl_add_u64 v[150:151], v[248:249], 0, s[92:93]
	s_mov_b32 m0, s56
	s_nop 0
	global_load_lds_dwordx4 v[150:151], off
	v_lshl_add_u64 v[150:151], v[250:251], 0, s[92:93]
	s_mov_b32 m0, s57
	s_nop 0
	global_load_lds_dwordx4 v[150:151], off
	s_waitcnt vmcnt(8)
	s_waitcnt lgkmcnt(0)
	s_barrier
	s_setprio 1
	v_mfma_f32_16x16x32_bf16 v[60:63], v[146:149], v[192:195], v[60:63]
	v_mfma_f32_16x16x32_bf16 v[56:59], v[160:163], v[192:195], v[56:59]
	v_mfma_f32_16x16x32_bf16 v[44:47], v[146:149], v[200:203], v[44:47]
	v_mfma_f32_16x16x32_bf16 v[40:43], v[160:163], v[200:203], v[40:43]
	v_mfma_f32_16x16x32_bf16 v[28:31], v[146:149], v[208:211], v[28:31]
	v_mfma_f32_16x16x32_bf16 v[24:27], v[160:163], v[208:211], v[24:27]
	v_mfma_f32_16x16x32_bf16 v[12:15], v[146:149], v[216:219], v[12:15]
	v_mfma_f32_16x16x32_bf16 v[8:11], v[160:163], v[216:219], v[8:11]
	v_mfma_f32_16x16x32_bf16 v[60:63], v[156:159], v[196:199], v[60:63]
	v_mfma_f32_16x16x32_bf16 v[56:59], v[164:167], v[196:199], v[56:59]
	v_mfma_f32_16x16x32_bf16 v[44:47], v[156:159], v[204:207], v[44:47]
	v_mfma_f32_16x16x32_bf16 v[40:43], v[164:167], v[204:207], v[40:43]
	v_mfma_f32_16x16x32_bf16 v[28:31], v[156:159], v[212:215], v[28:31]
	v_mfma_f32_16x16x32_bf16 v[24:27], v[164:167], v[212:215], v[24:27]
	v_mfma_f32_16x16x32_bf16 v[12:15], v[156:159], v[240:243], v[12:15]
	v_mfma_f32_16x16x32_bf16 v[8:11], v[164:167], v[240:243], v[8:11]
	s_setprio 0
	s_setprio 1
	v_mfma_f32_16x16x32_bf16 v[52:55], v[176:179], v[192:195], v[52:55]
	v_mfma_f32_16x16x32_bf16 v[48:51], v[184:187], v[192:195], v[48:51]
	v_mfma_f32_16x16x32_bf16 v[36:39], v[176:179], v[200:203], v[36:39]
	v_mfma_f32_16x16x32_bf16 v[32:35], v[184:187], v[200:203], v[32:35]
	v_mfma_f32_16x16x32_bf16 v[20:23], v[176:179], v[208:211], v[20:23]
	v_mfma_f32_16x16x32_bf16 v[16:19], v[184:187], v[208:211], v[16:19]
	v_mfma_f32_16x16x32_bf16 v[4:7], v[176:179], v[216:219], v[4:7]
	v_mfma_f32_16x16x32_bf16 v[0:3], v[184:187], v[216:219], v[0:3]
	v_mfma_f32_16x16x32_bf16 v[52:55], v[180:183], v[196:199], v[52:55]
	v_mfma_f32_16x16x32_bf16 v[48:51], v[188:191], v[196:199], v[48:51]
	v_mfma_f32_16x16x32_bf16 v[36:39], v[180:183], v[204:207], v[36:39]
	v_mfma_f32_16x16x32_bf16 v[32:35], v[188:191], v[204:207], v[32:35]
	v_mfma_f32_16x16x32_bf16 v[20:23], v[180:183], v[212:215], v[20:23]
	v_mfma_f32_16x16x32_bf16 v[16:19], v[188:191], v[212:215], v[16:19]
	v_mfma_f32_16x16x32_bf16 v[4:7], v[180:183], v[240:243], v[4:7]
	v_mfma_f32_16x16x32_bf16 v[0:3], v[188:191], v[240:243], v[0:3]
	s_setprio 0
	s_barrier
	v_lshl_add_u64 v[142:143], v[142:143], 0, s[80:81]
	v_lshl_add_u64 v[144:145], v[144:145], 0, s[80:81]
	s_cmp_ge_u32 s11, s55
	s_mov_b32 s10, s11
	s_cbranch_scc1 .Lpl4_after
.LBB0_331:
	s_add_i32 s11, s10, 2
	s_cmp_eq_u32 s58, s10
	v_lshl_add_u64 v[146:147], v[142:143], 0, s[92:93]
	s_cselect_b64 vcc, -1, 0
	v_add_u32_e32 v152, s33, v153
	s_add_i32 s10, 0, 0x14000
	v_cndmask_b32_e32 v151, v147, v139, vcc
	v_cndmask_b32_e32 v150, v146, v138, vcc
	ds_read_b128 v[146:149], v152
	ds_read_b128 v[156:159], v152 offset:1024
	ds_read_b128 v[160:163], v152 offset:2048
	ds_read_b128 v[164:167], v152 offset:3072
	v_add_u32_e32 v152, s10, v153
	ds_read_b128 v[176:179], v152
	ds_read_b128 v[180:183], v152 offset:1024
	ds_read_b128 v[184:187], v152 offset:2048
	ds_read_b128 v[188:191], v152 offset:3072
	v_cndmask_b32_e32 v221, v145, v141, vcc
	v_cndmask_b32_e32 v220, v144, v140, vcc
	v_lshl_add_u64 v[226:227], v[142:143], 0, v[134:135]
	s_add_i32 m0, s51, 0xc000
	ds_read_b128 v[192:195], v155
	ds_read_b128 v[196:199], v155 offset:1024
	ds_read_b128 v[200:203], v155 offset:2048
	ds_read_b128 v[204:207], v155 offset:3072
	ds_read_b128 v[208:211], v155 offset:4096
	ds_read_b128 v[212:215], v155 offset:5120
	ds_read_b128 v[216:219], v155 offset:6144
	ds_read_b128 v[240:243], v155 offset:7168
	global_load_lds_dwordx4 v[226:227], off
	v_lshl_add_u64 v[226:227], v[142:143], 0, v[136:137]
	s_add_i32 m0, s51, 0xe000
	s_nop 0
	global_load_lds_dwordx4 v[226:227], off
	s_waitcnt vmcnt(8)
	s_waitcnt lgkmcnt(0)
	s_barrier
; #define PG8_STAGE(bufoff, gbase, voff) do { _Pragma("unroll") for (int _i = 0; _i < 2; ++_i) \
;         __builtin_amdgcn_global_load_lds((const unsigned*)((const char*)(gbase) + (voff)[_i]), (LAS unsigned*)(lds + (bufoff) + ldsw + _i * 8192), 16, 0, 0); } while (0)
; #define PG8_LDA(dst, b, h) do { _Pragma("unroll") for (int m = 0; m < 4; ++m) _Pragma("unroll") for (int k = 0; k < 2; ++k) dst[m][k] = *(const LAS bf16x8*)(lds + PG8_SA(b, h) + aoff + m * 2048 + k * 1024); } while (0)
; #define PG8_LDB(dst, b, h) do { _Pragma("unroll") for (int n = 0; n < 2; ++n) _Pragma("unroll") for (int k = 0; k < 2; ++k) dst[n][k] = *(const LAS bf16x8*)(lds + PG8_SB(b, h) + boff + n * 2048 + k * 1024); } while (0)
; #define PG8_MMA(ai, bj, At, Bt) do { __builtin_amdgcn_s_setprio(1); _Pragma("unroll") for (int k = 0; k < 2; ++k) _Pragma("unroll") for (int m = 0; m < 4; ++m) _Pragma("unroll") for (int n = 0; n < 2; ++n) \
;         acc[ai][bj][m][n] = __builtin_amdgcn_mfma_f32_16x16x32_bf16(Bt[n][k], At[m][k], acc[ai][bj][m][n], 0, 0, 0); __builtin_amdgcn_s_setprio(0); } while (0)
; #define PG8_WAIT_V(n) asm volatile("s_waitcnt vmcnt(" #n ")" ::: "memory")
; #define PG8_WAIT_L(n) asm volatile("s_waitcnt lgkmcnt(" #n ")" ::: "memory")
; #define PG8_BAR __builtin_amdgcn_s_barrier()
; #define PG8_SCHED __builtin_amdgcn_sched_barrier(0)
; template <class Epi, bool ALIGN_EPI>
; __device__ __forceinline__ void gemm_phase(LAS unsigned char* lds, const Gemm g, const StaticOrder& S, const Epi& E, const int tid) {
;     ...
;             PG8_WAIT_V(8); PG8_WAIT_L(0); PG8_BAR; PG8_MMA(0, 0, At, B0); PG8_MMA(0, 1, At, B1); PG8_BAR; PG8_SCHED;
;             PG8_LDA(At, 0, 1); PG8_STAGE(PG8_SB(0, 0), b2, voffB); PG8_STAGE(PG8_SB(0, 1), b2 + hB, voffB); PG8_STAGE(PG8_SA(0, 0), a2, voffA);
;             PG8_WAIT_V(8); PG8_WAIT_L(0); PG8_BAR; PG8_MMA(1, 0, At, B0); PG8_MMA(1, 1, At, B1); PG8_BAR; PG8_SCHED;
;             PG8_LDB(B0, 1, 0); PG8_LDB(B1, 1, 1); PG8_SCHED; PG8_LDA(At, 1, 0); PG8_STAGE(PG8_SA(0, 1), a2 + hA, voffA);
;             PG8_WAIT_V(8); PG8_WAIT_L(0); PG8_BAR; PG8_MMA(0, 0, At, B0); PG8_MMA(0, 1, At, B1); PG8_BAR; PG8_SCHED;
	s_setprio 1
	v_mfma_f32_16x16x32_bf16 v[120:123], v[146:149], v[192:195], v[120:123]
	v_mfma_f32_16x16x32_bf16 v[124:127], v[160:163], v[192:195], v[124:127]
	v_mfma_f32_16x16x32_bf16 v[108:111], v[146:149], v[200:203], v[108:111]
	v_mfma_f32_16x16x32_bf16 v[104:107], v[160:163], v[200:203], v[104:107]
	v_mfma_f32_16x16x32_bf16 v[92:95], v[146:149], v[208:211], v[92:95]
	v_mfma_f32_16x16x32_bf16 v[88:91], v[160:163], v[208:211], v[88:91]
	v_mfma_f32_16x16x32_bf16 v[76:79], v[146:149], v[216:219], v[76:79]
	v_mfma_f32_16x16x32_bf16 v[72:75], v[160:163], v[216:219], v[72:75]
	v_mfma_f32_16x16x32_bf16 v[120:123], v[156:159], v[196:199], v[120:123]
	v_mfma_f32_16x16x32_bf16 v[124:127], v[164:167], v[196:199], v[124:127]
	v_mfma_f32_16x16x32_bf16 v[108:111], v[156:159], v[204:207], v[108:111]
	v_mfma_f32_16x16x32_bf16 v[104:107], v[164:167], v[204:207], v[104:107]
	v_mfma_f32_16x16x32_bf16 v[92:95], v[156:159], v[212:215], v[92:95]
	v_mfma_f32_16x16x32_bf16 v[88:91], v[164:167], v[212:215], v[88:91]
	v_mfma_f32_16x16x32_bf16 v[76:79], v[156:159], v[240:243], v[76:79]
	v_mfma_f32_16x16x32_bf16 v[72:75], v[164:167], v[240:243], v[72:75]
	s_setprio 0
	s_setprio 1
	v_mfma_f32_16x16x32_bf16 v[116:119], v[176:179], v[192:195], v[116:119]
	v_mfma_f32_16x16x32_bf16 v[112:115], v[184:187], v[192:195], v[112:115]
	v_mfma_f32_16x16x32_bf16 v[100:103], v[176:179], v[200:203], v[100:103]
	v_mfma_f32_16x16x32_bf16 v[96:99], v[184:187], v[200:203], v[96:99]
	v_mfma_f32_16x16x32_bf16 v[84:87], v[176:179], v[208:211], v[84:87]
	v_mfma_f32_16x16x32_bf16 v[80:83], v[184:187], v[208:211], v[80:83]
	v_mfma_f32_16x16x32_bf16 v[68:71], v[176:179], v[216:219], v[68:71]
	v_mfma_f32_16x16x32_bf16 v[64:67], v[184:187], v[216:219], v[64:67]
	v_mfma_f32_16x16x32_bf16 v[116:119], v[180:183], v[196:199], v[116:119]
	v_mfma_f32_16x16x32_bf16 v[112:115], v[188:191], v[196:199], v[112:115]
	v_mfma_f32_16x16x32_bf16 v[100:103], v[180:183], v[204:207], v[100:103]
	v_mfma_f32_16x16x32_bf16 v[96:99], v[188:191], v[204:207], v[96:99]
	v_mfma_f32_16x16x32_bf16 v[84:87], v[180:183], v[212:215], v[84:87]
	v_mfma_f32_16x16x32_bf16 v[80:83], v[188:191], v[212:215], v[80:83]
	v_mfma_f32_16x16x32_bf16 v[68:71], v[180:183], v[240:243], v[68:71]
	v_mfma_f32_16x16x32_bf16 v[64:67], v[188:191], v[240:243], v[64:67]
	s_setprio 0
	s_barrier
	s_add_i32 s65, s33, s45
	v_lshl_add_u64 v[226:227], v[220:221], 0, v[168:169]
	s_mov_b32 m0, s65
	ds_read_b128 v[192:195], v155 offset:16384
	ds_read_b128 v[196:199], v155 offset:17408
	ds_read_b128 v[200:203], v155 offset:18432
	ds_read_b128 v[204:207], v155 offset:19456
	ds_read_b128 v[208:211], v155 offset:20480
	ds_read_b128 v[212:215], v155 offset:21504
	ds_read_b128 v[216:219], v155 offset:22528
	ds_read_b128 v[240:243], v155 offset:23552
	global_load_lds_dwordx4 v[226:227], off
	v_lshl_add_u64 v[244:245], v[220:221], 0, v[128:129]
	s_add_i32 m0, s65, 0x2000
	v_lshl_add_u64 v[220:221], v[220:221], 0, s[12:13]
	s_add_i32 s10, s10, s45
	global_load_lds_dwordx4 v[244:245], off
	v_lshl_add_u64 v[246:247], v[220:221], 0, v[168:169]
	s_mov_b32 m0, s10
	v_lshl_add_u64 v[220:221], v[220:221], 0, v[128:129]
	global_load_lds_dwordx4 v[246:247], off
	s_add_i32 m0, s10, 0x2000
	v_lshl_add_u64 v[248:249], v[150:151], 0, v[132:133]
	global_load_lds_dwordx4 v[220:221], off
	s_mov_b32 m0, s51
	v_lshl_add_u64 v[250:251], v[150:151], 0, v[130:131]
	global_load_lds_dwordx4 v[248:249], off
	s_mov_b32 m0, s52
	s_nop 0
	global_load_lds_dwordx4 v[250:251], off
	s_waitcnt vmcnt(8)
	s_waitcnt lgkmcnt(0)
	s_barrier
	s_setprio 1
	v_mfma_f32_16x16x32_bf16 v[60:63], v[146:149], v[192:195], v[60:63]
	v_mfma_f32_16x16x32_bf16 v[56:59], v[160:163], v[192:195], v[56:59]
	v_mfma_f32_16x16x32_bf16 v[44:47], v[146:149], v[200:203], v[44:47]
	v_mfma_f32_16x16x32_bf16 v[40:43], v[160:163], v[200:203], v[40:43]
	v_mfma_f32_16x16x32_bf16 v[28:31], v[146:149], v[208:211], v[28:31]
	v_mfma_f32_16x16x32_bf16 v[24:27], v[160:163], v[208:211], v[24:27]
	v_mfma_f32_16x16x32_bf16 v[12:15], v[146:149], v[216:219], v[12:15]
	v_mfma_f32_16x16x32_bf16 v[8:11], v[160:163], v[216:219], v[8:11]
	v_mfma_f32_16x16x32_bf16 v[60:63], v[156:159], v[196:199], v[60:63]
	v_mfma_f32_16x16x32_bf16 v[56:59], v[164:167], v[196:199], v[56:59]
	v_mfma_f32_16x16x32_bf16 v[44:47], v[156:159], v[204:207], v[44:47]
	v_mfma_f32_16x16x32_bf16 v[40:43], v[164:167], v[204:207], v[40:43]
	v_mfma_f32_16x16x32_bf16 v[28:31], v[156:159], v[212:215], v[28:31]
	v_mfma_f32_16x16x32_bf16 v[24:27], v[164:167], v[212:215], v[24:27]
	v_mfma_f32_16x16x32_bf16 v[12:15], v[156:159], v[240:243], v[12:15]
	v_mfma_f32_16x16x32_bf16 v[8:11], v[164:167], v[240:243], v[8:11]
	s_setprio 0
	s_setprio 1
	v_mfma_f32_16x16x32_bf16 v[52:55], v[176:179], v[192:195], v[52:55]
	v_mfma_f32_16x16x32_bf16 v[48:51], v[184:187], v[192:195], v[48:51]
	v_mfma_f32_16x16x32_bf16 v[36:39], v[176:179], v[200:203], v[36:39]
	v_mfma_f32_16x16x32_bf16 v[32:35], v[184:187], v[200:203], v[32:35]
	v_mfma_f32_16x16x32_bf16 v[20:23], v[176:179], v[208:211], v[20:23]
	v_mfma_f32_16x16x32_bf16 v[16:19], v[184:187], v[208:211], v[16:19]
	v_mfma_f32_16x16x32_bf16 v[4:7], v[176:179], v[216:219], v[4:7]
	v_mfma_f32_16x16x32_bf16 v[0:3], v[184:187], v[216:219], v[0:3]
	v_mfma_f32_16x16x32_bf16 v[52:55], v[180:183], v[196:199], v[52:55]
	v_mfma_f32_16x16x32_bf16 v[48:51], v[188:191], v[196:199], v[48:51]
	v_mfma_f32_16x16x32_bf16 v[36:39], v[180:183], v[204:207], v[36:39]
	v_mfma_f32_16x16x32_bf16 v[32:35], v[188:191], v[204:207], v[32:35]
	v_mfma_f32_16x16x32_bf16 v[20:23], v[180:183], v[212:215], v[20:23]
	v_mfma_f32_16x16x32_bf16 v[16:19], v[188:191], v[212:215], v[16:19]
	v_mfma_f32_16x16x32_bf16 v[4:7], v[180:183], v[240:243], v[4:7]
	v_mfma_f32_16x16x32_bf16 v[0:3], v[188:191], v[240:243], v[0:3]
	s_setprio 0
	s_barrier
; #define PG8_STAGE(bufoff, gbase, voff) do { _Pragma("unroll") for (int _i = 0; _i < 2; ++_i) \
;         __builtin_amdgcn_global_load_lds((const unsigned*)((const char*)(gbase) + (voff)[_i]), (LAS unsigned*)(lds + (bufoff) + ldsw + _i * 8192), 16, 0, 0); } while (0)
; #define PG8_LDA(dst, b, h) do { _Pragma("unroll") for (int m = 0; m < 4; ++m) _Pragma("unroll") for (int k = 0; k < 2; ++k) dst[m][k] = *(const LAS bf16x8*)(lds + PG8_SA(b, h) + aoff + m * 2048 + k * 1024); } while (0)
; #define PG8_LDB(dst, b, h) do { _Pragma("unroll") for (int n = 0; n < 2; ++n) _Pragma("unroll") for (int k = 0; k < 2; ++k) dst[n][k] = *(const LAS bf16x8*)(lds + PG8_SB(b, h) + boff + n * 2048 + k * 1024); } while (0)
; #define PG8_MMA(ai, bj, At, Bt) do { __builtin_amdgcn_s_setprio(1); _Pragma("unroll") for (int k = 0; k < 2; ++k) _Pragma("unroll") for (int m = 0; m < 4; ++m) _Pragma("unroll") for (int n = 0; n < 2; ++n) \
;         acc[ai][bj][m][n] = __builtin_amdgcn_mfma_f32_16x16x32_bf16(Bt[n][k], At[m][k], acc[ai][bj][m][n], 0, 0, 0); __builtin_amdgcn_s_setprio(0); } while (0)
; #define PG8_WAIT_V(n) asm volatile("s_waitcnt vmcnt(" #n ")" ::: "memory")
; #define PG8_WAIT_L(n) asm volatile("s_waitcnt lgkmcnt(" #n ")" ::: "memory")
; #define PG8_BAR __builtin_amdgcn_s_barrier()
; #define PG8_SCHED __builtin_amdgcn_sched_barrier(0)
; template <class Epi, bool ALIGN_EPI>
; __device__ __forceinline__ void gemm_phase(LAS unsigned char* lds, const Gemm g, const StaticOrder& S, const Epi& E, const int tid) {
;     ...
;             PG8_LDB(B0, 1, 0); PG8_LDB(B1, 1, 1); PG8_SCHED; PG8_LDA(At, 1, 0); PG8_STAGE(PG8_SA(0, 1), a2 + hA, voffA);
;             PG8_WAIT_V(8); PG8_WAIT_L(0); PG8_BAR; PG8_MMA(0, 0, At, B0); PG8_MMA(0, 1, At, B1); PG8_BAR; PG8_SCHED;
	s_add_i32 s10, 0, 0x18000
	v_add_u32_e32 v152, s10, v153
	s_add_i32 s65, 0, 0x1c000
	ds_read_b128 v[146:149], v152
	ds_read_b128 v[156:159], v152 offset:1024
	ds_read_b128 v[160:163], v152 offset:2048
	ds_read_b128 v[164:167], v152 offset:3072
	v_add_u32_e32 v152, s65, v153
	ds_read_b128 v[176:179], v152
	ds_read_b128 v[180:183], v152 offset:1024
	ds_read_b128 v[184:187], v152 offset:2048
	ds_read_b128 v[188:191], v152 offset:3072
	v_lshl_add_u64 v[150:151], v[150:151], 0, s[94:95]
	s_mov_b32 m0, s53
	v_lshl_add_u64 v[252:253], v[150:151], 0, v[132:133]
	ds_read_b128 v[192:195], v155 offset:32768
	ds_read_b128 v[196:199], v155 offset:33792
	ds_read_b128 v[200:203], v155 offset:34816
	ds_read_b128 v[204:207], v155 offset:35840
	ds_read_b128 v[208:211], v155 offset:36864
	ds_read_b128 v[212:215], v155 offset:37888
	ds_read_b128 v[216:219], v155 offset:38912
	ds_read_b128 v[240:243], v155 offset:39936
	global_load_lds_dwordx4 v[252:253], off
	v_lshl_add_u64 v[150:151], v[150:151], 0, v[130:131]
	s_mov_b32 m0, s54
	s_nop 0
	global_load_lds_dwordx4 v[150:151], off
	s_waitcnt vmcnt(8)
	s_waitcnt lgkmcnt(0)
	s_barrier
	s_setprio 1
	v_mfma_f32_16x16x32_bf16 v[120:123], v[146:149], v[192:195], v[120:123]
	v_mfma_f32_16x16x32_bf16 v[124:127], v[160:163], v[192:195], v[124:127]
	v_mfma_f32_16x16x32_bf16 v[108:111], v[146:149], v[200:203], v[108:111]
	v_mfma_f32_16x16x32_bf16 v[104:107], v[160:163], v[200:203], v[104:107]
	v_mfma_f32_16x16x32_bf16 v[92:95], v[146:149], v[208:211], v[92:95]
	v_mfma_f32_16x16x32_bf16 v[88:91], v[160:163], v[208:211], v[88:91]
	v_mfma_f32_16x16x32_bf16 v[76:79], v[146:149], v[216:219], v[76:79]
	v_mfma_f32_16x16x32_bf16 v[72:75], v[160:163], v[216:219], v[72:75]
	v_mfma_f32_16x16x32_bf16 v[120:123], v[156:159], v[196:199], v[120:123]
	v_mfma_f32_16x16x32_bf16 v[124:127], v[164:167], v[196:199], v[124:127]
	v_mfma_f32_16x16x32_bf16 v[108:111], v[156:159], v[204:207], v[108:111]
	v_mfma_f32_16x16x32_bf16 v[104:107], v[164:167], v[204:207], v[104:107]
	v_mfma_f32_16x16x32_bf16 v[92:95], v[156:159], v[212:215], v[92:95]
	v_mfma_f32_16x16x32_bf16 v[88:91], v[164:167], v[212:215], v[88:91]
	v_mfma_f32_16x16x32_bf16 v[76:79], v[156:159], v[240:243], v[76:79]
	v_mfma_f32_16x16x32_bf16 v[72:75], v[164:167], v[240:243], v[72:75]
	s_setprio 0
	s_setprio 1
	v_mfma_f32_16x16x32_bf16 v[116:119], v[176:179], v[192:195], v[116:119]
	v_mfma_f32_16x16x32_bf16 v[112:115], v[184:187], v[192:195], v[112:115]
	v_mfma_f32_16x16x32_bf16 v[100:103], v[176:179], v[200:203], v[100:103]
	v_mfma_f32_16x16x32_bf16 v[96:99], v[184:187], v[200:203], v[96:99]
	v_mfma_f32_16x16x32_bf16 v[84:87], v[176:179], v[208:211], v[84:87]
	v_mfma_f32_16x16x32_bf16 v[80:83], v[184:187], v[208:211], v[80:83]
	v_mfma_f32_16x16x32_bf16 v[68:71], v[176:179], v[216:219], v[68:71]
	v_mfma_f32_16x16x32_bf16 v[64:67], v[184:187], v[216:219], v[64:67]
	v_mfma_f32_16x16x32_bf16 v[116:119], v[180:183], v[196:199], v[116:119]
	v_mfma_f32_16x16x32_bf16 v[112:115], v[188:191], v[196:199], v[112:115]
	v_mfma_f32_16x16x32_bf16 v[100:103], v[180:183], v[204:207], v[100:103]
	v_mfma_f32_16x16x32_bf16 v[96:99], v[188:191], v[204:207], v[96:99]
	v_mfma_f32_16x16x32_bf16 v[84:87], v[180:183], v[212:215], v[84:87]
	v_mfma_f32_16x16x32_bf16 v[80:83], v[188:191], v[212:215], v[80:83]
	v_mfma_f32_16x16x32_bf16 v[68:71], v[180:183], v[240:243], v[68:71]
	v_mfma_f32_16x16x32_bf16 v[64:67], v[188:191], v[240:243], v[64:67]
	s_setprio 0
	s_barrier
; #define PG8_STAGE(bufoff, gbase, voff) do { _Pragma("unroll") for (int _i = 0; _i < 2; ++_i) \
;         __builtin_amdgcn_global_load_lds((const unsigned*)((const char*)(gbase) + (voff)[_i]), (LAS unsigned*)(lds + (bufoff) + ldsw + _i * 8192), 16, 0, 0); } while (0)
; #define PG8_LDA(dst, b, h) do { _Pragma("unroll") for (int m = 0; m < 4; ++m) _Pragma("unroll") for (int k = 0; k < 2; ++k) dst[m][k] = *(const LAS bf16x8*)(lds + PG8_SA(b, h) + aoff + m * 2048 + k * 1024); } while (0)
; #define PG8_MMA(ai, bj, At, Bt) do { __builtin_amdgcn_s_setprio(1); _Pragma("unroll") for (int k = 0; k < 2; ++k) _Pragma("unroll") for (int m = 0; m < 4; ++m) _Pragma("unroll") for (int n = 0; n < 2; ++n) \
;         acc[ai][bj][m][n] = __builtin_amdgcn_mfma_f32_16x16x32_bf16(Bt[n][k], At[m][k], acc[ai][bj][m][n], 0, 0, 0); __builtin_amdgcn_s_setprio(0); } while (0)
; #define PG8_WAIT_V(n) asm volatile("s_waitcnt vmcnt(" #n ")" ::: "memory")
; #define PG8_WAIT_L(n) asm volatile("s_waitcnt lgkmcnt(" #n ")" ::: "memory")
; #define PG8_BAR __builtin_amdgcn_s_barrier()
; #define PG8_SCHED __builtin_amdgcn_sched_barrier(0)
; template <class Epi, bool ALIGN_EPI>
; __device__ __forceinline__ void gemm_phase(LAS unsigned char* lds, const Gemm g, const StaticOrder& S, const Epi& E, const int tid) {
;     ...
;             PG8_LDA(At, 1, 1); PG8_STAGE(PG8_SB(1, 0), b3, voffB); PG8_STAGE(PG8_SB(1, 1), b3 + hB, voffB); PG8_STAGE(PG8_SA(1, 0), a3, voffA);
;             PG8_WAIT_V(8); PG8_WAIT_L(0); PG8_BAR; PG8_MMA(1, 0, At, B0); PG8_MMA(1, 1, At, B1); PG8_BAR; PG8_SCHED;
;     ...
;         cur = nxt; cA = nA; cB = nB; ++ui;
	s_add_i32 s10, s10, s45
	v_lshl_add_u64 v[150:151], v[226:227], 0, s[92:93]
	s_mov_b32 m0, s10
	ds_read_b128 v[192:195], v155 offset:49152
	ds_read_b128 v[196:199], v155 offset:50176
	ds_read_b128 v[200:203], v155 offset:51200
	ds_read_b128 v[204:207], v155 offset:52224
	ds_read_b128 v[208:211], v155 offset:53248
	ds_read_b128 v[212:215], v155 offset:54272
	ds_read_b128 v[216:219], v155 offset:55296
	ds_read_b128 v[240:243], v155 offset:56320
	global_load_lds_dwordx4 v[150:151], off
	v_lshl_add_u64 v[150:151], v[244:245], 0, s[92:93]
	s_add_i32 m0, s10, 0x2000
	s_add_i32 s10, s65, s45
	global_load_lds_dwordx4 v[150:151], off
	v_lshl_add_u64 v[150:151], v[246:247], 0, s[92:93]
	s_mov_b32 m0, s10
	s_nop 0
	global_load_lds_dwordx4 v[150:151], off
	v_lshl_add_u64 v[150:151], v[220:221], 0, s[92:93]
	s_add_i32 m0, s10, 0x2000
	s_nop 0
	global_load_lds_dwordx4 v[150:151], off
	v_lshl_add_u64 v[150:151], v[248:249], 0, s[92:93]
	s_mov_b32 m0, s56
	s_nop 0
	global_load_lds_dwordx4 v[150:151], off
	v_lshl_add_u64 v[150:151], v[250:251], 0, s[92:93]
	s_mov_b32 m0, s57
	s_nop 0
	global_load_lds_dwordx4 v[150:151], off
	s_waitcnt vmcnt(8)
	s_waitcnt lgkmcnt(0)
	s_barrier
	s_setprio 1
	v_mfma_f32_16x16x32_bf16 v[60:63], v[146:149], v[192:195], v[60:63]
	v_mfma_f32_16x16x32_bf16 v[56:59], v[160:163], v[192:195], v[56:59]
	v_mfma_f32_16x16x32_bf16 v[44:47], v[146:149], v[200:203], v[44:47]
	v_mfma_f32_16x16x32_bf16 v[40:43], v[160:163], v[200:203], v[40:43]
	v_mfma_f32_16x16x32_bf16 v[28:31], v[146:149], v[208:211], v[28:31]
	v_mfma_f32_16x16x32_bf16 v[24:27], v[160:163], v[208:211], v[24:27]
	v_mfma_f32_16x16x32_bf16 v[12:15], v[146:149], v[216:219], v[12:15]
	v_mfma_f32_16x16x32_bf16 v[8:11], v[160:163], v[216:219], v[8:11]
	v_mfma_f32_16x16x32_bf16 v[60:63], v[156:159], v[196:199], v[60:63]
	v_mfma_f32_16x16x32_bf16 v[56:59], v[164:167], v[196:199], v[56:59]
	v_mfma_f32_16x16x32_bf16 v[44:47], v[156:159], v[204:207], v[44:47]
	v_mfma_f32_16x16x32_bf16 v[40:43], v[164:167], v[204:207], v[40:43]
	v_mfma_f32_16x16x32_bf16 v[28:31], v[156:159], v[212:215], v[28:31]
	v_mfma_f32_16x16x32_bf16 v[24:27], v[164:167], v[212:215], v[24:27]
	v_mfma_f32_16x16x32_bf16 v[12:15], v[156:159], v[240:243], v[12:15]
	v_mfma_f32_16x16x32_bf16 v[8:11], v[164:167], v[240:243], v[8:11]
	s_setprio 0
	s_setprio 1
	v_mfma_f32_16x16x32_bf16 v[52:55], v[176:179], v[192:195], v[52:55]
	v_mfma_f32_16x16x32_bf16 v[48:51], v[184:187], v[192:195], v[48:51]
	v_mfma_f32_16x16x32_bf16 v[36:39], v[176:179], v[200:203], v[36:39]
	v_mfma_f32_16x16x32_bf16 v[32:35], v[184:187], v[200:203], v[32:35]
	v_mfma_f32_16x16x32_bf16 v[20:23], v[176:179], v[208:211], v[20:23]
	v_mfma_f32_16x16x32_bf16 v[16:19], v[184:187], v[208:211], v[16:19]
	v_mfma_f32_16x16x32_bf16 v[4:7], v[176:179], v[216:219], v[4:7]
	v_mfma_f32_16x16x32_bf16 v[0:3], v[184:187], v[216:219], v[0:3]
	v_mfma_f32_16x16x32_bf16 v[52:55], v[180:183], v[196:199], v[52:55]
	v_mfma_f32_16x16x32_bf16 v[48:51], v[188:191], v[196:199], v[48:51]
	v_mfma_f32_16x16x32_bf16 v[36:39], v[180:183], v[204:207], v[36:39]
	v_mfma_f32_16x16x32_bf16 v[32:35], v[188:191], v[204:207], v[32:35]
	v_mfma_f32_16x16x32_bf16 v[20:23], v[180:183], v[212:215], v[20:23]
	v_mfma_f32_16x16x32_bf16 v[16:19], v[188:191], v[212:215], v[16:19]
	v_mfma_f32_16x16x32_bf16 v[4:7], v[180:183], v[240:243], v[4:7]
	v_mfma_f32_16x16x32_bf16 v[0:3], v[188:191], v[240:243], v[0:3]
	s_setprio 0
	s_barrier
	v_lshl_add_u64 v[142:143], v[142:143], 0, s[80:81]
	v_lshl_add_u64 v[144:145], v[144:145], 0, s[80:81]
	s_cmp_ge_u32 s11, s55
	s_mov_b32 s10, s11
	s_cbranch_scc0 .LBB0_331

; __device__ __forceinline__ unsigned cvt_pk_bf16(float lo, float hi) { unsigned r; asm volatile("v_cvt_pk_bf16_f32 %0, %1, %2" : "=v"(r) : "v"(lo), "v"(hi)); return r; }
; __device__ __forceinline__ float gelu_tanh(float x) { const float u = 0.7978845608028654f * (x + 0.044715f * x * x * x); return x * fast_rcp(1.0f + fast_exp2(-2.0f * LOG2E * u)); }
; #define PG8_STAGE(bufoff, gbase, voff) do { _Pragma("unroll") for (int _i = 0; _i < 2; ++_i) \
;         __builtin_amdgcn_global_load_lds((const unsigned*)((const char*)(gbase) + (voff)[_i]), (LAS unsigned*)(lds + (bufoff) + ldsw + _i * 8192), 16, 0, 0); } while (0)
; #define PG8_LDA(dst, b, h) do { _Pragma("unroll") for (int m = 0; m < 4; ++m) _Pragma("unroll") for (int k = 0; k < 2; ++k) dst[m][k] = *(const LAS bf16x8*)(lds + PG8_SA(b, h) + aoff + m * 2048 + k * 1024); } while (0)
; #define PG8_BAR __builtin_amdgcn_s_barrier()
;     __device__ __forceinline__ void operator()(const f32x4 (&acc)[2][2][4][2], const Unit& u, int wr, int wc, int fr, int fq) const {
;     ...
;             for (int m = 0; m < 4; ++m) { const int row = row0 + ai * HALF + m * 16; bf16_t* rowp = O + (size_t)row * ldc + col0; const float rs = rsv[ai][m];
; #pragma unroll
;                 for (int bj = 0; bj < 2; ++bj) { f32x4 v0 = acc[ai][bj][m][0] * rs, v1 = acc[ai][bj][m][1] * rs;
;                     if (ACT == 1) {
; #pragma unroll
;                         for (int j = 0; j < 4; ++j) { v0[j] = gelu_tanh(v0[j]); v1[j] = gelu_tanh(v1[j]); } }
;                     u32x4 w; w.x = cvt_pk_bf16(v0[0], v0[1]); w.y = cvt_pk_bf16(v0[2], v0[3]); w.z = cvt_pk_bf16(v1[0], v1[1]); w.w = cvt_pk_bf16(v1[2], v1[3]);
;                     *(u32x4*)(rowp + bj * HALF) = w; } }
; template <class Epi, bool ALIGN_EPI>
; __device__ __forceinline__ void gemm_phase(LAS unsigned char* lds, const Gemm g, const StaticOrder& S, const Epi& E, const int tid) {
;     ...
;             PG8_LDB(B0, 0, 0); PG8_LDB(B1, 0, 1); PG8_SCHED; PG8_LDA(At, 0, 0); PG8_STAGE(PG8_SA(1, 1), a1 + hA, voffA);
;             PG8_WAIT_V(8); PG8_WAIT_L(0); PG8_BAR; PG8_MMA(0, 0, At, B0); PG8_MMA(0, 1, At, B1); PG8_BAR; PG8_SCHED;
;             PG8_LDA(At, 0, 1); PG8_STAGE(PG8_SB(0, 0), b2, voffB); PG8_STAGE(PG8_SB(0, 1), b2 + hB, voffB); PG8_STAGE(PG8_SA(0, 0), a2, voffA);
;             PG8_WAIT_V(8); PG8_WAIT_L(0); PG8_BAR; PG8_MMA(1, 0, At, B0); PG8_MMA(1, 1, At, B1); PG8_BAR; PG8_SCHED;
.Lq5_first_epi:
	s_add_i32 s11, s10, 2
	s_cmp_eq_u32 s55, s10
	s_cselect_b64 vcc, -1, 0
	v_add_u32_e32 v148, s33, v149
	s_add_i32 s10, 0, 0x14000
	ds_read_b128 v[152:155], v148
	ds_read_b128 v[156:159], v148 offset:1024
	ds_read_b128 v[160:163], v148 offset:2048
	ds_read_b128 v[164:167], v148 offset:3072
	v_add_u32_e32 v148, s10, v149
	ds_read_b128 v[176:179], v148
	ds_read_b128 v[180:183], v148 offset:1024
	ds_read_b128 v[184:187], v148 offset:2048
	ds_read_b128 v[188:191], v148 offset:3072
	v_lshl_add_u64 v[146:147], v[142:143], 0, s[92:93]
	v_cndmask_b32_e32 v147, v147, v139, vcc
	v_cndmask_b32_e32 v146, v146, v138, vcc
	v_cndmask_b32_e32 v221, v145, v141, vcc
	v_cndmask_b32_e32 v220, v144, v140, vcc
	v_lshl_add_u64 v[244:245], v[142:143], 0, v[134:135]
	s_add_i32 m0, s25, 0xc000
	ds_read_b128 v[192:195], v151
	ds_read_b128 v[196:199], v151 offset:1024
	ds_read_b128 v[200:203], v151 offset:2048
	ds_read_b128 v[204:207], v151 offset:3072
	ds_read_b128 v[208:211], v151 offset:4096
	ds_read_b128 v[212:215], v151 offset:5120
	ds_read_b128 v[216:219], v151 offset:6144
	ds_read_b128 v[240:243], v151 offset:7168
	global_load_lds_dwordx4 v[244:245], off
	v_lshl_add_u64 v[244:245], v[142:143], 0, v[136:137]
	s_add_i32 m0, s25, 0xe000
	s_nop 0
	global_load_lds_dwordx4 v[244:245], off
	s_waitcnt vmcnt(16)
	s_waitcnt lgkmcnt(0)
	s_barrier
	s_setprio 1
	v_mfma_f32_16x16x32_bf16 v[124:127], v[152:155], v[192:195], 0
	s_lshl_b32 s98, s28, 5
	s_mov_b32 s99, 0
	v_mul_f32_e32 v60, v238, v60
	v_mul_f32_e32 v61, v238, v61
	v_mfma_f32_16x16x32_bf16 v[120:123], v[160:163], v[192:195], 0
	v_mul_f32_e32 v62, v238, v62
	v_mul_f32_e32 v63, v238, v63
	v_mul_f32_e32 v56, v238, v56
	v_mul_f32_e32 v57, v238, v57
	v_mfma_f32_16x16x32_bf16 v[108:111], v[152:155], v[200:203], 0
	v_mul_f32_e32 v58, v238, v58
	v_mul_f32_e32 v59, v238, v59
	v_cvt_pk_bf16_f32 v60, v60, v61
	v_cvt_pk_bf16_f32 v61, v62, v63
	v_mfma_f32_16x16x32_bf16 v[104:107], v[160:163], v[200:203], 0
	v_cvt_pk_bf16_f32 v62, v56, v57
	v_cvt_pk_bf16_f32 v63, v58, v59
	global_store_dwordx4 v[232:233], v[60:63], off
	v_mul_f32_e32 v52, v238, v52
	v_mfma_f32_16x16x32_bf16 v[92:95], v[152:155], v[208:211], 0
	v_mul_f32_e32 v53, v238, v53
	v_mul_f32_e32 v54, v238, v54
	v_mul_f32_e32 v55, v238, v55
	v_mul_f32_e32 v48, v238, v48
	v_mfma_f32_16x16x32_bf16 v[88:91], v[160:163], v[208:211], 0
	v_mul_f32_e32 v49, v238, v49
	v_mul_f32_e32 v50, v238, v50
	v_mul_f32_e32 v51, v238, v51
	v_cvt_pk_bf16_f32 v52, v52, v53
	v_mfma_f32_16x16x32_bf16 v[76:79], v[152:155], v[216:219], 0
	v_cvt_pk_bf16_f32 v53, v54, v55
	v_cvt_pk_bf16_f32 v54, v48, v49
	v_cvt_pk_bf16_f32 v55, v50, v51
	global_store_dwordx4 v[232:233], v[52:55], off offset:256
	v_mfma_f32_16x16x32_bf16 v[72:75], v[160:163], v[216:219], 0
	v_lshl_add_u64 v[232:233], v[232:233], 0, s[98:99]
	v_mul_f32_e32 v44, v239, v44
	v_mul_f32_e32 v45, v239, v45
	v_mul_f32_e32 v46, v239, v46
	v_mfma_f32_16x16x32_bf16 v[124:127], v[156:159], v[196:199], v[124:127]
	v_mul_f32_e32 v47, v239, v47
	v_mul_f32_e32 v40, v239, v40
	v_mul_f32_e32 v41, v239, v41
	v_mul_f32_e32 v42, v239, v42
	v_mfma_f32_16x16x32_bf16 v[120:123], v[164:167], v[196:199], v[120:123]
	v_mul_f32_e32 v43, v239, v43
	v_cvt_pk_bf16_f32 v44, v44, v45
	v_cvt_pk_bf16_f32 v45, v46, v47
	v_cvt_pk_bf16_f32 v46, v40, v41
	v_mfma_f32_16x16x32_bf16 v[108:111], v[156:159], v[204:207], v[108:111]
	v_cvt_pk_bf16_f32 v47, v42, v43
	global_store_dwordx4 v[232:233], v[44:47], off
	v_mul_f32_e32 v36, v239, v36
	v_mul_f32_e32 v37, v239, v37
	v_mfma_f32_16x16x32_bf16 v[104:107], v[164:167], v[204:207], v[104:107]
	v_mul_f32_e32 v38, v239, v38
	v_mul_f32_e32 v39, v239, v39
	v_mul_f32_e32 v32, v239, v32
	v_mul_f32_e32 v33, v239, v33
	v_mfma_f32_16x16x32_bf16 v[92:95], v[156:159], v[212:215], v[92:95]
	v_mul_f32_e32 v34, v239, v34
	v_mul_f32_e32 v35, v239, v35
	v_cvt_pk_bf16_f32 v36, v36, v37
	v_cvt_pk_bf16_f32 v37, v38, v39
	v_mfma_f32_16x16x32_bf16 v[88:91], v[164:167], v[212:215], v[88:91]
	v_cvt_pk_bf16_f32 v38, v32, v33
	v_cvt_pk_bf16_f32 v39, v34, v35
	global_store_dwordx4 v[232:233], v[36:39], off offset:256
	v_lshl_add_u64 v[232:233], v[232:233], 0, s[98:99]
	v_mfma_f32_16x16x32_bf16 v[76:79], v[156:159], v[240:243], v[76:79]
	v_mul_f32_e32 v28, v230, v28
	v_mul_f32_e32 v29, v230, v29
	v_mul_f32_e32 v30, v230, v30
	v_mul_f32_e32 v31, v230, v31
	v_mfma_f32_16x16x32_bf16 v[72:75], v[164:167], v[240:243], v[72:75]
	v_mul_f32_e32 v24, v230, v24
	v_mul_f32_e32 v25, v230, v25
	v_mul_f32_e32 v26, v230, v26
	v_mul_f32_e32 v27, v230, v27
	s_setprio 0
	s_setprio 1
	v_mfma_f32_16x16x32_bf16 v[116:119], v[176:179], v[192:195], 0
	v_cvt_pk_bf16_f32 v28, v28, v29
	v_cvt_pk_bf16_f32 v29, v30, v31
	v_cvt_pk_bf16_f32 v30, v24, v25
	v_cvt_pk_bf16_f32 v31, v26, v27
	v_mfma_f32_16x16x32_bf16 v[112:115], v[184:187], v[192:195], 0
	global_store_dwordx4 v[232:233], v[28:31], off
	v_mul_f32_e32 v20, v230, v20
	v_mul_f32_e32 v21, v230, v21
	v_mul_f32_e32 v22, v230, v22
	v_mfma_f32_16x16x32_bf16 v[100:103], v[176:179], v[200:203], 0
	v_mul_f32_e32 v23, v230, v23
	v_mul_f32_e32 v16, v230, v16
	v_mul_f32_e32 v17, v230, v17
	v_mul_f32_e32 v18, v230, v18
	v_mfma_f32_16x16x32_bf16 v[96:99], v[184:187], v[200:203], 0
	v_mul_f32_e32 v19, v230, v19
	v_cvt_pk_bf16_f32 v20, v20, v21
	v_cvt_pk_bf16_f32 v21, v22, v23
	v_cvt_pk_bf16_f32 v22, v16, v17
	v_mfma_f32_16x16x32_bf16 v[84:87], v[176:179], v[208:211], 0
	v_cvt_pk_bf16_f32 v23, v18, v19
	global_store_dwordx4 v[232:233], v[20:23], off offset:256
	v_lshl_add_u64 v[232:233], v[232:233], 0, s[98:99]
	v_mul_f32_e32 v12, v231, v12
	v_mfma_f32_16x16x32_bf16 v[80:83], v[184:187], v[208:211], 0
	v_mul_f32_e32 v13, v231, v13
; __device__ __forceinline__ unsigned cvt_pk_bf16(float lo, float hi) { unsigned r; asm volatile("v_cvt_pk_bf16_f32 %0, %1, %2" : "=v"(r) : "v"(lo), "v"(hi)); return r; }
; __device__ __forceinline__ float gelu_tanh(float x) { const float u = 0.7978845608028654f * (x + 0.044715f * x * x * x); return x * fast_rcp(1.0f + fast_exp2(-2.0f * LOG2E * u)); }
; #define PG8_STAGE(bufoff, gbase, voff) do { _Pragma("unroll") for (int _i = 0; _i < 2; ++_i) \
;         __builtin_amdgcn_global_load_lds((const unsigned*)((const char*)(gbase) + (voff)[_i]), (LAS unsigned*)(lds + (bufoff) + ldsw + _i * 8192), 16, 0, 0); } while (0)
; #define PG8_LDA(dst, b, h) do { _Pragma("unroll") for (int m = 0; m < 4; ++m) _Pragma("unroll") for (int k = 0; k < 2; ++k) dst[m][k] = *(const LAS bf16x8*)(lds + PG8_SA(b, h) + aoff + m * 2048 + k * 1024); } while (0)
; #define PG8_BAR __builtin_amdgcn_s_barrier()
;     __device__ __forceinline__ void operator()(const f32x4 (&acc)[2][2][4][2], const Unit& u, int wr, int wc, int fr, int fq) const {
;     ...
;             for (int m = 0; m < 4; ++m) { const int row = row0 + ai * HALF + m * 16; bf16_t* rowp = O + (size_t)row * ldc + col0; const float rs = rsv[ai][m];
; #pragma unroll
;                 for (int bj = 0; bj < 2; ++bj) { f32x4 v0 = acc[ai][bj][m][0] * rs, v1 = acc[ai][bj][m][1] * rs;
;                     if (ACT == 1) {
; #pragma unroll
;                         for (int j = 0; j < 4; ++j) { v0[j] = gelu_tanh(v0[j]); v1[j] = gelu_tanh(v1[j]); } }
;                     u32x4 w; w.x = cvt_pk_bf16(v0[0], v0[1]); w.y = cvt_pk_bf16(v0[2], v0[3]); w.z = cvt_pk_bf16(v1[0], v1[1]); w.w = cvt_pk_bf16(v1[2], v1[3]);
;                     *(u32x4*)(rowp + bj * HALF) = w; } }
; template <class Epi, bool ALIGN_EPI>
; __device__ __forceinline__ void gemm_phase(LAS unsigned char* lds, const Gemm g, const StaticOrder& S, const Epi& E, const int tid) {
;     ...
;             PG8_LDA(At, 0, 1); PG8_STAGE(PG8_SB(0, 0), b2, voffB); PG8_STAGE(PG8_SB(0, 1), b2 + hB, voffB); PG8_STAGE(PG8_SA(0, 0), a2, voffA);
;             PG8_WAIT_V(8); PG8_WAIT_L(0); PG8_BAR; PG8_MMA(1, 0, At, B0); PG8_MMA(1, 1, At, B1); PG8_BAR; PG8_SCHED;
;             PG8_LDB(B0, 1, 0); PG8_LDB(B1, 1, 1); PG8_SCHED; PG8_LDA(At, 1, 0); PG8_STAGE(PG8_SA(0, 1), a2 + hA, voffA);
;             PG8_WAIT_V(8); PG8_WAIT_L(0); PG8_BAR; PG8_MMA(0, 0, At, B0); PG8_MMA(0, 1, At, B1); PG8_BAR; PG8_SCHED;
	v_mul_f32_e32 v14, v231, v14
	v_mul_f32_e32 v15, v231, v15
	v_mul_f32_e32 v8, v231, v8
	v_mfma_f32_16x16x32_bf16 v[68:71], v[176:179], v[216:219], 0
	v_mul_f32_e32 v9, v231, v9
	v_mul_f32_e32 v10, v231, v10
	v_mul_f32_e32 v11, v231, v11
	v_cvt_pk_bf16_f32 v12, v12, v13
	v_mfma_f32_16x16x32_bf16 v[64:67], v[184:187], v[216:219], 0
	v_cvt_pk_bf16_f32 v13, v14, v15
	v_cvt_pk_bf16_f32 v14, v8, v9
	v_cvt_pk_bf16_f32 v15, v10, v11
	global_store_dwordx4 v[232:233], v[12:15], off
	v_mfma_f32_16x16x32_bf16 v[116:119], v[180:183], v[196:199], v[116:119]
	v_mul_f32_e32 v4, v231, v4
	v_mul_f32_e32 v5, v231, v5
	v_mul_f32_e32 v6, v231, v6
	v_mul_f32_e32 v7, v231, v7
	v_mfma_f32_16x16x32_bf16 v[112:115], v[188:191], v[196:199], v[112:115]
	v_mul_f32_e32 v0, v231, v0
	v_mul_f32_e32 v1, v231, v1
	v_mul_f32_e32 v2, v231, v2
	v_mul_f32_e32 v3, v231, v3
	v_mfma_f32_16x16x32_bf16 v[100:103], v[180:183], v[204:207], v[100:103]
	v_cvt_pk_bf16_f32 v4, v4, v5
	v_cvt_pk_bf16_f32 v5, v6, v7
	v_cvt_pk_bf16_f32 v6, v0, v1
	v_cvt_pk_bf16_f32 v7, v2, v3
	v_mfma_f32_16x16x32_bf16 v[96:99], v[188:191], v[204:207], v[96:99]
	global_store_dwordx4 v[232:233], v[4:7], off offset:256
	v_mfma_f32_16x16x32_bf16 v[84:87], v[180:183], v[212:215], v[84:87]
	v_mfma_f32_16x16x32_bf16 v[80:83], v[188:191], v[212:215], v[80:83]
	v_mfma_f32_16x16x32_bf16 v[68:71], v[180:183], v[240:243], v[68:71]
	v_mfma_f32_16x16x32_bf16 v[64:67], v[188:191], v[240:243], v[64:67]
	s_setprio 0
	s_barrier
	s_add_i32 s62, s33, s45
	v_lshl_add_u64 v[244:245], v[220:221], 0, v[168:169]
	s_mov_b32 m0, s62
	ds_read_b128 v[192:195], v151 offset:16384
	ds_read_b128 v[196:199], v151 offset:17408
	ds_read_b128 v[200:203], v151 offset:18432
	ds_read_b128 v[204:207], v151 offset:19456
	ds_read_b128 v[208:211], v151 offset:20480
	ds_read_b128 v[212:215], v151 offset:21504
	ds_read_b128 v[216:219], v151 offset:22528
	ds_read_b128 v[240:243], v151 offset:23552
	global_load_lds_dwordx4 v[244:245], off
	v_lshl_add_u64 v[246:247], v[220:221], 0, v[128:129]
	s_add_i32 m0, s62, 0x2000
	v_lshl_add_u64 v[220:221], v[220:221], 0, s[12:13]
	s_add_i32 s10, s10, s45
	global_load_lds_dwordx4 v[246:247], off
	v_lshl_add_u64 v[248:249], v[220:221], 0, v[168:169]
	s_mov_b32 m0, s10
	v_lshl_add_u64 v[220:221], v[220:221], 0, v[128:129]
	global_load_lds_dwordx4 v[248:249], off
	s_add_i32 m0, s10, 0x2000
	v_lshl_add_u64 v[250:251], v[146:147], 0, v[132:133]
	global_load_lds_dwordx4 v[220:221], off
	s_mov_b32 m0, s25
	v_lshl_add_u64 v[252:253], v[146:147], 0, v[130:131]
	global_load_lds_dwordx4 v[250:251], off
	s_mov_b32 m0, s50
	s_nop 0
	global_load_lds_dwordx4 v[252:253], off
	s_waitcnt vmcnt(24)
	s_waitcnt lgkmcnt(0)
	s_barrier
	s_setprio 1
	v_mfma_f32_16x16x32_bf16 v[60:63], v[152:155], v[192:195], 0
	v_mfma_f32_16x16x32_bf16 v[56:59], v[160:163], v[192:195], 0
	v_mfma_f32_16x16x32_bf16 v[44:47], v[152:155], v[200:203], 0
	v_mfma_f32_16x16x32_bf16 v[40:43], v[160:163], v[200:203], 0
	v_mfma_f32_16x16x32_bf16 v[28:31], v[152:155], v[208:211], 0
	v_mfma_f32_16x16x32_bf16 v[24:27], v[160:163], v[208:211], 0
	v_mfma_f32_16x16x32_bf16 v[12:15], v[152:155], v[216:219], 0
	v_mfma_f32_16x16x32_bf16 v[8:11], v[160:163], v[216:219], 0
	v_mfma_f32_16x16x32_bf16 v[60:63], v[156:159], v[196:199], v[60:63]
	v_mfma_f32_16x16x32_bf16 v[56:59], v[164:167], v[196:199], v[56:59]
	v_mfma_f32_16x16x32_bf16 v[44:47], v[156:159], v[204:207], v[44:47]
	v_mfma_f32_16x16x32_bf16 v[40:43], v[164:167], v[204:207], v[40:43]
	v_mfma_f32_16x16x32_bf16 v[28:31], v[156:159], v[212:215], v[28:31]
	v_mfma_f32_16x16x32_bf16 v[24:27], v[164:167], v[212:215], v[24:27]
	v_mfma_f32_16x16x32_bf16 v[12:15], v[156:159], v[240:243], v[12:15]
	v_mfma_f32_16x16x32_bf16 v[8:11], v[164:167], v[240:243], v[8:11]
	s_setprio 0
	s_setprio 1
	v_mfma_f32_16x16x32_bf16 v[52:55], v[176:179], v[192:195], 0
	v_mfma_f32_16x16x32_bf16 v[48:51], v[184:187], v[192:195], 0
	v_mfma_f32_16x16x32_bf16 v[36:39], v[176:179], v[200:203], 0
	v_mfma_f32_16x16x32_bf16 v[32:35], v[184:187], v[200:203], 0
	v_mfma_f32_16x16x32_bf16 v[20:23], v[176:179], v[208:211], 0
	v_mfma_f32_16x16x32_bf16 v[16:19], v[184:187], v[208:211], 0
	v_mfma_f32_16x16x32_bf16 v[4:7], v[176:179], v[216:219], 0
	v_mfma_f32_16x16x32_bf16 v[0:3], v[184:187], v[216:219], 0
	v_mfma_f32_16x16x32_bf16 v[52:55], v[180:183], v[196:199], v[52:55]
	v_mfma_f32_16x16x32_bf16 v[48:51], v[188:191], v[196:199], v[48:51]
	v_mfma_f32_16x16x32_bf16 v[36:39], v[180:183], v[204:207], v[36:39]
	v_mfma_f32_16x16x32_bf16 v[32:35], v[188:191], v[204:207], v[32:35]
	v_mfma_f32_16x16x32_bf16 v[20:23], v[180:183], v[212:215], v[20:23]
	v_mfma_f32_16x16x32_bf16 v[16:19], v[188:191], v[212:215], v[16:19]
	v_mfma_f32_16x16x32_bf16 v[4:7], v[180:183], v[240:243], v[4:7]
	v_mfma_f32_16x16x32_bf16 v[0:3], v[188:191], v[240:243], v[0:3]
	s_setprio 0
	s_barrier
	s_add_i32 s10, 0, 0x18000
	v_add_u32_e32 v148, s10, v149
	s_add_i32 s62, 0, 0x1c000
	ds_read_b128 v[152:155], v148
	ds_read_b128 v[156:159], v148 offset:1024
	ds_read_b128 v[160:163], v148 offset:2048
	ds_read_b128 v[164:167], v148 offset:3072
	v_add_u32_e32 v148, s62, v149
	ds_read_b128 v[176:179], v148
	ds_read_b128 v[180:183], v148 offset:1024
	ds_read_b128 v[184:187], v148 offset:2048
	ds_read_b128 v[188:191], v148 offset:3072
	v_lshl_add_u64 v[146:147], v[146:147], 0, s[94:95]
	s_mov_b32 m0, s51
	v_lshl_add_u64 v[226:227], v[146:147], 0, v[132:133]
	ds_read_b128 v[192:195], v151 offset:32768
	ds_read_b128 v[196:199], v151 offset:33792
	ds_read_b128 v[200:203], v151 offset:34816
	ds_read_b128 v[204:207], v151 offset:35840
	ds_read_b128 v[208:211], v151 offset:36864
	ds_read_b128 v[212:215], v151 offset:37888
	ds_read_b128 v[216:219], v151 offset:38912
	ds_read_b128 v[240:243], v151 offset:39936
	global_load_lds_dwordx4 v[226:227], off
	v_lshl_add_u64 v[146:147], v[146:147], 0, v[130:131]
	s_mov_b32 m0, s52
	s_nop 0
	global_load_lds_dwordx4 v[146:147], off
	s_waitcnt vmcnt(16)
	s_waitcnt lgkmcnt(0)
	s_barrier
; #define PG8_STAGE(bufoff, gbase, voff) do { _Pragma("unroll") for (int _i = 0; _i < 2; ++_i) \
;         __builtin_amdgcn_global_load_lds((const unsigned*)((const char*)(gbase) + (voff)[_i]), (LAS unsigned*)(lds + (bufoff) + ldsw + _i * 8192), 16, 0, 0); } while (0)
; #define PG8_LDA(dst, b, h) do { _Pragma("unroll") for (int m = 0; m < 4; ++m) _Pragma("unroll") for (int k = 0; k < 2; ++k) dst[m][k] = *(const LAS bf16x8*)(lds + PG8_SA(b, h) + aoff + m * 2048 + k * 1024); } while (0)
; #define PG8_LDB(dst, b, h) do { _Pragma("unroll") for (int n = 0; n < 2; ++n) _Pragma("unroll") for (int k = 0; k < 2; ++k) dst[n][k] = *(const LAS bf16x8*)(lds + PG8_SB(b, h) + boff + n * 2048 + k * 1024); } while (0)
; #define PG8_MMA(ai, bj, At, Bt) do { __builtin_amdgcn_s_setprio(1); _Pragma("unroll") for (int k = 0; k < 2; ++k) _Pragma("unroll") for (int m = 0; m < 4; ++m) _Pragma("unroll") for (int n = 0; n < 2; ++n) \
;         acc[ai][bj][m][n] = __builtin_amdgcn_mfma_f32_16x16x32_bf16(Bt[n][k], At[m][k], acc[ai][bj][m][n], 0, 0, 0); __builtin_amdgcn_s_setprio(0); } while (0)
; #define PG8_WAIT_V(n) asm volatile("s_waitcnt vmcnt(" #n ")" ::: "memory")
; #define PG8_WAIT_L(n) asm volatile("s_waitcnt lgkmcnt(" #n ")" ::: "memory")
; #define PG8_BAR __builtin_amdgcn_s_barrier()
; #define PG8_SCHED __builtin_amdgcn_sched_barrier(0)
; template <class Epi, bool ALIGN_EPI>
; __device__ __forceinline__ void gemm_phase(LAS unsigned char* lds, const Gemm g, const StaticOrder& S, const Epi& E, const int tid) {
;     ...
;             PG8_LDB(B0, 1, 0); PG8_LDB(B1, 1, 1); PG8_SCHED; PG8_LDA(At, 1, 0); PG8_STAGE(PG8_SA(0, 1), a2 + hA, voffA);
;             PG8_WAIT_V(8); PG8_WAIT_L(0); PG8_BAR; PG8_MMA(0, 0, At, B0); PG8_MMA(0, 1, At, B1); PG8_BAR; PG8_SCHED;
;             PG8_LDA(At, 1, 1); PG8_STAGE(PG8_SB(1, 0), b3, voffB); PG8_STAGE(PG8_SB(1, 1), b3 + hB, voffB); PG8_STAGE(PG8_SA(1, 0), a3, voffA);
;             PG8_WAIT_V(8); PG8_WAIT_L(0); PG8_BAR; PG8_MMA(1, 0, At, B0); PG8_MMA(1, 1, At, B1); PG8_BAR; PG8_SCHED;
;     ...
;         cur = nxt; cA = nA; cB = nB; ++ui;
	s_setprio 1
	v_mfma_f32_16x16x32_bf16 v[124:127], v[152:155], v[192:195], v[124:127]
	v_mfma_f32_16x16x32_bf16 v[120:123], v[160:163], v[192:195], v[120:123]
	v_mfma_f32_16x16x32_bf16 v[108:111], v[152:155], v[200:203], v[108:111]
	v_mfma_f32_16x16x32_bf16 v[104:107], v[160:163], v[200:203], v[104:107]
	v_mfma_f32_16x16x32_bf16 v[92:95], v[152:155], v[208:211], v[92:95]
	v_mfma_f32_16x16x32_bf16 v[88:91], v[160:163], v[208:211], v[88:91]
	v_mfma_f32_16x16x32_bf16 v[76:79], v[152:155], v[216:219], v[76:79]
	v_mfma_f32_16x16x32_bf16 v[72:75], v[160:163], v[216:219], v[72:75]
	v_mfma_f32_16x16x32_bf16 v[124:127], v[156:159], v[196:199], v[124:127]
	v_mfma_f32_16x16x32_bf16 v[120:123], v[164:167], v[196:199], v[120:123]
	v_mfma_f32_16x16x32_bf16 v[108:111], v[156:159], v[204:207], v[108:111]
	v_mfma_f32_16x16x32_bf16 v[104:107], v[164:167], v[204:207], v[104:107]
	v_mfma_f32_16x16x32_bf16 v[92:95], v[156:159], v[212:215], v[92:95]
	v_mfma_f32_16x16x32_bf16 v[88:91], v[164:167], v[212:215], v[88:91]
	v_mfma_f32_16x16x32_bf16 v[76:79], v[156:159], v[240:243], v[76:79]
	v_mfma_f32_16x16x32_bf16 v[72:75], v[164:167], v[240:243], v[72:75]
	s_setprio 0
	s_setprio 1
	v_mfma_f32_16x16x32_bf16 v[116:119], v[176:179], v[192:195], v[116:119]
	v_mfma_f32_16x16x32_bf16 v[112:115], v[184:187], v[192:195], v[112:115]
	v_mfma_f32_16x16x32_bf16 v[100:103], v[176:179], v[200:203], v[100:103]
	v_mfma_f32_16x16x32_bf16 v[96:99], v[184:187], v[200:203], v[96:99]
	v_mfma_f32_16x16x32_bf16 v[84:87], v[176:179], v[208:211], v[84:87]
	v_mfma_f32_16x16x32_bf16 v[80:83], v[184:187], v[208:211], v[80:83]
	v_mfma_f32_16x16x32_bf16 v[68:71], v[176:179], v[216:219], v[68:71]
	v_mfma_f32_16x16x32_bf16 v[64:67], v[184:187], v[216:219], v[64:67]
	v_mfma_f32_16x16x32_bf16 v[116:119], v[180:183], v[196:199], v[116:119]
	v_mfma_f32_16x16x32_bf16 v[112:115], v[188:191], v[196:199], v[112:115]
	v_mfma_f32_16x16x32_bf16 v[100:103], v[180:183], v[204:207], v[100:103]
	v_mfma_f32_16x16x32_bf16 v[96:99], v[188:191], v[204:207], v[96:99]
	v_mfma_f32_16x16x32_bf16 v[84:87], v[180:183], v[212:215], v[84:87]
	v_mfma_f32_16x16x32_bf16 v[80:83], v[188:191], v[212:215], v[80:83]
	v_mfma_f32_16x16x32_bf16 v[68:71], v[180:183], v[240:243], v[68:71]
	v_mfma_f32_16x16x32_bf16 v[64:67], v[188:191], v[240:243], v[64:67]
	s_setprio 0
	s_barrier
	s_add_i32 s10, s10, s45
	v_lshl_add_u64 v[146:147], v[244:245], 0, s[92:93]
	s_mov_b32 m0, s10
	ds_read_b128 v[192:195], v151 offset:49152
	ds_read_b128 v[196:199], v151 offset:50176
	ds_read_b128 v[200:203], v151 offset:51200
	ds_read_b128 v[204:207], v151 offset:52224
	ds_read_b128 v[208:211], v151 offset:53248
	ds_read_b128 v[212:215], v151 offset:54272
	ds_read_b128 v[216:219], v151 offset:55296
	ds_read_b128 v[240:243], v151 offset:56320
	global_load_lds_dwordx4 v[146:147], off
	v_lshl_add_u64 v[146:147], v[246:247], 0, s[92:93]
	s_add_i32 m0, s10, 0x2000
	s_add_i32 s10, s62, s45
	global_load_lds_dwordx4 v[146:147], off
	v_lshl_add_u64 v[146:147], v[248:249], 0, s[92:93]
	s_mov_b32 m0, s10
	s_nop 0
	global_load_lds_dwordx4 v[146:147], off
	v_lshl_add_u64 v[146:147], v[220:221], 0, s[92:93]
	s_add_i32 m0, s10, 0x2000
	s_nop 0
	global_load_lds_dwordx4 v[146:147], off
	v_lshl_add_u64 v[146:147], v[250:251], 0, s[92:93]
	s_mov_b32 m0, s53
	s_nop 0
	global_load_lds_dwordx4 v[146:147], off
	v_lshl_add_u64 v[146:147], v[252:253], 0, s[92:93]
	s_mov_b32 m0, s54
	s_nop 0
	global_load_lds_dwordx4 v[146:147], off
	s_waitcnt vmcnt(8)
	s_waitcnt lgkmcnt(0)
	s_barrier
	s_setprio 1
	v_mfma_f32_16x16x32_bf16 v[60:63], v[152:155], v[192:195], v[60:63]
	v_mfma_f32_16x16x32_bf16 v[56:59], v[160:163], v[192:195], v[56:59]
	v_mfma_f32_16x16x32_bf16 v[44:47], v[152:155], v[200:203], v[44:47]
	v_mfma_f32_16x16x32_bf16 v[40:43], v[160:163], v[200:203], v[40:43]
	v_mfma_f32_16x16x32_bf16 v[28:31], v[152:155], v[208:211], v[28:31]
	v_mfma_f32_16x16x32_bf16 v[24:27], v[160:163], v[208:211], v[24:27]
	v_mfma_f32_16x16x32_bf16 v[12:15], v[152:155], v[216:219], v[12:15]
	v_mfma_f32_16x16x32_bf16 v[8:11], v[160:163], v[216:219], v[8:11]
	v_mfma_f32_16x16x32_bf16 v[60:63], v[156:159], v[196:199], v[60:63]
	v_mfma_f32_16x16x32_bf16 v[56:59], v[164:167], v[196:199], v[56:59]
	v_mfma_f32_16x16x32_bf16 v[44:47], v[156:159], v[204:207], v[44:47]
	v_mfma_f32_16x16x32_bf16 v[40:43], v[164:167], v[204:207], v[40:43]
	v_mfma_f32_16x16x32_bf16 v[28:31], v[156:159], v[212:215], v[28:31]
	v_mfma_f32_16x16x32_bf16 v[24:27], v[164:167], v[212:215], v[24:27]
	v_mfma_f32_16x16x32_bf16 v[12:15], v[156:159], v[240:243], v[12:15]
	v_mfma_f32_16x16x32_bf16 v[8:11], v[164:167], v[240:243], v[8:11]
	s_setprio 0
	s_setprio 1
	v_mfma_f32_16x16x32_bf16 v[52:55], v[176:179], v[192:195], v[52:55]
	v_mfma_f32_16x16x32_bf16 v[48:51], v[184:187], v[192:195], v[48:51]
	v_mfma_f32_16x16x32_bf16 v[36:39], v[176:179], v[200:203], v[36:39]
	v_mfma_f32_16x16x32_bf16 v[32:35], v[184:187], v[200:203], v[32:35]
	v_mfma_f32_16x16x32_bf16 v[20:23], v[176:179], v[208:211], v[20:23]
	v_mfma_f32_16x16x32_bf16 v[16:19], v[184:187], v[208:211], v[16:19]
	v_mfma_f32_16x16x32_bf16 v[4:7], v[176:179], v[216:219], v[4:7]
	v_mfma_f32_16x16x32_bf16 v[0:3], v[184:187], v[216:219], v[0:3]
	v_mfma_f32_16x16x32_bf16 v[52:55], v[180:183], v[196:199], v[52:55]
	v_mfma_f32_16x16x32_bf16 v[48:51], v[188:191], v[196:199], v[48:51]
	v_mfma_f32_16x16x32_bf16 v[36:39], v[180:183], v[204:207], v[36:39]
	v_mfma_f32_16x16x32_bf16 v[32:35], v[188:191], v[204:207], v[32:35]
	v_mfma_f32_16x16x32_bf16 v[20:23], v[180:183], v[212:215], v[20:23]
	v_mfma_f32_16x16x32_bf16 v[16:19], v[188:191], v[212:215], v[16:19]
	v_mfma_f32_16x16x32_bf16 v[4:7], v[180:183], v[240:243], v[4:7]
	v_mfma_f32_16x16x32_bf16 v[0:3], v[188:191], v[240:243], v[0:3]
	s_setprio 0
	s_barrier
	v_lshl_add_u64 v[142:143], v[142:143], 0, s[80:81]
	v_lshl_add_u64 v[144:145], v[144:145], 0, s[80:81]
	s_mov_b32 s10, s11
	s_cmp_eq_u32 s10, s55
	s_cbranch_scc1 .Lq5_last
	s_branch .LBB0_354
; #define PG8_STAGE(bufoff, gbase, voff) do { _Pragma("unroll") for (int _i = 0; _i < 2; ++_i) \
;         __builtin_amdgcn_global_load_lds((const unsigned*)((const char*)(gbase) + (voff)[_i]), (LAS unsigned*)(lds + (bufoff) + ldsw + _i * 8192), 16, 0, 0); } while (0)
; #define PG8_LDA(dst, b, h) do { _Pragma("unroll") for (int m = 0; m < 4; ++m) _Pragma("unroll") for (int k = 0; k < 2; ++k) dst[m][k] = *(const LAS bf16x8*)(lds + PG8_SA(b, h) + aoff + m * 2048 + k * 1024); } while (0)
; #define PG8_LDB(dst, b, h) do { _Pragma("unroll") for (int n = 0; n < 2; ++n) _Pragma("unroll") for (int k = 0; k < 2; ++k) dst[n][k] = *(const LAS bf16x8*)(lds + PG8_SB(b, h) + boff + n * 2048 + k * 1024); } while (0)
; #define PG8_MMA(ai, bj, At, Bt) do { __builtin_amdgcn_s_setprio(1); _Pragma("unroll") for (int k = 0; k < 2; ++k) _Pragma("unroll") for (int m = 0; m < 4; ++m) _Pragma("unroll") for (int n = 0; n < 2; ++n) \
;         acc[ai][bj][m][n] = __builtin_amdgcn_mfma_f32_16x16x32_bf16(Bt[n][k], At[m][k], acc[ai][bj][m][n], 0, 0, 0); __builtin_amdgcn_s_setprio(0); } while (0)
; #define PG8_WAIT_V(n) asm volatile("s_waitcnt vmcnt(" #n ")" ::: "memory")
; #define PG8_WAIT_L(n) asm volatile("s_waitcnt lgkmcnt(" #n ")" ::: "memory")
; #define PG8_BAR __builtin_amdgcn_s_barrier()
; #define PG8_SCHED __builtin_amdgcn_sched_barrier(0)
; template <class Epi, bool ALIGN_EPI>
; __device__ __forceinline__ void gemm_phase(LAS unsigned char* lds, const Gemm g, const StaticOrder& S, const Epi& E, const int tid) {
;     ...
;             PG8_LDB(B0, 0, 0); PG8_LDB(B1, 0, 1); PG8_SCHED; PG8_LDA(At, 0, 0); PG8_STAGE(PG8_SA(1, 1), a1 + hA, voffA);
;             PG8_WAIT_V(8); PG8_WAIT_L(0); PG8_BAR; PG8_MMA(0, 0, At, B0); PG8_MMA(0, 1, At, B1); PG8_BAR; PG8_SCHED;
;             PG8_LDA(At, 0, 1); PG8_STAGE(PG8_SB(0, 0), b2, voffB); PG8_STAGE(PG8_SB(0, 1), b2 + hB, voffB); PG8_STAGE(PG8_SA(0, 0), a2, voffA);
;             PG8_WAIT_V(8); PG8_WAIT_L(0); PG8_BAR; PG8_MMA(1, 0, At, B0); PG8_MMA(1, 1, At, B1); PG8_BAR; PG8_SCHED;
.Lq5_first:
	s_add_i32 s11, s10, 2
	s_cmp_eq_u32 s55, s10
	s_cselect_b64 vcc, -1, 0
	v_add_u32_e32 v148, s33, v149
	s_add_i32 s10, 0, 0x14000
	ds_read_b128 v[152:155], v148
	ds_read_b128 v[156:159], v148 offset:1024
	ds_read_b128 v[160:163], v148 offset:2048
	ds_read_b128 v[164:167], v148 offset:3072
	v_add_u32_e32 v148, s10, v149
	ds_read_b128 v[176:179], v148
	ds_read_b128 v[180:183], v148 offset:1024
	ds_read_b128 v[184:187], v148 offset:2048
	ds_read_b128 v[188:191], v148 offset:3072
	v_lshl_add_u64 v[146:147], v[142:143], 0, s[92:93]
	v_cndmask_b32_e32 v147, v147, v139, vcc
	v_cndmask_b32_e32 v146, v146, v138, vcc
	v_cndmask_b32_e32 v221, v145, v141, vcc
	v_cndmask_b32_e32 v220, v144, v140, vcc
	v_lshl_add_u64 v[244:245], v[142:143], 0, v[134:135]
	s_add_i32 m0, s25, 0xc000
	ds_read_b128 v[192:195], v151
	ds_read_b128 v[196:199], v151 offset:1024
	ds_read_b128 v[200:203], v151 offset:2048
	ds_read_b128 v[204:207], v151 offset:3072
	ds_read_b128 v[208:211], v151 offset:4096
	ds_read_b128 v[212:215], v151 offset:5120
	ds_read_b128 v[216:219], v151 offset:6144
	ds_read_b128 v[240:243], v151 offset:7168
	global_load_lds_dwordx4 v[244:245], off
	v_lshl_add_u64 v[244:245], v[142:143], 0, v[136:137]
	s_add_i32 m0, s25, 0xe000
	s_nop 0
	global_load_lds_dwordx4 v[244:245], off
	s_waitcnt vmcnt(8)
	s_waitcnt lgkmcnt(0)
	s_barrier
	s_setprio 1
	v_mfma_f32_16x16x32_bf16 v[124:127], v[152:155], v[192:195], 0
	v_mfma_f32_16x16x32_bf16 v[120:123], v[160:163], v[192:195], 0
	v_mfma_f32_16x16x32_bf16 v[108:111], v[152:155], v[200:203], 0
	v_mfma_f32_16x16x32_bf16 v[104:107], v[160:163], v[200:203], 0
	v_mfma_f32_16x16x32_bf16 v[92:95], v[152:155], v[208:211], 0
	v_mfma_f32_16x16x32_bf16 v[88:91], v[160:163], v[208:211], 0
	v_mfma_f32_16x16x32_bf16 v[76:79], v[152:155], v[216:219], 0
	v_mfma_f32_16x16x32_bf16 v[72:75], v[160:163], v[216:219], 0
	v_mfma_f32_16x16x32_bf16 v[124:127], v[156:159], v[196:199], v[124:127]
	v_mfma_f32_16x16x32_bf16 v[120:123], v[164:167], v[196:199], v[120:123]
	v_mfma_f32_16x16x32_bf16 v[108:111], v[156:159], v[204:207], v[108:111]
	v_mfma_f32_16x16x32_bf16 v[104:107], v[164:167], v[204:207], v[104:107]
	v_mfma_f32_16x16x32_bf16 v[92:95], v[156:159], v[212:215], v[92:95]
	v_mfma_f32_16x16x32_bf16 v[88:91], v[164:167], v[212:215], v[88:91]
	v_mfma_f32_16x16x32_bf16 v[76:79], v[156:159], v[240:243], v[76:79]
	v_mfma_f32_16x16x32_bf16 v[72:75], v[164:167], v[240:243], v[72:75]
	s_setprio 0
	s_setprio 1
	v_mfma_f32_16x16x32_bf16 v[116:119], v[176:179], v[192:195], 0
	v_mfma_f32_16x16x32_bf16 v[112:115], v[184:187], v[192:195], 0
	v_mfma_f32_16x16x32_bf16 v[100:103], v[176:179], v[200:203], 0
	v_mfma_f32_16x16x32_bf16 v[96:99], v[184:187], v[200:203], 0
	v_mfma_f32_16x16x32_bf16 v[84:87], v[176:179], v[208:211], 0
	v_mfma_f32_16x16x32_bf16 v[80:83], v[184:187], v[208:211], 0
	v_mfma_f32_16x16x32_bf16 v[68:71], v[176:179], v[216:219], 0
	v_mfma_f32_16x16x32_bf16 v[64:67], v[184:187], v[216:219], 0
	v_mfma_f32_16x16x32_bf16 v[116:119], v[180:183], v[196:199], v[116:119]
	v_mfma_f32_16x16x32_bf16 v[112:115], v[188:191], v[196:199], v[112:115]
	v_mfma_f32_16x16x32_bf16 v[100:103], v[180:183], v[204:207], v[100:103]
	v_mfma_f32_16x16x32_bf16 v[96:99], v[188:191], v[204:207], v[96:99]
	v_mfma_f32_16x16x32_bf16 v[84:87], v[180:183], v[212:215], v[84:87]
	v_mfma_f32_16x16x32_bf16 v[80:83], v[188:191], v[212:215], v[80:83]
	v_mfma_f32_16x16x32_bf16 v[68:71], v[180:183], v[240:243], v[68:71]
	v_mfma_f32_16x16x32_bf16 v[64:67], v[188:191], v[240:243], v[64:67]
	s_setprio 0
	s_barrier
	s_add_i32 s62, s33, s45
	v_lshl_add_u64 v[244:245], v[220:221], 0, v[168:169]
	s_mov_b32 m0, s62
	ds_read_b128 v[192:195], v151 offset:16384
	ds_read_b128 v[196:199], v151 offset:17408
	ds_read_b128 v[200:203], v151 offset:18432
	ds_read_b128 v[204:207], v151 offset:19456
	ds_read_b128 v[208:211], v151 offset:20480
	ds_read_b128 v[212:215], v151 offset:21504
	ds_read_b128 v[216:219], v151 offset:22528
	ds_read_b128 v[240:243], v151 offset:23552
	global_load_lds_dwordx4 v[244:245], off
	v_lshl_add_u64 v[246:247], v[220:221], 0, v[128:129]
	s_add_i32 m0, s62, 0x2000
	v_lshl_add_u64 v[220:221], v[220:221], 0, s[12:13]
	s_add_i32 s10, s10, s45
	global_load_lds_dwordx4 v[246:247], off
	v_lshl_add_u64 v[248:249], v[220:221], 0, v[168:169]
	s_mov_b32 m0, s10
	v_lshl_add_u64 v[220:221], v[220:221], 0, v[128:129]
	global_load_lds_dwordx4 v[248:249], off
	s_add_i32 m0, s10, 0x2000
	v_lshl_add_u64 v[250:251], v[146:147], 0, v[132:133]
	global_load_lds_dwordx4 v[220:221], off
	s_mov_b32 m0, s25
	v_lshl_add_u64 v[252:253], v[146:147], 0, v[130:131]
	global_load_lds_dwordx4 v[250:251], off
	s_mov_b32 m0, s50
	s_nop 0
	global_load_lds_dwordx4 v[252:253], off
	s_waitcnt vmcnt(8)
	s_waitcnt lgkmcnt(0)
	s_barrier
; #define PG8_STAGE(bufoff, gbase, voff) do { _Pragma("unroll") for (int _i = 0; _i < 2; ++_i) \
;         __builtin_amdgcn_global_load_lds((const unsigned*)((const char*)(gbase) + (voff)[_i]), (LAS unsigned*)(lds + (bufoff) + ldsw + _i * 8192), 16, 0, 0); } while (0)
; #define PG8_LDA(dst, b, h) do { _Pragma("unroll") for (int m = 0; m < 4; ++m) _Pragma("unroll") for (int k = 0; k < 2; ++k) dst[m][k] = *(const LAS bf16x8*)(lds + PG8_SA(b, h) + aoff + m * 2048 + k * 1024); } while (0)
; #define PG8_LDB(dst, b, h) do { _Pragma("unroll") for (int n = 0; n < 2; ++n) _Pragma("unroll") for (int k = 0; k < 2; ++k) dst[n][k] = *(const LAS bf16x8*)(lds + PG8_SB(b, h) + boff + n * 2048 + k * 1024); } while (0)
; #define PG8_MMA(ai, bj, At, Bt) do { __builtin_amdgcn_s_setprio(1); _Pragma("unroll") for (int k = 0; k < 2; ++k) _Pragma("unroll") for (int m = 0; m < 4; ++m) _Pragma("unroll") for (int n = 0; n < 2; ++n) \
;         acc[ai][bj][m][n] = __builtin_amdgcn_mfma_f32_16x16x32_bf16(Bt[n][k], At[m][k], acc[ai][bj][m][n], 0, 0, 0); __builtin_amdgcn_s_setprio(0); } while (0)
; #define PG8_WAIT_V(n) asm volatile("s_waitcnt vmcnt(" #n ")" ::: "memory")
; #define PG8_WAIT_L(n) asm volatile("s_waitcnt lgkmcnt(" #n ")" ::: "memory")
; #define PG8_BAR __builtin_amdgcn_s_barrier()
; #define PG8_SCHED __builtin_amdgcn_sched_barrier(0)
; template <class Epi, bool ALIGN_EPI>
; __device__ __forceinline__ void gemm_phase(LAS unsigned char* lds, const Gemm g, const StaticOrder& S, const Epi& E, const int tid) {
;     ...
;             PG8_WAIT_V(8); PG8_WAIT_L(0); PG8_BAR; PG8_MMA(1, 0, At, B0); PG8_MMA(1, 1, At, B1); PG8_BAR; PG8_SCHED;
;             PG8_LDB(B0, 1, 0); PG8_LDB(B1, 1, 1); PG8_SCHED; PG8_LDA(At, 1, 0); PG8_STAGE(PG8_SA(0, 1), a2 + hA, voffA);
;             PG8_WAIT_V(8); PG8_WAIT_L(0); PG8_BAR; PG8_MMA(0, 0, At, B0); PG8_MMA(0, 1, At, B1); PG8_BAR; PG8_SCHED;
	s_setprio 1
	v_mfma_f32_16x16x32_bf16 v[60:63], v[152:155], v[192:195], 0
	v_mfma_f32_16x16x32_bf16 v[56:59], v[160:163], v[192:195], 0
	v_mfma_f32_16x16x32_bf16 v[44:47], v[152:155], v[200:203], 0
	v_mfma_f32_16x16x32_bf16 v[40:43], v[160:163], v[200:203], 0
	v_mfma_f32_16x16x32_bf16 v[28:31], v[152:155], v[208:211], 0
	v_mfma_f32_16x16x32_bf16 v[24:27], v[160:163], v[208:211], 0
	v_mfma_f32_16x16x32_bf16 v[12:15], v[152:155], v[216:219], 0
	v_mfma_f32_16x16x32_bf16 v[8:11], v[160:163], v[216:219], 0
	v_mfma_f32_16x16x32_bf16 v[60:63], v[156:159], v[196:199], v[60:63]
	v_mfma_f32_16x16x32_bf16 v[56:59], v[164:167], v[196:199], v[56:59]
	v_mfma_f32_16x16x32_bf16 v[44:47], v[156:159], v[204:207], v[44:47]
	v_mfma_f32_16x16x32_bf16 v[40:43], v[164:167], v[204:207], v[40:43]
	v_mfma_f32_16x16x32_bf16 v[28:31], v[156:159], v[212:215], v[28:31]
	v_mfma_f32_16x16x32_bf16 v[24:27], v[164:167], v[212:215], v[24:27]
	v_mfma_f32_16x16x32_bf16 v[12:15], v[156:159], v[240:243], v[12:15]
	v_mfma_f32_16x16x32_bf16 v[8:11], v[164:167], v[240:243], v[8:11]
	s_setprio 0
	s_setprio 1
	v_mfma_f32_16x16x32_bf16 v[52:55], v[176:179], v[192:195], 0
	v_mfma_f32_16x16x32_bf16 v[48:51], v[184:187], v[192:195], 0
	v_mfma_f32_16x16x32_bf16 v[36:39], v[176:179], v[200:203], 0
	v_mfma_f32_16x16x32_bf16 v[32:35], v[184:187], v[200:203], 0
	v_mfma_f32_16x16x32_bf16 v[20:23], v[176:179], v[208:211], 0
	v_mfma_f32_16x16x32_bf16 v[16:19], v[184:187], v[208:211], 0
	v_mfma_f32_16x16x32_bf16 v[4:7], v[176:179], v[216:219], 0
	v_mfma_f32_16x16x32_bf16 v[0:3], v[184:187], v[216:219], 0
	v_mfma_f32_16x16x32_bf16 v[52:55], v[180:183], v[196:199], v[52:55]
	v_mfma_f32_16x16x32_bf16 v[48:51], v[188:191], v[196:199], v[48:51]
	v_mfma_f32_16x16x32_bf16 v[36:39], v[180:183], v[204:207], v[36:39]
	v_mfma_f32_16x16x32_bf16 v[32:35], v[188:191], v[204:207], v[32:35]
	v_mfma_f32_16x16x32_bf16 v[20:23], v[180:183], v[212:215], v[20:23]
	v_mfma_f32_16x16x32_bf16 v[16:19], v[188:191], v[212:215], v[16:19]
	v_mfma_f32_16x16x32_bf16 v[4:7], v[180:183], v[240:243], v[4:7]
	v_mfma_f32_16x16x32_bf16 v[0:3], v[188:191], v[240:243], v[0:3]
	s_setprio 0
	s_barrier
	s_add_i32 s10, 0, 0x18000
	v_add_u32_e32 v148, s10, v149
	s_add_i32 s62, 0, 0x1c000
	ds_read_b128 v[152:155], v148
	ds_read_b128 v[156:159], v148 offset:1024
	ds_read_b128 v[160:163], v148 offset:2048
	ds_read_b128 v[164:167], v148 offset:3072
	v_add_u32_e32 v148, s62, v149
	ds_read_b128 v[176:179], v148
	ds_read_b128 v[180:183], v148 offset:1024
	ds_read_b128 v[184:187], v148 offset:2048
	ds_read_b128 v[188:191], v148 offset:3072
	v_lshl_add_u64 v[146:147], v[146:147], 0, s[94:95]
	s_mov_b32 m0, s51
	v_lshl_add_u64 v[226:227], v[146:147], 0, v[132:133]
	ds_read_b128 v[192:195], v151 offset:32768
	ds_read_b128 v[196:199], v151 offset:33792
	ds_read_b128 v[200:203], v151 offset:34816
	ds_read_b128 v[204:207], v151 offset:35840
	ds_read_b128 v[208:211], v151 offset:36864
	ds_read_b128 v[212:215], v151 offset:37888
	ds_read_b128 v[216:219], v151 offset:38912
	ds_read_b128 v[240:243], v151 offset:39936
	global_load_lds_dwordx4 v[226:227], off
	v_lshl_add_u64 v[146:147], v[146:147], 0, v[130:131]
	s_mov_b32 m0, s52
	s_nop 0
	global_load_lds_dwordx4 v[146:147], off
	s_waitcnt vmcnt(8)
	s_waitcnt lgkmcnt(0)
	s_barrier
	s_setprio 1
	v_mfma_f32_16x16x32_bf16 v[124:127], v[152:155], v[192:195], v[124:127]
	v_mfma_f32_16x16x32_bf16 v[120:123], v[160:163], v[192:195], v[120:123]
	v_mfma_f32_16x16x32_bf16 v[108:111], v[152:155], v[200:203], v[108:111]
	v_mfma_f32_16x16x32_bf16 v[104:107], v[160:163], v[200:203], v[104:107]
	v_mfma_f32_16x16x32_bf16 v[92:95], v[152:155], v[208:211], v[92:95]
	v_mfma_f32_16x16x32_bf16 v[88:91], v[160:163], v[208:211], v[88:91]
	v_mfma_f32_16x16x32_bf16 v[76:79], v[152:155], v[216:219], v[76:79]
	v_mfma_f32_16x16x32_bf16 v[72:75], v[160:163], v[216:219], v[72:75]
	v_mfma_f32_16x16x32_bf16 v[124:127], v[156:159], v[196:199], v[124:127]
	v_mfma_f32_16x16x32_bf16 v[120:123], v[164:167], v[196:199], v[120:123]
	v_mfma_f32_16x16x32_bf16 v[108:111], v[156:159], v[204:207], v[108:111]
	v_mfma_f32_16x16x32_bf16 v[104:107], v[164:167], v[204:207], v[104:107]
	v_mfma_f32_16x16x32_bf16 v[92:95], v[156:159], v[212:215], v[92:95]
	v_mfma_f32_16x16x32_bf16 v[88:91], v[164:167], v[212:215], v[88:91]
	v_mfma_f32_16x16x32_bf16 v[76:79], v[156:159], v[240:243], v[76:79]
	v_mfma_f32_16x16x32_bf16 v[72:75], v[164:167], v[240:243], v[72:75]
	s_setprio 0
	s_setprio 1
	v_mfma_f32_16x16x32_bf16 v[116:119], v[176:179], v[192:195], v[116:119]
	v_mfma_f32_16x16x32_bf16 v[112:115], v[184:187], v[192:195], v[112:115]
	v_mfma_f32_16x16x32_bf16 v[100:103], v[176:179], v[200:203], v[100:103]
	v_mfma_f32_16x16x32_bf16 v[96:99], v[184:187], v[200:203], v[96:99]
	v_mfma_f32_16x16x32_bf16 v[84:87], v[176:179], v[208:211], v[84:87]
	v_mfma_f32_16x16x32_bf16 v[80:83], v[184:187], v[208:211], v[80:83]
	v_mfma_f32_16x16x32_bf16 v[68:71], v[176:179], v[216:219], v[68:71]
	v_mfma_f32_16x16x32_bf16 v[64:67], v[184:187], v[216:219], v[64:67]
	v_mfma_f32_16x16x32_bf16 v[116:119], v[180:183], v[196:199], v[116:119]
	v_mfma_f32_16x16x32_bf16 v[112:115], v[188:191], v[196:199], v[112:115]
	v_mfma_f32_16x16x32_bf16 v[100:103], v[180:183], v[204:207], v[100:103]
	v_mfma_f32_16x16x32_bf16 v[96:99], v[188:191], v[204:207], v[96:99]
	v_mfma_f32_16x16x32_bf16 v[84:87], v[180:183], v[212:215], v[84:87]
	v_mfma_f32_16x16x32_bf16 v[80:83], v[188:191], v[212:215], v[80:83]
	v_mfma_f32_16x16x32_bf16 v[68:71], v[180:183], v[240:243], v[68:71]
	v_mfma_f32_16x16x32_bf16 v[64:67], v[188:191], v[240:243], v[64:67]
	s_setprio 0
	s_barrier
; #define PG8_STAGE(bufoff, gbase, voff) do { _Pragma("unroll") for (int _i = 0; _i < 2; ++_i) \
;         __builtin_amdgcn_global_load_lds((const unsigned*)((const char*)(gbase) + (voff)[_i]), (LAS unsigned*)(lds + (bufoff) + ldsw + _i * 8192), 16, 0, 0); } while (0)
; #define PG8_LDA(dst, b, h) do { _Pragma("unroll") for (int m = 0; m < 4; ++m) _Pragma("unroll") for (int k = 0; k < 2; ++k) dst[m][k] = *(const LAS bf16x8*)(lds + PG8_SA(b, h) + aoff + m * 2048 + k * 1024); } while (0)
; #define PG8_MMA(ai, bj, At, Bt) do { __builtin_amdgcn_s_setprio(1); _Pragma("unroll") for (int k = 0; k < 2; ++k) _Pragma("unroll") for (int m = 0; m < 4; ++m) _Pragma("unroll") for (int n = 0; n < 2; ++n) \
;         acc[ai][bj][m][n] = __builtin_amdgcn_mfma_f32_16x16x32_bf16(Bt[n][k], At[m][k], acc[ai][bj][m][n], 0, 0, 0); __builtin_amdgcn_s_setprio(0); } while (0)
; #define PG8_WAIT_V(n) asm volatile("s_waitcnt vmcnt(" #n ")" ::: "memory")
; #define PG8_WAIT_L(n) asm volatile("s_waitcnt lgkmcnt(" #n ")" ::: "memory")
; #define PG8_BAR __builtin_amdgcn_s_barrier()
; #define PG8_SCHED __builtin_amdgcn_sched_barrier(0)
; template <class Epi, bool ALIGN_EPI>
; __device__ __forceinline__ void gemm_phase(LAS unsigned char* lds, const Gemm g, const StaticOrder& S, const Epi& E, const int tid) {
;     ...
;             PG8_LDA(At, 1, 1); PG8_STAGE(PG8_SB(1, 0), b3, voffB); PG8_STAGE(PG8_SB(1, 1), b3 + hB, voffB); PG8_STAGE(PG8_SA(1, 0), a3, voffA);
;             PG8_WAIT_V(8); PG8_WAIT_L(0); PG8_BAR; PG8_MMA(1, 0, At, B0); PG8_MMA(1, 1, At, B1); PG8_BAR; PG8_SCHED;
;     ...
;         cur = nxt; cA = nA; cB = nB; ++ui;
	s_add_i32 s10, s10, s45
	v_lshl_add_u64 v[146:147], v[244:245], 0, s[92:93]
	s_mov_b32 m0, s10
	ds_read_b128 v[192:195], v151 offset:49152
	ds_read_b128 v[196:199], v151 offset:50176
	ds_read_b128 v[200:203], v151 offset:51200
	ds_read_b128 v[204:207], v151 offset:52224
	ds_read_b128 v[208:211], v151 offset:53248
	ds_read_b128 v[212:215], v151 offset:54272
	ds_read_b128 v[216:219], v151 offset:55296
	ds_read_b128 v[240:243], v151 offset:56320
	global_load_lds_dwordx4 v[146:147], off
	v_lshl_add_u64 v[146:147], v[246:247], 0, s[92:93]
	s_add_i32 m0, s10, 0x2000
	s_add_i32 s10, s62, s45
	global_load_lds_dwordx4 v[146:147], off
	v_lshl_add_u64 v[146:147], v[248:249], 0, s[92:93]
	s_mov_b32 m0, s10
	s_nop 0
	global_load_lds_dwordx4 v[146:147], off
	v_lshl_add_u64 v[146:147], v[220:221], 0, s[92:93]
	s_add_i32 m0, s10, 0x2000
	s_nop 0
	global_load_lds_dwordx4 v[146:147], off
	v_lshl_add_u64 v[146:147], v[250:251], 0, s[92:93]
	s_mov_b32 m0, s53
	s_nop 0
	global_load_lds_dwordx4 v[146:147], off
	v_lshl_add_u64 v[146:147], v[252:253], 0, s[92:93]
	s_mov_b32 m0, s54
	s_nop 0
	global_load_lds_dwordx4 v[146:147], off
	s_waitcnt vmcnt(8)
	s_waitcnt lgkmcnt(0)
	s_barrier
	s_setprio 1
	v_mfma_f32_16x16x32_bf16 v[60:63], v[152:155], v[192:195], v[60:63]
	v_mfma_f32_16x16x32_bf16 v[56:59], v[160:163], v[192:195], v[56:59]
	v_mfma_f32_16x16x32_bf16 v[44:47], v[152:155], v[200:203], v[44:47]
	v_mfma_f32_16x16x32_bf16 v[40:43], v[160:163], v[200:203], v[40:43]
	v_mfma_f32_16x16x32_bf16 v[28:31], v[152:155], v[208:211], v[28:31]
	v_mfma_f32_16x16x32_bf16 v[24:27], v[160:163], v[208:211], v[24:27]
	v_mfma_f32_16x16x32_bf16 v[12:15], v[152:155], v[216:219], v[12:15]
	v_mfma_f32_16x16x32_bf16 v[8:11], v[160:163], v[216:219], v[8:11]
	v_mfma_f32_16x16x32_bf16 v[60:63], v[156:159], v[196:199], v[60:63]
	v_mfma_f32_16x16x32_bf16 v[56:59], v[164:167], v[196:199], v[56:59]
	v_mfma_f32_16x16x32_bf16 v[44:47], v[156:159], v[204:207], v[44:47]
	v_mfma_f32_16x16x32_bf16 v[40:43], v[164:167], v[204:207], v[40:43]
	v_mfma_f32_16x16x32_bf16 v[28:31], v[156:159], v[212:215], v[28:31]
	v_mfma_f32_16x16x32_bf16 v[24:27], v[164:167], v[212:215], v[24:27]
	v_mfma_f32_16x16x32_bf16 v[12:15], v[156:159], v[240:243], v[12:15]
	v_mfma_f32_16x16x32_bf16 v[8:11], v[164:167], v[240:243], v[8:11]
	s_setprio 0
	s_setprio 1
	v_mfma_f32_16x16x32_bf16 v[52:55], v[176:179], v[192:195], v[52:55]
	v_mfma_f32_16x16x32_bf16 v[48:51], v[184:187], v[192:195], v[48:51]
	v_mfma_f32_16x16x32_bf16 v[36:39], v[176:179], v[200:203], v[36:39]
	v_mfma_f32_16x16x32_bf16 v[32:35], v[184:187], v[200:203], v[32:35]
	v_mfma_f32_16x16x32_bf16 v[20:23], v[176:179], v[208:211], v[20:23]
	v_mfma_f32_16x16x32_bf16 v[16:19], v[184:187], v[208:211], v[16:19]
	v_mfma_f32_16x16x32_bf16 v[4:7], v[176:179], v[216:219], v[4:7]
	v_mfma_f32_16x16x32_bf16 v[0:3], v[184:187], v[216:219], v[0:3]
	v_mfma_f32_16x16x32_bf16 v[52:55], v[180:183], v[196:199], v[52:55]
	v_mfma_f32_16x16x32_bf16 v[48:51], v[188:191], v[196:199], v[48:51]
	v_mfma_f32_16x16x32_bf16 v[36:39], v[180:183], v[204:207], v[36:39]
	v_mfma_f32_16x16x32_bf16 v[32:35], v[188:191], v[204:207], v[32:35]
	v_mfma_f32_16x16x32_bf16 v[20:23], v[180:183], v[212:215], v[20:23]
	v_mfma_f32_16x16x32_bf16 v[16:19], v[188:191], v[212:215], v[16:19]
	v_mfma_f32_16x16x32_bf16 v[4:7], v[180:183], v[240:243], v[4:7]
	v_mfma_f32_16x16x32_bf16 v[0:3], v[188:191], v[240:243], v[0:3]
	s_setprio 0
	s_barrier
	v_lshl_add_u64 v[142:143], v[142:143], 0, s[80:81]
	v_lshl_add_u64 v[144:145], v[144:145], 0, s[80:81]
	s_mov_b32 s10, s11
	s_cmp_eq_u32 s10, s55
	s_cbranch_scc1 .Lq5_last
.LBB0_354:
	s_add_i32 s11, s10, 2
	s_cmp_eq_u32 s55, s10
	s_cselect_b64 vcc, -1, 0
	v_add_u32_e32 v148, s33, v149
	s_add_i32 s10, 0, 0x14000
	ds_read_b128 v[152:155], v148
	ds_read_b128 v[156:159], v148 offset:1024
	ds_read_b128 v[160:163], v148 offset:2048
	ds_read_b128 v[164:167], v148 offset:3072
	v_add_u32_e32 v148, s10, v149
	ds_read_b128 v[176:179], v148
	ds_read_b128 v[180:183], v148 offset:1024
	ds_read_b128 v[184:187], v148 offset:2048
	ds_read_b128 v[188:191], v148 offset:3072
	v_lshl_add_u64 v[146:147], v[142:143], 0, s[92:93]
	v_cndmask_b32_e32 v147, v147, v139, vcc
	v_cndmask_b32_e32 v146, v146, v138, vcc
	v_cndmask_b32_e32 v221, v145, v141, vcc
	v_cndmask_b32_e32 v220, v144, v140, vcc
	v_lshl_add_u64 v[244:245], v[142:143], 0, v[134:135]
	s_add_i32 m0, s25, 0xc000
	ds_read_b128 v[192:195], v151
	ds_read_b128 v[196:199], v151 offset:1024
	ds_read_b128 v[200:203], v151 offset:2048
	ds_read_b128 v[204:207], v151 offset:3072
	ds_read_b128 v[208:211], v151 offset:4096
	ds_read_b128 v[212:215], v151 offset:5120
	ds_read_b128 v[216:219], v151 offset:6144
	ds_read_b128 v[240:243], v151 offset:7168
	global_load_lds_dwordx4 v[244:245], off
	v_lshl_add_u64 v[244:245], v[142:143], 0, v[136:137]
	s_add_i32 m0, s25, 0xe000
	s_nop 0
	global_load_lds_dwordx4 v[244:245], off
	s_waitcnt vmcnt(8)
	s_waitcnt lgkmcnt(0)
	s_barrier
; #define PG8_STAGE(bufoff, gbase, voff) do { _Pragma("unroll") for (int _i = 0; _i < 2; ++_i) \
;         __builtin_amdgcn_global_load_lds((const unsigned*)((const char*)(gbase) + (voff)[_i]), (LAS unsigned*)(lds + (bufoff) + ldsw + _i * 8192), 16, 0, 0); } while (0)
; #define PG8_LDA(dst, b, h) do { _Pragma("unroll") for (int m = 0; m < 4; ++m) _Pragma("unroll") for (int k = 0; k < 2; ++k) dst[m][k] = *(const LAS bf16x8*)(lds + PG8_SA(b, h) + aoff + m * 2048 + k * 1024); } while (0)
; #define PG8_LDB(dst, b, h) do { _Pragma("unroll") for (int n = 0; n < 2; ++n) _Pragma("unroll") for (int k = 0; k < 2; ++k) dst[n][k] = *(const LAS bf16x8*)(lds + PG8_SB(b, h) + boff + n * 2048 + k * 1024); } while (0)
; #define PG8_MMA(ai, bj, At, Bt) do { __builtin_amdgcn_s_setprio(1); _Pragma("unroll") for (int k = 0; k < 2; ++k) _Pragma("unroll") for (int m = 0; m < 4; ++m) _Pragma("unroll") for (int n = 0; n < 2; ++n) \
;         acc[ai][bj][m][n] = __builtin_amdgcn_mfma_f32_16x16x32_bf16(Bt[n][k], At[m][k], acc[ai][bj][m][n], 0, 0, 0); __builtin_amdgcn_s_setprio(0); } while (0)
; #define PG8_WAIT_V(n) asm volatile("s_waitcnt vmcnt(" #n ")" ::: "memory")
; #define PG8_WAIT_L(n) asm volatile("s_waitcnt lgkmcnt(" #n ")" ::: "memory")
; #define PG8_BAR __builtin_amdgcn_s_barrier()
; #define PG8_SCHED __builtin_amdgcn_sched_barrier(0)
; template <class Epi, bool ALIGN_EPI>
; __device__ __forceinline__ void gemm_phase(LAS unsigned char* lds, const Gemm g, const StaticOrder& S, const Epi& E, const int tid) {
;     ...
;             PG8_WAIT_V(8); PG8_WAIT_L(0); PG8_BAR; PG8_MMA(0, 0, At, B0); PG8_MMA(0, 1, At, B1); PG8_BAR; PG8_SCHED;
;             PG8_LDA(At, 0, 1); PG8_STAGE(PG8_SB(0, 0), b2, voffB); PG8_STAGE(PG8_SB(0, 1), b2 + hB, voffB); PG8_STAGE(PG8_SA(0, 0), a2, voffA);
;             PG8_WAIT_V(8); PG8_WAIT_L(0); PG8_BAR; PG8_MMA(1, 0, At, B0); PG8_MMA(1, 1, At, B1); PG8_BAR; PG8_SCHED;
;             PG8_LDB(B0, 1, 0); PG8_LDB(B1, 1, 1); PG8_SCHED; PG8_LDA(At, 1, 0); PG8_STAGE(PG8_SA(0, 1), a2 + hA, voffA);
;             PG8_WAIT_V(8); PG8_WAIT_L(0); PG8_BAR; PG8_MMA(0, 0, At, B0); PG8_MMA(0, 1, At, B1); PG8_BAR; PG8_SCHED;
	s_setprio 1
	v_mfma_f32_16x16x32_bf16 v[124:127], v[152:155], v[192:195], v[124:127]
	v_mfma_f32_16x16x32_bf16 v[120:123], v[160:163], v[192:195], v[120:123]
	v_mfma_f32_16x16x32_bf16 v[108:111], v[152:155], v[200:203], v[108:111]
	v_mfma_f32_16x16x32_bf16 v[104:107], v[160:163], v[200:203], v[104:107]
	v_mfma_f32_16x16x32_bf16 v[92:95], v[152:155], v[208:211], v[92:95]
	v_mfma_f32_16x16x32_bf16 v[88:91], v[160:163], v[208:211], v[88:91]
	v_mfma_f32_16x16x32_bf16 v[76:79], v[152:155], v[216:219], v[76:79]
	v_mfma_f32_16x16x32_bf16 v[72:75], v[160:163], v[216:219], v[72:75]
	v_mfma_f32_16x16x32_bf16 v[124:127], v[156:159], v[196:199], v[124:127]
	v_mfma_f32_16x16x32_bf16 v[120:123], v[164:167], v[196:199], v[120:123]
	v_mfma_f32_16x16x32_bf16 v[108:111], v[156:159], v[204:207], v[108:111]
	v_mfma_f32_16x16x32_bf16 v[104:107], v[164:167], v[204:207], v[104:107]
	v_mfma_f32_16x16x32_bf16 v[92:95], v[156:159], v[212:215], v[92:95]
	v_mfma_f32_16x16x32_bf16 v[88:91], v[164:167], v[212:215], v[88:91]
	v_mfma_f32_16x16x32_bf16 v[76:79], v[156:159], v[240:243], v[76:79]
	v_mfma_f32_16x16x32_bf16 v[72:75], v[164:167], v[240:243], v[72:75]
	s_setprio 0
	s_setprio 1
	v_mfma_f32_16x16x32_bf16 v[116:119], v[176:179], v[192:195], v[116:119]
	v_mfma_f32_16x16x32_bf16 v[112:115], v[184:187], v[192:195], v[112:115]
	v_mfma_f32_16x16x32_bf16 v[100:103], v[176:179], v[200:203], v[100:103]
	v_mfma_f32_16x16x32_bf16 v[96:99], v[184:187], v[200:203], v[96:99]
	v_mfma_f32_16x16x32_bf16 v[84:87], v[176:179], v[208:211], v[84:87]
	v_mfma_f32_16x16x32_bf16 v[80:83], v[184:187], v[208:211], v[80:83]
	v_mfma_f32_16x16x32_bf16 v[68:71], v[176:179], v[216:219], v[68:71]
	v_mfma_f32_16x16x32_bf16 v[64:67], v[184:187], v[216:219], v[64:67]
	v_mfma_f32_16x16x32_bf16 v[116:119], v[180:183], v[196:199], v[116:119]
	v_mfma_f32_16x16x32_bf16 v[112:115], v[188:191], v[196:199], v[112:115]
	v_mfma_f32_16x16x32_bf16 v[100:103], v[180:183], v[204:207], v[100:103]
	v_mfma_f32_16x16x32_bf16 v[96:99], v[188:191], v[204:207], v[96:99]
	v_mfma_f32_16x16x32_bf16 v[84:87], v[180:183], v[212:215], v[84:87]
	v_mfma_f32_16x16x32_bf16 v[80:83], v[188:191], v[212:215], v[80:83]
	v_mfma_f32_16x16x32_bf16 v[68:71], v[180:183], v[240:243], v[68:71]
	v_mfma_f32_16x16x32_bf16 v[64:67], v[188:191], v[240:243], v[64:67]
	s_setprio 0
	s_barrier
	s_add_i32 s62, s33, s45
	v_lshl_add_u64 v[244:245], v[220:221], 0, v[168:169]
	s_mov_b32 m0, s62
	ds_read_b128 v[192:195], v151 offset:16384
	ds_read_b128 v[196:199], v151 offset:17408
	ds_read_b128 v[200:203], v151 offset:18432
	ds_read_b128 v[204:207], v151 offset:19456
	ds_read_b128 v[208:211], v151 offset:20480
	ds_read_b128 v[212:215], v151 offset:21504
	ds_read_b128 v[216:219], v151 offset:22528
	ds_read_b128 v[240:243], v151 offset:23552
	global_load_lds_dwordx4 v[244:245], off
	v_lshl_add_u64 v[246:247], v[220:221], 0, v[128:129]
	s_add_i32 m0, s62, 0x2000
	v_lshl_add_u64 v[220:221], v[220:221], 0, s[12:13]
	s_add_i32 s10, s10, s45
	global_load_lds_dwordx4 v[246:247], off
	v_lshl_add_u64 v[248:249], v[220:221], 0, v[168:169]
	s_mov_b32 m0, s10
	v_lshl_add_u64 v[220:221], v[220:221], 0, v[128:129]
	global_load_lds_dwordx4 v[248:249], off
	s_add_i32 m0, s10, 0x2000
	v_lshl_add_u64 v[250:251], v[146:147], 0, v[132:133]
	global_load_lds_dwordx4 v[220:221], off
	s_mov_b32 m0, s25
	v_lshl_add_u64 v[252:253], v[146:147], 0, v[130:131]
	global_load_lds_dwordx4 v[250:251], off
	s_mov_b32 m0, s50
	s_nop 0
	global_load_lds_dwordx4 v[252:253], off
	s_waitcnt vmcnt(8)
	s_waitcnt lgkmcnt(0)
	s_barrier
	s_setprio 1
	v_mfma_f32_16x16x32_bf16 v[60:63], v[152:155], v[192:195], v[60:63]
	v_mfma_f32_16x16x32_bf16 v[56:59], v[160:163], v[192:195], v[56:59]
	v_mfma_f32_16x16x32_bf16 v[44:47], v[152:155], v[200:203], v[44:47]
	v_mfma_f32_16x16x32_bf16 v[40:43], v[160:163], v[200:203], v[40:43]
	v_mfma_f32_16x16x32_bf16 v[28:31], v[152:155], v[208:211], v[28:31]
	v_mfma_f32_16x16x32_bf16 v[24:27], v[160:163], v[208:211], v[24:27]
	v_mfma_f32_16x16x32_bf16 v[12:15], v[152:155], v[216:219], v[12:15]
	v_mfma_f32_16x16x32_bf16 v[8:11], v[160:163], v[216:219], v[8:11]
	v_mfma_f32_16x16x32_bf16 v[60:63], v[156:159], v[196:199], v[60:63]
	v_mfma_f32_16x16x32_bf16 v[56:59], v[164:167], v[196:199], v[56:59]
	v_mfma_f32_16x16x32_bf16 v[44:47], v[156:159], v[204:207], v[44:47]
	v_mfma_f32_16x16x32_bf16 v[40:43], v[164:167], v[204:207], v[40:43]
	v_mfma_f32_16x16x32_bf16 v[28:31], v[156:159], v[212:215], v[28:31]
	v_mfma_f32_16x16x32_bf16 v[24:27], v[164:167], v[212:215], v[24:27]
	v_mfma_f32_16x16x32_bf16 v[12:15], v[156:159], v[240:243], v[12:15]
	v_mfma_f32_16x16x32_bf16 v[8:11], v[164:167], v[240:243], v[8:11]
	s_setprio 0
	s_setprio 1
	v_mfma_f32_16x16x32_bf16 v[52:55], v[176:179], v[192:195], v[52:55]
	v_mfma_f32_16x16x32_bf16 v[48:51], v[184:187], v[192:195], v[48:51]
	v_mfma_f32_16x16x32_bf16 v[36:39], v[176:179], v[200:203], v[36:39]
	v_mfma_f32_16x16x32_bf16 v[32:35], v[184:187], v[200:203], v[32:35]
	v_mfma_f32_16x16x32_bf16 v[20:23], v[176:179], v[208:211], v[20:23]
	v_mfma_f32_16x16x32_bf16 v[16:19], v[184:187], v[208:211], v[16:19]
	v_mfma_f32_16x16x32_bf16 v[4:7], v[176:179], v[216:219], v[4:7]
	v_mfma_f32_16x16x32_bf16 v[0:3], v[184:187], v[216:219], v[0:3]
	v_mfma_f32_16x16x32_bf16 v[52:55], v[180:183], v[196:199], v[52:55]
	v_mfma_f32_16x16x32_bf16 v[48:51], v[188:191], v[196:199], v[48:51]
	v_mfma_f32_16x16x32_bf16 v[36:39], v[180:183], v[204:207], v[36:39]
	v_mfma_f32_16x16x32_bf16 v[32:35], v[188:191], v[204:207], v[32:35]
	v_mfma_f32_16x16x32_bf16 v[20:23], v[180:183], v[212:215], v[20:23]
	v_mfma_f32_16x16x32_bf16 v[16:19], v[188:191], v[212:215], v[16:19]
	v_mfma_f32_16x16x32_bf16 v[4:7], v[180:183], v[240:243], v[4:7]
	v_mfma_f32_16x16x32_bf16 v[0:3], v[188:191], v[240:243], v[0:3]
	s_setprio 0
	s_barrier
; #define PG8_STAGE(bufoff, gbase, voff) do { _Pragma("unroll") for (int _i = 0; _i < 2; ++_i) \
;         __builtin_amdgcn_global_load_lds((const unsigned*)((const char*)(gbase) + (voff)[_i]), (LAS unsigned*)(lds + (bufoff) + ldsw + _i * 8192), 16, 0, 0); } while (0)
; #define PG8_LDA(dst, b, h) do { _Pragma("unroll") for (int m = 0; m < 4; ++m) _Pragma("unroll") for (int k = 0; k < 2; ++k) dst[m][k] = *(const LAS bf16x8*)(lds + PG8_SA(b, h) + aoff + m * 2048 + k * 1024); } while (0)
; #define PG8_LDB(dst, b, h) do { _Pragma("unroll") for (int n = 0; n < 2; ++n) _Pragma("unroll") for (int k = 0; k < 2; ++k) dst[n][k] = *(const LAS bf16x8*)(lds + PG8_SB(b, h) + boff + n * 2048 + k * 1024); } while (0)
; #define PG8_MMA(ai, bj, At, Bt) do { __builtin_amdgcn_s_setprio(1); _Pragma("unroll") for (int k = 0; k < 2; ++k) _Pragma("unroll") for (int m = 0; m < 4; ++m) _Pragma("unroll") for (int n = 0; n < 2; ++n) \
;         acc[ai][bj][m][n] = __builtin_amdgcn_mfma_f32_16x16x32_bf16(Bt[n][k], At[m][k], acc[ai][bj][m][n], 0, 0, 0); __builtin_amdgcn_s_setprio(0); } while (0)
; #define PG8_WAIT_V(n) asm volatile("s_waitcnt vmcnt(" #n ")" ::: "memory")
; #define PG8_WAIT_L(n) asm volatile("s_waitcnt lgkmcnt(" #n ")" ::: "memory")
; #define PG8_BAR __builtin_amdgcn_s_barrier()
; #define PG8_SCHED __builtin_amdgcn_sched_barrier(0)
; template <class Epi, bool ALIGN_EPI>
; __device__ __forceinline__ void gemm_phase(LAS unsigned char* lds, const Gemm g, const StaticOrder& S, const Epi& E, const int tid) {
;     ...
;             PG8_LDB(B0, 1, 0); PG8_LDB(B1, 1, 1); PG8_SCHED; PG8_LDA(At, 1, 0); PG8_STAGE(PG8_SA(0, 1), a2 + hA, voffA);
;             PG8_WAIT_V(8); PG8_WAIT_L(0); PG8_BAR; PG8_MMA(0, 0, At, B0); PG8_MMA(0, 1, At, B1); PG8_BAR; PG8_SCHED;
;             PG8_LDA(At, 1, 1); PG8_STAGE(PG8_SB(1, 0), b3, voffB); PG8_STAGE(PG8_SB(1, 1), b3 + hB, voffB); PG8_STAGE(PG8_SA(1, 0), a3, voffA);
	s_add_i32 s10, 0, 0x18000
	v_add_u32_e32 v148, s10, v149
	s_add_i32 s62, 0, 0x1c000
	ds_read_b128 v[152:155], v148
	ds_read_b128 v[156:159], v148 offset:1024
	ds_read_b128 v[160:163], v148 offset:2048
	ds_read_b128 v[164:167], v148 offset:3072
	v_add_u32_e32 v148, s62, v149
	ds_read_b128 v[176:179], v148
	ds_read_b128 v[180:183], v148 offset:1024
	ds_read_b128 v[184:187], v148 offset:2048
	ds_read_b128 v[188:191], v148 offset:3072
	v_lshl_add_u64 v[146:147], v[146:147], 0, s[94:95]
	s_mov_b32 m0, s51
	v_lshl_add_u64 v[226:227], v[146:147], 0, v[132:133]
	ds_read_b128 v[192:195], v151 offset:32768
	ds_read_b128 v[196:199], v151 offset:33792
	ds_read_b128 v[200:203], v151 offset:34816
	ds_read_b128 v[204:207], v151 offset:35840
	ds_read_b128 v[208:211], v151 offset:36864
	ds_read_b128 v[212:215], v151 offset:37888
	ds_read_b128 v[216:219], v151 offset:38912
	ds_read_b128 v[240:243], v151 offset:39936
	global_load_lds_dwordx4 v[226:227], off
	v_lshl_add_u64 v[146:147], v[146:147], 0, v[130:131]
	s_mov_b32 m0, s52
	s_nop 0
	global_load_lds_dwordx4 v[146:147], off
	s_waitcnt vmcnt(8)
	s_waitcnt lgkmcnt(0)
	s_barrier
	s_setprio 1
	v_mfma_f32_16x16x32_bf16 v[124:127], v[152:155], v[192:195], v[124:127]
	v_mfma_f32_16x16x32_bf16 v[120:123], v[160:163], v[192:195], v[120:123]
	v_mfma_f32_16x16x32_bf16 v[108:111], v[152:155], v[200:203], v[108:111]
	v_mfma_f32_16x16x32_bf16 v[104:107], v[160:163], v[200:203], v[104:107]
	v_mfma_f32_16x16x32_bf16 v[92:95], v[152:155], v[208:211], v[92:95]
	v_mfma_f32_16x16x32_bf16 v[88:91], v[160:163], v[208:211], v[88:91]
	v_mfma_f32_16x16x32_bf16 v[76:79], v[152:155], v[216:219], v[76:79]
	v_mfma_f32_16x16x32_bf16 v[72:75], v[160:163], v[216:219], v[72:75]
	v_mfma_f32_16x16x32_bf16 v[124:127], v[156:159], v[196:199], v[124:127]
	v_mfma_f32_16x16x32_bf16 v[120:123], v[164:167], v[196:199], v[120:123]
	v_mfma_f32_16x16x32_bf16 v[108:111], v[156:159], v[204:207], v[108:111]
	v_mfma_f32_16x16x32_bf16 v[104:107], v[164:167], v[204:207], v[104:107]
	v_mfma_f32_16x16x32_bf16 v[92:95], v[156:159], v[212:215], v[92:95]
	v_mfma_f32_16x16x32_bf16 v[88:91], v[164:167], v[212:215], v[88:91]
	v_mfma_f32_16x16x32_bf16 v[76:79], v[156:159], v[240:243], v[76:79]
	v_mfma_f32_16x16x32_bf16 v[72:75], v[164:167], v[240:243], v[72:75]
	s_setprio 0
	s_setprio 1
	v_mfma_f32_16x16x32_bf16 v[116:119], v[176:179], v[192:195], v[116:119]
	v_mfma_f32_16x16x32_bf16 v[112:115], v[184:187], v[192:195], v[112:115]
	v_mfma_f32_16x16x32_bf16 v[100:103], v[176:179], v[200:203], v[100:103]
	v_mfma_f32_16x16x32_bf16 v[96:99], v[184:187], v[200:203], v[96:99]
	v_mfma_f32_16x16x32_bf16 v[84:87], v[176:179], v[208:211], v[84:87]
	v_mfma_f32_16x16x32_bf16 v[80:83], v[184:187], v[208:211], v[80:83]
	v_mfma_f32_16x16x32_bf16 v[68:71], v[176:179], v[216:219], v[68:71]
	v_mfma_f32_16x16x32_bf16 v[64:67], v[184:187], v[216:219], v[64:67]
	v_mfma_f32_16x16x32_bf16 v[116:119], v[180:183], v[196:199], v[116:119]
	v_mfma_f32_16x16x32_bf16 v[112:115], v[188:191], v[196:199], v[112:115]
	v_mfma_f32_16x16x32_bf16 v[100:103], v[180:183], v[204:207], v[100:103]
	v_mfma_f32_16x16x32_bf16 v[96:99], v[188:191], v[204:207], v[96:99]
	v_mfma_f32_16x16x32_bf16 v[84:87], v[180:183], v[212:215], v[84:87]
	v_mfma_f32_16x16x32_bf16 v[80:83], v[188:191], v[212:215], v[80:83]
	v_mfma_f32_16x16x32_bf16 v[68:71], v[180:183], v[240:243], v[68:71]
	v_mfma_f32_16x16x32_bf16 v[64:67], v[188:191], v[240:243], v[64:67]
	s_setprio 0
	s_barrier
	s_add_i32 s10, s10, s45
	v_lshl_add_u64 v[146:147], v[244:245], 0, s[92:93]
	s_mov_b32 m0, s10
	ds_read_b128 v[192:195], v151 offset:49152
	ds_read_b128 v[196:199], v151 offset:50176
	ds_read_b128 v[200:203], v151 offset:51200
	ds_read_b128 v[204:207], v151 offset:52224
	ds_read_b128 v[208:211], v151 offset:53248
	ds_read_b128 v[212:215], v151 offset:54272
	ds_read_b128 v[216:219], v151 offset:55296
	ds_read_b128 v[240:243], v151 offset:56320
	global_load_lds_dwordx4 v[146:147], off
	v_lshl_add_u64 v[146:147], v[246:247], 0, s[92:93]
	s_add_i32 m0, s10, 0x2000
	s_add_i32 s10, s62, s45
	global_load_lds_dwordx4 v[146:147], off
	v_lshl_add_u64 v[146:147], v[248:249], 0, s[92:93]
	s_mov_b32 m0, s10
	s_nop 0
	global_load_lds_dwordx4 v[146:147], off
	v_lshl_add_u64 v[146:147], v[220:221], 0, s[92:93]
	s_add_i32 m0, s10, 0x2000
	s_nop 0
	global_load_lds_dwordx4 v[146:147], off
	v_lshl_add_u64 v[146:147], v[250:251], 0, s[92:93]
	s_mov_b32 m0, s53
	s_nop 0
	global_load_lds_dwordx4 v[146:147], off
	v_lshl_add_u64 v[146:147], v[252:253], 0, s[92:93]
	s_mov_b32 m0, s54
	s_nop 0
	global_load_lds_dwordx4 v[146:147], off
	s_waitcnt vmcnt(8)
	s_waitcnt lgkmcnt(0)
	s_barrier
; #define PG8_STAGE(bufoff, gbase, voff) do { _Pragma("unroll") for (int _i = 0; _i < 2; ++_i) \
;         __builtin_amdgcn_global_load_lds((const unsigned*)((const char*)(gbase) + (voff)[_i]), (LAS unsigned*)(lds + (bufoff) + ldsw + _i * 8192), 16, 0, 0); } while (0)
; #define PG8_LDA(dst, b, h) do { _Pragma("unroll") for (int m = 0; m < 4; ++m) _Pragma("unroll") for (int k = 0; k < 2; ++k) dst[m][k] = *(const LAS bf16x8*)(lds + PG8_SA(b, h) + aoff + m * 2048 + k * 1024); } while (0)
; #define PG8_LDB(dst, b, h) do { _Pragma("unroll") for (int n = 0; n < 2; ++n) _Pragma("unroll") for (int k = 0; k < 2; ++k) dst[n][k] = *(const LAS bf16x8*)(lds + PG8_SB(b, h) + boff + n * 2048 + k * 1024); } while (0)
; #define PG8_WAIT_V(n) asm volatile("s_waitcnt vmcnt(" #n ")" ::: "memory")
; #define PG8_BAR __builtin_amdgcn_s_barrier()
; template <class Epi, bool ALIGN_EPI>
; __device__ __forceinline__ void gemm_phase(LAS unsigned char* lds, const Gemm g, const StaticOrder& S, const Epi& E, const int tid) {
;     ...
;         for (int t = 0; t < nt; t += 2) {
;             const bool last = (t == nt - 2);
;             const char* a1 = cA + (size_t)(t + 1) * kstep;
;             const char* a2 = last ? nA : cA + (size_t)(t + 2) * kstep; const char* b2 = last ? nB : cB + (size_t)(t + 2) * kstep;
;             const char* a3 = a2 + kstep; const char* b3 = b2 + kstep;
;             PG8_LDB(B0, 0, 0); PG8_LDB(B1, 0, 1); PG8_SCHED; PG8_LDA(At, 0, 0); PG8_STAGE(PG8_SA(1, 1), a1 + hA, voffA);
;             PG8_WAIT_V(8); PG8_WAIT_L(0); PG8_BAR; PG8_MMA(0, 0, At, B0); PG8_MMA(0, 1, At, B1); PG8_BAR; PG8_SCHED;
;             PG8_LDA(At, 0, 1); PG8_STAGE(PG8_SB(0, 0), b2, voffB); PG8_STAGE(PG8_SB(0, 1), b2 + hB, voffB); PG8_STAGE(PG8_SA(0, 0), a2, voffA);
;             PG8_WAIT_V(8); PG8_WAIT_L(0); PG8_BAR; PG8_MMA(1, 0, At, B0); PG8_MMA(1, 1, At, B1); PG8_BAR; PG8_SCHED;
;             PG8_LDB(B0, 1, 0); PG8_LDB(B1, 1, 1); PG8_SCHED; PG8_LDA(At, 1, 0); PG8_STAGE(PG8_SA(0, 1), a2 + hA, voffA);
;             PG8_WAIT_V(8); PG8_WAIT_L(0); PG8_BAR; PG8_MMA(0, 0, At, B0); PG8_MMA(0, 1, At, B1); PG8_BAR; PG8_SCHED;
;             PG8_LDA(At, 1, 1); PG8_STAGE(PG8_SB(1, 0), b3, voffB); PG8_STAGE(PG8_SB(1, 1), b3 + hB, voffB); PG8_STAGE(PG8_SA(1, 0), a3, voffA);
;             PG8_WAIT_V(8); PG8_WAIT_L(0); PG8_BAR; PG8_MMA(1, 0, At, B0); PG8_MMA(1, 1, At, B1); PG8_BAR; PG8_SCHED;
	s_setprio 1
	v_mfma_f32_16x16x32_bf16 v[60:63], v[152:155], v[192:195], v[60:63]
	v_mfma_f32_16x16x32_bf16 v[56:59], v[160:163], v[192:195], v[56:59]
	v_mfma_f32_16x16x32_bf16 v[44:47], v[152:155], v[200:203], v[44:47]
	v_mfma_f32_16x16x32_bf16 v[40:43], v[160:163], v[200:203], v[40:43]
	v_mfma_f32_16x16x32_bf16 v[28:31], v[152:155], v[208:211], v[28:31]
	v_mfma_f32_16x16x32_bf16 v[24:27], v[160:163], v[208:211], v[24:27]
	v_mfma_f32_16x16x32_bf16 v[12:15], v[152:155], v[216:219], v[12:15]
	v_mfma_f32_16x16x32_bf16 v[8:11], v[160:163], v[216:219], v[8:11]
	v_mfma_f32_16x16x32_bf16 v[60:63], v[156:159], v[196:199], v[60:63]
	v_mfma_f32_16x16x32_bf16 v[56:59], v[164:167], v[196:199], v[56:59]
	v_mfma_f32_16x16x32_bf16 v[44:47], v[156:159], v[204:207], v[44:47]
	v_mfma_f32_16x16x32_bf16 v[40:43], v[164:167], v[204:207], v[40:43]
	v_mfma_f32_16x16x32_bf16 v[28:31], v[156:159], v[212:215], v[28:31]
	v_mfma_f32_16x16x32_bf16 v[24:27], v[164:167], v[212:215], v[24:27]
	v_mfma_f32_16x16x32_bf16 v[12:15], v[156:159], v[240:243], v[12:15]
	v_mfma_f32_16x16x32_bf16 v[8:11], v[164:167], v[240:243], v[8:11]
	s_setprio 0
	s_setprio 1
	v_mfma_f32_16x16x32_bf16 v[52:55], v[176:179], v[192:195], v[52:55]
	v_mfma_f32_16x16x32_bf16 v[48:51], v[184:187], v[192:195], v[48:51]
	v_mfma_f32_16x16x32_bf16 v[36:39], v[176:179], v[200:203], v[36:39]
	v_mfma_f32_16x16x32_bf16 v[32:35], v[184:187], v[200:203], v[32:35]
	v_mfma_f32_16x16x32_bf16 v[20:23], v[176:179], v[208:211], v[20:23]
	v_mfma_f32_16x16x32_bf16 v[16:19], v[184:187], v[208:211], v[16:19]
	v_mfma_f32_16x16x32_bf16 v[4:7], v[176:179], v[216:219], v[4:7]
	v_mfma_f32_16x16x32_bf16 v[0:3], v[184:187], v[216:219], v[0:3]
	v_mfma_f32_16x16x32_bf16 v[52:55], v[180:183], v[196:199], v[52:55]
	v_mfma_f32_16x16x32_bf16 v[48:51], v[188:191], v[196:199], v[48:51]
	v_mfma_f32_16x16x32_bf16 v[36:39], v[180:183], v[204:207], v[36:39]
	v_mfma_f32_16x16x32_bf16 v[32:35], v[188:191], v[204:207], v[32:35]
	v_mfma_f32_16x16x32_bf16 v[20:23], v[180:183], v[212:215], v[20:23]
	v_mfma_f32_16x16x32_bf16 v[16:19], v[188:191], v[212:215], v[16:19]
	v_mfma_f32_16x16x32_bf16 v[4:7], v[180:183], v[240:243], v[4:7]
	v_mfma_f32_16x16x32_bf16 v[0:3], v[188:191], v[240:243], v[0:3]
	s_setprio 0
	s_barrier
	v_lshl_add_u64 v[142:143], v[142:143], 0, s[80:81]
	v_lshl_add_u64 v[144:145], v[144:145], 0, s[80:81]
	s_mov_b32 s10, s11
	s_cmp_lg_u32 s10, s55
	s_cbranch_scc1 .LBB0_354
.Lq5_last:
	s_add_i32 s11, s10, 2
	s_cmp_eq_u32 s55, s10
	s_cselect_b64 vcc, -1, 0
	v_add_u32_e32 v148, s33, v149
	s_add_i32 s10, 0, 0x14000
	ds_read_b128 v[152:155], v148
	ds_read_b128 v[156:159], v148 offset:1024
	ds_read_b128 v[160:163], v148 offset:2048
	ds_read_b128 v[164:167], v148 offset:3072
	v_add_u32_e32 v148, s10, v149
	ds_read_b128 v[176:179], v148
	ds_read_b128 v[180:183], v148 offset:1024
	ds_read_b128 v[184:187], v148 offset:2048
	ds_read_b128 v[188:191], v148 offset:3072
	v_lshl_add_u64 v[146:147], v[142:143], 0, s[92:93]
	v_cndmask_b32_e32 v147, v147, v139, vcc
	v_cndmask_b32_e32 v146, v146, v138, vcc
	v_cndmask_b32_e32 v221, v145, v141, vcc
	v_cndmask_b32_e32 v220, v144, v140, vcc
	v_lshl_add_u64 v[244:245], v[142:143], 0, v[134:135]
	s_add_i32 m0, s25, 0xc000
	ds_read_b128 v[192:195], v151
	ds_read_b128 v[196:199], v151 offset:1024
	ds_read_b128 v[200:203], v151 offset:2048
	ds_read_b128 v[204:207], v151 offset:3072
	ds_read_b128 v[208:211], v151 offset:4096
	ds_read_b128 v[212:215], v151 offset:5120
	ds_read_b128 v[216:219], v151 offset:6144
	ds_read_b128 v[240:243], v151 offset:7168
	global_load_lds_dwordx4 v[244:245], off
	v_lshl_add_u64 v[244:245], v[142:143], 0, v[136:137]
	s_add_i32 m0, s25, 0xe000
	s_nop 0
	global_load_lds_dwordx4 v[244:245], off
	s_waitcnt vmcnt(8)
	s_waitcnt lgkmcnt(0)
	s_barrier
	s_setprio 1
	v_mfma_f32_16x16x32_bf16 v[124:127], v[152:155], v[192:195], v[124:127]
	v_mfma_f32_16x16x32_bf16 v[120:123], v[160:163], v[192:195], v[120:123]
	v_mfma_f32_16x16x32_bf16 v[108:111], v[152:155], v[200:203], v[108:111]
	v_mfma_f32_16x16x32_bf16 v[104:107], v[160:163], v[200:203], v[104:107]
	v_mfma_f32_16x16x32_bf16 v[92:95], v[152:155], v[208:211], v[92:95]
	v_mfma_f32_16x16x32_bf16 v[88:91], v[160:163], v[208:211], v[88:91]
	v_mfma_f32_16x16x32_bf16 v[76:79], v[152:155], v[216:219], v[76:79]
	v_mfma_f32_16x16x32_bf16 v[72:75], v[160:163], v[216:219], v[72:75]
	v_mfma_f32_16x16x32_bf16 v[124:127], v[156:159], v[196:199], v[124:127]
	v_mfma_f32_16x16x32_bf16 v[120:123], v[164:167], v[196:199], v[120:123]
	v_mfma_f32_16x16x32_bf16 v[108:111], v[156:159], v[204:207], v[108:111]
	v_mfma_f32_16x16x32_bf16 v[104:107], v[164:167], v[204:207], v[104:107]
	v_mfma_f32_16x16x32_bf16 v[92:95], v[156:159], v[212:215], v[92:95]
	v_mfma_f32_16x16x32_bf16 v[88:91], v[164:167], v[212:215], v[88:91]
	v_mfma_f32_16x16x32_bf16 v[76:79], v[156:159], v[240:243], v[76:79]
	v_mfma_f32_16x16x32_bf16 v[72:75], v[164:167], v[240:243], v[72:75]
	s_setprio 0
	s_setprio 1
	v_mfma_f32_16x16x32_bf16 v[116:119], v[176:179], v[192:195], v[116:119]
	v_mfma_f32_16x16x32_bf16 v[112:115], v[184:187], v[192:195], v[112:115]
	v_mfma_f32_16x16x32_bf16 v[100:103], v[176:179], v[200:203], v[100:103]
	v_mfma_f32_16x16x32_bf16 v[96:99], v[184:187], v[200:203], v[96:99]
	v_mfma_f32_16x16x32_bf16 v[84:87], v[176:179], v[208:211], v[84:87]
	v_mfma_f32_16x16x32_bf16 v[80:83], v[184:187], v[208:211], v[80:83]
	v_mfma_f32_16x16x32_bf16 v[68:71], v[176:179], v[216:219], v[68:71]
	v_mfma_f32_16x16x32_bf16 v[64:67], v[184:187], v[216:219], v[64:67]
	v_mfma_f32_16x16x32_bf16 v[116:119], v[180:183], v[196:199], v[116:119]
	v_mfma_f32_16x16x32_bf16 v[112:115], v[188:191], v[196:199], v[112:115]
	v_mfma_f32_16x16x32_bf16 v[100:103], v[180:183], v[204:207], v[100:103]
	v_mfma_f32_16x16x32_bf16 v[96:99], v[188:191], v[204:207], v[96:99]
	v_mfma_f32_16x16x32_bf16 v[84:87], v[180:183], v[212:215], v[84:87]
	v_mfma_f32_16x16x32_bf16 v[80:83], v[188:191], v[212:215], v[80:83]
	v_mfma_f32_16x16x32_bf16 v[68:71], v[180:183], v[240:243], v[68:71]
	v_mfma_f32_16x16x32_bf16 v[64:67], v[188:191], v[240:243], v[64:67]
	s_setprio 0
	s_barrier
; #define PG8_STAGE(bufoff, gbase, voff) do { _Pragma("unroll") for (int _i = 0; _i < 2; ++_i) \
;         __builtin_amdgcn_global_load_lds((const unsigned*)((const char*)(gbase) + (voff)[_i]), (LAS unsigned*)(lds + (bufoff) + ldsw + _i * 8192), 16, 0, 0); } while (0)
; #define PG8_LDA(dst, b, h) do { _Pragma("unroll") for (int m = 0; m < 4; ++m) _Pragma("unroll") for (int k = 0; k < 2; ++k) dst[m][k] = *(const LAS bf16x8*)(lds + PG8_SA(b, h) + aoff + m * 2048 + k * 1024); } while (0)
; #define PG8_LDB(dst, b, h) do { _Pragma("unroll") for (int n = 0; n < 2; ++n) _Pragma("unroll") for (int k = 0; k < 2; ++k) dst[n][k] = *(const LAS bf16x8*)(lds + PG8_SB(b, h) + boff + n * 2048 + k * 1024); } while (0)
; #define PG8_MMA(ai, bj, At, Bt) do { __builtin_amdgcn_s_setprio(1); _Pragma("unroll") for (int k = 0; k < 2; ++k) _Pragma("unroll") for (int m = 0; m < 4; ++m) _Pragma("unroll") for (int n = 0; n < 2; ++n) \
;         acc[ai][bj][m][n] = __builtin_amdgcn_mfma_f32_16x16x32_bf16(Bt[n][k], At[m][k], acc[ai][bj][m][n], 0, 0, 0); __builtin_amdgcn_s_setprio(0); } while (0)
; #define PG8_WAIT_V(n) asm volatile("s_waitcnt vmcnt(" #n ")" ::: "memory")
; #define PG8_WAIT_L(n) asm volatile("s_waitcnt lgkmcnt(" #n ")" ::: "memory")
; #define PG8_BAR __builtin_amdgcn_s_barrier()
; #define PG8_SCHED __builtin_amdgcn_sched_barrier(0)
; template <class Epi, bool ALIGN_EPI>
; __device__ __forceinline__ void gemm_phase(LAS unsigned char* lds, const Gemm g, const StaticOrder& S, const Epi& E, const int tid) {
;     ...
;             PG8_LDA(At, 0, 1); PG8_STAGE(PG8_SB(0, 0), b2, voffB); PG8_STAGE(PG8_SB(0, 1), b2 + hB, voffB); PG8_STAGE(PG8_SA(0, 0), a2, voffA);
;             PG8_WAIT_V(8); PG8_WAIT_L(0); PG8_BAR; PG8_MMA(1, 0, At, B0); PG8_MMA(1, 1, At, B1); PG8_BAR; PG8_SCHED;
;             PG8_LDB(B0, 1, 0); PG8_LDB(B1, 1, 1); PG8_SCHED; PG8_LDA(At, 1, 0); PG8_STAGE(PG8_SA(0, 1), a2 + hA, voffA);
	s_add_i32 s62, s33, s45
	v_lshl_add_u64 v[244:245], v[220:221], 0, v[168:169]
	s_mov_b32 m0, s62
	ds_read_b128 v[192:195], v151 offset:16384
	ds_read_b128 v[196:199], v151 offset:17408
	ds_read_b128 v[200:203], v151 offset:18432
	ds_read_b128 v[204:207], v151 offset:19456
	ds_read_b128 v[208:211], v151 offset:20480
	ds_read_b128 v[212:215], v151 offset:21504
	ds_read_b128 v[216:219], v151 offset:22528
	ds_read_b128 v[240:243], v151 offset:23552
	global_load_lds_dwordx4 v[244:245], off
	v_lshl_add_u64 v[246:247], v[220:221], 0, v[128:129]
	s_add_i32 m0, s62, 0x2000
	v_lshl_add_u64 v[220:221], v[220:221], 0, s[12:13]
	s_add_i32 s10, s10, s45
	global_load_lds_dwordx4 v[246:247], off
	v_lshl_add_u64 v[248:249], v[220:221], 0, v[168:169]
	s_mov_b32 m0, s10
	v_lshl_add_u64 v[220:221], v[220:221], 0, v[128:129]
	global_load_lds_dwordx4 v[248:249], off
	s_add_i32 m0, s10, 0x2000
	v_lshl_add_u64 v[250:251], v[146:147], 0, v[132:133]
	global_load_lds_dwordx4 v[220:221], off
	s_mov_b32 m0, s25
	v_lshl_add_u64 v[252:253], v[146:147], 0, v[130:131]
	global_load_lds_dwordx4 v[250:251], off
	s_mov_b32 m0, s50
	s_nop 0
	global_load_lds_dwordx4 v[252:253], off
	s_waitcnt vmcnt(8)
	s_waitcnt lgkmcnt(0)
	s_barrier
	s_setprio 1
	v_mfma_f32_16x16x32_bf16 v[60:63], v[152:155], v[192:195], v[60:63]
	v_mfma_f32_16x16x32_bf16 v[56:59], v[160:163], v[192:195], v[56:59]
	v_mfma_f32_16x16x32_bf16 v[44:47], v[152:155], v[200:203], v[44:47]
	v_mfma_f32_16x16x32_bf16 v[40:43], v[160:163], v[200:203], v[40:43]
	v_mfma_f32_16x16x32_bf16 v[28:31], v[152:155], v[208:211], v[28:31]
	v_mfma_f32_16x16x32_bf16 v[24:27], v[160:163], v[208:211], v[24:27]
	v_mfma_f32_16x16x32_bf16 v[12:15], v[152:155], v[216:219], v[12:15]
	v_mfma_f32_16x16x32_bf16 v[8:11], v[160:163], v[216:219], v[8:11]
	v_mfma_f32_16x16x32_bf16 v[60:63], v[156:159], v[196:199], v[60:63]
	v_mfma_f32_16x16x32_bf16 v[56:59], v[164:167], v[196:199], v[56:59]
	v_mfma_f32_16x16x32_bf16 v[44:47], v[156:159], v[204:207], v[44:47]
	v_mfma_f32_16x16x32_bf16 v[40:43], v[164:167], v[204:207], v[40:43]
	v_mfma_f32_16x16x32_bf16 v[28:31], v[156:159], v[212:215], v[28:31]
	v_mfma_f32_16x16x32_bf16 v[24:27], v[164:167], v[212:215], v[24:27]
	v_mfma_f32_16x16x32_bf16 v[12:15], v[156:159], v[240:243], v[12:15]
	v_mfma_f32_16x16x32_bf16 v[8:11], v[164:167], v[240:243], v[8:11]
	s_setprio 0
	s_setprio 1
	v_mfma_f32_16x16x32_bf16 v[52:55], v[176:179], v[192:195], v[52:55]
	v_mfma_f32_16x16x32_bf16 v[48:51], v[184:187], v[192:195], v[48:51]
	v_mfma_f32_16x16x32_bf16 v[36:39], v[176:179], v[200:203], v[36:39]
	v_mfma_f32_16x16x32_bf16 v[32:35], v[184:187], v[200:203], v[32:35]
	v_mfma_f32_16x16x32_bf16 v[20:23], v[176:179], v[208:211], v[20:23]
	v_mfma_f32_16x16x32_bf16 v[16:19], v[184:187], v[208:211], v[16:19]
	v_mfma_f32_16x16x32_bf16 v[4:7], v[176:179], v[216:219], v[4:7]
	v_mfma_f32_16x16x32_bf16 v[0:3], v[184:187], v[216:219], v[0:3]
	v_mfma_f32_16x16x32_bf16 v[52:55], v[180:183], v[196:199], v[52:55]
	v_mfma_f32_16x16x32_bf16 v[48:51], v[188:191], v[196:199], v[48:51]
	v_mfma_f32_16x16x32_bf16 v[36:39], v[180:183], v[204:207], v[36:39]
	v_mfma_f32_16x16x32_bf16 v[32:35], v[188:191], v[204:207], v[32:35]
	v_mfma_f32_16x16x32_bf16 v[20:23], v[180:183], v[212:215], v[20:23]
	v_mfma_f32_16x16x32_bf16 v[16:19], v[188:191], v[212:215], v[16:19]
	v_mfma_f32_16x16x32_bf16 v[4:7], v[180:183], v[240:243], v[4:7]
	v_mfma_f32_16x16x32_bf16 v[0:3], v[188:191], v[240:243], v[0:3]
	s_setprio 0
	s_barrier
	s_add_i32 s10, 0, 0x18000
	v_add_u32_e32 v148, s10, v149
	s_add_i32 s62, 0, 0x1c000
	ds_read_b128 v[152:155], v148
	ds_read_b128 v[156:159], v148 offset:1024
	ds_read_b128 v[160:163], v148 offset:2048
	ds_read_b128 v[164:167], v148 offset:3072
	v_add_u32_e32 v148, s62, v149
	ds_read_b128 v[176:179], v148
	ds_read_b128 v[180:183], v148 offset:1024
	ds_read_b128 v[184:187], v148 offset:2048
	ds_read_b128 v[188:191], v148 offset:3072
	v_lshl_add_u64 v[146:147], v[146:147], 0, s[94:95]
	s_mov_b32 m0, s51
	v_lshl_add_u64 v[226:227], v[146:147], 0, v[132:133]
	ds_read_b128 v[192:195], v151 offset:32768
	ds_read_b128 v[196:199], v151 offset:33792
	ds_read_b128 v[200:203], v151 offset:34816
	ds_read_b128 v[204:207], v151 offset:35840
	ds_read_b128 v[208:211], v151 offset:36864
	ds_read_b128 v[212:215], v151 offset:37888
	ds_read_b128 v[216:219], v151 offset:38912
	ds_read_b128 v[240:243], v151 offset:39936
	global_load_lds_dwordx4 v[226:227], off
	v_lshl_add_u64 v[146:147], v[146:147], 0, v[130:131]
	s_mov_b32 m0, s52
	s_nop 0
	global_load_lds_dwordx4 v[146:147], off
	s_waitcnt vmcnt(8)
	s_waitcnt lgkmcnt(0)
	s_barrier
; __device__ __forceinline__ unsigned cvt_pk_bf16(float lo, float hi) { unsigned r; asm volatile("v_cvt_pk_bf16_f32 %0, %1, %2" : "=v"(r) : "v"(lo), "v"(hi)); return r; }
; __device__ __forceinline__ float gelu_tanh(float x) { const float u = 0.7978845608028654f * (x + 0.044715f * x * x * x); return x * fast_rcp(1.0f + fast_exp2(-2.0f * LOG2E * u)); }
; #define PG8_STAGE(bufoff, gbase, voff) do { _Pragma("unroll") for (int _i = 0; _i < 2; ++_i) \
;         __builtin_amdgcn_global_load_lds((const unsigned*)((const char*)(gbase) + (voff)[_i]), (LAS unsigned*)(lds + (bufoff) + ldsw + _i * 8192), 16, 0, 0); } while (0)
; #define PG8_LDA(dst, b, h) do { _Pragma("unroll") for (int m = 0; m < 4; ++m) _Pragma("unroll") for (int k = 0; k < 2; ++k) dst[m][k] = *(const LAS bf16x8*)(lds + PG8_SA(b, h) + aoff + m * 2048 + k * 1024); } while (0)
; #define PG8_WAIT_V(n) asm volatile("s_waitcnt vmcnt(" #n ")" ::: "memory")
; #define PG8_WAIT_L(n) asm volatile("s_waitcnt lgkmcnt(" #n ")" ::: "memory")
;     __device__ __forceinline__ void operator()(const f32x4 (&acc)[2][2][4][2], const Unit& u, int wr, int wc, int fr, int fq) const {
;     ...
;             for (int m = 0; m < 4; ++m) { const int row = row0 + ai * HALF + m * 16; bf16_t* rowp = O + (size_t)row * ldc + col0; const float rs = rsv[ai][m];
; #pragma unroll
;                 for (int bj = 0; bj < 2; ++bj) { f32x4 v0 = acc[ai][bj][m][0] * rs, v1 = acc[ai][bj][m][1] * rs;
;                     if (ACT == 1) {
; #pragma unroll
;                         for (int j = 0; j < 4; ++j) { v0[j] = gelu_tanh(v0[j]); v1[j] = gelu_tanh(v1[j]); } }
;                     u32x4 w; w.x = cvt_pk_bf16(v0[0], v0[1]); w.y = cvt_pk_bf16(v0[2], v0[3]); w.z = cvt_pk_bf16(v1[0], v1[1]); w.w = cvt_pk_bf16(v1[2], v1[3]);
;                     *(u32x4*)(rowp + bj * HALF) = w; } }
; template <class Epi, bool ALIGN_EPI>
; __device__ __forceinline__ void gemm_phase(LAS unsigned char* lds, const Gemm g, const StaticOrder& S, const Epi& E, const int tid) {
;     ...
;             PG8_WAIT_V(8); PG8_WAIT_L(0); PG8_BAR; PG8_MMA(0, 0, At, B0); PG8_MMA(0, 1, At, B1); PG8_BAR; PG8_SCHED;
;             PG8_LDA(At, 1, 1); PG8_STAGE(PG8_SB(1, 0), b3, voffB); PG8_STAGE(PG8_SB(1, 1), b3 + hB, voffB); PG8_STAGE(PG8_SA(1, 0), a3, voffA);
;             PG8_WAIT_V(8); PG8_WAIT_L(0); PG8_BAR; PG8_MMA(1, 0, At, B0); PG8_MMA(1, 1, At, B1); PG8_BAR; PG8_SCHED;
	s_setprio 1
	v_mfma_f32_16x16x32_bf16 v[124:127], v[152:155], v[192:195], v[124:127]
	v_mfma_f32_16x16x32_bf16 v[120:123], v[160:163], v[192:195], v[120:123]
	v_mfma_f32_16x16x32_bf16 v[108:111], v[152:155], v[200:203], v[108:111]
	v_mfma_f32_16x16x32_bf16 v[104:107], v[160:163], v[200:203], v[104:107]
	v_mfma_f32_16x16x32_bf16 v[92:95], v[152:155], v[208:211], v[92:95]
	v_mfma_f32_16x16x32_bf16 v[88:91], v[160:163], v[208:211], v[88:91]
	v_mfma_f32_16x16x32_bf16 v[76:79], v[152:155], v[216:219], v[76:79]
	v_mfma_f32_16x16x32_bf16 v[72:75], v[160:163], v[216:219], v[72:75]
	v_mfma_f32_16x16x32_bf16 v[124:127], v[156:159], v[196:199], v[124:127]
	v_mfma_f32_16x16x32_bf16 v[120:123], v[164:167], v[196:199], v[120:123]
	v_mfma_f32_16x16x32_bf16 v[108:111], v[156:159], v[204:207], v[108:111]
	v_mfma_f32_16x16x32_bf16 v[104:107], v[164:167], v[204:207], v[104:107]
	v_mfma_f32_16x16x32_bf16 v[92:95], v[156:159], v[212:215], v[92:95]
	v_mfma_f32_16x16x32_bf16 v[88:91], v[164:167], v[212:215], v[88:91]
	v_mfma_f32_16x16x32_bf16 v[76:79], v[156:159], v[240:243], v[76:79]
	v_mfma_f32_16x16x32_bf16 v[72:75], v[164:167], v[240:243], v[72:75]
	s_setprio 0
	s_setprio 1
	v_mfma_f32_16x16x32_bf16 v[116:119], v[176:179], v[192:195], v[116:119]
	v_mfma_f32_16x16x32_bf16 v[112:115], v[184:187], v[192:195], v[112:115]
	v_mfma_f32_16x16x32_bf16 v[100:103], v[176:179], v[200:203], v[100:103]
	v_mfma_f32_16x16x32_bf16 v[96:99], v[184:187], v[200:203], v[96:99]
	v_mfma_f32_16x16x32_bf16 v[84:87], v[176:179], v[208:211], v[84:87]
	v_mfma_f32_16x16x32_bf16 v[80:83], v[184:187], v[208:211], v[80:83]
	v_mfma_f32_16x16x32_bf16 v[68:71], v[176:179], v[216:219], v[68:71]
	v_mfma_f32_16x16x32_bf16 v[64:67], v[184:187], v[216:219], v[64:67]
	v_mfma_f32_16x16x32_bf16 v[116:119], v[180:183], v[196:199], v[116:119]
	v_mfma_f32_16x16x32_bf16 v[112:115], v[188:191], v[196:199], v[112:115]
	v_mfma_f32_16x16x32_bf16 v[100:103], v[180:183], v[204:207], v[100:103]
	v_mfma_f32_16x16x32_bf16 v[96:99], v[188:191], v[204:207], v[96:99]
	v_mfma_f32_16x16x32_bf16 v[84:87], v[180:183], v[212:215], v[84:87]
	v_mfma_f32_16x16x32_bf16 v[80:83], v[188:191], v[212:215], v[80:83]
	v_mfma_f32_16x16x32_bf16 v[68:71], v[180:183], v[240:243], v[68:71]
	v_mfma_f32_16x16x32_bf16 v[64:67], v[188:191], v[240:243], v[64:67]
	s_setprio 0
	s_barrier
	s_add_i32 s10, s10, s45
	v_lshl_add_u64 v[146:147], v[244:245], 0, s[92:93]
	s_mov_b32 m0, s10
	ds_read_b128 v[192:195], v151 offset:49152
	ds_read_b128 v[196:199], v151 offset:50176
	ds_read_b128 v[200:203], v151 offset:51200
	ds_read_b128 v[204:207], v151 offset:52224
	ds_read_b128 v[208:211], v151 offset:53248
	ds_read_b128 v[212:215], v151 offset:54272
	ds_read_b128 v[216:219], v151 offset:55296
	ds_read_b128 v[240:243], v151 offset:56320
	global_load_lds_dwordx4 v[146:147], off
	v_lshl_add_u64 v[146:147], v[246:247], 0, s[92:93]
	s_add_i32 m0, s10, 0x2000
	s_add_i32 s10, s62, s45
	global_load_lds_dwordx4 v[146:147], off
	v_lshl_add_u64 v[146:147], v[248:249], 0, s[92:93]
	s_mov_b32 m0, s10
	s_nop 0
	global_load_lds_dwordx4 v[146:147], off
	v_lshl_add_u64 v[146:147], v[220:221], 0, s[92:93]
	s_add_i32 m0, s10, 0x2000
	s_nop 0
	global_load_lds_dwordx4 v[146:147], off
	v_lshl_add_u64 v[146:147], v[250:251], 0, s[92:93]
	s_mov_b32 m0, s53
	s_nop 0
	global_load_lds_dwordx4 v[146:147], off
	v_lshl_add_u64 v[146:147], v[252:253], 0, s[92:93]
	s_mov_b32 m0, s54
	s_nop 0
	global_load_lds_dwordx4 v[146:147], off
	s_waitcnt vmcnt(8)
	s_waitcnt lgkmcnt(0)
	s_barrier
	s_setprio 1
	v_mfma_f32_16x16x32_bf16 v[60:63], v[152:155], v[192:195], v[60:63]
	v_lshrrev_b32_e32 v171, 8, v170
	v_and_b32_e32 v234, 15, v170
	v_lshl_add_u32 v171, v171, 6, v234
	s_lshl_b32 s98, s61, 8
	v_add_u32_e32 v171, s98, v171
	v_mfma_f32_16x16x32_bf16 v[56:59], v[160:163], v[192:195], v[56:59]
	v_mul_lo_u32 v171, v171, s28
	v_bfe_u32 v234, v170, 6, 2
	v_bfe_u32 v224, v170, 4, 2
	v_lshlrev_b32_e32 v234, 5, v234
	v_lshl_or_b32 v234, v224, 3, v234
	v_mfma_f32_16x16x32_bf16 v[44:47], v[152:155], v[200:203], v[44:47]
	s_lshl_b32 s98, s60, 8
	v_add_u32_e32 v234, s98, v234
	v_add_lshl_u32 v232, v171, v234, 1
	v_mov_b32_e32 v233, 0
	v_lshl_add_u64 v[232:233], v[232:233], 0, s[30:31]
	v_mfma_f32_16x16x32_bf16 v[40:43], v[160:163], v[200:203], v[40:43]
	s_lshl_b32 s98, s28, 5
	s_mov_b32 s99, 0
	v_mul_f32_e32 v124, v172, v124
	v_mul_f32_e32 v125, v172, v125
	v_mul_f32_e32 v126, v172, v126
	v_mfma_f32_16x16x32_bf16 v[28:31], v[152:155], v[208:211], v[28:31]
	v_mul_f32_e32 v127, v172, v127
	v_mul_f32_e32 v120, v172, v120
	v_mul_f32_e32 v121, v172, v121
	v_mul_f32_e32 v122, v172, v122
	v_mul_f32_e32 v123, v172, v123
	v_mfma_f32_16x16x32_bf16 v[24:27], v[160:163], v[208:211], v[24:27]
	v_cvt_pk_bf16_f32 v124, v124, v125
	v_cvt_pk_bf16_f32 v125, v126, v127
	v_cvt_pk_bf16_f32 v126, v120, v121
	v_cvt_pk_bf16_f32 v127, v122, v123
	global_store_dwordx4 v[232:233], v[124:127], off
	v_mfma_f32_16x16x32_bf16 v[12:15], v[152:155], v[216:219], v[12:15]
	v_mul_f32_e32 v116, v172, v116
	v_mul_f32_e32 v117, v172, v117
	v_mul_f32_e32 v118, v172, v118
	v_mul_f32_e32 v119, v172, v119
	v_mul_f32_e32 v112, v172, v112
	v_mfma_f32_16x16x32_bf16 v[8:11], v[160:163], v[216:219], v[8:11]
	v_mul_f32_e32 v113, v172, v113
	v_mul_f32_e32 v114, v172, v114
	v_mul_f32_e32 v115, v172, v115
; __device__ __forceinline__ unsigned cvt_pk_bf16(float lo, float hi) { unsigned r; asm volatile("v_cvt_pk_bf16_f32 %0, %1, %2" : "=v"(r) : "v"(lo), "v"(hi)); return r; }
; __device__ __forceinline__ float gelu_tanh(float x) { const float u = 0.7978845608028654f * (x + 0.044715f * x * x * x); return x * fast_rcp(1.0f + fast_exp2(-2.0f * LOG2E * u)); }
; #define PG8_MMA(ai, bj, At, Bt) do { __builtin_amdgcn_s_setprio(1); _Pragma("unroll") for (int k = 0; k < 2; ++k) _Pragma("unroll") for (int m = 0; m < 4; ++m) _Pragma("unroll") for (int n = 0; n < 2; ++n) \
;         acc[ai][bj][m][n] = __builtin_amdgcn_mfma_f32_16x16x32_bf16(Bt[n][k], At[m][k], acc[ai][bj][m][n], 0, 0, 0); __builtin_amdgcn_s_setprio(0); } while (0)
; #define PG8_WAIT_V(n) asm volatile("s_waitcnt vmcnt(" #n ")" ::: "memory")
; #define PG8_WAIT_L(n) asm volatile("s_waitcnt lgkmcnt(" #n ")" ::: "memory")
; #define PG8_BAR __builtin_amdgcn_s_barrier()
; #define PG8_SCHED __builtin_amdgcn_sched_barrier(0)
;     __device__ __forceinline__ void operator()(const f32x4 (&acc)[2][2][4][2], const Unit& u, int wr, int wc, int fr, int fq) const {
;     ...
;             for (int m = 0; m < 4; ++m) { const int row = row0 + ai * HALF + m * 16; bf16_t* rowp = O + (size_t)row * ldc + col0; const float rs = rsv[ai][m];
; #pragma unroll
;                 for (int bj = 0; bj < 2; ++bj) { f32x4 v0 = acc[ai][bj][m][0] * rs, v1 = acc[ai][bj][m][1] * rs;
;                     if (ACT == 1) {
; #pragma unroll
;                         for (int j = 0; j < 4; ++j) { v0[j] = gelu_tanh(v0[j]); v1[j] = gelu_tanh(v1[j]); } }
;                     u32x4 w; w.x = cvt_pk_bf16(v0[0], v0[1]); w.y = cvt_pk_bf16(v0[2], v0[3]); w.z = cvt_pk_bf16(v1[0], v1[1]); w.w = cvt_pk_bf16(v1[2], v1[3]);
;                     *(u32x4*)(rowp + bj * HALF) = w; } }
; template <class Epi, bool ALIGN_EPI>
; __device__ __forceinline__ void gemm_phase(LAS unsigned char* lds, const Gemm g, const StaticOrder& S, const Epi& E, const int tid) {
;     ...
;             PG8_WAIT_V(8); PG8_WAIT_L(0); PG8_BAR; PG8_MMA(1, 0, At, B0); PG8_MMA(1, 1, At, B1); PG8_BAR; PG8_SCHED;
;         }
;         if constexpr (ALIGN_EPI) { if (wr == 0) PG8_BAR; }
;         { int t2 = tid; asm volatile("" : "+v"(t2)); const int l2 = t2 & 63, w2 = __builtin_amdgcn_readfirstlane(t2 >> 6); E(acc, cur, w2 >> 2, w2 & 3, l2 & 15, l2 >> 4); }
;         if (!has_next) break;
	v_cvt_pk_bf16_f32 v116, v116, v117
	v_cvt_pk_bf16_f32 v117, v118, v119
	v_mfma_f32_16x16x32_bf16 v[60:63], v[156:159], v[196:199], v[60:63]
	v_cvt_pk_bf16_f32 v118, v112, v113
	v_cvt_pk_bf16_f32 v119, v114, v115
	global_store_dwordx4 v[232:233], v[116:119], off offset:256
	v_lshl_add_u64 v[232:233], v[232:233], 0, s[98:99]
	v_mul_f32_e32 v108, v173, v108
	v_mfma_f32_16x16x32_bf16 v[56:59], v[164:167], v[196:199], v[56:59]
	v_mul_f32_e32 v109, v173, v109
	v_mul_f32_e32 v110, v173, v110
	v_mul_f32_e32 v111, v173, v111
	v_mul_f32_e32 v104, v173, v104
	v_mul_f32_e32 v105, v173, v105
	v_mfma_f32_16x16x32_bf16 v[44:47], v[156:159], v[204:207], v[44:47]
	v_mul_f32_e32 v106, v173, v106
	v_mul_f32_e32 v107, v173, v107
	v_cvt_pk_bf16_f32 v108, v108, v109
	v_cvt_pk_bf16_f32 v109, v110, v111
	v_cvt_pk_bf16_f32 v110, v104, v105
	v_mfma_f32_16x16x32_bf16 v[40:43], v[164:167], v[204:207], v[40:43]
	v_cvt_pk_bf16_f32 v111, v106, v107
	global_store_dwordx4 v[232:233], v[108:111], off
	v_mul_f32_e32 v100, v173, v100
	v_mul_f32_e32 v101, v173, v101
	v_mul_f32_e32 v102, v173, v102
	v_mfma_f32_16x16x32_bf16 v[28:31], v[156:159], v[212:215], v[28:31]
	v_mul_f32_e32 v103, v173, v103
	v_mul_f32_e32 v96, v173, v96
	v_mul_f32_e32 v97, v173, v97
	v_mul_f32_e32 v98, v173, v98
	v_mul_f32_e32 v99, v173, v99
	v_mfma_f32_16x16x32_bf16 v[24:27], v[164:167], v[212:215], v[24:27]
	v_cvt_pk_bf16_f32 v100, v100, v101
	v_cvt_pk_bf16_f32 v101, v102, v103
	v_cvt_pk_bf16_f32 v102, v96, v97
	v_cvt_pk_bf16_f32 v103, v98, v99
	global_store_dwordx4 v[232:233], v[100:103], off offset:256
	v_mfma_f32_16x16x32_bf16 v[12:15], v[156:159], v[240:243], v[12:15]
	v_lshl_add_u64 v[232:233], v[232:233], 0, s[98:99]
	v_mul_f32_e32 v92, v236, v92
	v_mul_f32_e32 v93, v236, v93
	v_mul_f32_e32 v94, v236, v94
	v_mul_f32_e32 v95, v236, v95
	v_mfma_f32_16x16x32_bf16 v[8:11], v[164:167], v[240:243], v[8:11]
	v_mul_f32_e32 v88, v236, v88
	v_mul_f32_e32 v89, v236, v89
	v_mul_f32_e32 v90, v236, v90
	v_mul_f32_e32 v91, v236, v91
	v_cvt_pk_bf16_f32 v92, v92, v93
	s_setprio 0
	s_setprio 1
	v_mfma_f32_16x16x32_bf16 v[52:55], v[176:179], v[192:195], v[52:55]
	v_cvt_pk_bf16_f32 v93, v94, v95
	v_cvt_pk_bf16_f32 v94, v88, v89
	v_cvt_pk_bf16_f32 v95, v90, v91
	global_store_dwordx4 v[232:233], v[92:95], off
	v_mul_f32_e32 v84, v236, v84
	v_mfma_f32_16x16x32_bf16 v[48:51], v[184:187], v[192:195], v[48:51]
	v_mul_f32_e32 v85, v236, v85
	v_mul_f32_e32 v86, v236, v86
	v_mul_f32_e32 v87, v236, v87
	v_mul_f32_e32 v80, v236, v80
	v_mul_f32_e32 v81, v236, v81
	v_mfma_f32_16x16x32_bf16 v[36:39], v[176:179], v[200:203], v[36:39]
	v_mul_f32_e32 v82, v236, v82
	v_mul_f32_e32 v83, v236, v83
	v_cvt_pk_bf16_f32 v84, v84, v85
	v_cvt_pk_bf16_f32 v85, v86, v87
	v_cvt_pk_bf16_f32 v86, v80, v81
	v_mfma_f32_16x16x32_bf16 v[32:35], v[184:187], v[200:203], v[32:35]
	v_cvt_pk_bf16_f32 v87, v82, v83
	global_store_dwordx4 v[232:233], v[84:87], off offset:256
	v_lshl_add_u64 v[232:233], v[232:233], 0, s[98:99]
	v_mul_f32_e32 v76, v237, v76
	v_mul_f32_e32 v77, v237, v77
	v_mfma_f32_16x16x32_bf16 v[20:23], v[176:179], v[208:211], v[20:23]
	v_mul_f32_e32 v78, v237, v78
	v_mul_f32_e32 v79, v237, v79
	v_mul_f32_e32 v72, v237, v72
	v_mul_f32_e32 v73, v237, v73
	v_mul_f32_e32 v74, v237, v74
	v_mfma_f32_16x16x32_bf16 v[16:19], v[184:187], v[208:211], v[16:19]
	v_mul_f32_e32 v75, v237, v75
	v_cvt_pk_bf16_f32 v76, v76, v77
	v_cvt_pk_bf16_f32 v77, v78, v79
	v_cvt_pk_bf16_f32 v78, v72, v73
	v_cvt_pk_bf16_f32 v79, v74, v75
	v_mfma_f32_16x16x32_bf16 v[4:7], v[176:179], v[216:219], v[4:7]
	global_store_dwordx4 v[232:233], v[76:79], off
	v_mul_f32_e32 v68, v237, v68
	v_mul_f32_e32 v69, v237, v69
	v_mul_f32_e32 v70, v237, v70
	v_mul_f32_e32 v71, v237, v71
	v_mfma_f32_16x16x32_bf16 v[0:3], v[184:187], v[216:219], v[0:3]
	v_mul_f32_e32 v64, v237, v64
	v_mul_f32_e32 v65, v237, v65
	v_mul_f32_e32 v66, v237, v66
	v_mul_f32_e32 v67, v237, v67
	v_cvt_pk_bf16_f32 v68, v68, v69
	v_mfma_f32_16x16x32_bf16 v[52:55], v[180:183], v[196:199], v[52:55]
	v_cvt_pk_bf16_f32 v69, v70, v71
	v_cvt_pk_bf16_f32 v70, v64, v65
	v_cvt_pk_bf16_f32 v71, v66, v67
	global_store_dwordx4 v[232:233], v[68:71], off offset:256
	v_lshl_add_u64 v[232:233], v[232:233], 0, s[98:99]
	v_mfma_f32_16x16x32_bf16 v[48:51], v[188:191], v[196:199], v[48:51]
	v_lshl_add_u64 v[232:233], v[232:233], 0, s[98:99]
	v_lshl_add_u64 v[232:233], v[232:233], 0, s[98:99]
	v_lshl_add_u64 v[232:233], v[232:233], 0, s[98:99]
	v_lshl_add_u64 v[232:233], v[232:233], 0, s[98:99]
	v_mfma_f32_16x16x32_bf16 v[36:39], v[180:183], v[204:207], v[36:39]
	v_mfma_f32_16x16x32_bf16 v[32:35], v[188:191], v[204:207], v[32:35]
	v_mfma_f32_16x16x32_bf16 v[20:23], v[180:183], v[212:215], v[20:23]
	v_mfma_f32_16x16x32_bf16 v[16:19], v[188:191], v[212:215], v[16:19]
	v_mfma_f32_16x16x32_bf16 v[4:7], v[180:183], v[240:243], v[4:7]
	v_mfma_f32_16x16x32_bf16 v[0:3], v[188:191], v[240:243], v[0:3]
	s_setprio 0
	s_barrier
	v_lshl_add_u64 v[142:143], v[142:143], 0, s[80:81]
	v_lshl_add_u64 v[144:145], v[144:145], 0, s[80:81]
	s_and_b64 vcc, exec, s[8:9]
	s_cbranch_vccnz .Lq5_notdefer
	s_cmp_lg_u32 s59, s61
	s_cbranch_scc1 .Lq5_notdefer
	s_mov_b32 s101, 1
	s_mov_b32 s60, s58
	s_mov_b32 s61, s59
	v_mov_b64_e32 v[144:145], v[140:141]
	v_mov_b64_e32 v[142:143], v[138:139]
	s_branch .LBB0_346

; #define PG8_STAGE(bufoff, gbase, voff) do { _Pragma("unroll") for (int _i = 0; _i < 2; ++_i) \
;         __builtin_amdgcn_global_load_lds((const unsigned*)((const char*)(gbase) + (voff)[_i]), (LAS unsigned*)(lds + (bufoff) + ldsw + _i * 8192), 16, 0, 0); } while (0)
; #define PG8_LDA(dst, b, h) do { _Pragma("unroll") for (int m = 0; m < 4; ++m) _Pragma("unroll") for (int k = 0; k < 2; ++k) dst[m][k] = *(const LAS bf16x8*)(lds + PG8_SA(b, h) + aoff + m * 2048 + k * 1024); } while (0)
; #define PG8_LDB(dst, b, h) do { _Pragma("unroll") for (int n = 0; n < 2; ++n) _Pragma("unroll") for (int k = 0; k < 2; ++k) dst[n][k] = *(const LAS bf16x8*)(lds + PG8_SB(b, h) + boff + n * 2048 + k * 1024); } while (0)
; #define PG8_MMA(ai, bj, At, Bt) do { __builtin_amdgcn_s_setprio(1); _Pragma("unroll") for (int k = 0; k < 2; ++k) _Pragma("unroll") for (int m = 0; m < 4; ++m) _Pragma("unroll") for (int n = 0; n < 2; ++n) \
;         acc[ai][bj][m][n] = __builtin_amdgcn_mfma_f32_16x16x32_bf16(Bt[n][k], At[m][k], acc[ai][bj][m][n], 0, 0, 0); __builtin_amdgcn_s_setprio(0); } while (0)
; #define PG8_WAIT_V(n) asm volatile("s_waitcnt vmcnt(" #n ")" ::: "memory")
; #define PG8_WAIT_L(n) asm volatile("s_waitcnt lgkmcnt(" #n ")" ::: "memory")
; #define PG8_BAR __builtin_amdgcn_s_barrier()
; #define PG8_SCHED __builtin_amdgcn_sched_barrier(0)
; template <class Epi, bool ALIGN_EPI>
; __device__ __forceinline__ void gemm_phase(LAS unsigned char* lds, const Gemm g, const StaticOrder& S, const Epi& E, const int tid) {
;     ...
;         const bool has_next = S.next(ui + 1, nxt);
;         const char* nA = has_next ? (const char*)g.A + (size_t)nxt.pm * tA + (size_t)nxt.pn * g.apn * 2 : cA; const char* nB = has_next ? (const char*)g.Bt + (size_t)nxt.pn * tB : cB;
;         for (int t = 0; t < nt; t += 2) {
;             const bool last = (t == nt - 2);
;             const char* a1 = cA + (size_t)(t + 1) * kstep;
;             const char* a2 = last ? nA : cA + (size_t)(t + 2) * kstep; const char* b2 = last ? nB : cB + (size_t)(t + 2) * kstep;
;             const char* a3 = a2 + kstep; const char* b3 = b2 + kstep;
;             PG8_LDB(B0, 0, 0); PG8_LDB(B1, 0, 1); PG8_SCHED; PG8_LDA(At, 0, 0); PG8_STAGE(PG8_SA(1, 1), a1 + hA, voffA);
;             PG8_WAIT_V(8); PG8_WAIT_L(0); PG8_BAR; PG8_MMA(0, 0, At, B0); PG8_MMA(0, 1, At, B1); PG8_BAR; PG8_SCHED;
.LBB0_378:
	s_ashr_i32 s17, s16, 31
	s_lshl_b64 s[22:23], s[16:17], 17
	s_add_u32 s22, s4, s22
	s_addc_u32 s23, s5, s23
	s_and_b64 s[26:27], s[8:9], exec
	s_cselect_b32 s17, s23, s35
	s_cselect_b32 s59, s22, s34
	s_ashr_i32 s15, s14, 31
	s_lshl_b64 s[26:27], s[14:15], 17
	s_add_u32 s26, s7, s26
	s_addc_u32 s27, s25, s27
	s_and_b64 s[36:37], s[8:9], exec
	s_cselect_b32 s15, s27, s31
	s_cselect_b32 s60, s26, s30
	s_mov_b32 s40, 0
	s_mov_b64 s[36:37], -1
	s_mov_b64 s[38:39], 0
	s_add_u32 s41, s34, s40
	s_addc_u32 s46, s35, 0
	s_add_u32 s44, s41, 0x100
	s_addc_u32 s45, s46, 0
	s_and_b64 s[42:43], s[38:39], exec
	s_cselect_b32 s43, s17, s45
	s_cselect_b32 s42, s59, s44
	s_add_u32 s40, s30, s40
	s_addc_u32 s44, s31, 0
	s_add_u32 s40, s40, 0x100
	s_addc_u32 s44, s44, 0
	s_and_b64 s[38:39], s[38:39], exec
	s_cselect_b32 s45, s15, s44
	s_cselect_b32 s44, s60, s40
	s_add_i32 s39, 0, 0x14000
	s_add_u32 s48, s41, 0x10080
	s_addc_u32 s49, s46, 0
	s_add_i32 s68, s33, s50
	s_add_i32 m0, s51, 0xc000
	s_add_i32 s71, s51, 0xe000
	s_add_i32 s65, s68, 0x2000
	v_add_u32_e32 v138, s33, v141
	s_add_u32 s46, s44, 0x10000
	ds_read_b128 v[134:137], v138
	ds_read_b128 v[146:149], v138 offset:1024
	ds_read_b128 v[150:153], v138 offset:2048
	ds_read_b128 v[154:157], v138 offset:3072
	v_add_u32_e32 v138, s39, v141
	s_addc_u32 s47, s45, 0
	s_add_i32 s67, s39, s50
	ds_read_b128 v[158:161], v138
	ds_read_b128 v[162:165], v138 offset:1024
	ds_read_b128 v[174:177], v138 offset:2048
	ds_read_b128 v[178:181], v138 offset:3072
	s_add_i32 s66, s67, 0x2000
	s_add_i32 s64, 0, 0x18000
	s_add_i32 s63, 0, 0x1c000
	s_add_u32 s40, s42, 0x10000
	s_addc_u32 s41, s43, 0
	s_add_i32 s62, s64, s50
	s_add_i32 s61, s62, 0x2000
	s_add_u32 s38, s44, 0x10080
	s_addc_u32 s39, s45, 0
	s_add_i32 s70, s63, s50
	s_add_i32 s69, s70, 0x2000
	v_lshl_add_u64 v[138:139], s[48:49], 0, v[128:129]
	ds_read_b128 v[182:185], v145
	ds_read_b128 v[186:189], v145 offset:1024
	ds_read_b128 v[190:193], v145 offset:2048
	ds_read_b128 v[194:197], v145 offset:3072
	ds_read_b128 v[198:201], v145 offset:4096
	ds_read_b128 v[202:205], v145 offset:5120
	ds_read_b128 v[206:209], v145 offset:6144
	ds_read_b128 v[210:213], v145 offset:7168
	global_load_lds_dwordx4 v[138:139], off
	v_lshl_add_u64 v[138:139], s[48:49], 0, v[130:131]
	s_mov_b32 m0, s71
	s_nop 0
	global_load_lds_dwordx4 v[138:139], off
	s_waitcnt vmcnt(8)
	s_waitcnt lgkmcnt(0)
	s_barrier
	s_setprio 1
	v_mfma_f32_16x16x32_bf16 v[124:127], v[134:137], v[182:185], 0
	v_mfma_f32_16x16x32_bf16 v[120:123], v[150:153], v[182:185], 0
	v_mfma_f32_16x16x32_bf16 v[108:111], v[134:137], v[190:193], 0
	v_mfma_f32_16x16x32_bf16 v[104:107], v[150:153], v[190:193], 0
	v_mfma_f32_16x16x32_bf16 v[92:95], v[134:137], v[198:201], 0
	v_mfma_f32_16x16x32_bf16 v[88:91], v[150:153], v[198:201], 0
	v_mfma_f32_16x16x32_bf16 v[76:79], v[134:137], v[206:209], 0
	v_mfma_f32_16x16x32_bf16 v[72:75], v[150:153], v[206:209], 0
	v_mfma_f32_16x16x32_bf16 v[124:127], v[146:149], v[186:189], v[124:127]
	v_mfma_f32_16x16x32_bf16 v[120:123], v[154:157], v[186:189], v[120:123]
	v_mfma_f32_16x16x32_bf16 v[108:111], v[146:149], v[194:197], v[108:111]
	v_mfma_f32_16x16x32_bf16 v[104:107], v[154:157], v[194:197], v[104:107]
	v_mfma_f32_16x16x32_bf16 v[92:95], v[146:149], v[202:205], v[92:95]
	v_mfma_f32_16x16x32_bf16 v[88:91], v[154:157], v[202:205], v[88:91]
	v_mfma_f32_16x16x32_bf16 v[76:79], v[146:149], v[210:213], v[76:79]
	v_mfma_f32_16x16x32_bf16 v[72:75], v[154:157], v[210:213], v[72:75]
	s_setprio 0
	s_setprio 1
	v_mfma_f32_16x16x32_bf16 v[116:119], v[158:161], v[182:185], 0
	v_mfma_f32_16x16x32_bf16 v[112:115], v[174:177], v[182:185], 0
	v_mfma_f32_16x16x32_bf16 v[100:103], v[158:161], v[190:193], 0
	v_mfma_f32_16x16x32_bf16 v[96:99], v[174:177], v[190:193], 0
	v_mfma_f32_16x16x32_bf16 v[84:87], v[158:161], v[198:201], 0
	v_mfma_f32_16x16x32_bf16 v[80:83], v[174:177], v[198:201], 0
	v_mfma_f32_16x16x32_bf16 v[68:71], v[158:161], v[206:209], 0
	v_mfma_f32_16x16x32_bf16 v[64:67], v[174:177], v[206:209], 0
	v_mfma_f32_16x16x32_bf16 v[116:119], v[162:165], v[186:189], v[116:119]
	v_mfma_f32_16x16x32_bf16 v[112:115], v[178:181], v[186:189], v[112:115]
	v_mfma_f32_16x16x32_bf16 v[100:103], v[162:165], v[194:197], v[100:103]
	v_mfma_f32_16x16x32_bf16 v[96:99], v[178:181], v[194:197], v[96:99]
	v_mfma_f32_16x16x32_bf16 v[84:87], v[162:165], v[202:205], v[84:87]
	v_mfma_f32_16x16x32_bf16 v[80:83], v[178:181], v[202:205], v[80:83]
	v_mfma_f32_16x16x32_bf16 v[68:71], v[162:165], v[210:213], v[68:71]
	v_mfma_f32_16x16x32_bf16 v[64:67], v[178:181], v[210:213], v[64:67]
	s_setprio 0
	s_barrier
	s_mov_b32 m0, s68
	v_lshl_add_u64 v[138:139], s[44:45], 0, v[168:169]
	ds_read_b128 v[182:185], v145 offset:16384
	ds_read_b128 v[186:189], v145 offset:17408
	ds_read_b128 v[190:193], v145 offset:18432
	ds_read_b128 v[194:197], v145 offset:19456
	ds_read_b128 v[198:201], v145 offset:20480
	ds_read_b128 v[202:205], v145 offset:21504
	ds_read_b128 v[206:209], v145 offset:22528
	ds_read_b128 v[210:213], v145 offset:23552
	global_load_lds_dwordx4 v[138:139], off
	v_lshl_add_u64 v[142:143], s[44:45], 0, v[132:133]
	s_mov_b32 m0, s65
	v_lshl_add_u64 v[166:167], s[46:47], 0, v[168:169]
	global_load_lds_dwordx4 v[142:143], off
	s_mov_b32 m0, s67
	v_lshl_add_u64 v[214:215], s[42:43], 0, v[130:131]
	global_load_lds_dwordx4 v[166:167], off
	v_lshl_add_u64 v[166:167], s[46:47], 0, v[132:133]
	s_mov_b32 m0, s66
	s_nop 0
	global_load_lds_dwordx4 v[166:167], off
	v_lshl_add_u64 v[166:167], s[42:43], 0, v[128:129]
	s_mov_b32 m0, s51
	s_nop 0
	global_load_lds_dwordx4 v[166:167], off
	s_mov_b32 m0, s52
	s_nop 0
	global_load_lds_dwordx4 v[214:215], off
	s_waitcnt vmcnt(8)
	s_waitcnt lgkmcnt(0)
	s_barrier
; #define PG8_STAGE(bufoff, gbase, voff) do { _Pragma("unroll") for (int _i = 0; _i < 2; ++_i) \
;         __builtin_amdgcn_global_load_lds((const unsigned*)((const char*)(gbase) + (voff)[_i]), (LAS unsigned*)(lds + (bufoff) + ldsw + _i * 8192), 16, 0, 0); } while (0)
; #define PG8_LDA(dst, b, h) do { _Pragma("unroll") for (int m = 0; m < 4; ++m) _Pragma("unroll") for (int k = 0; k < 2; ++k) dst[m][k] = *(const LAS bf16x8*)(lds + PG8_SA(b, h) + aoff + m * 2048 + k * 1024); } while (0)
; #define PG8_LDB(dst, b, h) do { _Pragma("unroll") for (int n = 0; n < 2; ++n) _Pragma("unroll") for (int k = 0; k < 2; ++k) dst[n][k] = *(const LAS bf16x8*)(lds + PG8_SB(b, h) + boff + n * 2048 + k * 1024); } while (0)
; #define PG8_MMA(ai, bj, At, Bt) do { __builtin_amdgcn_s_setprio(1); _Pragma("unroll") for (int k = 0; k < 2; ++k) _Pragma("unroll") for (int m = 0; m < 4; ++m) _Pragma("unroll") for (int n = 0; n < 2; ++n) \
;         acc[ai][bj][m][n] = __builtin_amdgcn_mfma_f32_16x16x32_bf16(Bt[n][k], At[m][k], acc[ai][bj][m][n], 0, 0, 0); __builtin_amdgcn_s_setprio(0); } while (0)
; #define PG8_WAIT_V(n) asm volatile("s_waitcnt vmcnt(" #n ")" ::: "memory")
; #define PG8_WAIT_L(n) asm volatile("s_waitcnt lgkmcnt(" #n ")" ::: "memory")
; #define PG8_BAR __builtin_amdgcn_s_barrier()
; #define PG8_SCHED __builtin_amdgcn_sched_barrier(0)
; template <class Epi, bool ALIGN_EPI>
; __device__ __forceinline__ void gemm_phase(LAS unsigned char* lds, const Gemm g, const StaticOrder& S, const Epi& E, const int tid) {
;     ...
;             PG8_WAIT_V(8); PG8_WAIT_L(0); PG8_BAR; PG8_MMA(0, 0, At, B0); PG8_MMA(0, 1, At, B1); PG8_BAR; PG8_SCHED;
;             PG8_LDA(At, 0, 1); PG8_STAGE(PG8_SB(0, 0), b2, voffB); PG8_STAGE(PG8_SB(0, 1), b2 + hB, voffB); PG8_STAGE(PG8_SA(0, 0), a2, voffA);
;             PG8_WAIT_V(8); PG8_WAIT_L(0); PG8_BAR; PG8_MMA(1, 0, At, B0); PG8_MMA(1, 1, At, B1); PG8_BAR; PG8_SCHED;
;             PG8_LDB(B0, 1, 0); PG8_LDB(B1, 1, 1); PG8_SCHED; PG8_LDA(At, 1, 0); PG8_STAGE(PG8_SA(0, 1), a2 + hA, voffA);
;             PG8_WAIT_V(8); PG8_WAIT_L(0); PG8_BAR; PG8_MMA(0, 0, At, B0); PG8_MMA(0, 1, At, B1); PG8_BAR; PG8_SCHED;
	s_setprio 1
	v_mfma_f32_16x16x32_bf16 v[60:63], v[134:137], v[182:185], 0
	v_mfma_f32_16x16x32_bf16 v[56:59], v[150:153], v[182:185], 0
	v_mfma_f32_16x16x32_bf16 v[48:51], v[134:137], v[190:193], 0
	v_mfma_f32_16x16x32_bf16 v[40:43], v[150:153], v[190:193], 0
	v_mfma_f32_16x16x32_bf16 v[32:35], v[134:137], v[198:201], 0
	v_mfma_f32_16x16x32_bf16 v[24:27], v[150:153], v[198:201], 0
	v_mfma_f32_16x16x32_bf16 v[16:19], v[134:137], v[206:209], 0
	v_mfma_f32_16x16x32_bf16 v[8:11], v[150:153], v[206:209], 0
	v_mfma_f32_16x16x32_bf16 v[60:63], v[146:149], v[186:189], v[60:63]
	v_mfma_f32_16x16x32_bf16 v[56:59], v[154:157], v[186:189], v[56:59]
	v_mfma_f32_16x16x32_bf16 v[48:51], v[146:149], v[194:197], v[48:51]
	v_mfma_f32_16x16x32_bf16 v[40:43], v[154:157], v[194:197], v[40:43]
	v_mfma_f32_16x16x32_bf16 v[32:35], v[146:149], v[202:205], v[32:35]
	v_mfma_f32_16x16x32_bf16 v[24:27], v[154:157], v[202:205], v[24:27]
	v_mfma_f32_16x16x32_bf16 v[16:19], v[146:149], v[210:213], v[16:19]
	v_mfma_f32_16x16x32_bf16 v[8:11], v[154:157], v[210:213], v[8:11]
	s_setprio 0
	s_setprio 1
	v_mfma_f32_16x16x32_bf16 v[52:55], v[158:161], v[182:185], 0
	v_mfma_f32_16x16x32_bf16 v[44:47], v[174:177], v[182:185], 0
	v_mfma_f32_16x16x32_bf16 v[36:39], v[158:161], v[190:193], 0
	v_mfma_f32_16x16x32_bf16 v[28:31], v[174:177], v[190:193], 0
	v_mfma_f32_16x16x32_bf16 v[20:23], v[158:161], v[198:201], 0
	v_mfma_f32_16x16x32_bf16 v[12:15], v[174:177], v[198:201], 0
	v_mfma_f32_16x16x32_bf16 v[4:7], v[158:161], v[206:209], 0
	v_mfma_f32_16x16x32_bf16 v[0:3], v[174:177], v[206:209], 0
	v_mfma_f32_16x16x32_bf16 v[52:55], v[162:165], v[186:189], v[52:55]
	v_mfma_f32_16x16x32_bf16 v[44:47], v[178:181], v[186:189], v[44:47]
	v_mfma_f32_16x16x32_bf16 v[36:39], v[162:165], v[194:197], v[36:39]
	v_mfma_f32_16x16x32_bf16 v[28:31], v[178:181], v[194:197], v[28:31]
	v_mfma_f32_16x16x32_bf16 v[20:23], v[162:165], v[202:205], v[20:23]
	v_mfma_f32_16x16x32_bf16 v[12:15], v[178:181], v[202:205], v[12:15]
	v_mfma_f32_16x16x32_bf16 v[4:7], v[162:165], v[210:213], v[4:7]
	v_mfma_f32_16x16x32_bf16 v[0:3], v[178:181], v[210:213], v[0:3]
	s_setprio 0
	s_barrier
	v_add_u32_e32 v140, s64, v141
	ds_read_b128 v[134:137], v140
	ds_read_b128 v[146:149], v140 offset:1024
	ds_read_b128 v[150:153], v140 offset:2048
	ds_read_b128 v[154:157], v140 offset:3072
	v_add_u32_e32 v140, s63, v141
	ds_read_b128 v[158:161], v140
	ds_read_b128 v[162:165], v140 offset:1024
	ds_read_b128 v[174:177], v140 offset:2048
	ds_read_b128 v[178:181], v140 offset:3072
	s_mov_b32 m0, s53
	v_lshl_add_u64 v[216:217], s[40:41], 0, v[128:129]
	ds_read_b128 v[182:185], v145 offset:32768
	ds_read_b128 v[186:189], v145 offset:33792
	ds_read_b128 v[190:193], v145 offset:34816
	ds_read_b128 v[194:197], v145 offset:35840
	ds_read_b128 v[198:201], v145 offset:36864
	ds_read_b128 v[202:205], v145 offset:37888
	ds_read_b128 v[206:209], v145 offset:38912
	ds_read_b128 v[210:213], v145 offset:39936
	global_load_lds_dwordx4 v[216:217], off
	v_lshl_add_u64 v[216:217], s[40:41], 0, v[130:131]
	s_mov_b32 m0, s54
	s_nop 0
	global_load_lds_dwordx4 v[216:217], off
	s_waitcnt vmcnt(8)
	s_waitcnt lgkmcnt(0)
	s_barrier
	s_setprio 1
	v_mfma_f32_16x16x32_bf16 v[124:127], v[134:137], v[182:185], v[124:127]
	v_mfma_f32_16x16x32_bf16 v[120:123], v[150:153], v[182:185], v[120:123]
	v_mfma_f32_16x16x32_bf16 v[108:111], v[134:137], v[190:193], v[108:111]
	v_mfma_f32_16x16x32_bf16 v[104:107], v[150:153], v[190:193], v[104:107]
	v_mfma_f32_16x16x32_bf16 v[92:95], v[134:137], v[198:201], v[92:95]
	v_mfma_f32_16x16x32_bf16 v[88:91], v[150:153], v[198:201], v[88:91]
	v_mfma_f32_16x16x32_bf16 v[76:79], v[134:137], v[206:209], v[76:79]
	v_mfma_f32_16x16x32_bf16 v[72:75], v[150:153], v[206:209], v[72:75]
	v_mfma_f32_16x16x32_bf16 v[124:127], v[146:149], v[186:189], v[124:127]
	v_mfma_f32_16x16x32_bf16 v[120:123], v[154:157], v[186:189], v[120:123]
	v_mfma_f32_16x16x32_bf16 v[108:111], v[146:149], v[194:197], v[108:111]
	v_mfma_f32_16x16x32_bf16 v[104:107], v[154:157], v[194:197], v[104:107]
	v_mfma_f32_16x16x32_bf16 v[92:95], v[146:149], v[202:205], v[92:95]
	v_mfma_f32_16x16x32_bf16 v[88:91], v[154:157], v[202:205], v[88:91]
	v_mfma_f32_16x16x32_bf16 v[76:79], v[146:149], v[210:213], v[76:79]
	v_mfma_f32_16x16x32_bf16 v[72:75], v[154:157], v[210:213], v[72:75]
	s_setprio 0
	s_setprio 1
	v_mfma_f32_16x16x32_bf16 v[116:119], v[158:161], v[182:185], v[116:119]
	v_mfma_f32_16x16x32_bf16 v[112:115], v[174:177], v[182:185], v[112:115]
	v_mfma_f32_16x16x32_bf16 v[100:103], v[158:161], v[190:193], v[100:103]
	v_mfma_f32_16x16x32_bf16 v[96:99], v[174:177], v[190:193], v[96:99]
	v_mfma_f32_16x16x32_bf16 v[84:87], v[158:161], v[198:201], v[84:87]
	v_mfma_f32_16x16x32_bf16 v[80:83], v[174:177], v[198:201], v[80:83]
	v_mfma_f32_16x16x32_bf16 v[68:71], v[158:161], v[206:209], v[68:71]
	v_mfma_f32_16x16x32_bf16 v[64:67], v[174:177], v[206:209], v[64:67]
	v_mfma_f32_16x16x32_bf16 v[116:119], v[162:165], v[186:189], v[116:119]
	v_mfma_f32_16x16x32_bf16 v[112:115], v[178:181], v[186:189], v[112:115]
	v_mfma_f32_16x16x32_bf16 v[100:103], v[162:165], v[194:197], v[100:103]
	v_mfma_f32_16x16x32_bf16 v[96:99], v[178:181], v[194:197], v[96:99]
	v_mfma_f32_16x16x32_bf16 v[84:87], v[162:165], v[202:205], v[84:87]
	v_mfma_f32_16x16x32_bf16 v[80:83], v[178:181], v[202:205], v[80:83]
	v_mfma_f32_16x16x32_bf16 v[68:71], v[162:165], v[210:213], v[68:71]
	v_mfma_f32_16x16x32_bf16 v[64:67], v[178:181], v[210:213], v[64:67]
	s_setprio 0
	s_barrier
; #define PG8_STAGE(bufoff, gbase, voff) do { _Pragma("unroll") for (int _i = 0; _i < 2; ++_i) \
;         __builtin_amdgcn_global_load_lds((const unsigned*)((const char*)(gbase) + (voff)[_i]), (LAS unsigned*)(lds + (bufoff) + ldsw + _i * 8192), 16, 0, 0); } while (0)
; #define PG8_LDA(dst, b, h) do { _Pragma("unroll") for (int m = 0; m < 4; ++m) _Pragma("unroll") for (int k = 0; k < 2; ++k) dst[m][k] = *(const LAS bf16x8*)(lds + PG8_SA(b, h) + aoff + m * 2048 + k * 1024); } while (0)
; #define PG8_LDB(dst, b, h) do { _Pragma("unroll") for (int n = 0; n < 2; ++n) _Pragma("unroll") for (int k = 0; k < 2; ++k) dst[n][k] = *(const LAS bf16x8*)(lds + PG8_SB(b, h) + boff + n * 2048 + k * 1024); } while (0)
; #define PG8_WAIT_V(n) asm volatile("s_waitcnt vmcnt(" #n ")" ::: "memory")
; #define PG8_BAR __builtin_amdgcn_s_barrier()
; template <class Epi, bool ALIGN_EPI>
; __device__ __forceinline__ void gemm_phase(LAS unsigned char* lds, const Gemm g, const StaticOrder& S, const Epi& E, const int tid) {
;     ...
;         for (int t = 0; t < nt; t += 2) {
;             const bool last = (t == nt - 2);
;             const char* a1 = cA + (size_t)(t + 1) * kstep;
;             const char* a2 = last ? nA : cA + (size_t)(t + 2) * kstep; const char* b2 = last ? nB : cB + (size_t)(t + 2) * kstep;
;             const char* a3 = a2 + kstep; const char* b3 = b2 + kstep;
;             PG8_LDB(B0, 0, 0); PG8_LDB(B1, 0, 1); PG8_SCHED; PG8_LDA(At, 0, 0); PG8_STAGE(PG8_SA(1, 1), a1 + hA, voffA);
;             PG8_WAIT_V(8); PG8_WAIT_L(0); PG8_BAR; PG8_MMA(0, 0, At, B0); PG8_MMA(0, 1, At, B1); PG8_BAR; PG8_SCHED;
;             PG8_LDA(At, 0, 1); PG8_STAGE(PG8_SB(0, 0), b2, voffB); PG8_STAGE(PG8_SB(0, 1), b2 + hB, voffB); PG8_STAGE(PG8_SA(0, 0), a2, voffA);
;             PG8_WAIT_V(8); PG8_WAIT_L(0); PG8_BAR; PG8_MMA(1, 0, At, B0); PG8_MMA(1, 1, At, B1); PG8_BAR; PG8_SCHED;
;             PG8_LDB(B0, 1, 0); PG8_LDB(B1, 1, 1); PG8_SCHED; PG8_LDA(At, 1, 0); PG8_STAGE(PG8_SA(0, 1), a2 + hA, voffA);
;             PG8_WAIT_V(8); PG8_WAIT_L(0); PG8_BAR; PG8_MMA(0, 0, At, B0); PG8_MMA(0, 1, At, B1); PG8_BAR; PG8_SCHED;
;             PG8_LDA(At, 1, 1); PG8_STAGE(PG8_SB(1, 0), b3, voffB); PG8_STAGE(PG8_SB(1, 1), b3 + hB, voffB); PG8_STAGE(PG8_SA(1, 0), a3, voffA);
;             PG8_WAIT_V(8); PG8_WAIT_L(0); PG8_BAR; PG8_MMA(1, 0, At, B0); PG8_MMA(1, 1, At, B1); PG8_BAR; PG8_SCHED;
	s_mov_b32 m0, s62
	v_lshl_add_u64 v[138:139], v[138:139], 0, s[92:93]
	ds_read_b128 v[182:185], v145 offset:49152
	ds_read_b128 v[186:189], v145 offset:50176
	ds_read_b128 v[190:193], v145 offset:51200
	ds_read_b128 v[194:197], v145 offset:52224
	ds_read_b128 v[198:201], v145 offset:53248
	ds_read_b128 v[202:205], v145 offset:54272
	ds_read_b128 v[206:209], v145 offset:55296
	ds_read_b128 v[210:213], v145 offset:56320
	global_load_lds_dwordx4 v[138:139], off
	v_lshl_add_u64 v[138:139], v[142:143], 0, s[92:93]
	s_mov_b32 m0, s61
	s_nop 0
	global_load_lds_dwordx4 v[138:139], off
	v_lshl_add_u64 v[138:139], s[38:39], 0, v[168:169]
	s_mov_b32 m0, s70
	s_nop 0
	global_load_lds_dwordx4 v[138:139], off
	v_lshl_add_u64 v[138:139], s[38:39], 0, v[132:133]
	s_mov_b32 m0, s69
	s_nop 0
	global_load_lds_dwordx4 v[138:139], off
	v_lshl_add_u64 v[138:139], v[166:167], 0, s[92:93]
	s_mov_b32 m0, s55
	s_nop 0
	global_load_lds_dwordx4 v[138:139], off
	v_lshl_add_u64 v[138:139], v[214:215], 0, s[92:93]
	s_mov_b32 m0, s56
	s_nop 0
	global_load_lds_dwordx4 v[138:139], off
	s_waitcnt vmcnt(8)
	s_waitcnt lgkmcnt(0)
	s_barrier
	s_setprio 1
	v_mfma_f32_16x16x32_bf16 v[60:63], v[134:137], v[182:185], v[60:63]
	v_mfma_f32_16x16x32_bf16 v[56:59], v[150:153], v[182:185], v[56:59]
	v_mfma_f32_16x16x32_bf16 v[48:51], v[134:137], v[190:193], v[48:51]
	v_mfma_f32_16x16x32_bf16 v[40:43], v[150:153], v[190:193], v[40:43]
	v_mfma_f32_16x16x32_bf16 v[32:35], v[134:137], v[198:201], v[32:35]
	v_mfma_f32_16x16x32_bf16 v[24:27], v[150:153], v[198:201], v[24:27]
	v_mfma_f32_16x16x32_bf16 v[16:19], v[134:137], v[206:209], v[16:19]
	v_mfma_f32_16x16x32_bf16 v[8:11], v[150:153], v[206:209], v[8:11]
	v_mfma_f32_16x16x32_bf16 v[60:63], v[146:149], v[186:189], v[60:63]
	v_mfma_f32_16x16x32_bf16 v[56:59], v[154:157], v[186:189], v[56:59]
	v_mfma_f32_16x16x32_bf16 v[48:51], v[146:149], v[194:197], v[48:51]
	v_mfma_f32_16x16x32_bf16 v[40:43], v[154:157], v[194:197], v[40:43]
	v_mfma_f32_16x16x32_bf16 v[32:35], v[146:149], v[202:205], v[32:35]
	v_mfma_f32_16x16x32_bf16 v[24:27], v[154:157], v[202:205], v[24:27]
	v_mfma_f32_16x16x32_bf16 v[16:19], v[146:149], v[210:213], v[16:19]
	v_mfma_f32_16x16x32_bf16 v[8:11], v[154:157], v[210:213], v[8:11]
	s_setprio 0
	s_setprio 1
	v_mfma_f32_16x16x32_bf16 v[52:55], v[158:161], v[182:185], v[52:55]
	v_mfma_f32_16x16x32_bf16 v[44:47], v[174:177], v[182:185], v[44:47]
	v_mfma_f32_16x16x32_bf16 v[36:39], v[158:161], v[190:193], v[36:39]
	v_mfma_f32_16x16x32_bf16 v[28:31], v[174:177], v[190:193], v[28:31]
	v_mfma_f32_16x16x32_bf16 v[20:23], v[158:161], v[198:201], v[20:23]
	v_mfma_f32_16x16x32_bf16 v[12:15], v[174:177], v[198:201], v[12:15]
	v_mfma_f32_16x16x32_bf16 v[4:7], v[158:161], v[206:209], v[4:7]
	v_mfma_f32_16x16x32_bf16 v[0:3], v[174:177], v[206:209], v[0:3]
	v_mfma_f32_16x16x32_bf16 v[52:55], v[162:165], v[186:189], v[52:55]
	v_mfma_f32_16x16x32_bf16 v[44:47], v[178:181], v[186:189], v[44:47]
	v_mfma_f32_16x16x32_bf16 v[36:39], v[162:165], v[194:197], v[36:39]
	v_mfma_f32_16x16x32_bf16 v[28:31], v[178:181], v[194:197], v[28:31]
	v_mfma_f32_16x16x32_bf16 v[20:23], v[162:165], v[202:205], v[20:23]
	v_mfma_f32_16x16x32_bf16 v[12:15], v[178:181], v[202:205], v[12:15]
	v_mfma_f32_16x16x32_bf16 v[4:7], v[162:165], v[210:213], v[4:7]
	v_mfma_f32_16x16x32_bf16 v[0:3], v[178:181], v[210:213], v[0:3]
	s_setprio 0
	s_barrier
	s_movk_i32 s40, 0x100
	s_andn2_b64 vcc, exec, s[36:37]
	s_mov_b64 s[38:39], -1
	s_mov_b64 s[36:37], 0
.LBB0_379:
	s_add_u32 s41, s34, s40
	s_addc_u32 s46, s35, 0
	s_add_u32 s44, s41, 0x100
	s_addc_u32 s45, s46, 0
	s_and_b64 s[42:43], s[38:39], exec
	s_cselect_b32 s43, s17, s45
	s_cselect_b32 s42, s59, s44
	s_add_u32 s40, s30, s40
	s_addc_u32 s44, s31, 0
	s_add_u32 s40, s40, 0x100
	s_addc_u32 s44, s44, 0
	s_and_b64 s[38:39], s[38:39], exec
	s_cselect_b32 s45, s15, s44
	s_cselect_b32 s44, s60, s40
	s_add_i32 s39, 0, 0x14000
	s_add_u32 s48, s41, 0x10080
	s_addc_u32 s49, s46, 0
	s_add_i32 s68, s33, s50
	s_add_i32 m0, s51, 0xc000
	s_add_i32 s71, s51, 0xe000
	s_add_i32 s65, s68, 0x2000
	v_add_u32_e32 v138, s33, v141
	s_add_u32 s46, s44, 0x10000
	ds_read_b128 v[134:137], v138
	ds_read_b128 v[146:149], v138 offset:1024
	ds_read_b128 v[150:153], v138 offset:2048
	ds_read_b128 v[154:157], v138 offset:3072
	v_add_u32_e32 v138, s39, v141
	s_addc_u32 s47, s45, 0
	s_add_i32 s67, s39, s50
	ds_read_b128 v[158:161], v138
	ds_read_b128 v[162:165], v138 offset:1024
	ds_read_b128 v[174:177], v138 offset:2048
	ds_read_b128 v[178:181], v138 offset:3072
	s_add_i32 s66, s67, 0x2000
	s_add_i32 s64, 0, 0x18000
	s_add_i32 s63, 0, 0x1c000
	s_add_u32 s40, s42, 0x10000
	s_addc_u32 s41, s43, 0
	s_add_i32 s62, s64, s50
	s_add_i32 s61, s62, 0x2000
	s_add_u32 s38, s44, 0x10080
	s_addc_u32 s39, s45, 0
	s_add_i32 s70, s63, s50
	s_add_i32 s69, s70, 0x2000
	v_lshl_add_u64 v[138:139], s[48:49], 0, v[128:129]
	ds_read_b128 v[182:185], v145
	ds_read_b128 v[186:189], v145 offset:1024
	ds_read_b128 v[190:193], v145 offset:2048
	ds_read_b128 v[194:197], v145 offset:3072
	ds_read_b128 v[198:201], v145 offset:4096
	ds_read_b128 v[202:205], v145 offset:5120
	ds_read_b128 v[206:209], v145 offset:6144
	ds_read_b128 v[210:213], v145 offset:7168
	global_load_lds_dwordx4 v[138:139], off
	v_lshl_add_u64 v[138:139], s[48:49], 0, v[130:131]
	s_mov_b32 m0, s71
	s_nop 0
	global_load_lds_dwordx4 v[138:139], off
	s_waitcnt vmcnt(8)
	s_waitcnt lgkmcnt(0)
	s_barrier
; #define PG8_STAGE(bufoff, gbase, voff) do { _Pragma("unroll") for (int _i = 0; _i < 2; ++_i) \
;         __builtin_amdgcn_global_load_lds((const unsigned*)((const char*)(gbase) + (voff)[_i]), (LAS unsigned*)(lds + (bufoff) + ldsw + _i * 8192), 16, 0, 0); } while (0)
; #define PG8_LDA(dst, b, h) do { _Pragma("unroll") for (int m = 0; m < 4; ++m) _Pragma("unroll") for (int k = 0; k < 2; ++k) dst[m][k] = *(const LAS bf16x8*)(lds + PG8_SA(b, h) + aoff + m * 2048 + k * 1024); } while (0)
; #define PG8_MMA(ai, bj, At, Bt) do { __builtin_amdgcn_s_setprio(1); _Pragma("unroll") for (int k = 0; k < 2; ++k) _Pragma("unroll") for (int m = 0; m < 4; ++m) _Pragma("unroll") for (int n = 0; n < 2; ++n) \
;         acc[ai][bj][m][n] = __builtin_amdgcn_mfma_f32_16x16x32_bf16(Bt[n][k], At[m][k], acc[ai][bj][m][n], 0, 0, 0); __builtin_amdgcn_s_setprio(0); } while (0)
; #define PG8_WAIT_V(n) asm volatile("s_waitcnt vmcnt(" #n ")" ::: "memory")
; #define PG8_WAIT_L(n) asm volatile("s_waitcnt lgkmcnt(" #n ")" ::: "memory")
; #define PG8_BAR __builtin_amdgcn_s_barrier()
; #define PG8_SCHED __builtin_amdgcn_sched_barrier(0)
; template <class Epi, bool ALIGN_EPI>
; __device__ __forceinline__ void gemm_phase(LAS unsigned char* lds, const Gemm g, const StaticOrder& S, const Epi& E, const int tid) {
;     ...
;             PG8_WAIT_V(8); PG8_WAIT_L(0); PG8_BAR; PG8_MMA(0, 0, At, B0); PG8_MMA(0, 1, At, B1); PG8_BAR; PG8_SCHED;
;             PG8_LDA(At, 0, 1); PG8_STAGE(PG8_SB(0, 0), b2, voffB); PG8_STAGE(PG8_SB(0, 1), b2 + hB, voffB); PG8_STAGE(PG8_SA(0, 0), a2, voffA);
;             PG8_WAIT_V(8); PG8_WAIT_L(0); PG8_BAR; PG8_MMA(1, 0, At, B0); PG8_MMA(1, 1, At, B1); PG8_BAR; PG8_SCHED;
	s_setprio 1
	v_mfma_f32_16x16x32_bf16 v[124:127], v[134:137], v[182:185], v[124:127]
	v_mfma_f32_16x16x32_bf16 v[120:123], v[150:153], v[182:185], v[120:123]
	v_mfma_f32_16x16x32_bf16 v[108:111], v[134:137], v[190:193], v[108:111]
	v_mfma_f32_16x16x32_bf16 v[104:107], v[150:153], v[190:193], v[104:107]
	v_mfma_f32_16x16x32_bf16 v[92:95], v[134:137], v[198:201], v[92:95]
	v_mfma_f32_16x16x32_bf16 v[88:91], v[150:153], v[198:201], v[88:91]
	v_mfma_f32_16x16x32_bf16 v[76:79], v[134:137], v[206:209], v[76:79]
	v_mfma_f32_16x16x32_bf16 v[72:75], v[150:153], v[206:209], v[72:75]
	v_mfma_f32_16x16x32_bf16 v[124:127], v[146:149], v[186:189], v[124:127]
	v_mfma_f32_16x16x32_bf16 v[120:123], v[154:157], v[186:189], v[120:123]
	v_mfma_f32_16x16x32_bf16 v[108:111], v[146:149], v[194:197], v[108:111]
	v_mfma_f32_16x16x32_bf16 v[104:107], v[154:157], v[194:197], v[104:107]
	v_mfma_f32_16x16x32_bf16 v[92:95], v[146:149], v[202:205], v[92:95]
	v_mfma_f32_16x16x32_bf16 v[88:91], v[154:157], v[202:205], v[88:91]
	v_mfma_f32_16x16x32_bf16 v[76:79], v[146:149], v[210:213], v[76:79]
	v_mfma_f32_16x16x32_bf16 v[72:75], v[154:157], v[210:213], v[72:75]
	s_setprio 0
	s_setprio 1
	v_mfma_f32_16x16x32_bf16 v[116:119], v[158:161], v[182:185], v[116:119]
	v_mfma_f32_16x16x32_bf16 v[112:115], v[174:177], v[182:185], v[112:115]
	v_mfma_f32_16x16x32_bf16 v[100:103], v[158:161], v[190:193], v[100:103]
	v_mfma_f32_16x16x32_bf16 v[96:99], v[174:177], v[190:193], v[96:99]
	v_mfma_f32_16x16x32_bf16 v[84:87], v[158:161], v[198:201], v[84:87]
	v_mfma_f32_16x16x32_bf16 v[80:83], v[174:177], v[198:201], v[80:83]
	v_mfma_f32_16x16x32_bf16 v[68:71], v[158:161], v[206:209], v[68:71]
	v_mfma_f32_16x16x32_bf16 v[64:67], v[174:177], v[206:209], v[64:67]
	v_mfma_f32_16x16x32_bf16 v[116:119], v[162:165], v[186:189], v[116:119]
	v_mfma_f32_16x16x32_bf16 v[112:115], v[178:181], v[186:189], v[112:115]
	v_mfma_f32_16x16x32_bf16 v[100:103], v[162:165], v[194:197], v[100:103]
	v_mfma_f32_16x16x32_bf16 v[96:99], v[178:181], v[194:197], v[96:99]
	v_mfma_f32_16x16x32_bf16 v[84:87], v[162:165], v[202:205], v[84:87]
	v_mfma_f32_16x16x32_bf16 v[80:83], v[178:181], v[202:205], v[80:83]
	v_mfma_f32_16x16x32_bf16 v[68:71], v[162:165], v[210:213], v[68:71]
	v_mfma_f32_16x16x32_bf16 v[64:67], v[178:181], v[210:213], v[64:67]
	s_setprio 0
	s_barrier
	s_mov_b32 m0, s68
	v_lshl_add_u64 v[138:139], s[44:45], 0, v[168:169]
	ds_read_b128 v[182:185], v145 offset:16384
	ds_read_b128 v[186:189], v145 offset:17408
	ds_read_b128 v[190:193], v145 offset:18432
	ds_read_b128 v[194:197], v145 offset:19456
	ds_read_b128 v[198:201], v145 offset:20480
	ds_read_b128 v[202:205], v145 offset:21504
	ds_read_b128 v[206:209], v145 offset:22528
	ds_read_b128 v[210:213], v145 offset:23552
	global_load_lds_dwordx4 v[138:139], off
	v_lshl_add_u64 v[142:143], s[44:45], 0, v[132:133]
	s_mov_b32 m0, s65
	v_lshl_add_u64 v[166:167], s[46:47], 0, v[168:169]
	global_load_lds_dwordx4 v[142:143], off
	s_mov_b32 m0, s67
	v_lshl_add_u64 v[214:215], s[42:43], 0, v[130:131]
	global_load_lds_dwordx4 v[166:167], off
	v_lshl_add_u64 v[166:167], s[46:47], 0, v[132:133]
	s_mov_b32 m0, s66
	s_nop 0
	global_load_lds_dwordx4 v[166:167], off
	v_lshl_add_u64 v[166:167], s[42:43], 0, v[128:129]
	s_mov_b32 m0, s51
	s_nop 0
	global_load_lds_dwordx4 v[166:167], off
	s_mov_b32 m0, s52
	s_nop 0
	global_load_lds_dwordx4 v[214:215], off
	s_waitcnt vmcnt(8)
	s_waitcnt lgkmcnt(0)
	s_barrier
	s_setprio 1
	v_mfma_f32_16x16x32_bf16 v[60:63], v[134:137], v[182:185], v[60:63]
	v_mfma_f32_16x16x32_bf16 v[56:59], v[150:153], v[182:185], v[56:59]
	v_mfma_f32_16x16x32_bf16 v[48:51], v[134:137], v[190:193], v[48:51]
	v_mfma_f32_16x16x32_bf16 v[40:43], v[150:153], v[190:193], v[40:43]
	v_mfma_f32_16x16x32_bf16 v[32:35], v[134:137], v[198:201], v[32:35]
	v_mfma_f32_16x16x32_bf16 v[24:27], v[150:153], v[198:201], v[24:27]
	v_mfma_f32_16x16x32_bf16 v[16:19], v[134:137], v[206:209], v[16:19]
	v_mfma_f32_16x16x32_bf16 v[8:11], v[150:153], v[206:209], v[8:11]
	v_mfma_f32_16x16x32_bf16 v[60:63], v[146:149], v[186:189], v[60:63]
	v_mfma_f32_16x16x32_bf16 v[56:59], v[154:157], v[186:189], v[56:59]
	v_mfma_f32_16x16x32_bf16 v[48:51], v[146:149], v[194:197], v[48:51]
	v_mfma_f32_16x16x32_bf16 v[40:43], v[154:157], v[194:197], v[40:43]
	v_mfma_f32_16x16x32_bf16 v[32:35], v[146:149], v[202:205], v[32:35]
	v_mfma_f32_16x16x32_bf16 v[24:27], v[154:157], v[202:205], v[24:27]
	v_mfma_f32_16x16x32_bf16 v[16:19], v[146:149], v[210:213], v[16:19]
	v_mfma_f32_16x16x32_bf16 v[8:11], v[154:157], v[210:213], v[8:11]
	s_setprio 0
	s_setprio 1
	v_mfma_f32_16x16x32_bf16 v[52:55], v[158:161], v[182:185], v[52:55]
	v_mfma_f32_16x16x32_bf16 v[44:47], v[174:177], v[182:185], v[44:47]
	v_mfma_f32_16x16x32_bf16 v[36:39], v[158:161], v[190:193], v[36:39]
	v_mfma_f32_16x16x32_bf16 v[28:31], v[174:177], v[190:193], v[28:31]
	v_mfma_f32_16x16x32_bf16 v[20:23], v[158:161], v[198:201], v[20:23]
	v_mfma_f32_16x16x32_bf16 v[12:15], v[174:177], v[198:201], v[12:15]
	v_mfma_f32_16x16x32_bf16 v[4:7], v[158:161], v[206:209], v[4:7]
	v_mfma_f32_16x16x32_bf16 v[0:3], v[174:177], v[206:209], v[0:3]
	v_mfma_f32_16x16x32_bf16 v[52:55], v[162:165], v[186:189], v[52:55]
	v_mfma_f32_16x16x32_bf16 v[44:47], v[178:181], v[186:189], v[44:47]
	v_mfma_f32_16x16x32_bf16 v[36:39], v[162:165], v[194:197], v[36:39]
	v_mfma_f32_16x16x32_bf16 v[28:31], v[178:181], v[194:197], v[28:31]
	v_mfma_f32_16x16x32_bf16 v[20:23], v[162:165], v[202:205], v[20:23]
	v_mfma_f32_16x16x32_bf16 v[12:15], v[178:181], v[202:205], v[12:15]
	v_mfma_f32_16x16x32_bf16 v[4:7], v[162:165], v[210:213], v[4:7]
	v_mfma_f32_16x16x32_bf16 v[0:3], v[178:181], v[210:213], v[0:3]
	s_setprio 0
	s_barrier
; #define PG8_STAGE(bufoff, gbase, voff) do { _Pragma("unroll") for (int _i = 0; _i < 2; ++_i) \
;         __builtin_amdgcn_global_load_lds((const unsigned*)((const char*)(gbase) + (voff)[_i]), (LAS unsigned*)(lds + (bufoff) + ldsw + _i * 8192), 16, 0, 0); } while (0)
; #define PG8_LDA(dst, b, h) do { _Pragma("unroll") for (int m = 0; m < 4; ++m) _Pragma("unroll") for (int k = 0; k < 2; ++k) dst[m][k] = *(const LAS bf16x8*)(lds + PG8_SA(b, h) + aoff + m * 2048 + k * 1024); } while (0)
; #define PG8_LDB(dst, b, h) do { _Pragma("unroll") for (int n = 0; n < 2; ++n) _Pragma("unroll") for (int k = 0; k < 2; ++k) dst[n][k] = *(const LAS bf16x8*)(lds + PG8_SB(b, h) + boff + n * 2048 + k * 1024); } while (0)
; #define PG8_MMA(ai, bj, At, Bt) do { __builtin_amdgcn_s_setprio(1); _Pragma("unroll") for (int k = 0; k < 2; ++k) _Pragma("unroll") for (int m = 0; m < 4; ++m) _Pragma("unroll") for (int n = 0; n < 2; ++n) \
;         acc[ai][bj][m][n] = __builtin_amdgcn_mfma_f32_16x16x32_bf16(Bt[n][k], At[m][k], acc[ai][bj][m][n], 0, 0, 0); __builtin_amdgcn_s_setprio(0); } while (0)
; #define PG8_WAIT_V(n) asm volatile("s_waitcnt vmcnt(" #n ")" ::: "memory")
; #define PG8_WAIT_L(n) asm volatile("s_waitcnt lgkmcnt(" #n ")" ::: "memory")
; #define PG8_BAR __builtin_amdgcn_s_barrier()
; template <class Epi, bool ALIGN_EPI>
; __device__ __forceinline__ void gemm_phase(LAS unsigned char* lds, const Gemm g, const StaticOrder& S, const Epi& E, const int tid) {
;     ...
;             PG8_WAIT_V(8); PG8_WAIT_L(0); PG8_BAR; PG8_MMA(1, 0, At, B0); PG8_MMA(1, 1, At, B1); PG8_BAR; PG8_SCHED;
;             PG8_LDB(B0, 1, 0); PG8_LDB(B1, 1, 1); PG8_SCHED; PG8_LDA(At, 1, 0); PG8_STAGE(PG8_SA(0, 1), a2 + hA, voffA);
;             PG8_WAIT_V(8); PG8_WAIT_L(0); PG8_BAR; PG8_MMA(0, 0, At, B0); PG8_MMA(0, 1, At, B1); PG8_BAR; PG8_SCHED;
;             PG8_LDA(At, 1, 1); PG8_STAGE(PG8_SB(1, 0), b3, voffB); PG8_STAGE(PG8_SB(1, 1), b3 + hB, voffB); PG8_STAGE(PG8_SA(1, 0), a3, voffA);
;             PG8_WAIT_V(8); PG8_WAIT_L(0); PG8_BAR; PG8_MMA(1, 0, At, B0); PG8_MMA(1, 1, At, B1); PG8_BAR; PG8_SCHED;
;         }
;         if constexpr (ALIGN_EPI) { if (wr == 0) PG8_BAR; }
;         { int t2 = tid; asm volatile("" : "+v"(t2)); const int l2 = t2 & 63, w2 = __builtin_amdgcn_readfirstlane(t2 >> 6); E(acc, cur, w2 >> 2, w2 & 3, l2 & 15, l2 >> 4); }
;         if (!has_next) break;
	v_add_u32_e32 v140, s64, v141
	ds_read_b128 v[134:137], v140
	ds_read_b128 v[146:149], v140 offset:1024
	ds_read_b128 v[150:153], v140 offset:2048
	ds_read_b128 v[154:157], v140 offset:3072
	v_add_u32_e32 v140, s63, v141
	ds_read_b128 v[158:161], v140
	ds_read_b128 v[162:165], v140 offset:1024
	ds_read_b128 v[174:177], v140 offset:2048
	ds_read_b128 v[178:181], v140 offset:3072
	s_mov_b32 m0, s53
	v_lshl_add_u64 v[216:217], s[40:41], 0, v[128:129]
	ds_read_b128 v[182:185], v145 offset:32768
	ds_read_b128 v[186:189], v145 offset:33792
	ds_read_b128 v[190:193], v145 offset:34816
	ds_read_b128 v[194:197], v145 offset:35840
	ds_read_b128 v[198:201], v145 offset:36864
	ds_read_b128 v[202:205], v145 offset:37888
	ds_read_b128 v[206:209], v145 offset:38912
	ds_read_b128 v[210:213], v145 offset:39936
	global_load_lds_dwordx4 v[216:217], off
	v_lshl_add_u64 v[216:217], s[40:41], 0, v[130:131]
	s_mov_b32 m0, s54
	s_nop 0
	global_load_lds_dwordx4 v[216:217], off
	s_waitcnt vmcnt(8)
	s_waitcnt lgkmcnt(0)
	s_barrier
	s_setprio 1
	v_mfma_f32_16x16x32_bf16 v[124:127], v[134:137], v[182:185], v[124:127]
	v_mfma_f32_16x16x32_bf16 v[120:123], v[150:153], v[182:185], v[120:123]
	v_mfma_f32_16x16x32_bf16 v[108:111], v[134:137], v[190:193], v[108:111]
	v_mfma_f32_16x16x32_bf16 v[104:107], v[150:153], v[190:193], v[104:107]
	v_mfma_f32_16x16x32_bf16 v[92:95], v[134:137], v[198:201], v[92:95]
	v_mfma_f32_16x16x32_bf16 v[88:91], v[150:153], v[198:201], v[88:91]
	v_mfma_f32_16x16x32_bf16 v[76:79], v[134:137], v[206:209], v[76:79]
	v_mfma_f32_16x16x32_bf16 v[72:75], v[150:153], v[206:209], v[72:75]
	v_mfma_f32_16x16x32_bf16 v[124:127], v[146:149], v[186:189], v[124:127]
	v_mfma_f32_16x16x32_bf16 v[120:123], v[154:157], v[186:189], v[120:123]
	v_mfma_f32_16x16x32_bf16 v[108:111], v[146:149], v[194:197], v[108:111]
	v_mfma_f32_16x16x32_bf16 v[104:107], v[154:157], v[194:197], v[104:107]
	v_mfma_f32_16x16x32_bf16 v[92:95], v[146:149], v[202:205], v[92:95]
	v_mfma_f32_16x16x32_bf16 v[88:91], v[154:157], v[202:205], v[88:91]
	v_mfma_f32_16x16x32_bf16 v[76:79], v[146:149], v[210:213], v[76:79]
	v_mfma_f32_16x16x32_bf16 v[72:75], v[154:157], v[210:213], v[72:75]
	s_setprio 0
	s_setprio 1
	v_mfma_f32_16x16x32_bf16 v[116:119], v[158:161], v[182:185], v[116:119]
	v_mfma_f32_16x16x32_bf16 v[112:115], v[174:177], v[182:185], v[112:115]
	v_mfma_f32_16x16x32_bf16 v[100:103], v[158:161], v[190:193], v[100:103]
	v_mfma_f32_16x16x32_bf16 v[96:99], v[174:177], v[190:193], v[96:99]
	v_mfma_f32_16x16x32_bf16 v[84:87], v[158:161], v[198:201], v[84:87]
	v_mfma_f32_16x16x32_bf16 v[80:83], v[174:177], v[198:201], v[80:83]
	v_mfma_f32_16x16x32_bf16 v[68:71], v[158:161], v[206:209], v[68:71]
	v_mfma_f32_16x16x32_bf16 v[64:67], v[174:177], v[206:209], v[64:67]
	v_mfma_f32_16x16x32_bf16 v[116:119], v[162:165], v[186:189], v[116:119]
	v_mfma_f32_16x16x32_bf16 v[112:115], v[178:181], v[186:189], v[112:115]
	v_mfma_f32_16x16x32_bf16 v[100:103], v[162:165], v[194:197], v[100:103]
	v_mfma_f32_16x16x32_bf16 v[96:99], v[178:181], v[194:197], v[96:99]
	v_mfma_f32_16x16x32_bf16 v[84:87], v[162:165], v[202:205], v[84:87]
	v_mfma_f32_16x16x32_bf16 v[80:83], v[178:181], v[202:205], v[80:83]
	v_mfma_f32_16x16x32_bf16 v[68:71], v[162:165], v[210:213], v[68:71]
	v_mfma_f32_16x16x32_bf16 v[64:67], v[178:181], v[210:213], v[64:67]
	s_setprio 0
	s_barrier
	s_mov_b32 m0, s62
	v_lshl_add_u64 v[138:139], v[138:139], 0, s[92:93]
	ds_read_b128 v[182:185], v145 offset:49152
	ds_read_b128 v[186:189], v145 offset:50176
	ds_read_b128 v[190:193], v145 offset:51200
	ds_read_b128 v[194:197], v145 offset:52224
	ds_read_b128 v[198:201], v145 offset:53248
	ds_read_b128 v[202:205], v145 offset:54272
	ds_read_b128 v[206:209], v145 offset:55296
	ds_read_b128 v[210:213], v145 offset:56320
	global_load_lds_dwordx4 v[138:139], off
	v_lshl_add_u64 v[138:139], v[142:143], 0, s[92:93]
	s_mov_b32 m0, s61
	s_nop 0
	global_load_lds_dwordx4 v[138:139], off
	v_lshl_add_u64 v[138:139], s[38:39], 0, v[168:169]
	s_mov_b32 m0, s70
	s_nop 0
	global_load_lds_dwordx4 v[138:139], off
	v_lshl_add_u64 v[138:139], s[38:39], 0, v[132:133]
	s_mov_b32 m0, s69
	s_nop 0
	global_load_lds_dwordx4 v[138:139], off
	v_lshl_add_u64 v[138:139], v[166:167], 0, s[92:93]
	s_mov_b32 m0, s55
	s_nop 0
	global_load_lds_dwordx4 v[138:139], off
	v_lshl_add_u64 v[138:139], v[214:215], 0, s[92:93]
	s_mov_b32 m0, s56
	s_nop 0
	global_load_lds_dwordx4 v[138:139], off
	s_waitcnt vmcnt(8)
	s_waitcnt lgkmcnt(0)
	s_barrier
	s_setprio 1
	v_mfma_f32_16x16x32_bf16 v[60:63], v[134:137], v[182:185], v[60:63]
	v_mfma_f32_16x16x32_bf16 v[56:59], v[150:153], v[182:185], v[56:59]
	v_mfma_f32_16x16x32_bf16 v[48:51], v[134:137], v[190:193], v[48:51]
	v_mfma_f32_16x16x32_bf16 v[40:43], v[150:153], v[190:193], v[40:43]
	v_mfma_f32_16x16x32_bf16 v[32:35], v[134:137], v[198:201], v[32:35]
	v_mfma_f32_16x16x32_bf16 v[24:27], v[150:153], v[198:201], v[24:27]
	v_mfma_f32_16x16x32_bf16 v[16:19], v[134:137], v[206:209], v[16:19]
	v_mfma_f32_16x16x32_bf16 v[8:11], v[150:153], v[206:209], v[8:11]
	v_mfma_f32_16x16x32_bf16 v[60:63], v[146:149], v[186:189], v[60:63]
	v_mfma_f32_16x16x32_bf16 v[56:59], v[154:157], v[186:189], v[56:59]
	v_mfma_f32_16x16x32_bf16 v[48:51], v[146:149], v[194:197], v[48:51]
	v_mfma_f32_16x16x32_bf16 v[40:43], v[154:157], v[194:197], v[40:43]
	v_mfma_f32_16x16x32_bf16 v[32:35], v[146:149], v[202:205], v[32:35]
	v_mfma_f32_16x16x32_bf16 v[24:27], v[154:157], v[202:205], v[24:27]
	v_mfma_f32_16x16x32_bf16 v[16:19], v[146:149], v[210:213], v[16:19]
	v_mfma_f32_16x16x32_bf16 v[8:11], v[154:157], v[210:213], v[8:11]
	s_setprio 0
	s_setprio 1
	v_mfma_f32_16x16x32_bf16 v[52:55], v[158:161], v[182:185], v[52:55]
	v_mfma_f32_16x16x32_bf16 v[44:47], v[174:177], v[182:185], v[44:47]
	v_mfma_f32_16x16x32_bf16 v[36:39], v[158:161], v[190:193], v[36:39]
	v_mfma_f32_16x16x32_bf16 v[28:31], v[174:177], v[190:193], v[28:31]
	v_mfma_f32_16x16x32_bf16 v[20:23], v[158:161], v[198:201], v[20:23]
	v_mfma_f32_16x16x32_bf16 v[12:15], v[174:177], v[198:201], v[12:15]
	v_mfma_f32_16x16x32_bf16 v[4:7], v[158:161], v[206:209], v[4:7]
	v_mfma_f32_16x16x32_bf16 v[0:3], v[174:177], v[206:209], v[0:3]
	v_mfma_f32_16x16x32_bf16 v[52:55], v[162:165], v[186:189], v[52:55]
	v_mfma_f32_16x16x32_bf16 v[44:47], v[178:181], v[186:189], v[44:47]
	v_mfma_f32_16x16x32_bf16 v[36:39], v[162:165], v[194:197], v[36:39]
	v_mfma_f32_16x16x32_bf16 v[28:31], v[178:181], v[194:197], v[28:31]
	v_mfma_f32_16x16x32_bf16 v[20:23], v[162:165], v[202:205], v[20:23]
	v_mfma_f32_16x16x32_bf16 v[12:15], v[178:181], v[202:205], v[12:15]
	v_mfma_f32_16x16x32_bf16 v[4:7], v[162:165], v[210:213], v[4:7]
	v_mfma_f32_16x16x32_bf16 v[0:3], v[178:181], v[210:213], v[0:3]
	s_setprio 0
	s_barrier
	s_movk_i32 s40, 0x100
	s_andn2_b64 vcc, exec, s[36:37]
	s_mov_b64 s[38:39], -1
	s_mov_b64 s[36:37], 0
	s_cbranch_vccz .LBB0_379
	v_readlane_b32 s60, v255, 51
	s_and_b64 vcc, exec, s[12:13]
	v_readlane_b32 s61, v255, 52
	s_cbranch_vccz .LBB0_382
	s_barrier
